# K-loops: dropped placeholder s_nops not needed for the m0->LDS-DMA wait state and the back-to-back s_setprio 0/1 pairs between MFMA groups; on top of v38
# speedup vs baseline: 1.0210x; 1.0038x over previous
; #define PG8_STAGE(bufoff, gbase, voff) do { _Pragma("unroll") for (int _i = 0; _i < 2; ++_i) \
;         __builtin_amdgcn_global_load_lds((const unsigned*)((const char*)(gbase) + (voff)[_i]), (PG8_LAS unsigned*)(lds + (bufoff) + ldsw + _i * 8192), 16, 0, 0); } while (0)
; #define PG8_LDA(dst, b, h) do { _Pragma("unroll") for (int m = 0; m < 4; ++m) _Pragma("unroll") for (int k = 0; k < 2; ++k) dst[m][k] = *(const PG8_LAS bf16x8*)(lds + PG8_SA(b, h) + aoff + m * 2048 + k * 1024); } while (0)
; #define PG8_LDB(dst, b, h) do { _Pragma("unroll") for (int n = 0; n < 2; ++n) _Pragma("unroll") for (int k = 0; k < 2; ++k) dst[n][k] = *(const PG8_LAS bf16x8*)(lds + PG8_SB(b, h) + boff + n * 2048 + k * 1024); } while (0)
; #define PG8_SCHED __builtin_amdgcn_sched_barrier(0)
; template <class Epi, class Sched, bool ALIGN_EPI = false, bool SP2 = false>
; __device__ __forceinline__ void gemm_phase(PG8_LAS unsigned char* lds, const Gemm g, const Sched& S, const Epi& E) {
;     ...
;             const char* a1 = cA + (size_t)(t + 1) * kstep;
;             const char* a2 = last ? nA : cA + (size_t)(t + 2) * kstep; const char* b2 = last ? nB : cB + (size_t)(t + 2) * kstep;
;             const char* a3 = a2 + kstep; const char* b3 = b2 + kstep;
;             if (last && has_next) S.a_ready(nxt);
;             if constexpr (SP2) {
;             PG8_LDB(B0, 0, 0); PG8_LDB(B1, 0, 1); PG8_SCHED; PG8_LDA(At, 0, 0); PG8_STAGE(PG8_SA(1, 1), a1 + hstep, voffA);
.LBB0_66:
	ds_read_b128 v[152:155], v149
	ds_read_b128 v[156:159], v149 offset:1024
	ds_read_b128 v[160:163], v149 offset:2048
	ds_read_b128 v[164:167], v149 offset:3072
	ds_read_b128 v[168:171], v150
	ds_read_b128 v[172:175], v150 offset:1024
	ds_read_b128 v[176:179], v150 offset:2048
	ds_read_b128 v[180:183], v150 offset:3072
	s_add_u32 s42, s40, 0xfff80080
	s_addc_u32 s43, s41, -1
	s_cmp_eq_u32 s68, 28
	s_cselect_b32 s45, s35, s43
	s_cselect_b32 s44, s63, s42
	s_cselect_b32 s43, s31, s67
	s_cselect_b32 s42, s64, s65

; #define PG8_STAGE(bufoff, gbase, voff) do { _Pragma("unroll") for (int _i = 0; _i < 2; ++_i) \
;         __builtin_amdgcn_global_load_lds((const unsigned*)((const char*)(gbase) + (voff)[_i]), (PG8_LAS unsigned*)(lds + (bufoff) + ldsw + _i * 8192), 16, 0, 0); } while (0)
; #define PG8_LDA(dst, b, h) do { _Pragma("unroll") for (int m = 0; m < 4; ++m) _Pragma("unroll") for (int k = 0; k < 2; ++k) dst[m][k] = *(const PG8_LAS bf16x8*)(lds + PG8_SA(b, h) + aoff + m * 2048 + k * 1024); } while (0)
; #define PG8_LDB(dst, b, h) do { _Pragma("unroll") for (int n = 0; n < 2; ++n) _Pragma("unroll") for (int k = 0; k < 2; ++k) dst[n][k] = *(const PG8_LAS bf16x8*)(lds + PG8_SB(b, h) + boff + n * 2048 + k * 1024); } while (0)
; #define PG8_SCHED __builtin_amdgcn_sched_barrier(0)
; template <class Epi, class Sched, bool ALIGN_EPI = false, bool SP2 = false>
; __device__ __forceinline__ void gemm_phase(PG8_LAS unsigned char* lds, const Gemm g, const Sched& S, const Epi& E) {
;     ...
;             PG8_LDB(B0, 0, 0); PG8_LDB(B1, 0, 1); PG8_SCHED; PG8_LDA(At, 0, 0); PG8_STAGE(PG8_SA(1, 1), a1 + hstep, voffA);
	s_add_i32 m0, s29, 0xc000
	ds_read_b128 v[184:187], v151
	ds_read_b128 v[188:191], v151 offset:1024
	ds_read_b128 v[192:195], v151 offset:2048
	ds_read_b128 v[196:199], v151 offset:3072
	ds_read_b128 v[200:203], v151 offset:4096
	ds_read_b128 v[204:207], v151 offset:5120
	ds_read_b128 v[208:211], v151 offset:6144
	ds_read_b128 v[212:215], v151 offset:7168
	global_load_lds_dwordx4 v136, s[40:41]

; #define PG8_STAGE(bufoff, gbase, voff) do { _Pragma("unroll") for (int _i = 0; _i < 2; ++_i) \
;         __builtin_amdgcn_global_load_lds((const unsigned*)((const char*)(gbase) + (voff)[_i]), (PG8_LAS unsigned*)(lds + (bufoff) + ldsw + _i * 8192), 16, 0, 0); } while (0)
; #define PG8_LDA(dst, b, h) do { _Pragma("unroll") for (int m = 0; m < 4; ++m) _Pragma("unroll") for (int k = 0; k < 2; ++k) dst[m][k] = *(const PG8_LAS bf16x8*)(lds + PG8_SA(b, h) + aoff + m * 2048 + k * 1024); } while (0)
; #define PG8_LDB(dst, b, h) do { _Pragma("unroll") for (int n = 0; n < 2; ++n) _Pragma("unroll") for (int k = 0; k < 2; ++k) dst[n][k] = *(const PG8_LAS bf16x8*)(lds + PG8_SB(b, h) + boff + n * 2048 + k * 1024); } while (0)
; #define PG8_MMA(ai, bj, At, Bt) do { __builtin_amdgcn_s_setprio(1); _Pragma("unroll") for (int m = 0; m < 4; ++m) _Pragma("unroll") for (int n = 0; n < 2; ++n) _Pragma("unroll") for (int k = 0; k < 2; ++k) \
;         acc[ai][bj][m][n] = __builtin_amdgcn_mfma_f32_16x16x32_bf16(Bt[n][k], At[m][k], acc[ai][bj][m][n], 0, 0, 0); __builtin_amdgcn_s_setprio(0); } while (0)
; #define PG8_WAIT_V(n) asm volatile("s_waitcnt vmcnt(" #n ")" ::: "memory")
; #define PG8_WAIT_L(n) asm volatile("s_waitcnt lgkmcnt(" #n ")" ::: "memory")
; #define PG8_BAR __builtin_amdgcn_s_barrier()
; #define PG8_SCHED __builtin_amdgcn_sched_barrier(0)
; template <class Epi, class Sched, bool ALIGN_EPI = false, bool SP2 = false>
; __device__ __forceinline__ void gemm_phase(PG8_LAS unsigned char* lds, const Gemm g, const Sched& S, const Epi& E) {
;     ...
;             PG8_LDB(B0, 0, 0); PG8_LDB(B1, 0, 1); PG8_SCHED; PG8_LDA(At, 0, 0); PG8_STAGE(PG8_SA(1, 1), a1 + hstep, voffA);
;             PG8_WAIT_V(8); PG8_WAIT_L(0); PG8_BAR; PG8_MMA(0, 0, At, B0); PG8_MMA(0, 1, At, B1); PG8_BAR; PG8_SCHED;
	s_add_i32 m0, s29, 0xe000
	s_nop 0
	global_load_lds_dwordx4 v138, s[40:41]
	s_waitcnt vmcnt(8)
	s_waitcnt lgkmcnt(0)
	s_barrier
	s_setprio 1
	s_waitcnt lgkmcnt(0)
	v_mfma_f32_16x16x32_bf16 v[124:127], v[152:155], v[184:187], v[124:127]
	v_mfma_f32_16x16x32_bf16 v[120:123], v[160:163], v[184:187], v[120:123]
	v_mfma_f32_16x16x32_bf16 v[116:119], v[152:155], v[192:195], v[116:119]
	v_mfma_f32_16x16x32_bf16 v[112:115], v[160:163], v[192:195], v[112:115]
	v_mfma_f32_16x16x32_bf16 v[100:103], v[152:155], v[200:203], v[100:103]
	v_mfma_f32_16x16x32_bf16 v[96:99], v[160:163], v[200:203], v[96:99]
	v_mfma_f32_16x16x32_bf16 v[84:87], v[152:155], v[208:211], v[84:87]
	v_mfma_f32_16x16x32_bf16 v[80:83], v[160:163], v[208:211], v[80:83]
	v_mfma_f32_16x16x32_bf16 v[124:127], v[156:159], v[188:191], v[124:127]
	v_mfma_f32_16x16x32_bf16 v[120:123], v[164:167], v[188:191], v[120:123]
	v_mfma_f32_16x16x32_bf16 v[116:119], v[156:159], v[196:199], v[116:119]
	v_mfma_f32_16x16x32_bf16 v[112:115], v[164:167], v[196:199], v[112:115]
	v_mfma_f32_16x16x32_bf16 v[100:103], v[156:159], v[204:207], v[100:103]
	v_mfma_f32_16x16x32_bf16 v[96:99], v[164:167], v[204:207], v[96:99]
	v_mfma_f32_16x16x32_bf16 v[84:87], v[156:159], v[212:215], v[84:87]
	v_mfma_f32_16x16x32_bf16 v[80:83], v[164:167], v[212:215], v[80:83]


; #define PG8_STAGE(bufoff, gbase, voff) do { _Pragma("unroll") for (int _i = 0; _i < 2; ++_i) \
;         __builtin_amdgcn_global_load_lds((const unsigned*)((const char*)(gbase) + (voff)[_i]), (PG8_LAS unsigned*)(lds + (bufoff) + ldsw + _i * 8192), 16, 0, 0); } while (0)
; #define PG8_LDA(dst, b, h) do { _Pragma("unroll") for (int m = 0; m < 4; ++m) _Pragma("unroll") for (int k = 0; k < 2; ++k) dst[m][k] = *(const PG8_LAS bf16x8*)(lds + PG8_SA(b, h) + aoff + m * 2048 + k * 1024); } while (0)
; #define PG8_MMA(ai, bj, At, Bt) do { __builtin_amdgcn_s_setprio(1); _Pragma("unroll") for (int m = 0; m < 4; ++m) _Pragma("unroll") for (int n = 0; n < 2; ++n) _Pragma("unroll") for (int k = 0; k < 2; ++k) \
;         acc[ai][bj][m][n] = __builtin_amdgcn_mfma_f32_16x16x32_bf16(Bt[n][k], At[m][k], acc[ai][bj][m][n], 0, 0, 0); __builtin_amdgcn_s_setprio(0); } while (0)
; #define PG8_WAIT_V(n) asm volatile("s_waitcnt vmcnt(" #n ")" ::: "memory")
; #define PG8_WAIT_L(n) asm volatile("s_waitcnt lgkmcnt(" #n ")" ::: "memory")
; #define PG8_BAR __builtin_amdgcn_s_barrier()
; #define PG8_SCHED __builtin_amdgcn_sched_barrier(0)
; template <class Epi, class Sched, bool ALIGN_EPI = false, bool SP2 = false>
; __device__ __forceinline__ void gemm_phase(PG8_LAS unsigned char* lds, const Gemm g, const Sched& S, const Epi& E) {
;     ...
;             PG8_WAIT_V(8); PG8_WAIT_L(0); PG8_BAR; PG8_MMA(0, 0, At, B0); PG8_MMA(0, 1, At, B1); PG8_BAR; PG8_SCHED;
;             PG8_LDA(At, 0, 1); PG8_STAGE(PG8_SB(0, 0), b2, voffB); PG8_STAGE(PG8_SB(0, 1), b2 + hstep, voffB); PG8_STAGE(PG8_SA(0, 0), a2, voffA);
	v_mfma_f32_16x16x32_bf16 v[108:111], v[168:171], v[184:187], v[108:111]
	v_mfma_f32_16x16x32_bf16 v[104:107], v[176:179], v[184:187], v[104:107]
	v_mfma_f32_16x16x32_bf16 v[92:95], v[168:171], v[192:195], v[92:95]
	v_mfma_f32_16x16x32_bf16 v[88:91], v[176:179], v[192:195], v[88:91]
	v_mfma_f32_16x16x32_bf16 v[76:79], v[168:171], v[200:203], v[76:79]
	v_mfma_f32_16x16x32_bf16 v[72:75], v[176:179], v[200:203], v[72:75]
	v_mfma_f32_16x16x32_bf16 v[68:71], v[168:171], v[208:211], v[68:71]
	v_mfma_f32_16x16x32_bf16 v[64:67], v[176:179], v[208:211], v[64:67]
	v_mfma_f32_16x16x32_bf16 v[108:111], v[172:175], v[188:191], v[108:111]
	v_mfma_f32_16x16x32_bf16 v[104:107], v[180:183], v[188:191], v[104:107]
	v_mfma_f32_16x16x32_bf16 v[92:95], v[172:175], v[196:199], v[92:95]
	v_mfma_f32_16x16x32_bf16 v[88:91], v[180:183], v[196:199], v[88:91]
	v_mfma_f32_16x16x32_bf16 v[76:79], v[172:175], v[204:207], v[76:79]
	v_mfma_f32_16x16x32_bf16 v[72:75], v[180:183], v[204:207], v[72:75]
	v_mfma_f32_16x16x32_bf16 v[68:71], v[172:175], v[212:215], v[68:71]
	v_mfma_f32_16x16x32_bf16 v[64:67], v[180:183], v[212:215], v[64:67]
	s_setprio 0
	s_barrier
	s_add_i32 s69, s59, s48
	s_mov_b64 s[96:97], s[42:43]

; #define PG8_STAGE(bufoff, gbase, voff) do { _Pragma("unroll") for (int _i = 0; _i < 2; ++_i) \
;         __builtin_amdgcn_global_load_lds((const unsigned*)((const char*)(gbase) + (voff)[_i]), (PG8_LAS unsigned*)(lds + (bufoff) + ldsw + _i * 8192), 16, 0, 0); } while (0)
; #define PG8_LDA(dst, b, h) do { _Pragma("unroll") for (int m = 0; m < 4; ++m) _Pragma("unroll") for (int k = 0; k < 2; ++k) dst[m][k] = *(const PG8_LAS bf16x8*)(lds + PG8_SA(b, h) + aoff + m * 2048 + k * 1024); } while (0)
; template <class Epi, class Sched, bool ALIGN_EPI = false, bool SP2 = false>
; __device__ __forceinline__ void gemm_phase(PG8_LAS unsigned char* lds, const Gemm g, const Sched& S, const Epi& E) {
;     ...
;             PG8_LDA(At, 0, 1); PG8_STAGE(PG8_SB(0, 0), b2, voffB); PG8_STAGE(PG8_SB(0, 1), b2 + hstep, voffB); PG8_STAGE(PG8_SA(0, 0), a2, voffA);
	s_mov_b32 m0, s69
	ds_read_b128 v[184:187], v151 offset:16384
	ds_read_b128 v[188:191], v151 offset:17408
	ds_read_b128 v[192:195], v151 offset:18432
	ds_read_b128 v[196:199], v151 offset:19456
	ds_read_b128 v[200:203], v151 offset:20480
	ds_read_b128 v[204:207], v151 offset:21504
	ds_read_b128 v[208:211], v151 offset:22528
	ds_read_b128 v[212:215], v151 offset:23552
	global_load_lds_dwordx4 v132, s[42:43]
	s_add_i32 m0, s69, 0x2000
	s_add_u32 s70, s42, 0x80000

; #define PG8_STAGE(bufoff, gbase, voff) do { _Pragma("unroll") for (int _i = 0; _i < 2; ++_i) \
;         __builtin_amdgcn_global_load_lds((const unsigned*)((const char*)(gbase) + (voff)[_i]), (PG8_LAS unsigned*)(lds + (bufoff) + ldsw + _i * 8192), 16, 0, 0); } while (0)
; #define PG8_LDA(dst, b, h) do { _Pragma("unroll") for (int m = 0; m < 4; ++m) _Pragma("unroll") for (int k = 0; k < 2; ++k) dst[m][k] = *(const PG8_LAS bf16x8*)(lds + PG8_SA(b, h) + aoff + m * 2048 + k * 1024); } while (0)
; template <class Epi, class Sched, bool ALIGN_EPI = false, bool SP2 = false>
; __device__ __forceinline__ void gemm_phase(PG8_LAS unsigned char* lds, const Gemm g, const Sched& S, const Epi& E) {
;     ...
;             PG8_LDA(At, 0, 1); PG8_STAGE(PG8_SB(0, 0), b2, voffB); PG8_STAGE(PG8_SB(0, 1), b2 + hstep, voffB); PG8_STAGE(PG8_SA(0, 0), a2, voffA);
	s_addc_u32 s71, s43, 0
	s_add_i32 s69, s60, s48
	global_load_lds_dwordx4 v128, s[42:43]

; #define PG8_STAGE(bufoff, gbase, voff) do { _Pragma("unroll") for (int _i = 0; _i < 2; ++_i) \
;         __builtin_amdgcn_global_load_lds((const unsigned*)((const char*)(gbase) + (voff)[_i]), (PG8_LAS unsigned*)(lds + (bufoff) + ldsw + _i * 8192), 16, 0, 0); } while (0)
; #define PG8_LDA(dst, b, h) do { _Pragma("unroll") for (int m = 0; m < 4; ++m) _Pragma("unroll") for (int k = 0; k < 2; ++k) dst[m][k] = *(const PG8_LAS bf16x8*)(lds + PG8_SA(b, h) + aoff + m * 2048 + k * 1024); } while (0)
; template <class Epi, class Sched, bool ALIGN_EPI = false, bool SP2 = false>
; __device__ __forceinline__ void gemm_phase(PG8_LAS unsigned char* lds, const Gemm g, const Sched& S, const Epi& E) {
;     ...
;             PG8_LDA(At, 0, 1); PG8_STAGE(PG8_SB(0, 0), b2, voffB); PG8_STAGE(PG8_SB(0, 1), b2 + hstep, voffB); PG8_STAGE(PG8_SA(0, 0), a2, voffA);
	s_mov_b32 m0, s69
	s_nop 0
	global_load_lds_dwordx4 v132, s[70:71]

; #define PG8_STAGE(bufoff, gbase, voff) do { _Pragma("unroll") for (int _i = 0; _i < 2; ++_i) \
;         __builtin_amdgcn_global_load_lds((const unsigned*)((const char*)(gbase) + (voff)[_i]), (PG8_LAS unsigned*)(lds + (bufoff) + ldsw + _i * 8192), 16, 0, 0); } while (0)
; #define PG8_LDA(dst, b, h) do { _Pragma("unroll") for (int m = 0; m < 4; ++m) _Pragma("unroll") for (int k = 0; k < 2; ++k) dst[m][k] = *(const PG8_LAS bf16x8*)(lds + PG8_SA(b, h) + aoff + m * 2048 + k * 1024); } while (0)
; template <class Epi, class Sched, bool ALIGN_EPI = false, bool SP2 = false>
; __device__ __forceinline__ void gemm_phase(PG8_LAS unsigned char* lds, const Gemm g, const Sched& S, const Epi& E) {
;     ...
;             PG8_LDA(At, 0, 1); PG8_STAGE(PG8_SB(0, 0), b2, voffB); PG8_STAGE(PG8_SB(0, 1), b2 + hstep, voffB); PG8_STAGE(PG8_SA(0, 0), a2, voffA);
	s_add_i32 m0, s69, 0x2000
	s_nop 0
	global_load_lds_dwordx4 v128, s[70:71]
	s_mov_b64 s[98:99], s[44:45]

; #define PG8_STAGE(bufoff, gbase, voff) do { _Pragma("unroll") for (int _i = 0; _i < 2; ++_i) \
;         __builtin_amdgcn_global_load_lds((const unsigned*)((const char*)(gbase) + (voff)[_i]), (PG8_LAS unsigned*)(lds + (bufoff) + ldsw + _i * 8192), 16, 0, 0); } while (0)
; #define PG8_LDA(dst, b, h) do { _Pragma("unroll") for (int m = 0; m < 4; ++m) _Pragma("unroll") for (int k = 0; k < 2; ++k) dst[m][k] = *(const PG8_LAS bf16x8*)(lds + PG8_SA(b, h) + aoff + m * 2048 + k * 1024); } while (0)
; #define PG8_MMA(ai, bj, At, Bt) do { __builtin_amdgcn_s_setprio(1); _Pragma("unroll") for (int m = 0; m < 4; ++m) _Pragma("unroll") for (int n = 0; n < 2; ++n) _Pragma("unroll") for (int k = 0; k < 2; ++k) \
;         acc[ai][bj][m][n] = __builtin_amdgcn_mfma_f32_16x16x32_bf16(Bt[n][k], At[m][k], acc[ai][bj][m][n], 0, 0, 0); __builtin_amdgcn_s_setprio(0); } while (0)
; #define PG8_WAIT_V(n) asm volatile("s_waitcnt vmcnt(" #n ")" ::: "memory")
; #define PG8_WAIT_L(n) asm volatile("s_waitcnt lgkmcnt(" #n ")" ::: "memory")
; #define PG8_BAR __builtin_amdgcn_s_barrier()
; #define PG8_SCHED __builtin_amdgcn_sched_barrier(0)
; template <class Epi, class Sched, bool ALIGN_EPI = false, bool SP2 = false>
; __device__ __forceinline__ void gemm_phase(PG8_LAS unsigned char* lds, const Gemm g, const Sched& S, const Epi& E) {
;     ...
;             PG8_LDA(At, 0, 1); PG8_STAGE(PG8_SB(0, 0), b2, voffB); PG8_STAGE(PG8_SB(0, 1), b2 + hstep, voffB); PG8_STAGE(PG8_SA(0, 0), a2, voffA);
;             PG8_WAIT_V(8); PG8_WAIT_L(0); PG8_BAR; PG8_MMA(1, 0, At, B0); PG8_MMA(1, 1, At, B1); PG8_BAR; PG8_SCHED;
	s_mov_b32 m0, s29
	s_nop 0
	global_load_lds_dwordx4 v134, s[44:45]
	s_mov_b32 m0, s51
	s_nop 0
	global_load_lds_dwordx4 v130, s[44:45]
	s_waitcnt vmcnt(8)
	s_waitcnt lgkmcnt(0)
	s_barrier
	s_setprio 1
	s_waitcnt lgkmcnt(0)
	v_mfma_f32_16x16x32_bf16 v[60:63], v[152:155], v[184:187], v[60:63]
	v_mfma_f32_16x16x32_bf16 v[56:59], v[160:163], v[184:187], v[56:59]
	v_mfma_f32_16x16x32_bf16 v[52:55], v[152:155], v[192:195], v[52:55]
	v_mfma_f32_16x16x32_bf16 v[48:51], v[160:163], v[192:195], v[48:51]
	v_mfma_f32_16x16x32_bf16 v[36:39], v[152:155], v[200:203], v[36:39]
	v_mfma_f32_16x16x32_bf16 v[32:35], v[160:163], v[200:203], v[32:35]
	v_mfma_f32_16x16x32_bf16 v[20:23], v[152:155], v[208:211], v[20:23]
	v_mfma_f32_16x16x32_bf16 v[16:19], v[160:163], v[208:211], v[16:19]
	v_mfma_f32_16x16x32_bf16 v[60:63], v[156:159], v[188:191], v[60:63]
	v_mfma_f32_16x16x32_bf16 v[56:59], v[164:167], v[188:191], v[56:59]
	v_mfma_f32_16x16x32_bf16 v[52:55], v[156:159], v[196:199], v[52:55]
	v_mfma_f32_16x16x32_bf16 v[48:51], v[164:167], v[196:199], v[48:51]
	v_mfma_f32_16x16x32_bf16 v[36:39], v[156:159], v[204:207], v[36:39]
	v_mfma_f32_16x16x32_bf16 v[32:35], v[164:167], v[204:207], v[32:35]
	v_mfma_f32_16x16x32_bf16 v[20:23], v[156:159], v[212:215], v[20:23]
	v_mfma_f32_16x16x32_bf16 v[16:19], v[164:167], v[212:215], v[16:19]


; #define PG8_STAGE(bufoff, gbase, voff) do { _Pragma("unroll") for (int _i = 0; _i < 2; ++_i) \
;         __builtin_amdgcn_global_load_lds((const unsigned*)((const char*)(gbase) + (voff)[_i]), (PG8_LAS unsigned*)(lds + (bufoff) + ldsw + _i * 8192), 16, 0, 0); } while (0)
; #define PG8_LDA(dst, b, h) do { _Pragma("unroll") for (int m = 0; m < 4; ++m) _Pragma("unroll") for (int k = 0; k < 2; ++k) dst[m][k] = *(const PG8_LAS bf16x8*)(lds + PG8_SA(b, h) + aoff + m * 2048 + k * 1024); } while (0)
; #define PG8_LDB(dst, b, h) do { _Pragma("unroll") for (int n = 0; n < 2; ++n) _Pragma("unroll") for (int k = 0; k < 2; ++k) dst[n][k] = *(const PG8_LAS bf16x8*)(lds + PG8_SB(b, h) + boff + n * 2048 + k * 1024); } while (0)
; #define PG8_MMA(ai, bj, At, Bt) do { __builtin_amdgcn_s_setprio(1); _Pragma("unroll") for (int m = 0; m < 4; ++m) _Pragma("unroll") for (int n = 0; n < 2; ++n) _Pragma("unroll") for (int k = 0; k < 2; ++k) \
;         acc[ai][bj][m][n] = __builtin_amdgcn_mfma_f32_16x16x32_bf16(Bt[n][k], At[m][k], acc[ai][bj][m][n], 0, 0, 0); __builtin_amdgcn_s_setprio(0); } while (0)
; #define PG8_WAIT_V(n) asm volatile("s_waitcnt vmcnt(" #n ")" ::: "memory")
; #define PG8_WAIT_L(n) asm volatile("s_waitcnt lgkmcnt(" #n ")" ::: "memory")
; #define PG8_BAR __builtin_amdgcn_s_barrier()
; #define PG8_SCHED __builtin_amdgcn_sched_barrier(0)
; template <class Epi, class Sched, bool ALIGN_EPI = false, bool SP2 = false>
; __device__ __forceinline__ void gemm_phase(PG8_LAS unsigned char* lds, const Gemm g, const Sched& S, const Epi& E) {
;     ...
;             PG8_WAIT_V(8); PG8_WAIT_L(0); PG8_BAR; PG8_MMA(1, 0, At, B0); PG8_MMA(1, 1, At, B1); PG8_BAR; PG8_SCHED;
;             PG8_LDB(B0, 1, 0); PG8_LDB(B1, 1, 1); PG8_SCHED; PG8_LDA(At, 1, 0); PG8_STAGE(PG8_SA(0, 1), a2 + hstep, voffA);
	v_mfma_f32_16x16x32_bf16 v[44:47], v[168:171], v[184:187], v[44:47]
	v_mfma_f32_16x16x32_bf16 v[40:43], v[176:179], v[184:187], v[40:43]
	v_mfma_f32_16x16x32_bf16 v[28:31], v[168:171], v[192:195], v[28:31]
	v_mfma_f32_16x16x32_bf16 v[24:27], v[176:179], v[192:195], v[24:27]
	v_mfma_f32_16x16x32_bf16 v[12:15], v[168:171], v[200:203], v[12:15]
	v_mfma_f32_16x16x32_bf16 v[8:11], v[176:179], v[200:203], v[8:11]
	v_mfma_f32_16x16x32_bf16 v[4:7], v[168:171], v[208:211], v[4:7]
	v_mfma_f32_16x16x32_bf16 v[0:3], v[176:179], v[208:211], v[0:3]
	v_mfma_f32_16x16x32_bf16 v[44:47], v[172:175], v[188:191], v[44:47]
	v_mfma_f32_16x16x32_bf16 v[40:43], v[180:183], v[188:191], v[40:43]
	v_mfma_f32_16x16x32_bf16 v[28:31], v[172:175], v[196:199], v[28:31]
	v_mfma_f32_16x16x32_bf16 v[24:27], v[180:183], v[196:199], v[24:27]
	v_mfma_f32_16x16x32_bf16 v[12:15], v[172:175], v[204:207], v[12:15]
	v_mfma_f32_16x16x32_bf16 v[8:11], v[180:183], v[204:207], v[8:11]
	v_mfma_f32_16x16x32_bf16 v[4:7], v[172:175], v[212:215], v[4:7]
	v_mfma_f32_16x16x32_bf16 v[0:3], v[180:183], v[212:215], v[0:3]
	s_setprio 0
	s_barrier
	s_add_i32 s69, 0, 0x18000
	s_add_i32 s70, 0, 0x1c000
	v_add_u32_e32 v164, s69, v147
	v_add_u32_e32 v180, s70, v147
	ds_read_b128 v[152:155], v164
	ds_read_b128 v[156:159], v164 offset:1024
	ds_read_b128 v[160:163], v164 offset:2048
	ds_read_b128 v[164:167], v164 offset:3072
	ds_read_b128 v[168:171], v180
	ds_read_b128 v[172:175], v180 offset:1024
	ds_read_b128 v[176:179], v180 offset:2048
	ds_read_b128 v[180:183], v180 offset:3072
	s_add_u32 s44, s44, 0x80000
	s_addc_u32 s45, s45, 0
	s_mov_b32 m0, s52

; #define PG8_STAGE(bufoff, gbase, voff) do { _Pragma("unroll") for (int _i = 0; _i < 2; ++_i) \
;         __builtin_amdgcn_global_load_lds((const unsigned*)((const char*)(gbase) + (voff)[_i]), (PG8_LAS unsigned*)(lds + (bufoff) + ldsw + _i * 8192), 16, 0, 0); } while (0)
; #define PG8_LDA(dst, b, h) do { _Pragma("unroll") for (int m = 0; m < 4; ++m) _Pragma("unroll") for (int k = 0; k < 2; ++k) dst[m][k] = *(const PG8_LAS bf16x8*)(lds + PG8_SA(b, h) + aoff + m * 2048 + k * 1024); } while (0)
; #define PG8_LDB(dst, b, h) do { _Pragma("unroll") for (int n = 0; n < 2; ++n) _Pragma("unroll") for (int k = 0; k < 2; ++k) dst[n][k] = *(const PG8_LAS bf16x8*)(lds + PG8_SB(b, h) + boff + n * 2048 + k * 1024); } while (0)
; #define PG8_SCHED __builtin_amdgcn_sched_barrier(0)
; template <class Epi, class Sched, bool ALIGN_EPI = false, bool SP2 = false>
; __device__ __forceinline__ void gemm_phase(PG8_LAS unsigned char* lds, const Gemm g, const Sched& S, const Epi& E) {
;     ...
;             PG8_LDB(B0, 1, 0); PG8_LDB(B1, 1, 1); PG8_SCHED; PG8_LDA(At, 1, 0); PG8_STAGE(PG8_SA(0, 1), a2 + hstep, voffA);
	ds_read_b128 v[184:187], v151 offset:32768
	ds_read_b128 v[188:191], v151 offset:33792
	ds_read_b128 v[192:195], v151 offset:34816
	ds_read_b128 v[196:199], v151 offset:35840
	ds_read_b128 v[200:203], v151 offset:36864
	ds_read_b128 v[204:207], v151 offset:37888
	ds_read_b128 v[208:211], v151 offset:38912
	ds_read_b128 v[212:215], v151 offset:39936
	global_load_lds_dwordx4 v134, s[44:45]

; #define PG8_STAGE(bufoff, gbase, voff) do { _Pragma("unroll") for (int _i = 0; _i < 2; ++_i) \
;         __builtin_amdgcn_global_load_lds((const unsigned*)((const char*)(gbase) + (voff)[_i]), (PG8_LAS unsigned*)(lds + (bufoff) + ldsw + _i * 8192), 16, 0, 0); } while (0)
; #define PG8_LDA(dst, b, h) do { _Pragma("unroll") for (int m = 0; m < 4; ++m) _Pragma("unroll") for (int k = 0; k < 2; ++k) dst[m][k] = *(const PG8_LAS bf16x8*)(lds + PG8_SA(b, h) + aoff + m * 2048 + k * 1024); } while (0)
; #define PG8_LDB(dst, b, h) do { _Pragma("unroll") for (int n = 0; n < 2; ++n) _Pragma("unroll") for (int k = 0; k < 2; ++k) dst[n][k] = *(const PG8_LAS bf16x8*)(lds + PG8_SB(b, h) + boff + n * 2048 + k * 1024); } while (0)
; #define PG8_MMA(ai, bj, At, Bt) do { __builtin_amdgcn_s_setprio(1); _Pragma("unroll") for (int m = 0; m < 4; ++m) _Pragma("unroll") for (int n = 0; n < 2; ++n) _Pragma("unroll") for (int k = 0; k < 2; ++k) \
;         acc[ai][bj][m][n] = __builtin_amdgcn_mfma_f32_16x16x32_bf16(Bt[n][k], At[m][k], acc[ai][bj][m][n], 0, 0, 0); __builtin_amdgcn_s_setprio(0); } while (0)
; #define PG8_WAIT_V(n) asm volatile("s_waitcnt vmcnt(" #n ")" ::: "memory")
; #define PG8_WAIT_L(n) asm volatile("s_waitcnt lgkmcnt(" #n ")" ::: "memory")
; #define PG8_BAR __builtin_amdgcn_s_barrier()
; #define PG8_SCHED __builtin_amdgcn_sched_barrier(0)
; template <class Epi, class Sched, bool ALIGN_EPI = false, bool SP2 = false>
; __device__ __forceinline__ void gemm_phase(PG8_LAS unsigned char* lds, const Gemm g, const Sched& S, const Epi& E) {
;     ...
;             PG8_LDB(B0, 1, 0); PG8_LDB(B1, 1, 1); PG8_SCHED; PG8_LDA(At, 1, 0); PG8_STAGE(PG8_SA(0, 1), a2 + hstep, voffA);
;             PG8_WAIT_V(8); PG8_WAIT_L(0); PG8_BAR; PG8_MMA(0, 0, At, B0); PG8_MMA(0, 1, At, B1); PG8_BAR; PG8_SCHED;
	s_mov_b32 m0, s53
	s_nop 0
	global_load_lds_dwordx4 v130, s[44:45]
	s_waitcnt vmcnt(8)
	s_waitcnt lgkmcnt(0)
	s_barrier
	s_setprio 1
	s_waitcnt lgkmcnt(0)
	v_mfma_f32_16x16x32_bf16 v[124:127], v[152:155], v[184:187], v[124:127]
	v_mfma_f32_16x16x32_bf16 v[120:123], v[160:163], v[184:187], v[120:123]
	v_mfma_f32_16x16x32_bf16 v[116:119], v[152:155], v[192:195], v[116:119]
	v_mfma_f32_16x16x32_bf16 v[112:115], v[160:163], v[192:195], v[112:115]
	v_mfma_f32_16x16x32_bf16 v[100:103], v[152:155], v[200:203], v[100:103]
	v_mfma_f32_16x16x32_bf16 v[96:99], v[160:163], v[200:203], v[96:99]
	v_mfma_f32_16x16x32_bf16 v[84:87], v[152:155], v[208:211], v[84:87]
	v_mfma_f32_16x16x32_bf16 v[80:83], v[160:163], v[208:211], v[80:83]
	v_mfma_f32_16x16x32_bf16 v[124:127], v[156:159], v[188:191], v[124:127]
	v_mfma_f32_16x16x32_bf16 v[120:123], v[164:167], v[188:191], v[120:123]
	v_mfma_f32_16x16x32_bf16 v[116:119], v[156:159], v[196:199], v[116:119]
	v_mfma_f32_16x16x32_bf16 v[112:115], v[164:167], v[196:199], v[112:115]
	v_mfma_f32_16x16x32_bf16 v[100:103], v[156:159], v[204:207], v[100:103]
	v_mfma_f32_16x16x32_bf16 v[96:99], v[164:167], v[204:207], v[96:99]
	v_mfma_f32_16x16x32_bf16 v[84:87], v[156:159], v[212:215], v[84:87]
	v_mfma_f32_16x16x32_bf16 v[80:83], v[164:167], v[212:215], v[80:83]


; #define PG8_STAGE(bufoff, gbase, voff) do { _Pragma("unroll") for (int _i = 0; _i < 2; ++_i) \
;         __builtin_amdgcn_global_load_lds((const unsigned*)((const char*)(gbase) + (voff)[_i]), (PG8_LAS unsigned*)(lds + (bufoff) + ldsw + _i * 8192), 16, 0, 0); } while (0)
; #define PG8_LDA(dst, b, h) do { _Pragma("unroll") for (int m = 0; m < 4; ++m) _Pragma("unroll") for (int k = 0; k < 2; ++k) dst[m][k] = *(const PG8_LAS bf16x8*)(lds + PG8_SA(b, h) + aoff + m * 2048 + k * 1024); } while (0)
; #define PG8_MMA(ai, bj, At, Bt) do { __builtin_amdgcn_s_setprio(1); _Pragma("unroll") for (int m = 0; m < 4; ++m) _Pragma("unroll") for (int n = 0; n < 2; ++n) _Pragma("unroll") for (int k = 0; k < 2; ++k) \
;         acc[ai][bj][m][n] = __builtin_amdgcn_mfma_f32_16x16x32_bf16(Bt[n][k], At[m][k], acc[ai][bj][m][n], 0, 0, 0); __builtin_amdgcn_s_setprio(0); } while (0)
; #define PG8_WAIT_V(n) asm volatile("s_waitcnt vmcnt(" #n ")" ::: "memory")
; #define PG8_WAIT_L(n) asm volatile("s_waitcnt lgkmcnt(" #n ")" ::: "memory")
; #define PG8_BAR __builtin_amdgcn_s_barrier()
; #define PG8_SCHED __builtin_amdgcn_sched_barrier(0)
; template <class Epi, class Sched, bool ALIGN_EPI = false, bool SP2 = false>
; __device__ __forceinline__ void gemm_phase(PG8_LAS unsigned char* lds, const Gemm g, const Sched& S, const Epi& E) {
;     ...
;             PG8_WAIT_V(8); PG8_WAIT_L(0); PG8_BAR; PG8_MMA(0, 0, At, B0); PG8_MMA(0, 1, At, B1); PG8_BAR; PG8_SCHED;
;             PG8_LDA(At, 1, 1); PG8_STAGE(PG8_SB(1, 0), b3, voffB); PG8_STAGE(PG8_SB(1, 1), b3 + hstep, voffB); PG8_STAGE(PG8_SA(1, 0), a3, voffA);
	v_mfma_f32_16x16x32_bf16 v[108:111], v[168:171], v[184:187], v[108:111]
	v_mfma_f32_16x16x32_bf16 v[104:107], v[176:179], v[184:187], v[104:107]
	v_mfma_f32_16x16x32_bf16 v[92:95], v[168:171], v[192:195], v[92:95]
	v_mfma_f32_16x16x32_bf16 v[88:91], v[176:179], v[192:195], v[88:91]
	v_mfma_f32_16x16x32_bf16 v[76:79], v[168:171], v[200:203], v[76:79]
	v_mfma_f32_16x16x32_bf16 v[72:75], v[176:179], v[200:203], v[72:75]
	v_mfma_f32_16x16x32_bf16 v[68:71], v[168:171], v[208:211], v[68:71]
	v_mfma_f32_16x16x32_bf16 v[64:67], v[176:179], v[208:211], v[64:67]
	v_mfma_f32_16x16x32_bf16 v[108:111], v[172:175], v[188:191], v[108:111]
	v_mfma_f32_16x16x32_bf16 v[104:107], v[180:183], v[188:191], v[104:107]
	v_mfma_f32_16x16x32_bf16 v[92:95], v[172:175], v[196:199], v[92:95]
	v_mfma_f32_16x16x32_bf16 v[88:91], v[180:183], v[196:199], v[88:91]
	v_mfma_f32_16x16x32_bf16 v[76:79], v[172:175], v[204:207], v[76:79]
	v_mfma_f32_16x16x32_bf16 v[72:75], v[180:183], v[204:207], v[72:75]
	v_mfma_f32_16x16x32_bf16 v[68:71], v[172:175], v[212:215], v[68:71]
	v_mfma_f32_16x16x32_bf16 v[64:67], v[180:183], v[212:215], v[64:67]
	s_setprio 0
	s_barrier
	s_add_i32 s44, s69, s48

; #define PG8_STAGE(bufoff, gbase, voff) do { _Pragma("unroll") for (int _i = 0; _i < 2; ++_i) \
;         __builtin_amdgcn_global_load_lds((const unsigned*)((const char*)(gbase) + (voff)[_i]), (PG8_LAS unsigned*)(lds + (bufoff) + ldsw + _i * 8192), 16, 0, 0); } while (0)
; #define PG8_LDA(dst, b, h) do { _Pragma("unroll") for (int m = 0; m < 4; ++m) _Pragma("unroll") for (int k = 0; k < 2; ++k) dst[m][k] = *(const PG8_LAS bf16x8*)(lds + PG8_SA(b, h) + aoff + m * 2048 + k * 1024); } while (0)
; template <class Epi, class Sched, bool ALIGN_EPI = false, bool SP2 = false>
; __device__ __forceinline__ void gemm_phase(PG8_LAS unsigned char* lds, const Gemm g, const Sched& S, const Epi& E) {
;     ...
;             PG8_LDA(At, 1, 1); PG8_STAGE(PG8_SB(1, 0), b3, voffB); PG8_STAGE(PG8_SB(1, 1), b3 + hstep, voffB); PG8_STAGE(PG8_SA(1, 0), a3, voffA);
	s_mov_b32 m0, s44
	ds_read_b128 v[184:187], v151 offset:49152
	ds_read_b128 v[188:191], v151 offset:50176
	ds_read_b128 v[192:195], v151 offset:51200
	ds_read_b128 v[196:199], v151 offset:52224
	ds_read_b128 v[200:203], v151 offset:53248
	ds_read_b128 v[204:207], v151 offset:54272
	ds_read_b128 v[208:211], v151 offset:55296
	ds_read_b128 v[212:215], v151 offset:56320
	global_load_lds_dwordx4 v250, s[96:97]
	s_add_i32 m0, s44, 0x2000
	s_add_u32 s42, s42, 0x80080

; #define PG8_STAGE(bufoff, gbase, voff) do { _Pragma("unroll") for (int _i = 0; _i < 2; ++_i) \
;         __builtin_amdgcn_global_load_lds((const unsigned*)((const char*)(gbase) + (voff)[_i]), (PG8_LAS unsigned*)(lds + (bufoff) + ldsw + _i * 8192), 16, 0, 0); } while (0)
; #define PG8_LDA(dst, b, h) do { _Pragma("unroll") for (int m = 0; m < 4; ++m) _Pragma("unroll") for (int k = 0; k < 2; ++k) dst[m][k] = *(const PG8_LAS bf16x8*)(lds + PG8_SA(b, h) + aoff + m * 2048 + k * 1024); } while (0)
; template <class Epi, class Sched, bool ALIGN_EPI = false, bool SP2 = false>
; __device__ __forceinline__ void gemm_phase(PG8_LAS unsigned char* lds, const Gemm g, const Sched& S, const Epi& E) {
;     ...
;             PG8_LDA(At, 1, 1); PG8_STAGE(PG8_SB(1, 0), b3, voffB); PG8_STAGE(PG8_SB(1, 1), b3 + hstep, voffB); PG8_STAGE(PG8_SA(1, 0), a3, voffA);
	s_addc_u32 s43, s43, 0
	s_add_i32 s44, s70, s48
	global_load_lds_dwordx4 v251, s[96:97]

; #define PG8_STAGE(bufoff, gbase, voff) do { _Pragma("unroll") for (int _i = 0; _i < 2; ++_i) \
;         __builtin_amdgcn_global_load_lds((const unsigned*)((const char*)(gbase) + (voff)[_i]), (PG8_LAS unsigned*)(lds + (bufoff) + ldsw + _i * 8192), 16, 0, 0); } while (0)
; #define PG8_LDA(dst, b, h) do { _Pragma("unroll") for (int m = 0; m < 4; ++m) _Pragma("unroll") for (int k = 0; k < 2; ++k) dst[m][k] = *(const PG8_LAS bf16x8*)(lds + PG8_SA(b, h) + aoff + m * 2048 + k * 1024); } while (0)
; template <class Epi, class Sched, bool ALIGN_EPI = false, bool SP2 = false>
; __device__ __forceinline__ void gemm_phase(PG8_LAS unsigned char* lds, const Gemm g, const Sched& S, const Epi& E) {
;     ...
;             PG8_LDA(At, 1, 1); PG8_STAGE(PG8_SB(1, 0), b3, voffB); PG8_STAGE(PG8_SB(1, 1), b3 + hstep, voffB); PG8_STAGE(PG8_SA(1, 0), a3, voffA);
	s_mov_b32 m0, s44
	s_nop 0
	global_load_lds_dwordx4 v132, s[42:43]

; #define PG8_STAGE(bufoff, gbase, voff) do { _Pragma("unroll") for (int _i = 0; _i < 2; ++_i) \
;         __builtin_amdgcn_global_load_lds((const unsigned*)((const char*)(gbase) + (voff)[_i]), (PG8_LAS unsigned*)(lds + (bufoff) + ldsw + _i * 8192), 16, 0, 0); } while (0)
; #define PG8_LDA(dst, b, h) do { _Pragma("unroll") for (int m = 0; m < 4; ++m) _Pragma("unroll") for (int k = 0; k < 2; ++k) dst[m][k] = *(const PG8_LAS bf16x8*)(lds + PG8_SA(b, h) + aoff + m * 2048 + k * 1024); } while (0)
; template <class Epi, class Sched, bool ALIGN_EPI = false, bool SP2 = false>
; __device__ __forceinline__ void gemm_phase(PG8_LAS unsigned char* lds, const Gemm g, const Sched& S, const Epi& E) {
;     ...
;             PG8_LDA(At, 1, 1); PG8_STAGE(PG8_SB(1, 0), b3, voffB); PG8_STAGE(PG8_SB(1, 1), b3 + hstep, voffB); PG8_STAGE(PG8_SA(1, 0), a3, voffA);
	s_add_i32 m0, s44, 0x2000
	s_nop 0
	global_load_lds_dwordx4 v128, s[42:43]

; #define PG8_STAGE(bufoff, gbase, voff) do { _Pragma("unroll") for (int _i = 0; _i < 2; ++_i) \
;         __builtin_amdgcn_global_load_lds((const unsigned*)((const char*)(gbase) + (voff)[_i]), (PG8_LAS unsigned*)(lds + (bufoff) + ldsw + _i * 8192), 16, 0, 0); } while (0)
; #define PG8_LDA(dst, b, h) do { _Pragma("unroll") for (int m = 0; m < 4; ++m) _Pragma("unroll") for (int k = 0; k < 2; ++k) dst[m][k] = *(const PG8_LAS bf16x8*)(lds + PG8_SA(b, h) + aoff + m * 2048 + k * 1024); } while (0)
; template <class Epi, class Sched, bool ALIGN_EPI = false, bool SP2 = false>
; __device__ __forceinline__ void gemm_phase(PG8_LAS unsigned char* lds, const Gemm g, const Sched& S, const Epi& E) {
;     ...
;             PG8_LDA(At, 1, 1); PG8_STAGE(PG8_SB(1, 0), b3, voffB); PG8_STAGE(PG8_SB(1, 1), b3 + hstep, voffB); PG8_STAGE(PG8_SA(1, 0), a3, voffA);
	s_mov_b32 m0, s55
	s_nop 0
	global_load_lds_dwordx4 v252, s[98:99]

; #define PG8_STAGE(bufoff, gbase, voff) do { _Pragma("unroll") for (int _i = 0; _i < 2; ++_i) \
;         __builtin_amdgcn_global_load_lds((const unsigned*)((const char*)(gbase) + (voff)[_i]), (PG8_LAS unsigned*)(lds + (bufoff) + ldsw + _i * 8192), 16, 0, 0); } while (0)
; #define PG8_LDA(dst, b, h) do { _Pragma("unroll") for (int m = 0; m < 4; ++m) _Pragma("unroll") for (int k = 0; k < 2; ++k) dst[m][k] = *(const PG8_LAS bf16x8*)(lds + PG8_SA(b, h) + aoff + m * 2048 + k * 1024); } while (0)
; #define PG8_MMA(ai, bj, At, Bt) do { __builtin_amdgcn_s_setprio(1); _Pragma("unroll") for (int m = 0; m < 4; ++m) _Pragma("unroll") for (int n = 0; n < 2; ++n) _Pragma("unroll") for (int k = 0; k < 2; ++k) \
;         acc[ai][bj][m][n] = __builtin_amdgcn_mfma_f32_16x16x32_bf16(Bt[n][k], At[m][k], acc[ai][bj][m][n], 0, 0, 0); __builtin_amdgcn_s_setprio(0); } while (0)
; #define PG8_WAIT_V(n) asm volatile("s_waitcnt vmcnt(" #n ")" ::: "memory")
; #define PG8_WAIT_L(n) asm volatile("s_waitcnt lgkmcnt(" #n ")" ::: "memory")
; #define PG8_BAR __builtin_amdgcn_s_barrier()
; #define PG8_SCHED __builtin_amdgcn_sched_barrier(0)
; template <class Epi, class Sched, bool ALIGN_EPI = false, bool SP2 = false>
; __device__ __forceinline__ void gemm_phase(PG8_LAS unsigned char* lds, const Gemm g, const Sched& S, const Epi& E) {
;     ...
;             PG8_LDA(At, 1, 1); PG8_STAGE(PG8_SB(1, 0), b3, voffB); PG8_STAGE(PG8_SB(1, 1), b3 + hstep, voffB); PG8_STAGE(PG8_SA(1, 0), a3, voffA);
;             PG8_WAIT_V(8); PG8_WAIT_L(0); PG8_BAR; PG8_MMA(1, 0, At, B0); PG8_MMA(1, 1, At, B1); PG8_BAR; PG8_SCHED;
	s_mov_b32 m0, s56
	s_nop 0
	global_load_lds_dwordx4 v253, s[98:99]
	s_waitcnt vmcnt(8)
	s_waitcnt lgkmcnt(0)
	s_barrier
	s_setprio 1
	s_waitcnt lgkmcnt(0)
	v_mfma_f32_16x16x32_bf16 v[60:63], v[152:155], v[184:187], v[60:63]
	v_mfma_f32_16x16x32_bf16 v[56:59], v[160:163], v[184:187], v[56:59]
	v_mfma_f32_16x16x32_bf16 v[52:55], v[152:155], v[192:195], v[52:55]
	v_mfma_f32_16x16x32_bf16 v[48:51], v[160:163], v[192:195], v[48:51]
	v_mfma_f32_16x16x32_bf16 v[36:39], v[152:155], v[200:203], v[36:39]
	v_mfma_f32_16x16x32_bf16 v[32:35], v[160:163], v[200:203], v[32:35]
	v_mfma_f32_16x16x32_bf16 v[20:23], v[152:155], v[208:211], v[20:23]
	v_mfma_f32_16x16x32_bf16 v[16:19], v[160:163], v[208:211], v[16:19]
	v_mfma_f32_16x16x32_bf16 v[60:63], v[156:159], v[188:191], v[60:63]
	v_mfma_f32_16x16x32_bf16 v[56:59], v[164:167], v[188:191], v[56:59]
	v_mfma_f32_16x16x32_bf16 v[52:55], v[156:159], v[196:199], v[52:55]
	v_mfma_f32_16x16x32_bf16 v[48:51], v[164:167], v[196:199], v[48:51]
	v_mfma_f32_16x16x32_bf16 v[36:39], v[156:159], v[204:207], v[36:39]
	v_mfma_f32_16x16x32_bf16 v[32:35], v[164:167], v[204:207], v[32:35]
	v_mfma_f32_16x16x32_bf16 v[20:23], v[156:159], v[212:215], v[20:23]
	v_mfma_f32_16x16x32_bf16 v[16:19], v[164:167], v[212:215], v[16:19]


; #define PG8_MMA(ai, bj, At, Bt) do { __builtin_amdgcn_s_setprio(1); _Pragma("unroll") for (int m = 0; m < 4; ++m) _Pragma("unroll") for (int n = 0; n < 2; ++n) _Pragma("unroll") for (int k = 0; k < 2; ++k) \
;         acc[ai][bj][m][n] = __builtin_amdgcn_mfma_f32_16x16x32_bf16(Bt[n][k], At[m][k], acc[ai][bj][m][n], 0, 0, 0); __builtin_amdgcn_s_setprio(0); } while (0)
; #define PG8_WAIT_V(n) asm volatile("s_waitcnt vmcnt(" #n ")" ::: "memory")
; #define PG8_WAIT_L(n) asm volatile("s_waitcnt lgkmcnt(" #n ")" ::: "memory")
; #define PG8_BAR __builtin_amdgcn_s_barrier()
; #define PG8_SCHED __builtin_amdgcn_sched_barrier(0)
; template <class Epi, class Sched, bool ALIGN_EPI = false, bool SP2 = false>
; __device__ __forceinline__ void gemm_phase(PG8_LAS unsigned char* lds, const Gemm g, const Sched& S, const Epi& E) {
;     ...
;             PG8_WAIT_V(8); PG8_WAIT_L(0); PG8_BAR; PG8_MMA(1, 0, At, B0); PG8_MMA(1, 1, At, B1); PG8_BAR; PG8_SCHED;
;     ...
;         if constexpr (ALIGN_EPI) { if (wr == 0) PG8_BAR; }
	v_mfma_f32_16x16x32_bf16 v[44:47], v[168:171], v[184:187], v[44:47]
	v_mfma_f32_16x16x32_bf16 v[40:43], v[176:179], v[184:187], v[40:43]
	v_mfma_f32_16x16x32_bf16 v[28:31], v[168:171], v[192:195], v[28:31]
	v_mfma_f32_16x16x32_bf16 v[24:27], v[176:179], v[192:195], v[24:27]
	v_mfma_f32_16x16x32_bf16 v[12:15], v[168:171], v[200:203], v[12:15]
	v_mfma_f32_16x16x32_bf16 v[8:11], v[176:179], v[200:203], v[8:11]
	v_mfma_f32_16x16x32_bf16 v[4:7], v[168:171], v[208:211], v[4:7]
	v_mfma_f32_16x16x32_bf16 v[0:3], v[176:179], v[208:211], v[0:3]
	v_mfma_f32_16x16x32_bf16 v[44:47], v[172:175], v[188:191], v[44:47]
	v_mfma_f32_16x16x32_bf16 v[40:43], v[180:183], v[188:191], v[40:43]
	v_mfma_f32_16x16x32_bf16 v[28:31], v[172:175], v[196:199], v[28:31]
	v_mfma_f32_16x16x32_bf16 v[24:27], v[180:183], v[196:199], v[24:27]
	v_mfma_f32_16x16x32_bf16 v[12:15], v[172:175], v[204:207], v[12:15]
	v_mfma_f32_16x16x32_bf16 v[8:11], v[180:183], v[204:207], v[8:11]
	v_mfma_f32_16x16x32_bf16 v[4:7], v[172:175], v[212:215], v[4:7]
	v_mfma_f32_16x16x32_bf16 v[0:3], v[180:183], v[212:215], v[0:3]
	s_setprio 0
	s_barrier
	s_add_i32 s68, s68, 2
	s_add_u32 s40, s40, 0x100
	s_addc_u32 s41, s41, 0
	s_add_u32 s65, s65, 0x100
	s_addc_u32 s67, s67, 0
	s_cmp_gt_u32 s68, 29
	s_cbranch_scc0 .LBB0_66
	s_and_b64 vcc, exec, s[26:27]
	s_cbranch_vccz .LBB0_69
	s_barrier

; #define PG8_STAGE(bufoff, gbase, voff) do { _Pragma("unroll") for (int _i = 0; _i < 2; ++_i) \
;         __builtin_amdgcn_global_load_lds((const unsigned*)((const char*)(gbase) + (voff)[_i]), (PG8_LAS unsigned*)(lds + (bufoff) + ldsw + _i * 8192), 16, 0, 0); } while (0)
; #define PG8_LDA(dst, b, h) do { _Pragma("unroll") for (int m = 0; m < 4; ++m) _Pragma("unroll") for (int k = 0; k < 2; ++k) dst[m][k] = *(const PG8_LAS bf16x8*)(lds + PG8_SA(b, h) + aoff + m * 2048 + k * 1024); } while (0)
; #define PG8_LDB(dst, b, h) do { _Pragma("unroll") for (int n = 0; n < 2; ++n) _Pragma("unroll") for (int k = 0; k < 2; ++k) dst[n][k] = *(const PG8_LAS bf16x8*)(lds + PG8_SB(b, h) + boff + n * 2048 + k * 1024); } while (0)
; #define PG8_SCHED __builtin_amdgcn_sched_barrier(0)
; template <class Epi, class Sched, bool ALIGN_EPI = false, bool SP2 = false>
; __device__ __forceinline__ void gemm_phase(PG8_LAS unsigned char* lds, const Gemm g, const Sched& S, const Epi& E) {
;     ...
;             const char* a1 = cA + (size_t)(t + 1) * kstep;
;             const char* a2 = last ? nA : cA + (size_t)(t + 2) * kstep; const char* b2 = last ? nB : cB + (size_t)(t + 2) * kstep;
;             const char* a3 = a2 + kstep; const char* b3 = b2 + kstep;
;             if (last && has_next) S.a_ready(nxt);
;             if constexpr (SP2) {
;             PG8_LDB(B0, 0, 0); PG8_LDB(B1, 0, 1); PG8_SCHED; PG8_LDA(At, 0, 0); PG8_STAGE(PG8_SA(1, 1), a1 + hstep, voffA);
.LBB0_333:
	ds_read_b128 v[64:67], v211
	ds_read_b128 v[68:71], v211 offset:1024
	ds_read_b128 v[72:75], v211 offset:2048
	ds_read_b128 v[76:79], v211 offset:3072
	ds_read_b128 v[144:147], v212
	ds_read_b128 v[148:151], v212 offset:1024
	ds_read_b128 v[152:155], v212 offset:2048
	ds_read_b128 v[156:159], v212 offset:3072
	s_add_u32 s60, s58, 0xfff80080
	s_addc_u32 s61, s59, -1
	s_cmp_eq_u32 s81, 28
	s_cselect_b32 s63, s11, s61
	s_cselect_b32 s62, s51, s60
	s_cselect_b32 s61, s49, s80
	s_cselect_b32 s60, s78, s79

; #define PG8_STAGE(bufoff, gbase, voff) do { _Pragma("unroll") for (int _i = 0; _i < 2; ++_i) \
;         __builtin_amdgcn_global_load_lds((const unsigned*)((const char*)(gbase) + (voff)[_i]), (PG8_LAS unsigned*)(lds + (bufoff) + ldsw + _i * 8192), 16, 0, 0); } while (0)
; #define PG8_LDA(dst, b, h) do { _Pragma("unroll") for (int m = 0; m < 4; ++m) _Pragma("unroll") for (int k = 0; k < 2; ++k) dst[m][k] = *(const PG8_LAS bf16x8*)(lds + PG8_SA(b, h) + aoff + m * 2048 + k * 1024); } while (0)
; #define PG8_LDB(dst, b, h) do { _Pragma("unroll") for (int n = 0; n < 2; ++n) _Pragma("unroll") for (int k = 0; k < 2; ++k) dst[n][k] = *(const PG8_LAS bf16x8*)(lds + PG8_SB(b, h) + boff + n * 2048 + k * 1024); } while (0)
; #define PG8_SCHED __builtin_amdgcn_sched_barrier(0)
; template <class Epi, class Sched, bool ALIGN_EPI = false, bool SP2 = false>
; __device__ __forceinline__ void gemm_phase(PG8_LAS unsigned char* lds, const Gemm g, const Sched& S, const Epi& E) {
;     ...
;             PG8_LDB(B0, 0, 0); PG8_LDB(B1, 0, 1); PG8_SCHED; PG8_LDA(At, 0, 0); PG8_STAGE(PG8_SA(1, 1), a1 + hstep, voffA);
	s_add_i32 m0, s57, 0xc000
	ds_read_b128 v[176:179], v213
	ds_read_b128 v[180:183], v213 offset:1024
	ds_read_b128 v[184:187], v213 offset:2048
	ds_read_b128 v[188:191], v213 offset:3072
	ds_read_b128 v[192:195], v213 offset:4096
	ds_read_b128 v[196:199], v213 offset:5120
	ds_read_b128 v[200:203], v213 offset:6144
	ds_read_b128 v[204:207], v213 offset:7168
	global_load_lds_dwordx4 v168, s[58:59]

; #define PG8_STAGE(bufoff, gbase, voff) do { _Pragma("unroll") for (int _i = 0; _i < 2; ++_i) \
;         __builtin_amdgcn_global_load_lds((const unsigned*)((const char*)(gbase) + (voff)[_i]), (PG8_LAS unsigned*)(lds + (bufoff) + ldsw + _i * 8192), 16, 0, 0); } while (0)
; #define PG8_LDA(dst, b, h) do { _Pragma("unroll") for (int m = 0; m < 4; ++m) _Pragma("unroll") for (int k = 0; k < 2; ++k) dst[m][k] = *(const PG8_LAS bf16x8*)(lds + PG8_SA(b, h) + aoff + m * 2048 + k * 1024); } while (0)
; #define PG8_LDB(dst, b, h) do { _Pragma("unroll") for (int n = 0; n < 2; ++n) _Pragma("unroll") for (int k = 0; k < 2; ++k) dst[n][k] = *(const PG8_LAS bf16x8*)(lds + PG8_SB(b, h) + boff + n * 2048 + k * 1024); } while (0)
; #define PG8_MMA(ai, bj, At, Bt) do { __builtin_amdgcn_s_setprio(1); _Pragma("unroll") for (int m = 0; m < 4; ++m) _Pragma("unroll") for (int n = 0; n < 2; ++n) _Pragma("unroll") for (int k = 0; k < 2; ++k) \
;         acc[ai][bj][m][n] = __builtin_amdgcn_mfma_f32_16x16x32_bf16(Bt[n][k], At[m][k], acc[ai][bj][m][n], 0, 0, 0); __builtin_amdgcn_s_setprio(0); } while (0)
; #define PG8_WAIT_V(n) asm volatile("s_waitcnt vmcnt(" #n ")" ::: "memory")
; #define PG8_WAIT_L(n) asm volatile("s_waitcnt lgkmcnt(" #n ")" ::: "memory")
; #define PG8_BAR __builtin_amdgcn_s_barrier()
; #define PG8_SCHED __builtin_amdgcn_sched_barrier(0)
; template <class Epi, class Sched, bool ALIGN_EPI = false, bool SP2 = false>
; __device__ __forceinline__ void gemm_phase(PG8_LAS unsigned char* lds, const Gemm g, const Sched& S, const Epi& E) {
;     ...
;             PG8_LDB(B0, 0, 0); PG8_LDB(B1, 0, 1); PG8_SCHED; PG8_LDA(At, 0, 0); PG8_STAGE(PG8_SA(1, 1), a1 + hstep, voffA);
;             PG8_WAIT_V(8); PG8_WAIT_L(0); PG8_BAR; PG8_MMA(0, 0, At, B0); PG8_MMA(0, 1, At, B1); PG8_BAR; PG8_SCHED;
	s_add_i32 m0, s57, 0xe000
	s_nop 0
	global_load_lds_dwordx4 v170, s[58:59]
	s_waitcnt vmcnt(8)
	s_waitcnt lgkmcnt(0)
	s_barrier
	s_setprio 1
	s_waitcnt lgkmcnt(0)
	v_mfma_f32_16x16x32_bf16 v[140:143], v[64:67], v[176:179], v[140:143]
	v_mfma_f32_16x16x32_bf16 v[136:139], v[72:75], v[176:179], v[136:139]
	v_mfma_f32_16x16x32_bf16 v[124:127], v[64:67], v[184:187], v[124:127]
	v_mfma_f32_16x16x32_bf16 v[120:123], v[72:75], v[184:187], v[120:123]
	v_mfma_f32_16x16x32_bf16 v[108:111], v[64:67], v[192:195], v[108:111]
	v_mfma_f32_16x16x32_bf16 v[104:107], v[72:75], v[192:195], v[104:107]
	v_mfma_f32_16x16x32_bf16 v[92:95], v[64:67], v[200:203], v[92:95]
	v_mfma_f32_16x16x32_bf16 v[88:91], v[72:75], v[200:203], v[88:91]
	v_mfma_f32_16x16x32_bf16 v[140:143], v[68:71], v[180:183], v[140:143]
	v_mfma_f32_16x16x32_bf16 v[136:139], v[76:79], v[180:183], v[136:139]
	v_mfma_f32_16x16x32_bf16 v[124:127], v[68:71], v[188:191], v[124:127]
	v_mfma_f32_16x16x32_bf16 v[120:123], v[76:79], v[188:191], v[120:123]
	v_mfma_f32_16x16x32_bf16 v[108:111], v[68:71], v[196:199], v[108:111]
	v_mfma_f32_16x16x32_bf16 v[104:107], v[76:79], v[196:199], v[104:107]
	v_mfma_f32_16x16x32_bf16 v[92:95], v[68:71], v[204:207], v[92:95]
	v_mfma_f32_16x16x32_bf16 v[88:91], v[76:79], v[204:207], v[88:91]


; #define PG8_STAGE(bufoff, gbase, voff) do { _Pragma("unroll") for (int _i = 0; _i < 2; ++_i) \
;         __builtin_amdgcn_global_load_lds((const unsigned*)((const char*)(gbase) + (voff)[_i]), (PG8_LAS unsigned*)(lds + (bufoff) + ldsw + _i * 8192), 16, 0, 0); } while (0)
; #define PG8_LDA(dst, b, h) do { _Pragma("unroll") for (int m = 0; m < 4; ++m) _Pragma("unroll") for (int k = 0; k < 2; ++k) dst[m][k] = *(const PG8_LAS bf16x8*)(lds + PG8_SA(b, h) + aoff + m * 2048 + k * 1024); } while (0)
; #define PG8_MMA(ai, bj, At, Bt) do { __builtin_amdgcn_s_setprio(1); _Pragma("unroll") for (int m = 0; m < 4; ++m) _Pragma("unroll") for (int n = 0; n < 2; ++n) _Pragma("unroll") for (int k = 0; k < 2; ++k) \
;         acc[ai][bj][m][n] = __builtin_amdgcn_mfma_f32_16x16x32_bf16(Bt[n][k], At[m][k], acc[ai][bj][m][n], 0, 0, 0); __builtin_amdgcn_s_setprio(0); } while (0)
; #define PG8_WAIT_V(n) asm volatile("s_waitcnt vmcnt(" #n ")" ::: "memory")
; #define PG8_WAIT_L(n) asm volatile("s_waitcnt lgkmcnt(" #n ")" ::: "memory")
; #define PG8_BAR __builtin_amdgcn_s_barrier()
; #define PG8_SCHED __builtin_amdgcn_sched_barrier(0)
; template <class Epi, class Sched, bool ALIGN_EPI = false, bool SP2 = false>
; __device__ __forceinline__ void gemm_phase(PG8_LAS unsigned char* lds, const Gemm g, const Sched& S, const Epi& E) {
;     ...
;             PG8_WAIT_V(8); PG8_WAIT_L(0); PG8_BAR; PG8_MMA(0, 0, At, B0); PG8_MMA(0, 1, At, B1); PG8_BAR; PG8_SCHED;
;             PG8_LDA(At, 0, 1); PG8_STAGE(PG8_SB(0, 0), b2, voffB); PG8_STAGE(PG8_SB(0, 1), b2 + hstep, voffB); PG8_STAGE(PG8_SA(0, 0), a2, voffA);
	v_mfma_f32_16x16x32_bf16 v[132:135], v[144:147], v[176:179], v[132:135]
	v_mfma_f32_16x16x32_bf16 v[128:131], v[152:155], v[176:179], v[128:131]
	v_mfma_f32_16x16x32_bf16 v[116:119], v[144:147], v[184:187], v[116:119]
	v_mfma_f32_16x16x32_bf16 v[112:115], v[152:155], v[184:187], v[112:115]
	v_mfma_f32_16x16x32_bf16 v[100:103], v[144:147], v[192:195], v[100:103]
	v_mfma_f32_16x16x32_bf16 v[96:99], v[152:155], v[192:195], v[96:99]
	v_mfma_f32_16x16x32_bf16 v[84:87], v[144:147], v[200:203], v[84:87]
	v_mfma_f32_16x16x32_bf16 v[80:83], v[152:155], v[200:203], v[80:83]
	v_mfma_f32_16x16x32_bf16 v[132:135], v[148:151], v[180:183], v[132:135]
	v_mfma_f32_16x16x32_bf16 v[128:131], v[156:159], v[180:183], v[128:131]
	v_mfma_f32_16x16x32_bf16 v[116:119], v[148:151], v[188:191], v[116:119]
	v_mfma_f32_16x16x32_bf16 v[112:115], v[156:159], v[188:191], v[112:115]
	v_mfma_f32_16x16x32_bf16 v[100:103], v[148:151], v[196:199], v[100:103]
	v_mfma_f32_16x16x32_bf16 v[96:99], v[156:159], v[196:199], v[96:99]
	v_mfma_f32_16x16x32_bf16 v[84:87], v[148:151], v[204:207], v[84:87]
	v_mfma_f32_16x16x32_bf16 v[80:83], v[156:159], v[204:207], v[80:83]
	s_setprio 0
	s_barrier
	s_add_i32 s82, s75, s64
	s_mov_b64 s[96:97], s[60:61]

; #define PG8_STAGE(bufoff, gbase, voff) do { _Pragma("unroll") for (int _i = 0; _i < 2; ++_i) \
;         __builtin_amdgcn_global_load_lds((const unsigned*)((const char*)(gbase) + (voff)[_i]), (PG8_LAS unsigned*)(lds + (bufoff) + ldsw + _i * 8192), 16, 0, 0); } while (0)
; #define PG8_LDA(dst, b, h) do { _Pragma("unroll") for (int m = 0; m < 4; ++m) _Pragma("unroll") for (int k = 0; k < 2; ++k) dst[m][k] = *(const PG8_LAS bf16x8*)(lds + PG8_SA(b, h) + aoff + m * 2048 + k * 1024); } while (0)
; template <class Epi, class Sched, bool ALIGN_EPI = false, bool SP2 = false>
; __device__ __forceinline__ void gemm_phase(PG8_LAS unsigned char* lds, const Gemm g, const Sched& S, const Epi& E) {
;     ...
;             PG8_LDA(At, 0, 1); PG8_STAGE(PG8_SB(0, 0), b2, voffB); PG8_STAGE(PG8_SB(0, 1), b2 + hstep, voffB); PG8_STAGE(PG8_SA(0, 0), a2, voffA);
	s_mov_b32 m0, s82
	ds_read_b128 v[176:179], v213 offset:16384
	ds_read_b128 v[180:183], v213 offset:17408
	ds_read_b128 v[184:187], v213 offset:18432
	ds_read_b128 v[188:191], v213 offset:19456
	ds_read_b128 v[192:195], v213 offset:20480
	ds_read_b128 v[196:199], v213 offset:21504
	ds_read_b128 v[200:203], v213 offset:22528
	ds_read_b128 v[204:207], v213 offset:23552
	global_load_lds_dwordx4 v162, s[60:61]
	s_add_i32 m0, s82, 0x2000
	s_add_u32 s82, s60, 0x80000

; #define PG8_STAGE(bufoff, gbase, voff) do { _Pragma("unroll") for (int _i = 0; _i < 2; ++_i) \
;         __builtin_amdgcn_global_load_lds((const unsigned*)((const char*)(gbase) + (voff)[_i]), (PG8_LAS unsigned*)(lds + (bufoff) + ldsw + _i * 8192), 16, 0, 0); } while (0)
; #define PG8_LDA(dst, b, h) do { _Pragma("unroll") for (int m = 0; m < 4; ++m) _Pragma("unroll") for (int k = 0; k < 2; ++k) dst[m][k] = *(const PG8_LAS bf16x8*)(lds + PG8_SA(b, h) + aoff + m * 2048 + k * 1024); } while (0)
; template <class Epi, class Sched, bool ALIGN_EPI = false, bool SP2 = false>
; __device__ __forceinline__ void gemm_phase(PG8_LAS unsigned char* lds, const Gemm g, const Sched& S, const Epi& E) {
;     ...
;             PG8_LDA(At, 0, 1); PG8_STAGE(PG8_SB(0, 0), b2, voffB); PG8_STAGE(PG8_SB(0, 1), b2 + hstep, voffB); PG8_STAGE(PG8_SA(0, 0), a2, voffA);
	s_addc_u32 s83, s61, 0
	s_add_i32 s84, s76, s64
	global_load_lds_dwordx4 v166, s[60:61]

; #define PG8_STAGE(bufoff, gbase, voff) do { _Pragma("unroll") for (int _i = 0; _i < 2; ++_i) \
;         __builtin_amdgcn_global_load_lds((const unsigned*)((const char*)(gbase) + (voff)[_i]), (PG8_LAS unsigned*)(lds + (bufoff) + ldsw + _i * 8192), 16, 0, 0); } while (0)
; #define PG8_LDA(dst, b, h) do { _Pragma("unroll") for (int m = 0; m < 4; ++m) _Pragma("unroll") for (int k = 0; k < 2; ++k) dst[m][k] = *(const PG8_LAS bf16x8*)(lds + PG8_SA(b, h) + aoff + m * 2048 + k * 1024); } while (0)
; template <class Epi, class Sched, bool ALIGN_EPI = false, bool SP2 = false>
; __device__ __forceinline__ void gemm_phase(PG8_LAS unsigned char* lds, const Gemm g, const Sched& S, const Epi& E) {
;     ...
;             PG8_LDA(At, 0, 1); PG8_STAGE(PG8_SB(0, 0), b2, voffB); PG8_STAGE(PG8_SB(0, 1), b2 + hstep, voffB); PG8_STAGE(PG8_SA(0, 0), a2, voffA);
	s_mov_b32 m0, s84
	s_nop 0
	global_load_lds_dwordx4 v162, s[82:83]

; #define PG8_STAGE(bufoff, gbase, voff) do { _Pragma("unroll") for (int _i = 0; _i < 2; ++_i) \
;         __builtin_amdgcn_global_load_lds((const unsigned*)((const char*)(gbase) + (voff)[_i]), (PG8_LAS unsigned*)(lds + (bufoff) + ldsw + _i * 8192), 16, 0, 0); } while (0)
; #define PG8_LDA(dst, b, h) do { _Pragma("unroll") for (int m = 0; m < 4; ++m) _Pragma("unroll") for (int k = 0; k < 2; ++k) dst[m][k] = *(const PG8_LAS bf16x8*)(lds + PG8_SA(b, h) + aoff + m * 2048 + k * 1024); } while (0)
; template <class Epi, class Sched, bool ALIGN_EPI = false, bool SP2 = false>
; __device__ __forceinline__ void gemm_phase(PG8_LAS unsigned char* lds, const Gemm g, const Sched& S, const Epi& E) {
;     ...
;             PG8_LDA(At, 0, 1); PG8_STAGE(PG8_SB(0, 0), b2, voffB); PG8_STAGE(PG8_SB(0, 1), b2 + hstep, voffB); PG8_STAGE(PG8_SA(0, 0), a2, voffA);
	s_add_i32 m0, s84, 0x2000
	s_nop 0
	global_load_lds_dwordx4 v166, s[82:83]
	s_mov_b64 s[98:99], s[62:63]

; #define PG8_STAGE(bufoff, gbase, voff) do { _Pragma("unroll") for (int _i = 0; _i < 2; ++_i) \
;         __builtin_amdgcn_global_load_lds((const unsigned*)((const char*)(gbase) + (voff)[_i]), (PG8_LAS unsigned*)(lds + (bufoff) + ldsw + _i * 8192), 16, 0, 0); } while (0)
; #define PG8_LDA(dst, b, h) do { _Pragma("unroll") for (int m = 0; m < 4; ++m) _Pragma("unroll") for (int k = 0; k < 2; ++k) dst[m][k] = *(const PG8_LAS bf16x8*)(lds + PG8_SA(b, h) + aoff + m * 2048 + k * 1024); } while (0)
; #define PG8_MMA(ai, bj, At, Bt) do { __builtin_amdgcn_s_setprio(1); _Pragma("unroll") for (int m = 0; m < 4; ++m) _Pragma("unroll") for (int n = 0; n < 2; ++n) _Pragma("unroll") for (int k = 0; k < 2; ++k) \
;         acc[ai][bj][m][n] = __builtin_amdgcn_mfma_f32_16x16x32_bf16(Bt[n][k], At[m][k], acc[ai][bj][m][n], 0, 0, 0); __builtin_amdgcn_s_setprio(0); } while (0)
; #define PG8_WAIT_V(n) asm volatile("s_waitcnt vmcnt(" #n ")" ::: "memory")
; #define PG8_WAIT_L(n) asm volatile("s_waitcnt lgkmcnt(" #n ")" ::: "memory")
; #define PG8_BAR __builtin_amdgcn_s_barrier()
; #define PG8_SCHED __builtin_amdgcn_sched_barrier(0)
; template <class Epi, class Sched, bool ALIGN_EPI = false, bool SP2 = false>
; __device__ __forceinline__ void gemm_phase(PG8_LAS unsigned char* lds, const Gemm g, const Sched& S, const Epi& E) {
;     ...
;             PG8_LDA(At, 0, 1); PG8_STAGE(PG8_SB(0, 0), b2, voffB); PG8_STAGE(PG8_SB(0, 1), b2 + hstep, voffB); PG8_STAGE(PG8_SA(0, 0), a2, voffA);
;             PG8_WAIT_V(8); PG8_WAIT_L(0); PG8_BAR; PG8_MMA(1, 0, At, B0); PG8_MMA(1, 1, At, B1); PG8_BAR; PG8_SCHED;
	s_mov_b32 m0, s57
	s_nop 0
	global_load_lds_dwordx4 v160, s[62:63]
	s_mov_b32 m0, s65
	s_nop 0
	global_load_lds_dwordx4 v164, s[62:63]
	s_waitcnt vmcnt(8)
	s_waitcnt lgkmcnt(0)
	s_barrier
	s_setprio 1
	s_waitcnt lgkmcnt(0)
	v_mfma_f32_16x16x32_bf16 v[60:63], v[64:67], v[176:179], v[60:63]
	v_mfma_f32_16x16x32_bf16 v[56:59], v[72:75], v[176:179], v[56:59]
	v_mfma_f32_16x16x32_bf16 v[44:47], v[64:67], v[184:187], v[44:47]
	v_mfma_f32_16x16x32_bf16 v[40:43], v[72:75], v[184:187], v[40:43]
	v_mfma_f32_16x16x32_bf16 v[28:31], v[64:67], v[192:195], v[28:31]
	v_mfma_f32_16x16x32_bf16 v[24:27], v[72:75], v[192:195], v[24:27]
	v_mfma_f32_16x16x32_bf16 v[12:15], v[64:67], v[200:203], v[12:15]
	v_mfma_f32_16x16x32_bf16 v[8:11], v[72:75], v[200:203], v[8:11]
	v_mfma_f32_16x16x32_bf16 v[60:63], v[68:71], v[180:183], v[60:63]
	v_mfma_f32_16x16x32_bf16 v[56:59], v[76:79], v[180:183], v[56:59]
	v_mfma_f32_16x16x32_bf16 v[44:47], v[68:71], v[188:191], v[44:47]
	v_mfma_f32_16x16x32_bf16 v[40:43], v[76:79], v[188:191], v[40:43]
	v_mfma_f32_16x16x32_bf16 v[28:31], v[68:71], v[196:199], v[28:31]
	v_mfma_f32_16x16x32_bf16 v[24:27], v[76:79], v[196:199], v[24:27]
	v_mfma_f32_16x16x32_bf16 v[12:15], v[68:71], v[204:207], v[12:15]
	v_mfma_f32_16x16x32_bf16 v[8:11], v[76:79], v[204:207], v[8:11]


; #define PG8_STAGE(bufoff, gbase, voff) do { _Pragma("unroll") for (int _i = 0; _i < 2; ++_i) \
;         __builtin_amdgcn_global_load_lds((const unsigned*)((const char*)(gbase) + (voff)[_i]), (PG8_LAS unsigned*)(lds + (bufoff) + ldsw + _i * 8192), 16, 0, 0); } while (0)
; #define PG8_LDA(dst, b, h) do { _Pragma("unroll") for (int m = 0; m < 4; ++m) _Pragma("unroll") for (int k = 0; k < 2; ++k) dst[m][k] = *(const PG8_LAS bf16x8*)(lds + PG8_SA(b, h) + aoff + m * 2048 + k * 1024); } while (0)
; #define PG8_LDB(dst, b, h) do { _Pragma("unroll") for (int n = 0; n < 2; ++n) _Pragma("unroll") for (int k = 0; k < 2; ++k) dst[n][k] = *(const PG8_LAS bf16x8*)(lds + PG8_SB(b, h) + boff + n * 2048 + k * 1024); } while (0)
; #define PG8_MMA(ai, bj, At, Bt) do { __builtin_amdgcn_s_setprio(1); _Pragma("unroll") for (int m = 0; m < 4; ++m) _Pragma("unroll") for (int n = 0; n < 2; ++n) _Pragma("unroll") for (int k = 0; k < 2; ++k) \
;         acc[ai][bj][m][n] = __builtin_amdgcn_mfma_f32_16x16x32_bf16(Bt[n][k], At[m][k], acc[ai][bj][m][n], 0, 0, 0); __builtin_amdgcn_s_setprio(0); } while (0)
; #define PG8_WAIT_V(n) asm volatile("s_waitcnt vmcnt(" #n ")" ::: "memory")
; #define PG8_WAIT_L(n) asm volatile("s_waitcnt lgkmcnt(" #n ")" ::: "memory")
; #define PG8_BAR __builtin_amdgcn_s_barrier()
; #define PG8_SCHED __builtin_amdgcn_sched_barrier(0)
; template <class Epi, class Sched, bool ALIGN_EPI = false, bool SP2 = false>
; __device__ __forceinline__ void gemm_phase(PG8_LAS unsigned char* lds, const Gemm g, const Sched& S, const Epi& E) {
;     ...
;             PG8_WAIT_V(8); PG8_WAIT_L(0); PG8_BAR; PG8_MMA(1, 0, At, B0); PG8_MMA(1, 1, At, B1); PG8_BAR; PG8_SCHED;
;             PG8_LDB(B0, 1, 0); PG8_LDB(B1, 1, 1); PG8_SCHED; PG8_LDA(At, 1, 0); PG8_STAGE(PG8_SA(0, 1), a2 + hstep, voffA);
	v_mfma_f32_16x16x32_bf16 v[52:55], v[144:147], v[176:179], v[52:55]
	v_mfma_f32_16x16x32_bf16 v[48:51], v[152:155], v[176:179], v[48:51]
	v_mfma_f32_16x16x32_bf16 v[36:39], v[144:147], v[184:187], v[36:39]
	v_mfma_f32_16x16x32_bf16 v[32:35], v[152:155], v[184:187], v[32:35]
	v_mfma_f32_16x16x32_bf16 v[20:23], v[144:147], v[192:195], v[20:23]
	v_mfma_f32_16x16x32_bf16 v[16:19], v[152:155], v[192:195], v[16:19]
	v_mfma_f32_16x16x32_bf16 v[4:7], v[144:147], v[200:203], v[4:7]
	v_mfma_f32_16x16x32_bf16 v[0:3], v[152:155], v[200:203], v[0:3]
	v_mfma_f32_16x16x32_bf16 v[52:55], v[148:151], v[180:183], v[52:55]
	v_mfma_f32_16x16x32_bf16 v[48:51], v[156:159], v[180:183], v[48:51]
	v_mfma_f32_16x16x32_bf16 v[36:39], v[148:151], v[188:191], v[36:39]
	v_mfma_f32_16x16x32_bf16 v[32:35], v[156:159], v[188:191], v[32:35]
	v_mfma_f32_16x16x32_bf16 v[20:23], v[148:151], v[196:199], v[20:23]
	v_mfma_f32_16x16x32_bf16 v[16:19], v[156:159], v[196:199], v[16:19]
	v_mfma_f32_16x16x32_bf16 v[4:7], v[148:151], v[204:207], v[4:7]
	v_mfma_f32_16x16x32_bf16 v[0:3], v[156:159], v[204:207], v[0:3]
	s_setprio 0
	s_barrier
	s_add_i32 s82, 0, 0x18000
	s_add_i32 s83, 0, 0x1c000
	v_add_u32_e32 v76, s82, v209
	v_add_u32_e32 v156, s83, v209
	ds_read_b128 v[64:67], v76
	ds_read_b128 v[68:71], v76 offset:1024
	ds_read_b128 v[72:75], v76 offset:2048
	ds_read_b128 v[76:79], v76 offset:3072
	ds_read_b128 v[144:147], v156
	ds_read_b128 v[148:151], v156 offset:1024
	ds_read_b128 v[152:155], v156 offset:2048
	ds_read_b128 v[156:159], v156 offset:3072
	s_add_u32 s62, s62, 0x80000
	s_addc_u32 s63, s63, 0
	s_mov_b32 m0, s67

; #define PG8_STAGE(bufoff, gbase, voff) do { _Pragma("unroll") for (int _i = 0; _i < 2; ++_i) \
;         __builtin_amdgcn_global_load_lds((const unsigned*)((const char*)(gbase) + (voff)[_i]), (PG8_LAS unsigned*)(lds + (bufoff) + ldsw + _i * 8192), 16, 0, 0); } while (0)
; #define PG8_LDA(dst, b, h) do { _Pragma("unroll") for (int m = 0; m < 4; ++m) _Pragma("unroll") for (int k = 0; k < 2; ++k) dst[m][k] = *(const PG8_LAS bf16x8*)(lds + PG8_SA(b, h) + aoff + m * 2048 + k * 1024); } while (0)
; #define PG8_LDB(dst, b, h) do { _Pragma("unroll") for (int n = 0; n < 2; ++n) _Pragma("unroll") for (int k = 0; k < 2; ++k) dst[n][k] = *(const PG8_LAS bf16x8*)(lds + PG8_SB(b, h) + boff + n * 2048 + k * 1024); } while (0)
; #define PG8_SCHED __builtin_amdgcn_sched_barrier(0)
; template <class Epi, class Sched, bool ALIGN_EPI = false, bool SP2 = false>
; __device__ __forceinline__ void gemm_phase(PG8_LAS unsigned char* lds, const Gemm g, const Sched& S, const Epi& E) {
;     ...
;             PG8_LDB(B0, 1, 0); PG8_LDB(B1, 1, 1); PG8_SCHED; PG8_LDA(At, 1, 0); PG8_STAGE(PG8_SA(0, 1), a2 + hstep, voffA);
	ds_read_b128 v[176:179], v213 offset:32768
	ds_read_b128 v[180:183], v213 offset:33792
	ds_read_b128 v[184:187], v213 offset:34816
	ds_read_b128 v[188:191], v213 offset:35840
	ds_read_b128 v[192:195], v213 offset:36864
	ds_read_b128 v[196:199], v213 offset:37888
	ds_read_b128 v[200:203], v213 offset:38912
	ds_read_b128 v[204:207], v213 offset:39936
	global_load_lds_dwordx4 v160, s[62:63]

; #define PG8_STAGE(bufoff, gbase, voff) do { _Pragma("unroll") for (int _i = 0; _i < 2; ++_i) \
;         __builtin_amdgcn_global_load_lds((const unsigned*)((const char*)(gbase) + (voff)[_i]), (PG8_LAS unsigned*)(lds + (bufoff) + ldsw + _i * 8192), 16, 0, 0); } while (0)
; #define PG8_LDA(dst, b, h) do { _Pragma("unroll") for (int m = 0; m < 4; ++m) _Pragma("unroll") for (int k = 0; k < 2; ++k) dst[m][k] = *(const PG8_LAS bf16x8*)(lds + PG8_SA(b, h) + aoff + m * 2048 + k * 1024); } while (0)
; #define PG8_LDB(dst, b, h) do { _Pragma("unroll") for (int n = 0; n < 2; ++n) _Pragma("unroll") for (int k = 0; k < 2; ++k) dst[n][k] = *(const PG8_LAS bf16x8*)(lds + PG8_SB(b, h) + boff + n * 2048 + k * 1024); } while (0)
; #define PG8_MMA(ai, bj, At, Bt) do { __builtin_amdgcn_s_setprio(1); _Pragma("unroll") for (int m = 0; m < 4; ++m) _Pragma("unroll") for (int n = 0; n < 2; ++n) _Pragma("unroll") for (int k = 0; k < 2; ++k) \
;         acc[ai][bj][m][n] = __builtin_amdgcn_mfma_f32_16x16x32_bf16(Bt[n][k], At[m][k], acc[ai][bj][m][n], 0, 0, 0); __builtin_amdgcn_s_setprio(0); } while (0)
; #define PG8_WAIT_V(n) asm volatile("s_waitcnt vmcnt(" #n ")" ::: "memory")
; #define PG8_WAIT_L(n) asm volatile("s_waitcnt lgkmcnt(" #n ")" ::: "memory")
; #define PG8_BAR __builtin_amdgcn_s_barrier()
; #define PG8_SCHED __builtin_amdgcn_sched_barrier(0)
; template <class Epi, class Sched, bool ALIGN_EPI = false, bool SP2 = false>
; __device__ __forceinline__ void gemm_phase(PG8_LAS unsigned char* lds, const Gemm g, const Sched& S, const Epi& E) {
;     ...
;             PG8_LDB(B0, 1, 0); PG8_LDB(B1, 1, 1); PG8_SCHED; PG8_LDA(At, 1, 0); PG8_STAGE(PG8_SA(0, 1), a2 + hstep, voffA);
;             PG8_WAIT_V(8); PG8_WAIT_L(0); PG8_BAR; PG8_MMA(0, 0, At, B0); PG8_MMA(0, 1, At, B1); PG8_BAR; PG8_SCHED;
	s_mov_b32 m0, s68
	s_nop 0
	global_load_lds_dwordx4 v164, s[62:63]
	s_waitcnt vmcnt(8)
	s_waitcnt lgkmcnt(0)
	s_barrier
	s_setprio 1
	s_waitcnt lgkmcnt(0)
	v_mfma_f32_16x16x32_bf16 v[140:143], v[64:67], v[176:179], v[140:143]
	v_mfma_f32_16x16x32_bf16 v[136:139], v[72:75], v[176:179], v[136:139]
	v_mfma_f32_16x16x32_bf16 v[124:127], v[64:67], v[184:187], v[124:127]
	v_mfma_f32_16x16x32_bf16 v[120:123], v[72:75], v[184:187], v[120:123]
	v_mfma_f32_16x16x32_bf16 v[108:111], v[64:67], v[192:195], v[108:111]
	v_mfma_f32_16x16x32_bf16 v[104:107], v[72:75], v[192:195], v[104:107]
	v_mfma_f32_16x16x32_bf16 v[92:95], v[64:67], v[200:203], v[92:95]
	v_mfma_f32_16x16x32_bf16 v[88:91], v[72:75], v[200:203], v[88:91]
	v_mfma_f32_16x16x32_bf16 v[140:143], v[68:71], v[180:183], v[140:143]
	v_mfma_f32_16x16x32_bf16 v[136:139], v[76:79], v[180:183], v[136:139]
	v_mfma_f32_16x16x32_bf16 v[124:127], v[68:71], v[188:191], v[124:127]
	v_mfma_f32_16x16x32_bf16 v[120:123], v[76:79], v[188:191], v[120:123]
	v_mfma_f32_16x16x32_bf16 v[108:111], v[68:71], v[196:199], v[108:111]
	v_mfma_f32_16x16x32_bf16 v[104:107], v[76:79], v[196:199], v[104:107]
	v_mfma_f32_16x16x32_bf16 v[92:95], v[68:71], v[204:207], v[92:95]
	v_mfma_f32_16x16x32_bf16 v[88:91], v[76:79], v[204:207], v[88:91]


; #define PG8_STAGE(bufoff, gbase, voff) do { _Pragma("unroll") for (int _i = 0; _i < 2; ++_i) \
;         __builtin_amdgcn_global_load_lds((const unsigned*)((const char*)(gbase) + (voff)[_i]), (PG8_LAS unsigned*)(lds + (bufoff) + ldsw + _i * 8192), 16, 0, 0); } while (0)
; #define PG8_LDA(dst, b, h) do { _Pragma("unroll") for (int m = 0; m < 4; ++m) _Pragma("unroll") for (int k = 0; k < 2; ++k) dst[m][k] = *(const PG8_LAS bf16x8*)(lds + PG8_SA(b, h) + aoff + m * 2048 + k * 1024); } while (0)
; #define PG8_MMA(ai, bj, At, Bt) do { __builtin_amdgcn_s_setprio(1); _Pragma("unroll") for (int m = 0; m < 4; ++m) _Pragma("unroll") for (int n = 0; n < 2; ++n) _Pragma("unroll") for (int k = 0; k < 2; ++k) \
;         acc[ai][bj][m][n] = __builtin_amdgcn_mfma_f32_16x16x32_bf16(Bt[n][k], At[m][k], acc[ai][bj][m][n], 0, 0, 0); __builtin_amdgcn_s_setprio(0); } while (0)
; #define PG8_WAIT_V(n) asm volatile("s_waitcnt vmcnt(" #n ")" ::: "memory")
; #define PG8_WAIT_L(n) asm volatile("s_waitcnt lgkmcnt(" #n ")" ::: "memory")
; #define PG8_BAR __builtin_amdgcn_s_barrier()
; #define PG8_SCHED __builtin_amdgcn_sched_barrier(0)
; template <class Epi, class Sched, bool ALIGN_EPI = false, bool SP2 = false>
; __device__ __forceinline__ void gemm_phase(PG8_LAS unsigned char* lds, const Gemm g, const Sched& S, const Epi& E) {
;     ...
;             PG8_WAIT_V(8); PG8_WAIT_L(0); PG8_BAR; PG8_MMA(0, 0, At, B0); PG8_MMA(0, 1, At, B1); PG8_BAR; PG8_SCHED;
;             PG8_LDA(At, 1, 1); PG8_STAGE(PG8_SB(1, 0), b3, voffB); PG8_STAGE(PG8_SB(1, 1), b3 + hstep, voffB); PG8_STAGE(PG8_SA(1, 0), a3, voffA);
	v_mfma_f32_16x16x32_bf16 v[132:135], v[144:147], v[176:179], v[132:135]
	v_mfma_f32_16x16x32_bf16 v[128:131], v[152:155], v[176:179], v[128:131]
	v_mfma_f32_16x16x32_bf16 v[116:119], v[144:147], v[184:187], v[116:119]
	v_mfma_f32_16x16x32_bf16 v[112:115], v[152:155], v[184:187], v[112:115]
	v_mfma_f32_16x16x32_bf16 v[100:103], v[144:147], v[192:195], v[100:103]
	v_mfma_f32_16x16x32_bf16 v[96:99], v[152:155], v[192:195], v[96:99]
	v_mfma_f32_16x16x32_bf16 v[84:87], v[144:147], v[200:203], v[84:87]
	v_mfma_f32_16x16x32_bf16 v[80:83], v[152:155], v[200:203], v[80:83]
	v_mfma_f32_16x16x32_bf16 v[132:135], v[148:151], v[180:183], v[132:135]
	v_mfma_f32_16x16x32_bf16 v[128:131], v[156:159], v[180:183], v[128:131]
	v_mfma_f32_16x16x32_bf16 v[116:119], v[148:151], v[188:191], v[116:119]
	v_mfma_f32_16x16x32_bf16 v[112:115], v[156:159], v[188:191], v[112:115]
	v_mfma_f32_16x16x32_bf16 v[100:103], v[148:151], v[196:199], v[100:103]
	v_mfma_f32_16x16x32_bf16 v[96:99], v[156:159], v[196:199], v[96:99]
	v_mfma_f32_16x16x32_bf16 v[84:87], v[148:151], v[204:207], v[84:87]
	v_mfma_f32_16x16x32_bf16 v[80:83], v[156:159], v[204:207], v[80:83]
	s_setprio 0
	s_barrier
	s_add_i32 s62, s82, s64

; #define PG8_STAGE(bufoff, gbase, voff) do { _Pragma("unroll") for (int _i = 0; _i < 2; ++_i) \
;         __builtin_amdgcn_global_load_lds((const unsigned*)((const char*)(gbase) + (voff)[_i]), (PG8_LAS unsigned*)(lds + (bufoff) + ldsw + _i * 8192), 16, 0, 0); } while (0)
; #define PG8_LDA(dst, b, h) do { _Pragma("unroll") for (int m = 0; m < 4; ++m) _Pragma("unroll") for (int k = 0; k < 2; ++k) dst[m][k] = *(const PG8_LAS bf16x8*)(lds + PG8_SA(b, h) + aoff + m * 2048 + k * 1024); } while (0)
; template <class Epi, class Sched, bool ALIGN_EPI = false, bool SP2 = false>
; __device__ __forceinline__ void gemm_phase(PG8_LAS unsigned char* lds, const Gemm g, const Sched& S, const Epi& E) {
;     ...
;             PG8_LDA(At, 1, 1); PG8_STAGE(PG8_SB(1, 0), b3, voffB); PG8_STAGE(PG8_SB(1, 1), b3 + hstep, voffB); PG8_STAGE(PG8_SA(1, 0), a3, voffA);
	s_mov_b32 m0, s62
	ds_read_b128 v[176:179], v213 offset:49152
	ds_read_b128 v[180:183], v213 offset:50176
	ds_read_b128 v[184:187], v213 offset:51200
	ds_read_b128 v[188:191], v213 offset:52224
	ds_read_b128 v[192:195], v213 offset:53248
	ds_read_b128 v[196:199], v213 offset:54272
	ds_read_b128 v[200:203], v213 offset:55296
	ds_read_b128 v[204:207], v213 offset:56320
	global_load_lds_dwordx4 v250, s[96:97]
	s_add_i32 m0, s62, 0x2000
	s_add_u32 s60, s60, 0x80080

; #define PG8_STAGE(bufoff, gbase, voff) do { _Pragma("unroll") for (int _i = 0; _i < 2; ++_i) \
;         __builtin_amdgcn_global_load_lds((const unsigned*)((const char*)(gbase) + (voff)[_i]), (PG8_LAS unsigned*)(lds + (bufoff) + ldsw + _i * 8192), 16, 0, 0); } while (0)
; #define PG8_LDA(dst, b, h) do { _Pragma("unroll") for (int m = 0; m < 4; ++m) _Pragma("unroll") for (int k = 0; k < 2; ++k) dst[m][k] = *(const PG8_LAS bf16x8*)(lds + PG8_SA(b, h) + aoff + m * 2048 + k * 1024); } while (0)
; template <class Epi, class Sched, bool ALIGN_EPI = false, bool SP2 = false>
; __device__ __forceinline__ void gemm_phase(PG8_LAS unsigned char* lds, const Gemm g, const Sched& S, const Epi& E) {
;     ...
;             PG8_LDA(At, 1, 1); PG8_STAGE(PG8_SB(1, 0), b3, voffB); PG8_STAGE(PG8_SB(1, 1), b3 + hstep, voffB); PG8_STAGE(PG8_SA(1, 0), a3, voffA);
	s_addc_u32 s61, s61, 0
	s_add_i32 s62, s83, s64
	global_load_lds_dwordx4 v251, s[96:97]

; #define PG8_STAGE(bufoff, gbase, voff) do { _Pragma("unroll") for (int _i = 0; _i < 2; ++_i) \
;         __builtin_amdgcn_global_load_lds((const unsigned*)((const char*)(gbase) + (voff)[_i]), (PG8_LAS unsigned*)(lds + (bufoff) + ldsw + _i * 8192), 16, 0, 0); } while (0)
; #define PG8_LDA(dst, b, h) do { _Pragma("unroll") for (int m = 0; m < 4; ++m) _Pragma("unroll") for (int k = 0; k < 2; ++k) dst[m][k] = *(const PG8_LAS bf16x8*)(lds + PG8_SA(b, h) + aoff + m * 2048 + k * 1024); } while (0)
; template <class Epi, class Sched, bool ALIGN_EPI = false, bool SP2 = false>
; __device__ __forceinline__ void gemm_phase(PG8_LAS unsigned char* lds, const Gemm g, const Sched& S, const Epi& E) {
;     ...
;             PG8_LDA(At, 1, 1); PG8_STAGE(PG8_SB(1, 0), b3, voffB); PG8_STAGE(PG8_SB(1, 1), b3 + hstep, voffB); PG8_STAGE(PG8_SA(1, 0), a3, voffA);
	s_mov_b32 m0, s62
	s_nop 0
	global_load_lds_dwordx4 v162, s[60:61]

; #define PG8_STAGE(bufoff, gbase, voff) do { _Pragma("unroll") for (int _i = 0; _i < 2; ++_i) \
;         __builtin_amdgcn_global_load_lds((const unsigned*)((const char*)(gbase) + (voff)[_i]), (PG8_LAS unsigned*)(lds + (bufoff) + ldsw + _i * 8192), 16, 0, 0); } while (0)
; #define PG8_LDA(dst, b, h) do { _Pragma("unroll") for (int m = 0; m < 4; ++m) _Pragma("unroll") for (int k = 0; k < 2; ++k) dst[m][k] = *(const PG8_LAS bf16x8*)(lds + PG8_SA(b, h) + aoff + m * 2048 + k * 1024); } while (0)
; template <class Epi, class Sched, bool ALIGN_EPI = false, bool SP2 = false>
; __device__ __forceinline__ void gemm_phase(PG8_LAS unsigned char* lds, const Gemm g, const Sched& S, const Epi& E) {
;     ...
;             PG8_LDA(At, 1, 1); PG8_STAGE(PG8_SB(1, 0), b3, voffB); PG8_STAGE(PG8_SB(1, 1), b3 + hstep, voffB); PG8_STAGE(PG8_SA(1, 0), a3, voffA);
	s_add_i32 m0, s62, 0x2000
	s_nop 0
	global_load_lds_dwordx4 v166, s[60:61]

; #define PG8_STAGE(bufoff, gbase, voff) do { _Pragma("unroll") for (int _i = 0; _i < 2; ++_i) \
;         __builtin_amdgcn_global_load_lds((const unsigned*)((const char*)(gbase) + (voff)[_i]), (PG8_LAS unsigned*)(lds + (bufoff) + ldsw + _i * 8192), 16, 0, 0); } while (0)
; #define PG8_LDA(dst, b, h) do { _Pragma("unroll") for (int m = 0; m < 4; ++m) _Pragma("unroll") for (int k = 0; k < 2; ++k) dst[m][k] = *(const PG8_LAS bf16x8*)(lds + PG8_SA(b, h) + aoff + m * 2048 + k * 1024); } while (0)
; template <class Epi, class Sched, bool ALIGN_EPI = false, bool SP2 = false>
; __device__ __forceinline__ void gemm_phase(PG8_LAS unsigned char* lds, const Gemm g, const Sched& S, const Epi& E) {
;     ...
;             PG8_LDA(At, 1, 1); PG8_STAGE(PG8_SB(1, 0), b3, voffB); PG8_STAGE(PG8_SB(1, 1), b3 + hstep, voffB); PG8_STAGE(PG8_SA(1, 0), a3, voffA);
	s_mov_b32 m0, s70
	s_nop 0
	global_load_lds_dwordx4 v252, s[98:99]

; #define PG8_STAGE(bufoff, gbase, voff) do { _Pragma("unroll") for (int _i = 0; _i < 2; ++_i) \
;         __builtin_amdgcn_global_load_lds((const unsigned*)((const char*)(gbase) + (voff)[_i]), (PG8_LAS unsigned*)(lds + (bufoff) + ldsw + _i * 8192), 16, 0, 0); } while (0)
; #define PG8_LDA(dst, b, h) do { _Pragma("unroll") for (int m = 0; m < 4; ++m) _Pragma("unroll") for (int k = 0; k < 2; ++k) dst[m][k] = *(const PG8_LAS bf16x8*)(lds + PG8_SA(b, h) + aoff + m * 2048 + k * 1024); } while (0)
; #define PG8_MMA(ai, bj, At, Bt) do { __builtin_amdgcn_s_setprio(1); _Pragma("unroll") for (int m = 0; m < 4; ++m) _Pragma("unroll") for (int n = 0; n < 2; ++n) _Pragma("unroll") for (int k = 0; k < 2; ++k) \
;         acc[ai][bj][m][n] = __builtin_amdgcn_mfma_f32_16x16x32_bf16(Bt[n][k], At[m][k], acc[ai][bj][m][n], 0, 0, 0); __builtin_amdgcn_s_setprio(0); } while (0)
; #define PG8_WAIT_V(n) asm volatile("s_waitcnt vmcnt(" #n ")" ::: "memory")
; #define PG8_WAIT_L(n) asm volatile("s_waitcnt lgkmcnt(" #n ")" ::: "memory")
; #define PG8_BAR __builtin_amdgcn_s_barrier()
; #define PG8_SCHED __builtin_amdgcn_sched_barrier(0)
; template <class Epi, class Sched, bool ALIGN_EPI = false, bool SP2 = false>
; __device__ __forceinline__ void gemm_phase(PG8_LAS unsigned char* lds, const Gemm g, const Sched& S, const Epi& E) {
;     ...
;             PG8_LDA(At, 1, 1); PG8_STAGE(PG8_SB(1, 0), b3, voffB); PG8_STAGE(PG8_SB(1, 1), b3 + hstep, voffB); PG8_STAGE(PG8_SA(1, 0), a3, voffA);
;             PG8_WAIT_V(8); PG8_WAIT_L(0); PG8_BAR; PG8_MMA(1, 0, At, B0); PG8_MMA(1, 1, At, B1); PG8_BAR; PG8_SCHED;
	s_mov_b32 m0, s71
	s_nop 0
	global_load_lds_dwordx4 v253, s[98:99]
	s_waitcnt vmcnt(8)
	s_waitcnt lgkmcnt(0)
	s_barrier
	s_setprio 1
	s_waitcnt lgkmcnt(0)
	v_mfma_f32_16x16x32_bf16 v[60:63], v[64:67], v[176:179], v[60:63]
	v_mfma_f32_16x16x32_bf16 v[56:59], v[72:75], v[176:179], v[56:59]
	v_mfma_f32_16x16x32_bf16 v[44:47], v[64:67], v[184:187], v[44:47]
	v_mfma_f32_16x16x32_bf16 v[40:43], v[72:75], v[184:187], v[40:43]
	v_mfma_f32_16x16x32_bf16 v[28:31], v[64:67], v[192:195], v[28:31]
	v_mfma_f32_16x16x32_bf16 v[24:27], v[72:75], v[192:195], v[24:27]
	v_mfma_f32_16x16x32_bf16 v[12:15], v[64:67], v[200:203], v[12:15]
	v_mfma_f32_16x16x32_bf16 v[8:11], v[72:75], v[200:203], v[8:11]
	v_mfma_f32_16x16x32_bf16 v[60:63], v[68:71], v[180:183], v[60:63]
	v_mfma_f32_16x16x32_bf16 v[56:59], v[76:79], v[180:183], v[56:59]
	v_mfma_f32_16x16x32_bf16 v[44:47], v[68:71], v[188:191], v[44:47]
	v_mfma_f32_16x16x32_bf16 v[40:43], v[76:79], v[188:191], v[40:43]
	v_mfma_f32_16x16x32_bf16 v[28:31], v[68:71], v[196:199], v[28:31]
	v_mfma_f32_16x16x32_bf16 v[24:27], v[76:79], v[196:199], v[24:27]
	v_mfma_f32_16x16x32_bf16 v[12:15], v[68:71], v[204:207], v[12:15]
	v_mfma_f32_16x16x32_bf16 v[8:11], v[76:79], v[204:207], v[8:11]


; #define PG8_MMA(ai, bj, At, Bt) do { __builtin_amdgcn_s_setprio(1); _Pragma("unroll") for (int m = 0; m < 4; ++m) _Pragma("unroll") for (int n = 0; n < 2; ++n) _Pragma("unroll") for (int k = 0; k < 2; ++k) \
;         acc[ai][bj][m][n] = __builtin_amdgcn_mfma_f32_16x16x32_bf16(Bt[n][k], At[m][k], acc[ai][bj][m][n], 0, 0, 0); __builtin_amdgcn_s_setprio(0); } while (0)
; #define PG8_WAIT_V(n) asm volatile("s_waitcnt vmcnt(" #n ")" ::: "memory")
; #define PG8_WAIT_L(n) asm volatile("s_waitcnt lgkmcnt(" #n ")" ::: "memory")
; #define PG8_BAR __builtin_amdgcn_s_barrier()
; #define PG8_SCHED __builtin_amdgcn_sched_barrier(0)
; template <class Epi, class Sched, bool ALIGN_EPI = false, bool SP2 = false>
; __device__ __forceinline__ void gemm_phase(PG8_LAS unsigned char* lds, const Gemm g, const Sched& S, const Epi& E) {
;     ...
;             PG8_WAIT_V(8); PG8_WAIT_L(0); PG8_BAR; PG8_MMA(1, 0, At, B0); PG8_MMA(1, 1, At, B1); PG8_BAR; PG8_SCHED;
;     ...
;         if constexpr (ALIGN_EPI) { if (wr == 0) PG8_BAR; }
	v_mfma_f32_16x16x32_bf16 v[52:55], v[144:147], v[176:179], v[52:55]
	v_mfma_f32_16x16x32_bf16 v[48:51], v[152:155], v[176:179], v[48:51]
	v_mfma_f32_16x16x32_bf16 v[36:39], v[144:147], v[184:187], v[36:39]
	v_mfma_f32_16x16x32_bf16 v[32:35], v[152:155], v[184:187], v[32:35]
	v_mfma_f32_16x16x32_bf16 v[20:23], v[144:147], v[192:195], v[20:23]
	v_mfma_f32_16x16x32_bf16 v[16:19], v[152:155], v[192:195], v[16:19]
	v_mfma_f32_16x16x32_bf16 v[4:7], v[144:147], v[200:203], v[4:7]
	v_mfma_f32_16x16x32_bf16 v[0:3], v[152:155], v[200:203], v[0:3]
	v_mfma_f32_16x16x32_bf16 v[52:55], v[148:151], v[180:183], v[52:55]
	v_mfma_f32_16x16x32_bf16 v[48:51], v[156:159], v[180:183], v[48:51]
	v_mfma_f32_16x16x32_bf16 v[36:39], v[148:151], v[188:191], v[36:39]
	v_mfma_f32_16x16x32_bf16 v[32:35], v[156:159], v[188:191], v[32:35]
	v_mfma_f32_16x16x32_bf16 v[20:23], v[148:151], v[196:199], v[20:23]
	v_mfma_f32_16x16x32_bf16 v[16:19], v[156:159], v[196:199], v[16:19]
	v_mfma_f32_16x16x32_bf16 v[4:7], v[148:151], v[204:207], v[4:7]
	v_mfma_f32_16x16x32_bf16 v[0:3], v[156:159], v[204:207], v[0:3]
	s_setprio 0
	s_barrier
	s_add_i32 s81, s81, 2
	s_add_u32 s58, s58, 0x100
	s_addc_u32 s59, s59, 0
	s_add_u32 s79, s79, 0x100
	s_addc_u32 s80, s80, 0
	s_cmp_gt_u32 s81, 29
	s_cbranch_scc0 .LBB0_333
	s_and_b64 vcc, exec, s[42:43]
	s_cbranch_vccz .LBB0_336
	s_barrier

; #define PG8_STAGE(bufoff, gbase, voff) do { _Pragma("unroll") for (int _i = 0; _i < 2; ++_i) \
;         __builtin_amdgcn_global_load_lds((const unsigned*)((const char*)(gbase) + (voff)[_i]), (PG8_LAS unsigned*)(lds + (bufoff) + ldsw + _i * 8192), 16, 0, 0); } while (0)
; #define PG8_LDA(dst, b, h) do { _Pragma("unroll") for (int m = 0; m < 4; ++m) _Pragma("unroll") for (int k = 0; k < 2; ++k) dst[m][k] = *(const PG8_LAS bf16x8*)(lds + PG8_SA(b, h) + aoff + m * 2048 + k * 1024); } while (0)
; #define PG8_LDB(dst, b, h) do { _Pragma("unroll") for (int n = 0; n < 2; ++n) _Pragma("unroll") for (int k = 0; k < 2; ++k) dst[n][k] = *(const PG8_LAS bf16x8*)(lds + PG8_SB(b, h) + boff + n * 2048 + k * 1024); } while (0)
; #define PG8_SCHED __builtin_amdgcn_sched_barrier(0)
; template <class Epi, class Sched, bool ALIGN_EPI = false, bool SP2 = false>
; __device__ __forceinline__ void gemm_phase(PG8_LAS unsigned char* lds, const Gemm g, const Sched& S, const Epi& E) {
;     ...
;             const char* a1 = cA + (size_t)(t + 1) * kstep;
;             const char* a2 = last ? nA : cA + (size_t)(t + 2) * kstep; const char* b2 = last ? nB : cB + (size_t)(t + 2) * kstep;
;             const char* a3 = a2 + kstep; const char* b3 = b2 + kstep;
;             if (last && has_next) S.a_ready(nxt);
;             if constexpr (SP2) {
;             PG8_LDB(B0, 0, 0); PG8_LDB(B1, 0, 1); PG8_SCHED; PG8_LDA(At, 0, 0); PG8_STAGE(PG8_SA(1, 1), a1 + hstep, voffA);
.LBB0_428:
	ds_read_b128 v[128:131], v201
	ds_read_b128 v[132:135], v201 offset:1024
	ds_read_b128 v[136:139], v201 offset:2048
	ds_read_b128 v[140:143], v201 offset:3072
	ds_read_b128 v[144:147], v205
	ds_read_b128 v[148:151], v205 offset:1024
	ds_read_b128 v[152:155], v205 offset:2048
	ds_read_b128 v[156:159], v205 offset:3072
	s_add_u32 s12, s10, 0xfff80080
	s_addc_u32 s13, s11, -1
	s_cmp_eq_u32 s85, 28
	s_cselect_b32 s61, s55, s13
	s_cselect_b32 s60, s81, s12
	s_cselect_b32 s13, s53, s84
	s_cselect_b32 s12, s82, s83

; #define PG8_STAGE(bufoff, gbase, voff) do { _Pragma("unroll") for (int _i = 0; _i < 2; ++_i) \
;         __builtin_amdgcn_global_load_lds((const unsigned*)((const char*)(gbase) + (voff)[_i]), (PG8_LAS unsigned*)(lds + (bufoff) + ldsw + _i * 8192), 16, 0, 0); } while (0)
; #define PG8_LDA(dst, b, h) do { _Pragma("unroll") for (int m = 0; m < 4; ++m) _Pragma("unroll") for (int k = 0; k < 2; ++k) dst[m][k] = *(const PG8_LAS bf16x8*)(lds + PG8_SA(b, h) + aoff + m * 2048 + k * 1024); } while (0)
; #define PG8_LDB(dst, b, h) do { _Pragma("unroll") for (int n = 0; n < 2; ++n) _Pragma("unroll") for (int k = 0; k < 2; ++k) dst[n][k] = *(const PG8_LAS bf16x8*)(lds + PG8_SB(b, h) + boff + n * 2048 + k * 1024); } while (0)
; #define PG8_SCHED __builtin_amdgcn_sched_barrier(0)
; template <class Epi, class Sched, bool ALIGN_EPI = false, bool SP2 = false>
; __device__ __forceinline__ void gemm_phase(PG8_LAS unsigned char* lds, const Gemm g, const Sched& S, const Epi& E) {
;     ...
;             PG8_LDB(B0, 0, 0); PG8_LDB(B1, 0, 1); PG8_SCHED; PG8_LDA(At, 0, 0); PG8_STAGE(PG8_SA(1, 1), a1 + hstep, voffA);
	s_add_i32 m0, s65, 0xc000
	ds_read_b128 v[176:179], v207
	ds_read_b128 v[184:187], v207 offset:1024
	ds_read_b128 v[190:193], v207 offset:2048
	ds_read_b128 v[210:213], v207 offset:3072
	ds_read_b128 v[214:217], v207 offset:4096
	ds_read_b128 v[218:221], v207 offset:5120
	ds_read_b128 v[222:225], v207 offset:6144
	ds_read_b128 v[226:229], v207 offset:7168
	global_load_lds_dwordx4 v168, s[10:11]

; #define PG8_STAGE(bufoff, gbase, voff) do { _Pragma("unroll") for (int _i = 0; _i < 2; ++_i) \
;         __builtin_amdgcn_global_load_lds((const unsigned*)((const char*)(gbase) + (voff)[_i]), (PG8_LAS unsigned*)(lds + (bufoff) + ldsw + _i * 8192), 16, 0, 0); } while (0)
; #define PG8_LDA(dst, b, h) do { _Pragma("unroll") for (int m = 0; m < 4; ++m) _Pragma("unroll") for (int k = 0; k < 2; ++k) dst[m][k] = *(const PG8_LAS bf16x8*)(lds + PG8_SA(b, h) + aoff + m * 2048 + k * 1024); } while (0)
; #define PG8_LDB(dst, b, h) do { _Pragma("unroll") for (int n = 0; n < 2; ++n) _Pragma("unroll") for (int k = 0; k < 2; ++k) dst[n][k] = *(const PG8_LAS bf16x8*)(lds + PG8_SB(b, h) + boff + n * 2048 + k * 1024); } while (0)
; #define PG8_MMA(ai, bj, At, Bt) do { __builtin_amdgcn_s_setprio(1); _Pragma("unroll") for (int m = 0; m < 4; ++m) _Pragma("unroll") for (int n = 0; n < 2; ++n) _Pragma("unroll") for (int k = 0; k < 2; ++k) \
;         acc[ai][bj][m][n] = __builtin_amdgcn_mfma_f32_16x16x32_bf16(Bt[n][k], At[m][k], acc[ai][bj][m][n], 0, 0, 0); __builtin_amdgcn_s_setprio(0); } while (0)
; #define PG8_WAIT_V(n) asm volatile("s_waitcnt vmcnt(" #n ")" ::: "memory")
; #define PG8_WAIT_L(n) asm volatile("s_waitcnt lgkmcnt(" #n ")" ::: "memory")
; #define PG8_BAR __builtin_amdgcn_s_barrier()
; #define PG8_SCHED __builtin_amdgcn_sched_barrier(0)
; template <class Epi, class Sched, bool ALIGN_EPI = false, bool SP2 = false>
; __device__ __forceinline__ void gemm_phase(PG8_LAS unsigned char* lds, const Gemm g, const Sched& S, const Epi& E) {
;     ...
;             PG8_LDB(B0, 0, 0); PG8_LDB(B1, 0, 1); PG8_SCHED; PG8_LDA(At, 0, 0); PG8_STAGE(PG8_SA(1, 1), a1 + hstep, voffA);
;             PG8_WAIT_V(8); PG8_WAIT_L(0); PG8_BAR; PG8_MMA(0, 0, At, B0); PG8_MMA(0, 1, At, B1); PG8_BAR; PG8_SCHED;
	s_add_i32 m0, s65, 0xe000
	s_nop 0
	global_load_lds_dwordx4 v170, s[10:11]
	s_waitcnt vmcnt(8)
	s_waitcnt lgkmcnt(0)
	s_barrier
	s_setprio 1
	s_waitcnt lgkmcnt(0)
	v_mfma_f32_16x16x32_bf16 v[124:127], v[128:131], v[176:179], v[124:127]
	v_mfma_f32_16x16x32_bf16 v[120:123], v[136:139], v[176:179], v[120:123]
	v_mfma_f32_16x16x32_bf16 v[108:111], v[128:131], v[190:193], v[108:111]
	v_mfma_f32_16x16x32_bf16 v[104:107], v[136:139], v[190:193], v[104:107]
	v_mfma_f32_16x16x32_bf16 v[92:95], v[128:131], v[214:217], v[92:95]
	v_mfma_f32_16x16x32_bf16 v[88:91], v[136:139], v[214:217], v[88:91]
	v_mfma_f32_16x16x32_bf16 v[76:79], v[128:131], v[222:225], v[76:79]
	v_mfma_f32_16x16x32_bf16 v[72:75], v[136:139], v[222:225], v[72:75]
	v_mfma_f32_16x16x32_bf16 v[124:127], v[132:135], v[184:187], v[124:127]
	v_mfma_f32_16x16x32_bf16 v[120:123], v[140:143], v[184:187], v[120:123]
	v_mfma_f32_16x16x32_bf16 v[108:111], v[132:135], v[210:213], v[108:111]
	v_mfma_f32_16x16x32_bf16 v[104:107], v[140:143], v[210:213], v[104:107]
	v_mfma_f32_16x16x32_bf16 v[92:95], v[132:135], v[218:221], v[92:95]
	v_mfma_f32_16x16x32_bf16 v[88:91], v[140:143], v[218:221], v[88:91]
	v_mfma_f32_16x16x32_bf16 v[76:79], v[132:135], v[226:229], v[76:79]
	v_mfma_f32_16x16x32_bf16 v[72:75], v[140:143], v[226:229], v[72:75]


; #define PG8_STAGE(bufoff, gbase, voff) do { _Pragma("unroll") for (int _i = 0; _i < 2; ++_i) \
;         __builtin_amdgcn_global_load_lds((const unsigned*)((const char*)(gbase) + (voff)[_i]), (PG8_LAS unsigned*)(lds + (bufoff) + ldsw + _i * 8192), 16, 0, 0); } while (0)
; #define PG8_LDA(dst, b, h) do { _Pragma("unroll") for (int m = 0; m < 4; ++m) _Pragma("unroll") for (int k = 0; k < 2; ++k) dst[m][k] = *(const PG8_LAS bf16x8*)(lds + PG8_SA(b, h) + aoff + m * 2048 + k * 1024); } while (0)
; #define PG8_MMA(ai, bj, At, Bt) do { __builtin_amdgcn_s_setprio(1); _Pragma("unroll") for (int m = 0; m < 4; ++m) _Pragma("unroll") for (int n = 0; n < 2; ++n) _Pragma("unroll") for (int k = 0; k < 2; ++k) \
;         acc[ai][bj][m][n] = __builtin_amdgcn_mfma_f32_16x16x32_bf16(Bt[n][k], At[m][k], acc[ai][bj][m][n], 0, 0, 0); __builtin_amdgcn_s_setprio(0); } while (0)
; #define PG8_WAIT_V(n) asm volatile("s_waitcnt vmcnt(" #n ")" ::: "memory")
; #define PG8_WAIT_L(n) asm volatile("s_waitcnt lgkmcnt(" #n ")" ::: "memory")
; #define PG8_BAR __builtin_amdgcn_s_barrier()
; #define PG8_SCHED __builtin_amdgcn_sched_barrier(0)
; template <class Epi, class Sched, bool ALIGN_EPI = false, bool SP2 = false>
; __device__ __forceinline__ void gemm_phase(PG8_LAS unsigned char* lds, const Gemm g, const Sched& S, const Epi& E) {
;     ...
;             PG8_WAIT_V(8); PG8_WAIT_L(0); PG8_BAR; PG8_MMA(0, 0, At, B0); PG8_MMA(0, 1, At, B1); PG8_BAR; PG8_SCHED;
;             PG8_LDA(At, 0, 1); PG8_STAGE(PG8_SB(0, 0), b2, voffB); PG8_STAGE(PG8_SB(0, 1), b2 + hstep, voffB); PG8_STAGE(PG8_SA(0, 0), a2, voffA);
	v_mfma_f32_16x16x32_bf16 v[116:119], v[144:147], v[176:179], v[116:119]
	v_mfma_f32_16x16x32_bf16 v[112:115], v[152:155], v[176:179], v[112:115]
	v_mfma_f32_16x16x32_bf16 v[100:103], v[144:147], v[190:193], v[100:103]
	v_mfma_f32_16x16x32_bf16 v[96:99], v[152:155], v[190:193], v[96:99]
	v_mfma_f32_16x16x32_bf16 v[84:87], v[144:147], v[214:217], v[84:87]
	v_mfma_f32_16x16x32_bf16 v[80:83], v[152:155], v[214:217], v[80:83]
	v_mfma_f32_16x16x32_bf16 v[68:71], v[144:147], v[222:225], v[68:71]
	v_mfma_f32_16x16x32_bf16 v[64:67], v[152:155], v[222:225], v[64:67]
	v_mfma_f32_16x16x32_bf16 v[116:119], v[148:151], v[184:187], v[116:119]
	v_mfma_f32_16x16x32_bf16 v[112:115], v[156:159], v[184:187], v[112:115]
	v_mfma_f32_16x16x32_bf16 v[100:103], v[148:151], v[210:213], v[100:103]
	v_mfma_f32_16x16x32_bf16 v[96:99], v[156:159], v[210:213], v[96:99]
	v_mfma_f32_16x16x32_bf16 v[84:87], v[148:151], v[218:221], v[84:87]
	v_mfma_f32_16x16x32_bf16 v[80:83], v[156:159], v[218:221], v[80:83]
	v_mfma_f32_16x16x32_bf16 v[68:71], v[148:151], v[226:229], v[68:71]
	v_mfma_f32_16x16x32_bf16 v[64:67], v[156:159], v[226:229], v[64:67]
	s_setprio 0
	s_barrier
	s_add_i32 s86, s75, s64
	s_mov_b64 s[96:97], s[12:13]

; #define PG8_STAGE(bufoff, gbase, voff) do { _Pragma("unroll") for (int _i = 0; _i < 2; ++_i) \
;         __builtin_amdgcn_global_load_lds((const unsigned*)((const char*)(gbase) + (voff)[_i]), (PG8_LAS unsigned*)(lds + (bufoff) + ldsw + _i * 8192), 16, 0, 0); } while (0)
; #define PG8_LDA(dst, b, h) do { _Pragma("unroll") for (int m = 0; m < 4; ++m) _Pragma("unroll") for (int k = 0; k < 2; ++k) dst[m][k] = *(const PG8_LAS bf16x8*)(lds + PG8_SA(b, h) + aoff + m * 2048 + k * 1024); } while (0)
; template <class Epi, class Sched, bool ALIGN_EPI = false, bool SP2 = false>
; __device__ __forceinline__ void gemm_phase(PG8_LAS unsigned char* lds, const Gemm g, const Sched& S, const Epi& E) {
;     ...
;             PG8_LDA(At, 0, 1); PG8_STAGE(PG8_SB(0, 0), b2, voffB); PG8_STAGE(PG8_SB(0, 1), b2 + hstep, voffB); PG8_STAGE(PG8_SA(0, 0), a2, voffA);
	s_mov_b32 m0, s86
	ds_read_b128 v[176:179], v207 offset:16384
	ds_read_b128 v[184:187], v207 offset:17408
	ds_read_b128 v[190:193], v207 offset:18432
	ds_read_b128 v[210:213], v207 offset:19456
	ds_read_b128 v[214:217], v207 offset:20480
	ds_read_b128 v[218:221], v207 offset:21504
	ds_read_b128 v[222:225], v207 offset:22528
	ds_read_b128 v[226:229], v207 offset:23552
	global_load_lds_dwordx4 v162, s[12:13]
	s_add_i32 m0, s86, 0x2000
	s_add_u32 s86, s12, 0x80000

; #define PG8_STAGE(bufoff, gbase, voff) do { _Pragma("unroll") for (int _i = 0; _i < 2; ++_i) \
;         __builtin_amdgcn_global_load_lds((const unsigned*)((const char*)(gbase) + (voff)[_i]), (PG8_LAS unsigned*)(lds + (bufoff) + ldsw + _i * 8192), 16, 0, 0); } while (0)
; #define PG8_LDA(dst, b, h) do { _Pragma("unroll") for (int m = 0; m < 4; ++m) _Pragma("unroll") for (int k = 0; k < 2; ++k) dst[m][k] = *(const PG8_LAS bf16x8*)(lds + PG8_SA(b, h) + aoff + m * 2048 + k * 1024); } while (0)
; template <class Epi, class Sched, bool ALIGN_EPI = false, bool SP2 = false>
; __device__ __forceinline__ void gemm_phase(PG8_LAS unsigned char* lds, const Gemm g, const Sched& S, const Epi& E) {
;     ...
;             PG8_LDA(At, 0, 1); PG8_STAGE(PG8_SB(0, 0), b2, voffB); PG8_STAGE(PG8_SB(0, 1), b2 + hstep, voffB); PG8_STAGE(PG8_SA(0, 0), a2, voffA);
	s_addc_u32 s87, s13, 0
	s_add_i32 s88, s76, s64
	global_load_lds_dwordx4 v166, s[12:13]

; #define PG8_STAGE(bufoff, gbase, voff) do { _Pragma("unroll") for (int _i = 0; _i < 2; ++_i) \
;         __builtin_amdgcn_global_load_lds((const unsigned*)((const char*)(gbase) + (voff)[_i]), (PG8_LAS unsigned*)(lds + (bufoff) + ldsw + _i * 8192), 16, 0, 0); } while (0)
; #define PG8_LDA(dst, b, h) do { _Pragma("unroll") for (int m = 0; m < 4; ++m) _Pragma("unroll") for (int k = 0; k < 2; ++k) dst[m][k] = *(const PG8_LAS bf16x8*)(lds + PG8_SA(b, h) + aoff + m * 2048 + k * 1024); } while (0)
; template <class Epi, class Sched, bool ALIGN_EPI = false, bool SP2 = false>
; __device__ __forceinline__ void gemm_phase(PG8_LAS unsigned char* lds, const Gemm g, const Sched& S, const Epi& E) {
;     ...
;             PG8_LDA(At, 0, 1); PG8_STAGE(PG8_SB(0, 0), b2, voffB); PG8_STAGE(PG8_SB(0, 1), b2 + hstep, voffB); PG8_STAGE(PG8_SA(0, 0), a2, voffA);
	s_mov_b32 m0, s88
	s_nop 0
	global_load_lds_dwordx4 v162, s[86:87]

; #define PG8_STAGE(bufoff, gbase, voff) do { _Pragma("unroll") for (int _i = 0; _i < 2; ++_i) \
;         __builtin_amdgcn_global_load_lds((const unsigned*)((const char*)(gbase) + (voff)[_i]), (PG8_LAS unsigned*)(lds + (bufoff) + ldsw + _i * 8192), 16, 0, 0); } while (0)
; #define PG8_LDA(dst, b, h) do { _Pragma("unroll") for (int m = 0; m < 4; ++m) _Pragma("unroll") for (int k = 0; k < 2; ++k) dst[m][k] = *(const PG8_LAS bf16x8*)(lds + PG8_SA(b, h) + aoff + m * 2048 + k * 1024); } while (0)
; template <class Epi, class Sched, bool ALIGN_EPI = false, bool SP2 = false>
; __device__ __forceinline__ void gemm_phase(PG8_LAS unsigned char* lds, const Gemm g, const Sched& S, const Epi& E) {
;     ...
;             PG8_LDA(At, 0, 1); PG8_STAGE(PG8_SB(0, 0), b2, voffB); PG8_STAGE(PG8_SB(0, 1), b2 + hstep, voffB); PG8_STAGE(PG8_SA(0, 0), a2, voffA);
	s_add_i32 m0, s88, 0x2000
	s_nop 0
	global_load_lds_dwordx4 v166, s[86:87]
	s_mov_b64 s[98:99], s[60:61]

; #define PG8_STAGE(bufoff, gbase, voff) do { _Pragma("unroll") for (int _i = 0; _i < 2; ++_i) \
;         __builtin_amdgcn_global_load_lds((const unsigned*)((const char*)(gbase) + (voff)[_i]), (PG8_LAS unsigned*)(lds + (bufoff) + ldsw + _i * 8192), 16, 0, 0); } while (0)
; #define PG8_LDA(dst, b, h) do { _Pragma("unroll") for (int m = 0; m < 4; ++m) _Pragma("unroll") for (int k = 0; k < 2; ++k) dst[m][k] = *(const PG8_LAS bf16x8*)(lds + PG8_SA(b, h) + aoff + m * 2048 + k * 1024); } while (0)
; #define PG8_MMA(ai, bj, At, Bt) do { __builtin_amdgcn_s_setprio(1); _Pragma("unroll") for (int m = 0; m < 4; ++m) _Pragma("unroll") for (int n = 0; n < 2; ++n) _Pragma("unroll") for (int k = 0; k < 2; ++k) \
;         acc[ai][bj][m][n] = __builtin_amdgcn_mfma_f32_16x16x32_bf16(Bt[n][k], At[m][k], acc[ai][bj][m][n], 0, 0, 0); __builtin_amdgcn_s_setprio(0); } while (0)
; #define PG8_WAIT_V(n) asm volatile("s_waitcnt vmcnt(" #n ")" ::: "memory")
; #define PG8_WAIT_L(n) asm volatile("s_waitcnt lgkmcnt(" #n ")" ::: "memory")
; #define PG8_BAR __builtin_amdgcn_s_barrier()
; #define PG8_SCHED __builtin_amdgcn_sched_barrier(0)
; template <class Epi, class Sched, bool ALIGN_EPI = false, bool SP2 = false>
; __device__ __forceinline__ void gemm_phase(PG8_LAS unsigned char* lds, const Gemm g, const Sched& S, const Epi& E) {
;     ...
;             PG8_LDA(At, 0, 1); PG8_STAGE(PG8_SB(0, 0), b2, voffB); PG8_STAGE(PG8_SB(0, 1), b2 + hstep, voffB); PG8_STAGE(PG8_SA(0, 0), a2, voffA);
;             PG8_WAIT_V(8); PG8_WAIT_L(0); PG8_BAR; PG8_MMA(1, 0, At, B0); PG8_MMA(1, 1, At, B1); PG8_BAR; PG8_SCHED;
	s_mov_b32 m0, s65
	s_nop 0
	global_load_lds_dwordx4 v160, s[60:61]
	s_mov_b32 m0, s67
	s_nop 0
	global_load_lds_dwordx4 v164, s[60:61]
	s_waitcnt vmcnt(8)
	s_waitcnt lgkmcnt(0)
	s_barrier
	s_setprio 1
	s_waitcnt lgkmcnt(0)
	v_mfma_f32_16x16x32_bf16 v[60:63], v[128:131], v[176:179], v[60:63]
	v_mfma_f32_16x16x32_bf16 v[56:59], v[136:139], v[176:179], v[56:59]
	v_mfma_f32_16x16x32_bf16 v[44:47], v[128:131], v[190:193], v[44:47]
	v_mfma_f32_16x16x32_bf16 v[40:43], v[136:139], v[190:193], v[40:43]
	v_mfma_f32_16x16x32_bf16 v[28:31], v[128:131], v[214:217], v[28:31]
	v_mfma_f32_16x16x32_bf16 v[24:27], v[136:139], v[214:217], v[24:27]
	v_mfma_f32_16x16x32_bf16 v[12:15], v[128:131], v[222:225], v[12:15]
	v_mfma_f32_16x16x32_bf16 v[8:11], v[136:139], v[222:225], v[8:11]
	v_mfma_f32_16x16x32_bf16 v[60:63], v[132:135], v[184:187], v[60:63]
	v_mfma_f32_16x16x32_bf16 v[56:59], v[140:143], v[184:187], v[56:59]
	v_mfma_f32_16x16x32_bf16 v[44:47], v[132:135], v[210:213], v[44:47]
	v_mfma_f32_16x16x32_bf16 v[40:43], v[140:143], v[210:213], v[40:43]
	v_mfma_f32_16x16x32_bf16 v[28:31], v[132:135], v[218:221], v[28:31]
	v_mfma_f32_16x16x32_bf16 v[24:27], v[140:143], v[218:221], v[24:27]
	v_mfma_f32_16x16x32_bf16 v[12:15], v[132:135], v[226:229], v[12:15]
	v_mfma_f32_16x16x32_bf16 v[8:11], v[140:143], v[226:229], v[8:11]


; #define PG8_STAGE(bufoff, gbase, voff) do { _Pragma("unroll") for (int _i = 0; _i < 2; ++_i) \
;         __builtin_amdgcn_global_load_lds((const unsigned*)((const char*)(gbase) + (voff)[_i]), (PG8_LAS unsigned*)(lds + (bufoff) + ldsw + _i * 8192), 16, 0, 0); } while (0)
; #define PG8_LDA(dst, b, h) do { _Pragma("unroll") for (int m = 0; m < 4; ++m) _Pragma("unroll") for (int k = 0; k < 2; ++k) dst[m][k] = *(const PG8_LAS bf16x8*)(lds + PG8_SA(b, h) + aoff + m * 2048 + k * 1024); } while (0)
; #define PG8_LDB(dst, b, h) do { _Pragma("unroll") for (int n = 0; n < 2; ++n) _Pragma("unroll") for (int k = 0; k < 2; ++k) dst[n][k] = *(const PG8_LAS bf16x8*)(lds + PG8_SB(b, h) + boff + n * 2048 + k * 1024); } while (0)
; #define PG8_MMA(ai, bj, At, Bt) do { __builtin_amdgcn_s_setprio(1); _Pragma("unroll") for (int m = 0; m < 4; ++m) _Pragma("unroll") for (int n = 0; n < 2; ++n) _Pragma("unroll") for (int k = 0; k < 2; ++k) \
;         acc[ai][bj][m][n] = __builtin_amdgcn_mfma_f32_16x16x32_bf16(Bt[n][k], At[m][k], acc[ai][bj][m][n], 0, 0, 0); __builtin_amdgcn_s_setprio(0); } while (0)
; #define PG8_WAIT_V(n) asm volatile("s_waitcnt vmcnt(" #n ")" ::: "memory")
; #define PG8_WAIT_L(n) asm volatile("s_waitcnt lgkmcnt(" #n ")" ::: "memory")
; #define PG8_BAR __builtin_amdgcn_s_barrier()
; #define PG8_SCHED __builtin_amdgcn_sched_barrier(0)
; template <class Epi, class Sched, bool ALIGN_EPI = false, bool SP2 = false>
; __device__ __forceinline__ void gemm_phase(PG8_LAS unsigned char* lds, const Gemm g, const Sched& S, const Epi& E) {
;     ...
;             PG8_WAIT_V(8); PG8_WAIT_L(0); PG8_BAR; PG8_MMA(1, 0, At, B0); PG8_MMA(1, 1, At, B1); PG8_BAR; PG8_SCHED;
;             PG8_LDB(B0, 1, 0); PG8_LDB(B1, 1, 1); PG8_SCHED; PG8_LDA(At, 1, 0); PG8_STAGE(PG8_SA(0, 1), a2 + hstep, voffA);
	v_mfma_f32_16x16x32_bf16 v[52:55], v[144:147], v[176:179], v[52:55]
	v_mfma_f32_16x16x32_bf16 v[48:51], v[152:155], v[176:179], v[48:51]
	v_mfma_f32_16x16x32_bf16 v[36:39], v[144:147], v[190:193], v[36:39]
	v_mfma_f32_16x16x32_bf16 v[32:35], v[152:155], v[190:193], v[32:35]
	v_mfma_f32_16x16x32_bf16 v[20:23], v[144:147], v[214:217], v[20:23]
	v_mfma_f32_16x16x32_bf16 v[16:19], v[152:155], v[214:217], v[16:19]
	v_mfma_f32_16x16x32_bf16 v[4:7], v[144:147], v[222:225], v[4:7]
	v_mfma_f32_16x16x32_bf16 v[0:3], v[152:155], v[222:225], v[0:3]
	v_mfma_f32_16x16x32_bf16 v[52:55], v[148:151], v[184:187], v[52:55]
	v_mfma_f32_16x16x32_bf16 v[48:51], v[156:159], v[184:187], v[48:51]
	v_mfma_f32_16x16x32_bf16 v[36:39], v[148:151], v[210:213], v[36:39]
	v_mfma_f32_16x16x32_bf16 v[32:35], v[156:159], v[210:213], v[32:35]
	v_mfma_f32_16x16x32_bf16 v[20:23], v[148:151], v[218:221], v[20:23]
	v_mfma_f32_16x16x32_bf16 v[16:19], v[156:159], v[218:221], v[16:19]
	v_mfma_f32_16x16x32_bf16 v[4:7], v[148:151], v[226:229], v[4:7]
	v_mfma_f32_16x16x32_bf16 v[0:3], v[156:159], v[226:229], v[0:3]
	s_setprio 0
	s_barrier
	s_add_i32 s86, 0, 0x18000
	s_add_i32 s87, 0, 0x1c000
	v_add_u32_e32 v140, s86, v189
	v_add_u32_e32 v156, s87, v189
	ds_read_b128 v[128:131], v140
	ds_read_b128 v[132:135], v140 offset:1024
	ds_read_b128 v[136:139], v140 offset:2048
	ds_read_b128 v[140:143], v140 offset:3072
	ds_read_b128 v[144:147], v156
	ds_read_b128 v[148:151], v156 offset:1024
	ds_read_b128 v[152:155], v156 offset:2048
	ds_read_b128 v[156:159], v156 offset:3072
	s_add_u32 s60, s60, 0x80000
	s_addc_u32 s61, s61, 0
	s_mov_b32 m0, s68

; #define PG8_STAGE(bufoff, gbase, voff) do { _Pragma("unroll") for (int _i = 0; _i < 2; ++_i) \
;         __builtin_amdgcn_global_load_lds((const unsigned*)((const char*)(gbase) + (voff)[_i]), (PG8_LAS unsigned*)(lds + (bufoff) + ldsw + _i * 8192), 16, 0, 0); } while (0)
; #define PG8_LDA(dst, b, h) do { _Pragma("unroll") for (int m = 0; m < 4; ++m) _Pragma("unroll") for (int k = 0; k < 2; ++k) dst[m][k] = *(const PG8_LAS bf16x8*)(lds + PG8_SA(b, h) + aoff + m * 2048 + k * 1024); } while (0)
; #define PG8_LDB(dst, b, h) do { _Pragma("unroll") for (int n = 0; n < 2; ++n) _Pragma("unroll") for (int k = 0; k < 2; ++k) dst[n][k] = *(const PG8_LAS bf16x8*)(lds + PG8_SB(b, h) + boff + n * 2048 + k * 1024); } while (0)
; #define PG8_SCHED __builtin_amdgcn_sched_barrier(0)
; template <class Epi, class Sched, bool ALIGN_EPI = false, bool SP2 = false>
; __device__ __forceinline__ void gemm_phase(PG8_LAS unsigned char* lds, const Gemm g, const Sched& S, const Epi& E) {
;     ...
;             PG8_LDB(B0, 1, 0); PG8_LDB(B1, 1, 1); PG8_SCHED; PG8_LDA(At, 1, 0); PG8_STAGE(PG8_SA(0, 1), a2 + hstep, voffA);
	ds_read_b128 v[176:179], v207 offset:32768
	ds_read_b128 v[184:187], v207 offset:33792
	ds_read_b128 v[190:193], v207 offset:34816
	ds_read_b128 v[210:213], v207 offset:35840
	ds_read_b128 v[214:217], v207 offset:36864
	ds_read_b128 v[218:221], v207 offset:37888
	ds_read_b128 v[222:225], v207 offset:38912
	ds_read_b128 v[226:229], v207 offset:39936
	global_load_lds_dwordx4 v160, s[60:61]

; #define PG8_STAGE(bufoff, gbase, voff) do { _Pragma("unroll") for (int _i = 0; _i < 2; ++_i) \
;         __builtin_amdgcn_global_load_lds((const unsigned*)((const char*)(gbase) + (voff)[_i]), (PG8_LAS unsigned*)(lds + (bufoff) + ldsw + _i * 8192), 16, 0, 0); } while (0)
; #define PG8_LDA(dst, b, h) do { _Pragma("unroll") for (int m = 0; m < 4; ++m) _Pragma("unroll") for (int k = 0; k < 2; ++k) dst[m][k] = *(const PG8_LAS bf16x8*)(lds + PG8_SA(b, h) + aoff + m * 2048 + k * 1024); } while (0)
; #define PG8_LDB(dst, b, h) do { _Pragma("unroll") for (int n = 0; n < 2; ++n) _Pragma("unroll") for (int k = 0; k < 2; ++k) dst[n][k] = *(const PG8_LAS bf16x8*)(lds + PG8_SB(b, h) + boff + n * 2048 + k * 1024); } while (0)
; #define PG8_MMA(ai, bj, At, Bt) do { __builtin_amdgcn_s_setprio(1); _Pragma("unroll") for (int m = 0; m < 4; ++m) _Pragma("unroll") for (int n = 0; n < 2; ++n) _Pragma("unroll") for (int k = 0; k < 2; ++k) \
;         acc[ai][bj][m][n] = __builtin_amdgcn_mfma_f32_16x16x32_bf16(Bt[n][k], At[m][k], acc[ai][bj][m][n], 0, 0, 0); __builtin_amdgcn_s_setprio(0); } while (0)
; #define PG8_WAIT_V(n) asm volatile("s_waitcnt vmcnt(" #n ")" ::: "memory")
; #define PG8_WAIT_L(n) asm volatile("s_waitcnt lgkmcnt(" #n ")" ::: "memory")
; #define PG8_BAR __builtin_amdgcn_s_barrier()
; #define PG8_SCHED __builtin_amdgcn_sched_barrier(0)
; template <class Epi, class Sched, bool ALIGN_EPI = false, bool SP2 = false>
; __device__ __forceinline__ void gemm_phase(PG8_LAS unsigned char* lds, const Gemm g, const Sched& S, const Epi& E) {
;     ...
;             PG8_LDB(B0, 1, 0); PG8_LDB(B1, 1, 1); PG8_SCHED; PG8_LDA(At, 1, 0); PG8_STAGE(PG8_SA(0, 1), a2 + hstep, voffA);
;             PG8_WAIT_V(8); PG8_WAIT_L(0); PG8_BAR; PG8_MMA(0, 0, At, B0); PG8_MMA(0, 1, At, B1); PG8_BAR; PG8_SCHED;
	s_mov_b32 m0, s69
	s_nop 0
	global_load_lds_dwordx4 v164, s[60:61]
	s_waitcnt vmcnt(8)
	s_waitcnt lgkmcnt(0)
	s_barrier
	s_setprio 1
	s_waitcnt lgkmcnt(0)
	v_mfma_f32_16x16x32_bf16 v[124:127], v[128:131], v[176:179], v[124:127]
	v_mfma_f32_16x16x32_bf16 v[120:123], v[136:139], v[176:179], v[120:123]
	v_mfma_f32_16x16x32_bf16 v[108:111], v[128:131], v[190:193], v[108:111]
	v_mfma_f32_16x16x32_bf16 v[104:107], v[136:139], v[190:193], v[104:107]
	v_mfma_f32_16x16x32_bf16 v[92:95], v[128:131], v[214:217], v[92:95]
	v_mfma_f32_16x16x32_bf16 v[88:91], v[136:139], v[214:217], v[88:91]
	v_mfma_f32_16x16x32_bf16 v[76:79], v[128:131], v[222:225], v[76:79]
	v_mfma_f32_16x16x32_bf16 v[72:75], v[136:139], v[222:225], v[72:75]
	v_mfma_f32_16x16x32_bf16 v[124:127], v[132:135], v[184:187], v[124:127]
	v_mfma_f32_16x16x32_bf16 v[120:123], v[140:143], v[184:187], v[120:123]
	v_mfma_f32_16x16x32_bf16 v[108:111], v[132:135], v[210:213], v[108:111]
	v_mfma_f32_16x16x32_bf16 v[104:107], v[140:143], v[210:213], v[104:107]
	v_mfma_f32_16x16x32_bf16 v[92:95], v[132:135], v[218:221], v[92:95]
	v_mfma_f32_16x16x32_bf16 v[88:91], v[140:143], v[218:221], v[88:91]
	v_mfma_f32_16x16x32_bf16 v[76:79], v[132:135], v[226:229], v[76:79]
	v_mfma_f32_16x16x32_bf16 v[72:75], v[140:143], v[226:229], v[72:75]


; #define PG8_STAGE(bufoff, gbase, voff) do { _Pragma("unroll") for (int _i = 0; _i < 2; ++_i) \
;         __builtin_amdgcn_global_load_lds((const unsigned*)((const char*)(gbase) + (voff)[_i]), (PG8_LAS unsigned*)(lds + (bufoff) + ldsw + _i * 8192), 16, 0, 0); } while (0)
; #define PG8_LDA(dst, b, h) do { _Pragma("unroll") for (int m = 0; m < 4; ++m) _Pragma("unroll") for (int k = 0; k < 2; ++k) dst[m][k] = *(const PG8_LAS bf16x8*)(lds + PG8_SA(b, h) + aoff + m * 2048 + k * 1024); } while (0)
; #define PG8_MMA(ai, bj, At, Bt) do { __builtin_amdgcn_s_setprio(1); _Pragma("unroll") for (int m = 0; m < 4; ++m) _Pragma("unroll") for (int n = 0; n < 2; ++n) _Pragma("unroll") for (int k = 0; k < 2; ++k) \
;         acc[ai][bj][m][n] = __builtin_amdgcn_mfma_f32_16x16x32_bf16(Bt[n][k], At[m][k], acc[ai][bj][m][n], 0, 0, 0); __builtin_amdgcn_s_setprio(0); } while (0)
; #define PG8_WAIT_V(n) asm volatile("s_waitcnt vmcnt(" #n ")" ::: "memory")
; #define PG8_WAIT_L(n) asm volatile("s_waitcnt lgkmcnt(" #n ")" ::: "memory")
; #define PG8_BAR __builtin_amdgcn_s_barrier()
; #define PG8_SCHED __builtin_amdgcn_sched_barrier(0)
; template <class Epi, class Sched, bool ALIGN_EPI = false, bool SP2 = false>
; __device__ __forceinline__ void gemm_phase(PG8_LAS unsigned char* lds, const Gemm g, const Sched& S, const Epi& E) {
;     ...
;             PG8_WAIT_V(8); PG8_WAIT_L(0); PG8_BAR; PG8_MMA(0, 0, At, B0); PG8_MMA(0, 1, At, B1); PG8_BAR; PG8_SCHED;
;             PG8_LDA(At, 1, 1); PG8_STAGE(PG8_SB(1, 0), b3, voffB); PG8_STAGE(PG8_SB(1, 1), b3 + hstep, voffB); PG8_STAGE(PG8_SA(1, 0), a3, voffA);
	v_mfma_f32_16x16x32_bf16 v[116:119], v[144:147], v[176:179], v[116:119]
	v_mfma_f32_16x16x32_bf16 v[112:115], v[152:155], v[176:179], v[112:115]
	v_mfma_f32_16x16x32_bf16 v[100:103], v[144:147], v[190:193], v[100:103]
	v_mfma_f32_16x16x32_bf16 v[96:99], v[152:155], v[190:193], v[96:99]
	v_mfma_f32_16x16x32_bf16 v[84:87], v[144:147], v[214:217], v[84:87]
	v_mfma_f32_16x16x32_bf16 v[80:83], v[152:155], v[214:217], v[80:83]
	v_mfma_f32_16x16x32_bf16 v[68:71], v[144:147], v[222:225], v[68:71]
	v_mfma_f32_16x16x32_bf16 v[64:67], v[152:155], v[222:225], v[64:67]
	v_mfma_f32_16x16x32_bf16 v[116:119], v[148:151], v[184:187], v[116:119]
	v_mfma_f32_16x16x32_bf16 v[112:115], v[156:159], v[184:187], v[112:115]
	v_mfma_f32_16x16x32_bf16 v[100:103], v[148:151], v[210:213], v[100:103]
	v_mfma_f32_16x16x32_bf16 v[96:99], v[156:159], v[210:213], v[96:99]
	v_mfma_f32_16x16x32_bf16 v[84:87], v[148:151], v[218:221], v[84:87]
	v_mfma_f32_16x16x32_bf16 v[80:83], v[156:159], v[218:221], v[80:83]
	v_mfma_f32_16x16x32_bf16 v[68:71], v[148:151], v[226:229], v[68:71]
	v_mfma_f32_16x16x32_bf16 v[64:67], v[156:159], v[226:229], v[64:67]
	s_setprio 0
	s_barrier
	s_add_i32 s60, s86, s64

; #define PG8_STAGE(bufoff, gbase, voff) do { _Pragma("unroll") for (int _i = 0; _i < 2; ++_i) \
;         __builtin_amdgcn_global_load_lds((const unsigned*)((const char*)(gbase) + (voff)[_i]), (PG8_LAS unsigned*)(lds + (bufoff) + ldsw + _i * 8192), 16, 0, 0); } while (0)
; #define PG8_LDA(dst, b, h) do { _Pragma("unroll") for (int m = 0; m < 4; ++m) _Pragma("unroll") for (int k = 0; k < 2; ++k) dst[m][k] = *(const PG8_LAS bf16x8*)(lds + PG8_SA(b, h) + aoff + m * 2048 + k * 1024); } while (0)
; template <class Epi, class Sched, bool ALIGN_EPI = false, bool SP2 = false>
; __device__ __forceinline__ void gemm_phase(PG8_LAS unsigned char* lds, const Gemm g, const Sched& S, const Epi& E) {
;     ...
;             PG8_LDA(At, 1, 1); PG8_STAGE(PG8_SB(1, 0), b3, voffB); PG8_STAGE(PG8_SB(1, 1), b3 + hstep, voffB); PG8_STAGE(PG8_SA(1, 0), a3, voffA);
	s_mov_b32 m0, s60
	ds_read_b128 v[176:179], v207 offset:49152
	ds_read_b128 v[184:187], v207 offset:50176
	ds_read_b128 v[190:193], v207 offset:51200
	ds_read_b128 v[210:213], v207 offset:52224
	ds_read_b128 v[214:217], v207 offset:53248
	ds_read_b128 v[218:221], v207 offset:54272
	ds_read_b128 v[222:225], v207 offset:55296
	ds_read_b128 v[226:229], v207 offset:56320
	global_load_lds_dwordx4 v250, s[96:97]
	s_add_i32 m0, s60, 0x2000
	s_add_u32 s12, s12, 0x80080

; #define PG8_STAGE(bufoff, gbase, voff) do { _Pragma("unroll") for (int _i = 0; _i < 2; ++_i) \
;         __builtin_amdgcn_global_load_lds((const unsigned*)((const char*)(gbase) + (voff)[_i]), (PG8_LAS unsigned*)(lds + (bufoff) + ldsw + _i * 8192), 16, 0, 0); } while (0)
; #define PG8_LDA(dst, b, h) do { _Pragma("unroll") for (int m = 0; m < 4; ++m) _Pragma("unroll") for (int k = 0; k < 2; ++k) dst[m][k] = *(const PG8_LAS bf16x8*)(lds + PG8_SA(b, h) + aoff + m * 2048 + k * 1024); } while (0)
; template <class Epi, class Sched, bool ALIGN_EPI = false, bool SP2 = false>
; __device__ __forceinline__ void gemm_phase(PG8_LAS unsigned char* lds, const Gemm g, const Sched& S, const Epi& E) {
;     ...
;             PG8_LDA(At, 1, 1); PG8_STAGE(PG8_SB(1, 0), b3, voffB); PG8_STAGE(PG8_SB(1, 1), b3 + hstep, voffB); PG8_STAGE(PG8_SA(1, 0), a3, voffA);
	s_addc_u32 s13, s13, 0
	s_add_i32 s60, s87, s64
	global_load_lds_dwordx4 v251, s[96:97]

; #define PG8_STAGE(bufoff, gbase, voff) do { _Pragma("unroll") for (int _i = 0; _i < 2; ++_i) \
;         __builtin_amdgcn_global_load_lds((const unsigned*)((const char*)(gbase) + (voff)[_i]), (PG8_LAS unsigned*)(lds + (bufoff) + ldsw + _i * 8192), 16, 0, 0); } while (0)
; #define PG8_LDA(dst, b, h) do { _Pragma("unroll") for (int m = 0; m < 4; ++m) _Pragma("unroll") for (int k = 0; k < 2; ++k) dst[m][k] = *(const PG8_LAS bf16x8*)(lds + PG8_SA(b, h) + aoff + m * 2048 + k * 1024); } while (0)
; template <class Epi, class Sched, bool ALIGN_EPI = false, bool SP2 = false>
; __device__ __forceinline__ void gemm_phase(PG8_LAS unsigned char* lds, const Gemm g, const Sched& S, const Epi& E) {
;     ...
;             PG8_LDA(At, 1, 1); PG8_STAGE(PG8_SB(1, 0), b3, voffB); PG8_STAGE(PG8_SB(1, 1), b3 + hstep, voffB); PG8_STAGE(PG8_SA(1, 0), a3, voffA);
	s_mov_b32 m0, s60
	s_nop 0
	global_load_lds_dwordx4 v162, s[12:13]

; #define PG8_STAGE(bufoff, gbase, voff) do { _Pragma("unroll") for (int _i = 0; _i < 2; ++_i) \
;         __builtin_amdgcn_global_load_lds((const unsigned*)((const char*)(gbase) + (voff)[_i]), (PG8_LAS unsigned*)(lds + (bufoff) + ldsw + _i * 8192), 16, 0, 0); } while (0)
; #define PG8_LDA(dst, b, h) do { _Pragma("unroll") for (int m = 0; m < 4; ++m) _Pragma("unroll") for (int k = 0; k < 2; ++k) dst[m][k] = *(const PG8_LAS bf16x8*)(lds + PG8_SA(b, h) + aoff + m * 2048 + k * 1024); } while (0)
; template <class Epi, class Sched, bool ALIGN_EPI = false, bool SP2 = false>
; __device__ __forceinline__ void gemm_phase(PG8_LAS unsigned char* lds, const Gemm g, const Sched& S, const Epi& E) {
;     ...
;             PG8_LDA(At, 1, 1); PG8_STAGE(PG8_SB(1, 0), b3, voffB); PG8_STAGE(PG8_SB(1, 1), b3 + hstep, voffB); PG8_STAGE(PG8_SA(1, 0), a3, voffA);
	s_add_i32 m0, s60, 0x2000
	s_nop 0
	global_load_lds_dwordx4 v166, s[12:13]

; #define PG8_STAGE(bufoff, gbase, voff) do { _Pragma("unroll") for (int _i = 0; _i < 2; ++_i) \
;         __builtin_amdgcn_global_load_lds((const unsigned*)((const char*)(gbase) + (voff)[_i]), (PG8_LAS unsigned*)(lds + (bufoff) + ldsw + _i * 8192), 16, 0, 0); } while (0)
; #define PG8_LDA(dst, b, h) do { _Pragma("unroll") for (int m = 0; m < 4; ++m) _Pragma("unroll") for (int k = 0; k < 2; ++k) dst[m][k] = *(const PG8_LAS bf16x8*)(lds + PG8_SA(b, h) + aoff + m * 2048 + k * 1024); } while (0)
; template <class Epi, class Sched, bool ALIGN_EPI = false, bool SP2 = false>
; __device__ __forceinline__ void gemm_phase(PG8_LAS unsigned char* lds, const Gemm g, const Sched& S, const Epi& E) {
;     ...
;             PG8_LDA(At, 1, 1); PG8_STAGE(PG8_SB(1, 0), b3, voffB); PG8_STAGE(PG8_SB(1, 1), b3 + hstep, voffB); PG8_STAGE(PG8_SA(1, 0), a3, voffA);
	s_mov_b32 m0, s71
	s_nop 0
	global_load_lds_dwordx4 v252, s[98:99]

; #define PG8_STAGE(bufoff, gbase, voff) do { _Pragma("unroll") for (int _i = 0; _i < 2; ++_i) \
;         __builtin_amdgcn_global_load_lds((const unsigned*)((const char*)(gbase) + (voff)[_i]), (PG8_LAS unsigned*)(lds + (bufoff) + ldsw + _i * 8192), 16, 0, 0); } while (0)
; #define PG8_LDA(dst, b, h) do { _Pragma("unroll") for (int m = 0; m < 4; ++m) _Pragma("unroll") for (int k = 0; k < 2; ++k) dst[m][k] = *(const PG8_LAS bf16x8*)(lds + PG8_SA(b, h) + aoff + m * 2048 + k * 1024); } while (0)
; #define PG8_MMA(ai, bj, At, Bt) do { __builtin_amdgcn_s_setprio(1); _Pragma("unroll") for (int m = 0; m < 4; ++m) _Pragma("unroll") for (int n = 0; n < 2; ++n) _Pragma("unroll") for (int k = 0; k < 2; ++k) \
;         acc[ai][bj][m][n] = __builtin_amdgcn_mfma_f32_16x16x32_bf16(Bt[n][k], At[m][k], acc[ai][bj][m][n], 0, 0, 0); __builtin_amdgcn_s_setprio(0); } while (0)
; #define PG8_WAIT_V(n) asm volatile("s_waitcnt vmcnt(" #n ")" ::: "memory")
; #define PG8_WAIT_L(n) asm volatile("s_waitcnt lgkmcnt(" #n ")" ::: "memory")
; #define PG8_BAR __builtin_amdgcn_s_barrier()
; #define PG8_SCHED __builtin_amdgcn_sched_barrier(0)
; template <class Epi, class Sched, bool ALIGN_EPI = false, bool SP2 = false>
; __device__ __forceinline__ void gemm_phase(PG8_LAS unsigned char* lds, const Gemm g, const Sched& S, const Epi& E) {
;     ...
;             PG8_LDA(At, 1, 1); PG8_STAGE(PG8_SB(1, 0), b3, voffB); PG8_STAGE(PG8_SB(1, 1), b3 + hstep, voffB); PG8_STAGE(PG8_SA(1, 0), a3, voffA);
;             PG8_WAIT_V(8); PG8_WAIT_L(0); PG8_BAR; PG8_MMA(1, 0, At, B0); PG8_MMA(1, 1, At, B1); PG8_BAR; PG8_SCHED;
	s_mov_b32 m0, s72
	s_nop 0
	global_load_lds_dwordx4 v253, s[98:99]
	s_waitcnt vmcnt(8)
	s_waitcnt lgkmcnt(0)
	s_barrier
	s_setprio 1
	s_waitcnt lgkmcnt(0)
	v_mfma_f32_16x16x32_bf16 v[60:63], v[128:131], v[176:179], v[60:63]
	v_mfma_f32_16x16x32_bf16 v[56:59], v[136:139], v[176:179], v[56:59]
	v_mfma_f32_16x16x32_bf16 v[44:47], v[128:131], v[190:193], v[44:47]
	v_mfma_f32_16x16x32_bf16 v[40:43], v[136:139], v[190:193], v[40:43]
	v_mfma_f32_16x16x32_bf16 v[28:31], v[128:131], v[214:217], v[28:31]
	v_mfma_f32_16x16x32_bf16 v[24:27], v[136:139], v[214:217], v[24:27]
	v_mfma_f32_16x16x32_bf16 v[12:15], v[128:131], v[222:225], v[12:15]
	v_mfma_f32_16x16x32_bf16 v[8:11], v[136:139], v[222:225], v[8:11]
	v_mfma_f32_16x16x32_bf16 v[60:63], v[132:135], v[184:187], v[60:63]
	v_mfma_f32_16x16x32_bf16 v[56:59], v[140:143], v[184:187], v[56:59]
	v_mfma_f32_16x16x32_bf16 v[44:47], v[132:135], v[210:213], v[44:47]
	v_mfma_f32_16x16x32_bf16 v[40:43], v[140:143], v[210:213], v[40:43]
	v_mfma_f32_16x16x32_bf16 v[28:31], v[132:135], v[218:221], v[28:31]
	v_mfma_f32_16x16x32_bf16 v[24:27], v[140:143], v[218:221], v[24:27]
	v_mfma_f32_16x16x32_bf16 v[12:15], v[132:135], v[226:229], v[12:15]
	v_mfma_f32_16x16x32_bf16 v[8:11], v[140:143], v[226:229], v[8:11]


; #define PG8_MMA(ai, bj, At, Bt) do { __builtin_amdgcn_s_setprio(1); _Pragma("unroll") for (int m = 0; m < 4; ++m) _Pragma("unroll") for (int n = 0; n < 2; ++n) _Pragma("unroll") for (int k = 0; k < 2; ++k) \
;         acc[ai][bj][m][n] = __builtin_amdgcn_mfma_f32_16x16x32_bf16(Bt[n][k], At[m][k], acc[ai][bj][m][n], 0, 0, 0); __builtin_amdgcn_s_setprio(0); } while (0)
; #define PG8_WAIT_V(n) asm volatile("s_waitcnt vmcnt(" #n ")" ::: "memory")
; #define PG8_WAIT_L(n) asm volatile("s_waitcnt lgkmcnt(" #n ")" ::: "memory")
; #define PG8_BAR __builtin_amdgcn_s_barrier()
; #define PG8_SCHED __builtin_amdgcn_sched_barrier(0)
; template <class Epi, class Sched, bool ALIGN_EPI = false, bool SP2 = false>
; __device__ __forceinline__ void gemm_phase(PG8_LAS unsigned char* lds, const Gemm g, const Sched& S, const Epi& E) {
;     ...
;         for (int t = 0; t < nt; t += 2) {
;     ...
;             PG8_WAIT_V(8); PG8_WAIT_L(0); PG8_BAR; PG8_MMA(1, 0, At, B0); PG8_MMA(1, 1, At, B1); PG8_BAR; PG8_SCHED;
;     ...
;         if constexpr (ALIGN_EPI) { if (wr == 0) PG8_BAR; }
	v_mfma_f32_16x16x32_bf16 v[52:55], v[144:147], v[176:179], v[52:55]
	v_mfma_f32_16x16x32_bf16 v[48:51], v[152:155], v[176:179], v[48:51]
	v_mfma_f32_16x16x32_bf16 v[36:39], v[144:147], v[190:193], v[36:39]
	v_mfma_f32_16x16x32_bf16 v[32:35], v[152:155], v[190:193], v[32:35]
	v_mfma_f32_16x16x32_bf16 v[20:23], v[144:147], v[214:217], v[20:23]
	v_mfma_f32_16x16x32_bf16 v[16:19], v[152:155], v[214:217], v[16:19]
	v_mfma_f32_16x16x32_bf16 v[4:7], v[144:147], v[222:225], v[4:7]
	v_mfma_f32_16x16x32_bf16 v[0:3], v[152:155], v[222:225], v[0:3]
	v_mfma_f32_16x16x32_bf16 v[52:55], v[148:151], v[184:187], v[52:55]
	v_mfma_f32_16x16x32_bf16 v[48:51], v[156:159], v[184:187], v[48:51]
	v_mfma_f32_16x16x32_bf16 v[36:39], v[148:151], v[210:213], v[36:39]
	v_mfma_f32_16x16x32_bf16 v[32:35], v[156:159], v[210:213], v[32:35]
	v_mfma_f32_16x16x32_bf16 v[20:23], v[148:151], v[218:221], v[20:23]
	v_mfma_f32_16x16x32_bf16 v[16:19], v[156:159], v[218:221], v[16:19]
	v_mfma_f32_16x16x32_bf16 v[4:7], v[148:151], v[226:229], v[4:7]
	v_mfma_f32_16x16x32_bf16 v[0:3], v[156:159], v[226:229], v[0:3]
	s_setprio 0
	s_barrier
	s_add_i32 s85, s85, 2
	s_add_u32 s10, s10, 0x100
	s_addc_u32 s11, s11, 0
	s_add_u32 s83, s83, 0x100
	s_addc_u32 s84, s84, 0
	s_cmp_gt_u32 s85, 29
	s_cbranch_scc0 .LBB0_428
	s_and_b64 vcc, exec, s[42:43]
	s_cbranch_vccz .LBB0_431
	s_barrier

; #define PG8_STAGE(bufoff, gbase, voff) do { _Pragma("unroll") for (int _i = 0; _i < 2; ++_i) \
;         __builtin_amdgcn_global_load_lds((const unsigned*)((const char*)(gbase) + (voff)[_i]), (PG8_LAS unsigned*)(lds + (bufoff) + ldsw + _i * 8192), 16, 0, 0); } while (0)
; #define PG8_LDA(dst, b, h) do { _Pragma("unroll") for (int m = 0; m < 4; ++m) _Pragma("unroll") for (int k = 0; k < 2; ++k) dst[m][k] = *(const PG8_LAS bf16x8*)(lds + PG8_SA(b, h) + aoff + m * 2048 + k * 1024); } while (0)
; #define PG8_LDB(dst, b, h) do { _Pragma("unroll") for (int n = 0; n < 2; ++n) _Pragma("unroll") for (int k = 0; k < 2; ++k) dst[n][k] = *(const PG8_LAS bf16x8*)(lds + PG8_SB(b, h) + boff + n * 2048 + k * 1024); } while (0)
; #define PG8_SCHED __builtin_amdgcn_sched_barrier(0)
; template <class Epi, class Sched, bool ALIGN_EPI = false, bool SP2 = false>
; __device__ __forceinline__ void gemm_phase(PG8_LAS unsigned char* lds, const Gemm g, const Sched& S, const Epi& E) {
;     ...
;             const bool last = (t == nt - 2);
;             const char* a1 = cA + (size_t)(t + 1) * kstep;
;             const char* a2 = last ? nA : cA + (size_t)(t + 2) * kstep; const char* b2 = last ? nB : cB + (size_t)(t + 2) * kstep;
;             const char* a3 = a2 + kstep; const char* b3 = b2 + kstep;
;     ...
;             PG8_LDB(B0, 0, 0); PG8_LDB(B1, 0, 1); PG8_SCHED; PG8_LDA(At, 0, 0); PG8_STAGE(PG8_SA(1, 1), a1 + hstep, voffA);
.LBB0_509:
	ds_read_b128 v[64:67], v213
	ds_read_b128 v[68:71], v213 offset:1024
	ds_read_b128 v[72:75], v213 offset:2048
	ds_read_b128 v[76:79], v213 offset:3072
	ds_read_b128 v[144:147], v214
	ds_read_b128 v[148:151], v214 offset:1024
	ds_read_b128 v[152:155], v214 offset:2048
	ds_read_b128 v[156:159], v214 offset:3072
	s_add_u32 s60, s58, 0xffe00080
	s_addc_u32 s61, s59, -1
	s_cmpk_eq_i32 s81, 0x7c
	s_cselect_b32 s63, s11, s61
	s_cselect_b32 s62, s51, s60
	s_cselect_b32 s61, s49, s80
	s_cselect_b32 s60, s78, s79

; #define PG8_STAGE(bufoff, gbase, voff) do { _Pragma("unroll") for (int _i = 0; _i < 2; ++_i) \
;         __builtin_amdgcn_global_load_lds((const unsigned*)((const char*)(gbase) + (voff)[_i]), (PG8_LAS unsigned*)(lds + (bufoff) + ldsw + _i * 8192), 16, 0, 0); } while (0)
; #define PG8_LDA(dst, b, h) do { _Pragma("unroll") for (int m = 0; m < 4; ++m) _Pragma("unroll") for (int k = 0; k < 2; ++k) dst[m][k] = *(const PG8_LAS bf16x8*)(lds + PG8_SA(b, h) + aoff + m * 2048 + k * 1024); } while (0)
; #define PG8_LDB(dst, b, h) do { _Pragma("unroll") for (int n = 0; n < 2; ++n) _Pragma("unroll") for (int k = 0; k < 2; ++k) dst[n][k] = *(const PG8_LAS bf16x8*)(lds + PG8_SB(b, h) + boff + n * 2048 + k * 1024); } while (0)
; #define PG8_SCHED __builtin_amdgcn_sched_barrier(0)
; template <class Epi, class Sched, bool ALIGN_EPI = false, bool SP2 = false>
; __device__ __forceinline__ void gemm_phase(PG8_LAS unsigned char* lds, const Gemm g, const Sched& S, const Epi& E) {
;     ...
;             PG8_LDB(B0, 0, 0); PG8_LDB(B1, 0, 1); PG8_SCHED; PG8_LDA(At, 0, 0); PG8_STAGE(PG8_SA(1, 1), a1 + hstep, voffA);
	s_add_i32 m0, s57, 0xc000
	ds_read_b128 v[176:179], v215
	ds_read_b128 v[180:183], v215 offset:1024
	ds_read_b128 v[184:187], v215 offset:2048
	ds_read_b128 v[188:191], v215 offset:3072
	ds_read_b128 v[192:195], v215 offset:4096
	ds_read_b128 v[196:199], v215 offset:5120
	ds_read_b128 v[200:203], v215 offset:6144
	ds_read_b128 v[204:207], v215 offset:7168
	global_load_lds_dwordx4 v168, s[58:59]

; #define PG8_STAGE(bufoff, gbase, voff) do { _Pragma("unroll") for (int _i = 0; _i < 2; ++_i) \
;         __builtin_amdgcn_global_load_lds((const unsigned*)((const char*)(gbase) + (voff)[_i]), (PG8_LAS unsigned*)(lds + (bufoff) + ldsw + _i * 8192), 16, 0, 0); } while (0)
; #define PG8_LDA(dst, b, h) do { _Pragma("unroll") for (int m = 0; m < 4; ++m) _Pragma("unroll") for (int k = 0; k < 2; ++k) dst[m][k] = *(const PG8_LAS bf16x8*)(lds + PG8_SA(b, h) + aoff + m * 2048 + k * 1024); } while (0)
; #define PG8_LDB(dst, b, h) do { _Pragma("unroll") for (int n = 0; n < 2; ++n) _Pragma("unroll") for (int k = 0; k < 2; ++k) dst[n][k] = *(const PG8_LAS bf16x8*)(lds + PG8_SB(b, h) + boff + n * 2048 + k * 1024); } while (0)
; #define PG8_MMA(ai, bj, At, Bt) do { __builtin_amdgcn_s_setprio(1); _Pragma("unroll") for (int m = 0; m < 4; ++m) _Pragma("unroll") for (int n = 0; n < 2; ++n) _Pragma("unroll") for (int k = 0; k < 2; ++k) \
;         acc[ai][bj][m][n] = __builtin_amdgcn_mfma_f32_16x16x32_bf16(Bt[n][k], At[m][k], acc[ai][bj][m][n], 0, 0, 0); __builtin_amdgcn_s_setprio(0); } while (0)
; #define PG8_WAIT_V(n) asm volatile("s_waitcnt vmcnt(" #n ")" ::: "memory")
; #define PG8_WAIT_L(n) asm volatile("s_waitcnt lgkmcnt(" #n ")" ::: "memory")
; #define PG8_BAR __builtin_amdgcn_s_barrier()
; #define PG8_SCHED __builtin_amdgcn_sched_barrier(0)
; template <class Epi, class Sched, bool ALIGN_EPI = false, bool SP2 = false>
; __device__ __forceinline__ void gemm_phase(PG8_LAS unsigned char* lds, const Gemm g, const Sched& S, const Epi& E) {
;     ...
;             PG8_LDB(B0, 0, 0); PG8_LDB(B1, 0, 1); PG8_SCHED; PG8_LDA(At, 0, 0); PG8_STAGE(PG8_SA(1, 1), a1 + hstep, voffA);
;             PG8_WAIT_V(8); PG8_WAIT_L(0); PG8_BAR; PG8_MMA(0, 0, At, B0); PG8_MMA(0, 1, At, B1); PG8_BAR; PG8_SCHED;
	s_add_i32 m0, s57, 0xe000
	s_nop 0
	global_load_lds_dwordx4 v170, s[58:59]
	s_waitcnt vmcnt(8)
	s_waitcnt lgkmcnt(0)
	s_barrier
	s_setprio 1
	s_waitcnt lgkmcnt(0)
	v_mfma_f32_16x16x32_bf16 v[140:143], v[64:67], v[176:179], v[140:143]
	v_mfma_f32_16x16x32_bf16 v[136:139], v[72:75], v[176:179], v[136:139]
	v_mfma_f32_16x16x32_bf16 v[124:127], v[64:67], v[184:187], v[124:127]
	v_mfma_f32_16x16x32_bf16 v[120:123], v[72:75], v[184:187], v[120:123]
	v_mfma_f32_16x16x32_bf16 v[108:111], v[64:67], v[192:195], v[108:111]
	v_mfma_f32_16x16x32_bf16 v[104:107], v[72:75], v[192:195], v[104:107]
	v_mfma_f32_16x16x32_bf16 v[92:95], v[64:67], v[200:203], v[92:95]
	v_mfma_f32_16x16x32_bf16 v[88:91], v[72:75], v[200:203], v[88:91]
	v_mfma_f32_16x16x32_bf16 v[140:143], v[68:71], v[180:183], v[140:143]
	v_mfma_f32_16x16x32_bf16 v[136:139], v[76:79], v[180:183], v[136:139]
	v_mfma_f32_16x16x32_bf16 v[124:127], v[68:71], v[188:191], v[124:127]
	v_mfma_f32_16x16x32_bf16 v[120:123], v[76:79], v[188:191], v[120:123]
	v_mfma_f32_16x16x32_bf16 v[108:111], v[68:71], v[196:199], v[108:111]
	v_mfma_f32_16x16x32_bf16 v[104:107], v[76:79], v[196:199], v[104:107]
	v_mfma_f32_16x16x32_bf16 v[92:95], v[68:71], v[204:207], v[92:95]
	v_mfma_f32_16x16x32_bf16 v[88:91], v[76:79], v[204:207], v[88:91]


; #define PG8_STAGE(bufoff, gbase, voff) do { _Pragma("unroll") for (int _i = 0; _i < 2; ++_i) \
;         __builtin_amdgcn_global_load_lds((const unsigned*)((const char*)(gbase) + (voff)[_i]), (PG8_LAS unsigned*)(lds + (bufoff) + ldsw + _i * 8192), 16, 0, 0); } while (0)
; #define PG8_LDA(dst, b, h) do { _Pragma("unroll") for (int m = 0; m < 4; ++m) _Pragma("unroll") for (int k = 0; k < 2; ++k) dst[m][k] = *(const PG8_LAS bf16x8*)(lds + PG8_SA(b, h) + aoff + m * 2048 + k * 1024); } while (0)
; #define PG8_MMA(ai, bj, At, Bt) do { __builtin_amdgcn_s_setprio(1); _Pragma("unroll") for (int m = 0; m < 4; ++m) _Pragma("unroll") for (int n = 0; n < 2; ++n) _Pragma("unroll") for (int k = 0; k < 2; ++k) \
;         acc[ai][bj][m][n] = __builtin_amdgcn_mfma_f32_16x16x32_bf16(Bt[n][k], At[m][k], acc[ai][bj][m][n], 0, 0, 0); __builtin_amdgcn_s_setprio(0); } while (0)
; #define PG8_WAIT_V(n) asm volatile("s_waitcnt vmcnt(" #n ")" ::: "memory")
; #define PG8_WAIT_L(n) asm volatile("s_waitcnt lgkmcnt(" #n ")" ::: "memory")
; #define PG8_BAR __builtin_amdgcn_s_barrier()
; #define PG8_SCHED __builtin_amdgcn_sched_barrier(0)
; template <class Epi, class Sched, bool ALIGN_EPI = false, bool SP2 = false>
; __device__ __forceinline__ void gemm_phase(PG8_LAS unsigned char* lds, const Gemm g, const Sched& S, const Epi& E) {
;     ...
;             PG8_WAIT_V(8); PG8_WAIT_L(0); PG8_BAR; PG8_MMA(0, 0, At, B0); PG8_MMA(0, 1, At, B1); PG8_BAR; PG8_SCHED;
;             PG8_LDA(At, 0, 1); PG8_STAGE(PG8_SB(0, 0), b2, voffB); PG8_STAGE(PG8_SB(0, 1), b2 + hstep, voffB); PG8_STAGE(PG8_SA(0, 0), a2, voffA);
	v_mfma_f32_16x16x32_bf16 v[132:135], v[144:147], v[176:179], v[132:135]
	v_mfma_f32_16x16x32_bf16 v[128:131], v[152:155], v[176:179], v[128:131]
	v_mfma_f32_16x16x32_bf16 v[116:119], v[144:147], v[184:187], v[116:119]
	v_mfma_f32_16x16x32_bf16 v[112:115], v[152:155], v[184:187], v[112:115]
	v_mfma_f32_16x16x32_bf16 v[100:103], v[144:147], v[192:195], v[100:103]
	v_mfma_f32_16x16x32_bf16 v[96:99], v[152:155], v[192:195], v[96:99]
	v_mfma_f32_16x16x32_bf16 v[84:87], v[144:147], v[200:203], v[84:87]
	v_mfma_f32_16x16x32_bf16 v[80:83], v[152:155], v[200:203], v[80:83]
	v_mfma_f32_16x16x32_bf16 v[132:135], v[148:151], v[180:183], v[132:135]
	v_mfma_f32_16x16x32_bf16 v[128:131], v[156:159], v[180:183], v[128:131]
	v_mfma_f32_16x16x32_bf16 v[116:119], v[148:151], v[188:191], v[116:119]
	v_mfma_f32_16x16x32_bf16 v[112:115], v[156:159], v[188:191], v[112:115]
	v_mfma_f32_16x16x32_bf16 v[100:103], v[148:151], v[196:199], v[100:103]
	v_mfma_f32_16x16x32_bf16 v[96:99], v[156:159], v[196:199], v[96:99]
	v_mfma_f32_16x16x32_bf16 v[84:87], v[148:151], v[204:207], v[84:87]
	v_mfma_f32_16x16x32_bf16 v[80:83], v[156:159], v[204:207], v[80:83]
	s_setprio 0
	s_barrier
	s_add_i32 s82, s75, s64
	s_mov_b64 s[96:97], s[60:61]

; #define PG8_STAGE(bufoff, gbase, voff) do { _Pragma("unroll") for (int _i = 0; _i < 2; ++_i) \
;         __builtin_amdgcn_global_load_lds((const unsigned*)((const char*)(gbase) + (voff)[_i]), (PG8_LAS unsigned*)(lds + (bufoff) + ldsw + _i * 8192), 16, 0, 0); } while (0)
; #define PG8_LDA(dst, b, h) do { _Pragma("unroll") for (int m = 0; m < 4; ++m) _Pragma("unroll") for (int k = 0; k < 2; ++k) dst[m][k] = *(const PG8_LAS bf16x8*)(lds + PG8_SA(b, h) + aoff + m * 2048 + k * 1024); } while (0)
; template <class Epi, class Sched, bool ALIGN_EPI = false, bool SP2 = false>
; __device__ __forceinline__ void gemm_phase(PG8_LAS unsigned char* lds, const Gemm g, const Sched& S, const Epi& E) {
;     ...
;             PG8_LDA(At, 0, 1); PG8_STAGE(PG8_SB(0, 0), b2, voffB); PG8_STAGE(PG8_SB(0, 1), b2 + hstep, voffB); PG8_STAGE(PG8_SA(0, 0), a2, voffA);
	s_mov_b32 m0, s82
	ds_read_b128 v[176:179], v215 offset:16384
	ds_read_b128 v[180:183], v215 offset:17408
	ds_read_b128 v[184:187], v215 offset:18432
	ds_read_b128 v[188:191], v215 offset:19456
	ds_read_b128 v[192:195], v215 offset:20480
	ds_read_b128 v[196:199], v215 offset:21504
	ds_read_b128 v[200:203], v215 offset:22528
	ds_read_b128 v[204:207], v215 offset:23552
	global_load_lds_dwordx4 v162, s[60:61]
	s_add_i32 m0, s82, 0x2000
	s_add_u32 s82, s60, 0x200000

; #define PG8_STAGE(bufoff, gbase, voff) do { _Pragma("unroll") for (int _i = 0; _i < 2; ++_i) \
;         __builtin_amdgcn_global_load_lds((const unsigned*)((const char*)(gbase) + (voff)[_i]), (PG8_LAS unsigned*)(lds + (bufoff) + ldsw + _i * 8192), 16, 0, 0); } while (0)
; #define PG8_LDA(dst, b, h) do { _Pragma("unroll") for (int m = 0; m < 4; ++m) _Pragma("unroll") for (int k = 0; k < 2; ++k) dst[m][k] = *(const PG8_LAS bf16x8*)(lds + PG8_SA(b, h) + aoff + m * 2048 + k * 1024); } while (0)
; template <class Epi, class Sched, bool ALIGN_EPI = false, bool SP2 = false>
; __device__ __forceinline__ void gemm_phase(PG8_LAS unsigned char* lds, const Gemm g, const Sched& S, const Epi& E) {
;     ...
;             PG8_LDA(At, 0, 1); PG8_STAGE(PG8_SB(0, 0), b2, voffB); PG8_STAGE(PG8_SB(0, 1), b2 + hstep, voffB); PG8_STAGE(PG8_SA(0, 0), a2, voffA);
	s_addc_u32 s83, s61, 0
	s_add_i32 s84, s76, s64
	global_load_lds_dwordx4 v166, s[60:61]

; #define PG8_STAGE(bufoff, gbase, voff) do { _Pragma("unroll") for (int _i = 0; _i < 2; ++_i) \
;         __builtin_amdgcn_global_load_lds((const unsigned*)((const char*)(gbase) + (voff)[_i]), (PG8_LAS unsigned*)(lds + (bufoff) + ldsw + _i * 8192), 16, 0, 0); } while (0)
; #define PG8_LDA(dst, b, h) do { _Pragma("unroll") for (int m = 0; m < 4; ++m) _Pragma("unroll") for (int k = 0; k < 2; ++k) dst[m][k] = *(const PG8_LAS bf16x8*)(lds + PG8_SA(b, h) + aoff + m * 2048 + k * 1024); } while (0)
; template <class Epi, class Sched, bool ALIGN_EPI = false, bool SP2 = false>
; __device__ __forceinline__ void gemm_phase(PG8_LAS unsigned char* lds, const Gemm g, const Sched& S, const Epi& E) {
;     ...
;             PG8_LDA(At, 0, 1); PG8_STAGE(PG8_SB(0, 0), b2, voffB); PG8_STAGE(PG8_SB(0, 1), b2 + hstep, voffB); PG8_STAGE(PG8_SA(0, 0), a2, voffA);
	s_mov_b32 m0, s84
	s_nop 0
	global_load_lds_dwordx4 v162, s[82:83]

; #define PG8_STAGE(bufoff, gbase, voff) do { _Pragma("unroll") for (int _i = 0; _i < 2; ++_i) \
;         __builtin_amdgcn_global_load_lds((const unsigned*)((const char*)(gbase) + (voff)[_i]), (PG8_LAS unsigned*)(lds + (bufoff) + ldsw + _i * 8192), 16, 0, 0); } while (0)
; #define PG8_LDA(dst, b, h) do { _Pragma("unroll") for (int m = 0; m < 4; ++m) _Pragma("unroll") for (int k = 0; k < 2; ++k) dst[m][k] = *(const PG8_LAS bf16x8*)(lds + PG8_SA(b, h) + aoff + m * 2048 + k * 1024); } while (0)
; template <class Epi, class Sched, bool ALIGN_EPI = false, bool SP2 = false>
; __device__ __forceinline__ void gemm_phase(PG8_LAS unsigned char* lds, const Gemm g, const Sched& S, const Epi& E) {
;     ...
;             PG8_LDA(At, 0, 1); PG8_STAGE(PG8_SB(0, 0), b2, voffB); PG8_STAGE(PG8_SB(0, 1), b2 + hstep, voffB); PG8_STAGE(PG8_SA(0, 0), a2, voffA);
	s_add_i32 m0, s84, 0x2000
	s_nop 0
	global_load_lds_dwordx4 v166, s[82:83]
	s_mov_b64 s[98:99], s[62:63]

; #define PG8_STAGE(bufoff, gbase, voff) do { _Pragma("unroll") for (int _i = 0; _i < 2; ++_i) \
;         __builtin_amdgcn_global_load_lds((const unsigned*)((const char*)(gbase) + (voff)[_i]), (PG8_LAS unsigned*)(lds + (bufoff) + ldsw + _i * 8192), 16, 0, 0); } while (0)
; #define PG8_LDA(dst, b, h) do { _Pragma("unroll") for (int m = 0; m < 4; ++m) _Pragma("unroll") for (int k = 0; k < 2; ++k) dst[m][k] = *(const PG8_LAS bf16x8*)(lds + PG8_SA(b, h) + aoff + m * 2048 + k * 1024); } while (0)
; #define PG8_MMA(ai, bj, At, Bt) do { __builtin_amdgcn_s_setprio(1); _Pragma("unroll") for (int m = 0; m < 4; ++m) _Pragma("unroll") for (int n = 0; n < 2; ++n) _Pragma("unroll") for (int k = 0; k < 2; ++k) \
;         acc[ai][bj][m][n] = __builtin_amdgcn_mfma_f32_16x16x32_bf16(Bt[n][k], At[m][k], acc[ai][bj][m][n], 0, 0, 0); __builtin_amdgcn_s_setprio(0); } while (0)
; #define PG8_WAIT_V(n) asm volatile("s_waitcnt vmcnt(" #n ")" ::: "memory")
; #define PG8_WAIT_L(n) asm volatile("s_waitcnt lgkmcnt(" #n ")" ::: "memory")
; #define PG8_BAR __builtin_amdgcn_s_barrier()
; #define PG8_SCHED __builtin_amdgcn_sched_barrier(0)
; template <class Epi, class Sched, bool ALIGN_EPI = false, bool SP2 = false>
; __device__ __forceinline__ void gemm_phase(PG8_LAS unsigned char* lds, const Gemm g, const Sched& S, const Epi& E) {
;     ...
;             PG8_LDA(At, 0, 1); PG8_STAGE(PG8_SB(0, 0), b2, voffB); PG8_STAGE(PG8_SB(0, 1), b2 + hstep, voffB); PG8_STAGE(PG8_SA(0, 0), a2, voffA);
;             PG8_WAIT_V(8); PG8_WAIT_L(0); PG8_BAR; PG8_MMA(1, 0, At, B0); PG8_MMA(1, 1, At, B1); PG8_BAR; PG8_SCHED;
	s_mov_b32 m0, s57
	s_nop 0
	global_load_lds_dwordx4 v160, s[62:63]
	s_mov_b32 m0, s65
	s_nop 0
	global_load_lds_dwordx4 v164, s[62:63]
	s_waitcnt vmcnt(8)
	s_waitcnt lgkmcnt(0)
	s_barrier
	s_setprio 1
	s_waitcnt lgkmcnt(0)
	v_mfma_f32_16x16x32_bf16 v[60:63], v[64:67], v[176:179], v[60:63]
	v_mfma_f32_16x16x32_bf16 v[56:59], v[72:75], v[176:179], v[56:59]
	v_mfma_f32_16x16x32_bf16 v[44:47], v[64:67], v[184:187], v[44:47]
	v_mfma_f32_16x16x32_bf16 v[40:43], v[72:75], v[184:187], v[40:43]
	v_mfma_f32_16x16x32_bf16 v[28:31], v[64:67], v[192:195], v[28:31]
	v_mfma_f32_16x16x32_bf16 v[24:27], v[72:75], v[192:195], v[24:27]
	v_mfma_f32_16x16x32_bf16 v[12:15], v[64:67], v[200:203], v[12:15]
	v_mfma_f32_16x16x32_bf16 v[8:11], v[72:75], v[200:203], v[8:11]
	v_mfma_f32_16x16x32_bf16 v[60:63], v[68:71], v[180:183], v[60:63]
	v_mfma_f32_16x16x32_bf16 v[56:59], v[76:79], v[180:183], v[56:59]
	v_mfma_f32_16x16x32_bf16 v[44:47], v[68:71], v[188:191], v[44:47]
	v_mfma_f32_16x16x32_bf16 v[40:43], v[76:79], v[188:191], v[40:43]
	v_mfma_f32_16x16x32_bf16 v[28:31], v[68:71], v[196:199], v[28:31]
	v_mfma_f32_16x16x32_bf16 v[24:27], v[76:79], v[196:199], v[24:27]
	v_mfma_f32_16x16x32_bf16 v[12:15], v[68:71], v[204:207], v[12:15]
	v_mfma_f32_16x16x32_bf16 v[8:11], v[76:79], v[204:207], v[8:11]


; #define PG8_STAGE(bufoff, gbase, voff) do { _Pragma("unroll") for (int _i = 0; _i < 2; ++_i) \
;         __builtin_amdgcn_global_load_lds((const unsigned*)((const char*)(gbase) + (voff)[_i]), (PG8_LAS unsigned*)(lds + (bufoff) + ldsw + _i * 8192), 16, 0, 0); } while (0)
; #define PG8_LDA(dst, b, h) do { _Pragma("unroll") for (int m = 0; m < 4; ++m) _Pragma("unroll") for (int k = 0; k < 2; ++k) dst[m][k] = *(const PG8_LAS bf16x8*)(lds + PG8_SA(b, h) + aoff + m * 2048 + k * 1024); } while (0)
; #define PG8_LDB(dst, b, h) do { _Pragma("unroll") for (int n = 0; n < 2; ++n) _Pragma("unroll") for (int k = 0; k < 2; ++k) dst[n][k] = *(const PG8_LAS bf16x8*)(lds + PG8_SB(b, h) + boff + n * 2048 + k * 1024); } while (0)
; #define PG8_MMA(ai, bj, At, Bt) do { __builtin_amdgcn_s_setprio(1); _Pragma("unroll") for (int m = 0; m < 4; ++m) _Pragma("unroll") for (int n = 0; n < 2; ++n) _Pragma("unroll") for (int k = 0; k < 2; ++k) \
;         acc[ai][bj][m][n] = __builtin_amdgcn_mfma_f32_16x16x32_bf16(Bt[n][k], At[m][k], acc[ai][bj][m][n], 0, 0, 0); __builtin_amdgcn_s_setprio(0); } while (0)
; #define PG8_WAIT_V(n) asm volatile("s_waitcnt vmcnt(" #n ")" ::: "memory")
; #define PG8_WAIT_L(n) asm volatile("s_waitcnt lgkmcnt(" #n ")" ::: "memory")
; #define PG8_BAR __builtin_amdgcn_s_barrier()
; #define PG8_SCHED __builtin_amdgcn_sched_barrier(0)
; template <class Epi, class Sched, bool ALIGN_EPI = false, bool SP2 = false>
; __device__ __forceinline__ void gemm_phase(PG8_LAS unsigned char* lds, const Gemm g, const Sched& S, const Epi& E) {
;     ...
;             PG8_WAIT_V(8); PG8_WAIT_L(0); PG8_BAR; PG8_MMA(1, 0, At, B0); PG8_MMA(1, 1, At, B1); PG8_BAR; PG8_SCHED;
;             PG8_LDB(B0, 1, 0); PG8_LDB(B1, 1, 1); PG8_SCHED; PG8_LDA(At, 1, 0); PG8_STAGE(PG8_SA(0, 1), a2 + hstep, voffA);
	v_mfma_f32_16x16x32_bf16 v[52:55], v[144:147], v[176:179], v[52:55]
	v_mfma_f32_16x16x32_bf16 v[48:51], v[152:155], v[176:179], v[48:51]
	v_mfma_f32_16x16x32_bf16 v[36:39], v[144:147], v[184:187], v[36:39]
	v_mfma_f32_16x16x32_bf16 v[32:35], v[152:155], v[184:187], v[32:35]
	v_mfma_f32_16x16x32_bf16 v[20:23], v[144:147], v[192:195], v[20:23]
	v_mfma_f32_16x16x32_bf16 v[16:19], v[152:155], v[192:195], v[16:19]
	v_mfma_f32_16x16x32_bf16 v[4:7], v[144:147], v[200:203], v[4:7]
	v_mfma_f32_16x16x32_bf16 v[0:3], v[152:155], v[200:203], v[0:3]
	v_mfma_f32_16x16x32_bf16 v[52:55], v[148:151], v[180:183], v[52:55]
	v_mfma_f32_16x16x32_bf16 v[48:51], v[156:159], v[180:183], v[48:51]
	v_mfma_f32_16x16x32_bf16 v[36:39], v[148:151], v[188:191], v[36:39]
	v_mfma_f32_16x16x32_bf16 v[32:35], v[156:159], v[188:191], v[32:35]
	v_mfma_f32_16x16x32_bf16 v[20:23], v[148:151], v[196:199], v[20:23]
	v_mfma_f32_16x16x32_bf16 v[16:19], v[156:159], v[196:199], v[16:19]
	v_mfma_f32_16x16x32_bf16 v[4:7], v[148:151], v[204:207], v[4:7]
	v_mfma_f32_16x16x32_bf16 v[0:3], v[156:159], v[204:207], v[0:3]
	s_setprio 0
	s_barrier
	s_add_i32 s82, 0, 0x18000
	s_add_i32 s83, 0, 0x1c000
	v_add_u32_e32 v76, s82, v211
	v_add_u32_e32 v156, s83, v211
	ds_read_b128 v[64:67], v76
	ds_read_b128 v[68:71], v76 offset:1024
	ds_read_b128 v[72:75], v76 offset:2048
	ds_read_b128 v[76:79], v76 offset:3072
	ds_read_b128 v[144:147], v156
	ds_read_b128 v[148:151], v156 offset:1024
	ds_read_b128 v[152:155], v156 offset:2048
	ds_read_b128 v[156:159], v156 offset:3072
	s_add_u32 s62, s62, 0x200000
	s_addc_u32 s63, s63, 0
	s_mov_b32 m0, s67

; #define PG8_STAGE(bufoff, gbase, voff) do { _Pragma("unroll") for (int _i = 0; _i < 2; ++_i) \
;         __builtin_amdgcn_global_load_lds((const unsigned*)((const char*)(gbase) + (voff)[_i]), (PG8_LAS unsigned*)(lds + (bufoff) + ldsw + _i * 8192), 16, 0, 0); } while (0)
; #define PG8_LDA(dst, b, h) do { _Pragma("unroll") for (int m = 0; m < 4; ++m) _Pragma("unroll") for (int k = 0; k < 2; ++k) dst[m][k] = *(const PG8_LAS bf16x8*)(lds + PG8_SA(b, h) + aoff + m * 2048 + k * 1024); } while (0)
; #define PG8_LDB(dst, b, h) do { _Pragma("unroll") for (int n = 0; n < 2; ++n) _Pragma("unroll") for (int k = 0; k < 2; ++k) dst[n][k] = *(const PG8_LAS bf16x8*)(lds + PG8_SB(b, h) + boff + n * 2048 + k * 1024); } while (0)
; #define PG8_SCHED __builtin_amdgcn_sched_barrier(0)
; template <class Epi, class Sched, bool ALIGN_EPI = false, bool SP2 = false>
; __device__ __forceinline__ void gemm_phase(PG8_LAS unsigned char* lds, const Gemm g, const Sched& S, const Epi& E) {
;     ...
;             PG8_LDB(B0, 1, 0); PG8_LDB(B1, 1, 1); PG8_SCHED; PG8_LDA(At, 1, 0); PG8_STAGE(PG8_SA(0, 1), a2 + hstep, voffA);
	ds_read_b128 v[176:179], v215 offset:32768
	ds_read_b128 v[180:183], v215 offset:33792
	ds_read_b128 v[184:187], v215 offset:34816
	ds_read_b128 v[188:191], v215 offset:35840
	ds_read_b128 v[192:195], v215 offset:36864
	ds_read_b128 v[196:199], v215 offset:37888
	ds_read_b128 v[200:203], v215 offset:38912
	ds_read_b128 v[204:207], v215 offset:39936
	global_load_lds_dwordx4 v160, s[62:63]

; #define PG8_STAGE(bufoff, gbase, voff) do { _Pragma("unroll") for (int _i = 0; _i < 2; ++_i) \
;         __builtin_amdgcn_global_load_lds((const unsigned*)((const char*)(gbase) + (voff)[_i]), (PG8_LAS unsigned*)(lds + (bufoff) + ldsw + _i * 8192), 16, 0, 0); } while (0)
; #define PG8_LDA(dst, b, h) do { _Pragma("unroll") for (int m = 0; m < 4; ++m) _Pragma("unroll") for (int k = 0; k < 2; ++k) dst[m][k] = *(const PG8_LAS bf16x8*)(lds + PG8_SA(b, h) + aoff + m * 2048 + k * 1024); } while (0)
; #define PG8_LDB(dst, b, h) do { _Pragma("unroll") for (int n = 0; n < 2; ++n) _Pragma("unroll") for (int k = 0; k < 2; ++k) dst[n][k] = *(const PG8_LAS bf16x8*)(lds + PG8_SB(b, h) + boff + n * 2048 + k * 1024); } while (0)
; #define PG8_MMA(ai, bj, At, Bt) do { __builtin_amdgcn_s_setprio(1); _Pragma("unroll") for (int m = 0; m < 4; ++m) _Pragma("unroll") for (int n = 0; n < 2; ++n) _Pragma("unroll") for (int k = 0; k < 2; ++k) \
;         acc[ai][bj][m][n] = __builtin_amdgcn_mfma_f32_16x16x32_bf16(Bt[n][k], At[m][k], acc[ai][bj][m][n], 0, 0, 0); __builtin_amdgcn_s_setprio(0); } while (0)
; #define PG8_WAIT_V(n) asm volatile("s_waitcnt vmcnt(" #n ")" ::: "memory")
; #define PG8_WAIT_L(n) asm volatile("s_waitcnt lgkmcnt(" #n ")" ::: "memory")
; #define PG8_BAR __builtin_amdgcn_s_barrier()
; #define PG8_SCHED __builtin_amdgcn_sched_barrier(0)
; template <class Epi, class Sched, bool ALIGN_EPI = false, bool SP2 = false>
; __device__ __forceinline__ void gemm_phase(PG8_LAS unsigned char* lds, const Gemm g, const Sched& S, const Epi& E) {
;     ...
;             PG8_LDB(B0, 1, 0); PG8_LDB(B1, 1, 1); PG8_SCHED; PG8_LDA(At, 1, 0); PG8_STAGE(PG8_SA(0, 1), a2 + hstep, voffA);
;             PG8_WAIT_V(8); PG8_WAIT_L(0); PG8_BAR; PG8_MMA(0, 0, At, B0); PG8_MMA(0, 1, At, B1); PG8_BAR; PG8_SCHED;
	s_mov_b32 m0, s68
	s_nop 0
	global_load_lds_dwordx4 v164, s[62:63]
	s_waitcnt vmcnt(8)
	s_waitcnt lgkmcnt(0)
	s_barrier
	s_setprio 1
	s_waitcnt lgkmcnt(0)
	v_mfma_f32_16x16x32_bf16 v[140:143], v[64:67], v[176:179], v[140:143]
	v_mfma_f32_16x16x32_bf16 v[136:139], v[72:75], v[176:179], v[136:139]
	v_mfma_f32_16x16x32_bf16 v[124:127], v[64:67], v[184:187], v[124:127]
	v_mfma_f32_16x16x32_bf16 v[120:123], v[72:75], v[184:187], v[120:123]
	v_mfma_f32_16x16x32_bf16 v[108:111], v[64:67], v[192:195], v[108:111]
	v_mfma_f32_16x16x32_bf16 v[104:107], v[72:75], v[192:195], v[104:107]
	v_mfma_f32_16x16x32_bf16 v[92:95], v[64:67], v[200:203], v[92:95]
	v_mfma_f32_16x16x32_bf16 v[88:91], v[72:75], v[200:203], v[88:91]
	v_mfma_f32_16x16x32_bf16 v[140:143], v[68:71], v[180:183], v[140:143]
	v_mfma_f32_16x16x32_bf16 v[136:139], v[76:79], v[180:183], v[136:139]
	v_mfma_f32_16x16x32_bf16 v[124:127], v[68:71], v[188:191], v[124:127]
	v_mfma_f32_16x16x32_bf16 v[120:123], v[76:79], v[188:191], v[120:123]
	v_mfma_f32_16x16x32_bf16 v[108:111], v[68:71], v[196:199], v[108:111]
	v_mfma_f32_16x16x32_bf16 v[104:107], v[76:79], v[196:199], v[104:107]
	v_mfma_f32_16x16x32_bf16 v[92:95], v[68:71], v[204:207], v[92:95]
	v_mfma_f32_16x16x32_bf16 v[88:91], v[76:79], v[204:207], v[88:91]


; #define PG8_STAGE(bufoff, gbase, voff) do { _Pragma("unroll") for (int _i = 0; _i < 2; ++_i) \
;         __builtin_amdgcn_global_load_lds((const unsigned*)((const char*)(gbase) + (voff)[_i]), (PG8_LAS unsigned*)(lds + (bufoff) + ldsw + _i * 8192), 16, 0, 0); } while (0)
; #define PG8_LDA(dst, b, h) do { _Pragma("unroll") for (int m = 0; m < 4; ++m) _Pragma("unroll") for (int k = 0; k < 2; ++k) dst[m][k] = *(const PG8_LAS bf16x8*)(lds + PG8_SA(b, h) + aoff + m * 2048 + k * 1024); } while (0)
; #define PG8_MMA(ai, bj, At, Bt) do { __builtin_amdgcn_s_setprio(1); _Pragma("unroll") for (int m = 0; m < 4; ++m) _Pragma("unroll") for (int n = 0; n < 2; ++n) _Pragma("unroll") for (int k = 0; k < 2; ++k) \
;         acc[ai][bj][m][n] = __builtin_amdgcn_mfma_f32_16x16x32_bf16(Bt[n][k], At[m][k], acc[ai][bj][m][n], 0, 0, 0); __builtin_amdgcn_s_setprio(0); } while (0)
; #define PG8_WAIT_V(n) asm volatile("s_waitcnt vmcnt(" #n ")" ::: "memory")
; #define PG8_WAIT_L(n) asm volatile("s_waitcnt lgkmcnt(" #n ")" ::: "memory")
; #define PG8_BAR __builtin_amdgcn_s_barrier()
; #define PG8_SCHED __builtin_amdgcn_sched_barrier(0)
; template <class Epi, class Sched, bool ALIGN_EPI = false, bool SP2 = false>
; __device__ __forceinline__ void gemm_phase(PG8_LAS unsigned char* lds, const Gemm g, const Sched& S, const Epi& E) {
;     ...
;             PG8_WAIT_V(8); PG8_WAIT_L(0); PG8_BAR; PG8_MMA(0, 0, At, B0); PG8_MMA(0, 1, At, B1); PG8_BAR; PG8_SCHED;
;             PG8_LDA(At, 1, 1); PG8_STAGE(PG8_SB(1, 0), b3, voffB); PG8_STAGE(PG8_SB(1, 1), b3 + hstep, voffB); PG8_STAGE(PG8_SA(1, 0), a3, voffA);
	v_mfma_f32_16x16x32_bf16 v[132:135], v[144:147], v[176:179], v[132:135]
	v_mfma_f32_16x16x32_bf16 v[128:131], v[152:155], v[176:179], v[128:131]
	v_mfma_f32_16x16x32_bf16 v[116:119], v[144:147], v[184:187], v[116:119]
	v_mfma_f32_16x16x32_bf16 v[112:115], v[152:155], v[184:187], v[112:115]
	v_mfma_f32_16x16x32_bf16 v[100:103], v[144:147], v[192:195], v[100:103]
	v_mfma_f32_16x16x32_bf16 v[96:99], v[152:155], v[192:195], v[96:99]
	v_mfma_f32_16x16x32_bf16 v[84:87], v[144:147], v[200:203], v[84:87]
	v_mfma_f32_16x16x32_bf16 v[80:83], v[152:155], v[200:203], v[80:83]
	v_mfma_f32_16x16x32_bf16 v[132:135], v[148:151], v[180:183], v[132:135]
	v_mfma_f32_16x16x32_bf16 v[128:131], v[156:159], v[180:183], v[128:131]
	v_mfma_f32_16x16x32_bf16 v[116:119], v[148:151], v[188:191], v[116:119]
	v_mfma_f32_16x16x32_bf16 v[112:115], v[156:159], v[188:191], v[112:115]
	v_mfma_f32_16x16x32_bf16 v[100:103], v[148:151], v[196:199], v[100:103]
	v_mfma_f32_16x16x32_bf16 v[96:99], v[156:159], v[196:199], v[96:99]
	v_mfma_f32_16x16x32_bf16 v[84:87], v[148:151], v[204:207], v[84:87]
	v_mfma_f32_16x16x32_bf16 v[80:83], v[156:159], v[204:207], v[80:83]
	s_setprio 0
	s_barrier
	s_add_i32 s62, s82, s64

; #define PG8_STAGE(bufoff, gbase, voff) do { _Pragma("unroll") for (int _i = 0; _i < 2; ++_i) \
;         __builtin_amdgcn_global_load_lds((const unsigned*)((const char*)(gbase) + (voff)[_i]), (PG8_LAS unsigned*)(lds + (bufoff) + ldsw + _i * 8192), 16, 0, 0); } while (0)
; #define PG8_LDA(dst, b, h) do { _Pragma("unroll") for (int m = 0; m < 4; ++m) _Pragma("unroll") for (int k = 0; k < 2; ++k) dst[m][k] = *(const PG8_LAS bf16x8*)(lds + PG8_SA(b, h) + aoff + m * 2048 + k * 1024); } while (0)
; template <class Epi, class Sched, bool ALIGN_EPI = false, bool SP2 = false>
; __device__ __forceinline__ void gemm_phase(PG8_LAS unsigned char* lds, const Gemm g, const Sched& S, const Epi& E) {
;     ...
;             PG8_LDA(At, 1, 1); PG8_STAGE(PG8_SB(1, 0), b3, voffB); PG8_STAGE(PG8_SB(1, 1), b3 + hstep, voffB); PG8_STAGE(PG8_SA(1, 0), a3, voffA);
	s_mov_b32 m0, s62
	ds_read_b128 v[176:179], v215 offset:49152
	ds_read_b128 v[180:183], v215 offset:50176
	ds_read_b128 v[184:187], v215 offset:51200
	ds_read_b128 v[188:191], v215 offset:52224
	ds_read_b128 v[192:195], v215 offset:53248
	ds_read_b128 v[196:199], v215 offset:54272
	ds_read_b128 v[200:203], v215 offset:55296
	ds_read_b128 v[204:207], v215 offset:56320
	global_load_lds_dwordx4 v250, s[96:97]
	s_add_i32 m0, s62, 0x2000
	s_add_u32 s60, s60, 0x200080

; #define PG8_STAGE(bufoff, gbase, voff) do { _Pragma("unroll") for (int _i = 0; _i < 2; ++_i) \
;         __builtin_amdgcn_global_load_lds((const unsigned*)((const char*)(gbase) + (voff)[_i]), (PG8_LAS unsigned*)(lds + (bufoff) + ldsw + _i * 8192), 16, 0, 0); } while (0)
; #define PG8_LDA(dst, b, h) do { _Pragma("unroll") for (int m = 0; m < 4; ++m) _Pragma("unroll") for (int k = 0; k < 2; ++k) dst[m][k] = *(const PG8_LAS bf16x8*)(lds + PG8_SA(b, h) + aoff + m * 2048 + k * 1024); } while (0)
; template <class Epi, class Sched, bool ALIGN_EPI = false, bool SP2 = false>
; __device__ __forceinline__ void gemm_phase(PG8_LAS unsigned char* lds, const Gemm g, const Sched& S, const Epi& E) {
;     ...
;             PG8_LDA(At, 1, 1); PG8_STAGE(PG8_SB(1, 0), b3, voffB); PG8_STAGE(PG8_SB(1, 1), b3 + hstep, voffB); PG8_STAGE(PG8_SA(1, 0), a3, voffA);
	s_addc_u32 s61, s61, 0
	s_add_i32 s62, s83, s64
	global_load_lds_dwordx4 v251, s[96:97]

; #define PG8_STAGE(bufoff, gbase, voff) do { _Pragma("unroll") for (int _i = 0; _i < 2; ++_i) \
;         __builtin_amdgcn_global_load_lds((const unsigned*)((const char*)(gbase) + (voff)[_i]), (PG8_LAS unsigned*)(lds + (bufoff) + ldsw + _i * 8192), 16, 0, 0); } while (0)
; #define PG8_LDA(dst, b, h) do { _Pragma("unroll") for (int m = 0; m < 4; ++m) _Pragma("unroll") for (int k = 0; k < 2; ++k) dst[m][k] = *(const PG8_LAS bf16x8*)(lds + PG8_SA(b, h) + aoff + m * 2048 + k * 1024); } while (0)
; template <class Epi, class Sched, bool ALIGN_EPI = false, bool SP2 = false>
; __device__ __forceinline__ void gemm_phase(PG8_LAS unsigned char* lds, const Gemm g, const Sched& S, const Epi& E) {
;     ...
;             PG8_LDA(At, 1, 1); PG8_STAGE(PG8_SB(1, 0), b3, voffB); PG8_STAGE(PG8_SB(1, 1), b3 + hstep, voffB); PG8_STAGE(PG8_SA(1, 0), a3, voffA);
	s_mov_b32 m0, s62
	s_nop 0
	global_load_lds_dwordx4 v162, s[60:61]

; #define PG8_STAGE(bufoff, gbase, voff) do { _Pragma("unroll") for (int _i = 0; _i < 2; ++_i) \
;         __builtin_amdgcn_global_load_lds((const unsigned*)((const char*)(gbase) + (voff)[_i]), (PG8_LAS unsigned*)(lds + (bufoff) + ldsw + _i * 8192), 16, 0, 0); } while (0)
; #define PG8_LDA(dst, b, h) do { _Pragma("unroll") for (int m = 0; m < 4; ++m) _Pragma("unroll") for (int k = 0; k < 2; ++k) dst[m][k] = *(const PG8_LAS bf16x8*)(lds + PG8_SA(b, h) + aoff + m * 2048 + k * 1024); } while (0)
; template <class Epi, class Sched, bool ALIGN_EPI = false, bool SP2 = false>
; __device__ __forceinline__ void gemm_phase(PG8_LAS unsigned char* lds, const Gemm g, const Sched& S, const Epi& E) {
;     ...
;             PG8_LDA(At, 1, 1); PG8_STAGE(PG8_SB(1, 0), b3, voffB); PG8_STAGE(PG8_SB(1, 1), b3 + hstep, voffB); PG8_STAGE(PG8_SA(1, 0), a3, voffA);
	s_add_i32 m0, s62, 0x2000
	s_nop 0
	global_load_lds_dwordx4 v166, s[60:61]

; #define PG8_STAGE(bufoff, gbase, voff) do { _Pragma("unroll") for (int _i = 0; _i < 2; ++_i) \
;         __builtin_amdgcn_global_load_lds((const unsigned*)((const char*)(gbase) + (voff)[_i]), (PG8_LAS unsigned*)(lds + (bufoff) + ldsw + _i * 8192), 16, 0, 0); } while (0)
; #define PG8_LDA(dst, b, h) do { _Pragma("unroll") for (int m = 0; m < 4; ++m) _Pragma("unroll") for (int k = 0; k < 2; ++k) dst[m][k] = *(const PG8_LAS bf16x8*)(lds + PG8_SA(b, h) + aoff + m * 2048 + k * 1024); } while (0)
; template <class Epi, class Sched, bool ALIGN_EPI = false, bool SP2 = false>
; __device__ __forceinline__ void gemm_phase(PG8_LAS unsigned char* lds, const Gemm g, const Sched& S, const Epi& E) {
;     ...
;             PG8_LDA(At, 1, 1); PG8_STAGE(PG8_SB(1, 0), b3, voffB); PG8_STAGE(PG8_SB(1, 1), b3 + hstep, voffB); PG8_STAGE(PG8_SA(1, 0), a3, voffA);
	s_mov_b32 m0, s70
	s_nop 0
	global_load_lds_dwordx4 v252, s[98:99]

; #define PG8_STAGE(bufoff, gbase, voff) do { _Pragma("unroll") for (int _i = 0; _i < 2; ++_i) \
;         __builtin_amdgcn_global_load_lds((const unsigned*)((const char*)(gbase) + (voff)[_i]), (PG8_LAS unsigned*)(lds + (bufoff) + ldsw + _i * 8192), 16, 0, 0); } while (0)
; #define PG8_LDA(dst, b, h) do { _Pragma("unroll") for (int m = 0; m < 4; ++m) _Pragma("unroll") for (int k = 0; k < 2; ++k) dst[m][k] = *(const PG8_LAS bf16x8*)(lds + PG8_SA(b, h) + aoff + m * 2048 + k * 1024); } while (0)
; #define PG8_MMA(ai, bj, At, Bt) do { __builtin_amdgcn_s_setprio(1); _Pragma("unroll") for (int m = 0; m < 4; ++m) _Pragma("unroll") for (int n = 0; n < 2; ++n) _Pragma("unroll") for (int k = 0; k < 2; ++k) \
;         acc[ai][bj][m][n] = __builtin_amdgcn_mfma_f32_16x16x32_bf16(Bt[n][k], At[m][k], acc[ai][bj][m][n], 0, 0, 0); __builtin_amdgcn_s_setprio(0); } while (0)
; #define PG8_WAIT_V(n) asm volatile("s_waitcnt vmcnt(" #n ")" ::: "memory")
; #define PG8_WAIT_L(n) asm volatile("s_waitcnt lgkmcnt(" #n ")" ::: "memory")
; #define PG8_BAR __builtin_amdgcn_s_barrier()
; #define PG8_SCHED __builtin_amdgcn_sched_barrier(0)
; template <class Epi, class Sched, bool ALIGN_EPI = false, bool SP2 = false>
; __device__ __forceinline__ void gemm_phase(PG8_LAS unsigned char* lds, const Gemm g, const Sched& S, const Epi& E) {
;     ...
;             PG8_LDA(At, 1, 1); PG8_STAGE(PG8_SB(1, 0), b3, voffB); PG8_STAGE(PG8_SB(1, 1), b3 + hstep, voffB); PG8_STAGE(PG8_SA(1, 0), a3, voffA);
;             PG8_WAIT_V(8); PG8_WAIT_L(0); PG8_BAR; PG8_MMA(1, 0, At, B0); PG8_MMA(1, 1, At, B1); PG8_BAR; PG8_SCHED;
	s_mov_b32 m0, s71
	s_nop 0
	global_load_lds_dwordx4 v253, s[98:99]
	s_waitcnt vmcnt(8)
	s_waitcnt lgkmcnt(0)
	s_barrier
	s_setprio 1
	s_waitcnt lgkmcnt(0)
	v_mfma_f32_16x16x32_bf16 v[60:63], v[64:67], v[176:179], v[60:63]
	v_mfma_f32_16x16x32_bf16 v[56:59], v[72:75], v[176:179], v[56:59]
	v_mfma_f32_16x16x32_bf16 v[44:47], v[64:67], v[184:187], v[44:47]
	v_mfma_f32_16x16x32_bf16 v[40:43], v[72:75], v[184:187], v[40:43]
	v_mfma_f32_16x16x32_bf16 v[28:31], v[64:67], v[192:195], v[28:31]
	v_mfma_f32_16x16x32_bf16 v[24:27], v[72:75], v[192:195], v[24:27]
	v_mfma_f32_16x16x32_bf16 v[12:15], v[64:67], v[200:203], v[12:15]
	v_mfma_f32_16x16x32_bf16 v[8:11], v[72:75], v[200:203], v[8:11]
	v_mfma_f32_16x16x32_bf16 v[60:63], v[68:71], v[180:183], v[60:63]
	v_mfma_f32_16x16x32_bf16 v[56:59], v[76:79], v[180:183], v[56:59]
	v_mfma_f32_16x16x32_bf16 v[44:47], v[68:71], v[188:191], v[44:47]
	v_mfma_f32_16x16x32_bf16 v[40:43], v[76:79], v[188:191], v[40:43]
	v_mfma_f32_16x16x32_bf16 v[28:31], v[68:71], v[196:199], v[28:31]
	v_mfma_f32_16x16x32_bf16 v[24:27], v[76:79], v[196:199], v[24:27]
	v_mfma_f32_16x16x32_bf16 v[12:15], v[68:71], v[204:207], v[12:15]
	v_mfma_f32_16x16x32_bf16 v[8:11], v[76:79], v[204:207], v[8:11]


; #define PG8_MMA(ai, bj, At, Bt) do { __builtin_amdgcn_s_setprio(1); _Pragma("unroll") for (int m = 0; m < 4; ++m) _Pragma("unroll") for (int n = 0; n < 2; ++n) _Pragma("unroll") for (int k = 0; k < 2; ++k) \
;         acc[ai][bj][m][n] = __builtin_amdgcn_mfma_f32_16x16x32_bf16(Bt[n][k], At[m][k], acc[ai][bj][m][n], 0, 0, 0); __builtin_amdgcn_s_setprio(0); } while (0)
; #define PG8_WAIT_V(n) asm volatile("s_waitcnt vmcnt(" #n ")" ::: "memory")
; #define PG8_WAIT_L(n) asm volatile("s_waitcnt lgkmcnt(" #n ")" ::: "memory")
; #define PG8_BAR __builtin_amdgcn_s_barrier()
; #define PG8_SCHED __builtin_amdgcn_sched_barrier(0)
; template <class Epi, class Sched, bool ALIGN_EPI = false, bool SP2 = false>
; __device__ __forceinline__ void gemm_phase(PG8_LAS unsigned char* lds, const Gemm g, const Sched& S, const Epi& E) {
;     ...
;         for (int t = 0; t < nt; t += 2) {
;     ...
;             PG8_WAIT_V(8); PG8_WAIT_L(0); PG8_BAR; PG8_MMA(1, 0, At, B0); PG8_MMA(1, 1, At, B1); PG8_BAR; PG8_SCHED;
;     ...
;         if constexpr (ALIGN_EPI) { if (wr == 0) PG8_BAR; }
	v_mfma_f32_16x16x32_bf16 v[52:55], v[144:147], v[176:179], v[52:55]
	v_mfma_f32_16x16x32_bf16 v[48:51], v[152:155], v[176:179], v[48:51]
	v_mfma_f32_16x16x32_bf16 v[36:39], v[144:147], v[184:187], v[36:39]
	v_mfma_f32_16x16x32_bf16 v[32:35], v[152:155], v[184:187], v[32:35]
	v_mfma_f32_16x16x32_bf16 v[20:23], v[144:147], v[192:195], v[20:23]
	v_mfma_f32_16x16x32_bf16 v[16:19], v[152:155], v[192:195], v[16:19]
	v_mfma_f32_16x16x32_bf16 v[4:7], v[144:147], v[200:203], v[4:7]
	v_mfma_f32_16x16x32_bf16 v[0:3], v[152:155], v[200:203], v[0:3]
	v_mfma_f32_16x16x32_bf16 v[52:55], v[148:151], v[180:183], v[52:55]
	v_mfma_f32_16x16x32_bf16 v[48:51], v[156:159], v[180:183], v[48:51]
	v_mfma_f32_16x16x32_bf16 v[36:39], v[148:151], v[188:191], v[36:39]
	v_mfma_f32_16x16x32_bf16 v[32:35], v[156:159], v[188:191], v[32:35]
	v_mfma_f32_16x16x32_bf16 v[20:23], v[148:151], v[196:199], v[20:23]
	v_mfma_f32_16x16x32_bf16 v[16:19], v[156:159], v[196:199], v[16:19]
	v_mfma_f32_16x16x32_bf16 v[4:7], v[148:151], v[204:207], v[4:7]
	v_mfma_f32_16x16x32_bf16 v[0:3], v[156:159], v[204:207], v[0:3]
	s_setprio 0
	s_barrier
	s_add_i32 s81, s81, 2
	s_add_u32 s58, s58, 0x100
	s_addc_u32 s59, s59, 0
	s_add_u32 s79, s79, 0x100
	s_addc_u32 s80, s80, 0
	s_cmpk_gt_u32 s81, 0x7d
	s_cbranch_scc0 .LBB0_509
	s_and_b64 vcc, exec, s[42:43]
	s_cbranch_vccz .LBB0_512
	s_barrier

; #define PG8_STAGE(bufoff, gbase, voff) do { _Pragma("unroll") for (int _i = 0; _i < 2; ++_i) \
;         __builtin_amdgcn_global_load_lds((const unsigned*)((const char*)(gbase) + (voff)[_i]), (PG8_LAS unsigned*)(lds + (bufoff) + ldsw + _i * 8192), 16, 0, 0); } while (0)
; #define PG8_LDA(dst, b, h) do { _Pragma("unroll") for (int m = 0; m < 4; ++m) _Pragma("unroll") for (int k = 0; k < 2; ++k) dst[m][k] = *(const PG8_LAS bf16x8*)(lds + PG8_SA(b, h) + aoff + m * 2048 + k * 1024); } while (0)
; #define PG8_LDB(dst, b, h) do { _Pragma("unroll") for (int n = 0; n < 2; ++n) _Pragma("unroll") for (int k = 0; k < 2; ++k) dst[n][k] = *(const PG8_LAS bf16x8*)(lds + PG8_SB(b, h) + boff + n * 2048 + k * 1024); } while (0)
; #define PG8_SCHED __builtin_amdgcn_sched_barrier(0)
; template <class Epi, class Sched, bool ALIGN_EPI = false, bool SP2 = false>
; __device__ __forceinline__ void gemm_phase(PG8_LAS unsigned char* lds, const Gemm g, const Sched& S, const Epi& E) {
;     ...
;             const bool last = (t == nt - 2);
;             const char* a1 = cA + (size_t)(t + 1) * kstep;
;             const char* a2 = last ? nA : cA + (size_t)(t + 2) * kstep; const char* b2 = last ? nB : cB + (size_t)(t + 2) * kstep;
;             const char* a3 = a2 + kstep; const char* b3 = b2 + kstep;
;     ...
;             PG8_LDB(B0, 0, 0); PG8_LDB(B1, 0, 1); PG8_SCHED; PG8_LDA(At, 0, 0); PG8_STAGE(PG8_SA(1, 1), a1 + hstep, voffA);
.LBB0_679:
	ds_read_b128 v[128:131], v203
	ds_read_b128 v[132:135], v203 offset:1024
	ds_read_b128 v[136:139], v203 offset:2048
	ds_read_b128 v[140:143], v203 offset:3072
	ds_read_b128 v[144:147], v205
	ds_read_b128 v[148:151], v205 offset:1024
	ds_read_b128 v[152:155], v205 offset:2048
	ds_read_b128 v[156:159], v205 offset:3072
	s_add_u32 s12, s10, 0xfff80080
	s_addc_u32 s13, s11, -1
	s_cmp_eq_u32 s78, 28
	s_cselect_b32 s55, s49, s13
	s_cselect_b32 s54, s74, s12
	s_cselect_b32 s13, s47, s77
	s_cselect_b32 s12, s75, s76

; #define PG8_STAGE(bufoff, gbase, voff) do { _Pragma("unroll") for (int _i = 0; _i < 2; ++_i) \
;         __builtin_amdgcn_global_load_lds((const unsigned*)((const char*)(gbase) + (voff)[_i]), (PG8_LAS unsigned*)(lds + (bufoff) + ldsw + _i * 8192), 16, 0, 0); } while (0)
; #define PG8_LDA(dst, b, h) do { _Pragma("unroll") for (int m = 0; m < 4; ++m) _Pragma("unroll") for (int k = 0; k < 2; ++k) dst[m][k] = *(const PG8_LAS bf16x8*)(lds + PG8_SA(b, h) + aoff + m * 2048 + k * 1024); } while (0)
; #define PG8_LDB(dst, b, h) do { _Pragma("unroll") for (int n = 0; n < 2; ++n) _Pragma("unroll") for (int k = 0; k < 2; ++k) dst[n][k] = *(const PG8_LAS bf16x8*)(lds + PG8_SB(b, h) + boff + n * 2048 + k * 1024); } while (0)
; #define PG8_SCHED __builtin_amdgcn_sched_barrier(0)
; template <class Epi, class Sched, bool ALIGN_EPI = false, bool SP2 = false>
; __device__ __forceinline__ void gemm_phase(PG8_LAS unsigned char* lds, const Gemm g, const Sched& S, const Epi& E) {
;     ...
;             PG8_LDB(B0, 0, 0); PG8_LDB(B1, 0, 1); PG8_SCHED; PG8_LDA(At, 0, 0); PG8_STAGE(PG8_SA(1, 1), a1 + hstep, voffA);
	s_add_i32 m0, s60, 0xc000
	ds_read_b128 v[176:179], v207
	ds_read_b128 v[180:183], v207 offset:1024
	ds_read_b128 v[184:187], v207 offset:2048
	ds_read_b128 v[192:195], v207 offset:3072
	ds_read_b128 v[210:213], v207 offset:4096
	ds_read_b128 v[214:217], v207 offset:5120
	ds_read_b128 v[218:221], v207 offset:6144
	ds_read_b128 v[222:225], v207 offset:7168
	global_load_lds_dwordx4 v168, s[10:11]

; #define PG8_STAGE(bufoff, gbase, voff) do { _Pragma("unroll") for (int _i = 0; _i < 2; ++_i) \
;         __builtin_amdgcn_global_load_lds((const unsigned*)((const char*)(gbase) + (voff)[_i]), (PG8_LAS unsigned*)(lds + (bufoff) + ldsw + _i * 8192), 16, 0, 0); } while (0)
; #define PG8_LDA(dst, b, h) do { _Pragma("unroll") for (int m = 0; m < 4; ++m) _Pragma("unroll") for (int k = 0; k < 2; ++k) dst[m][k] = *(const PG8_LAS bf16x8*)(lds + PG8_SA(b, h) + aoff + m * 2048 + k * 1024); } while (0)
; #define PG8_LDB(dst, b, h) do { _Pragma("unroll") for (int n = 0; n < 2; ++n) _Pragma("unroll") for (int k = 0; k < 2; ++k) dst[n][k] = *(const PG8_LAS bf16x8*)(lds + PG8_SB(b, h) + boff + n * 2048 + k * 1024); } while (0)
; #define PG8_MMA(ai, bj, At, Bt) do { __builtin_amdgcn_s_setprio(1); _Pragma("unroll") for (int m = 0; m < 4; ++m) _Pragma("unroll") for (int n = 0; n < 2; ++n) _Pragma("unroll") for (int k = 0; k < 2; ++k) \
;         acc[ai][bj][m][n] = __builtin_amdgcn_mfma_f32_16x16x32_bf16(Bt[n][k], At[m][k], acc[ai][bj][m][n], 0, 0, 0); __builtin_amdgcn_s_setprio(0); } while (0)
; #define PG8_WAIT_V(n) asm volatile("s_waitcnt vmcnt(" #n ")" ::: "memory")
; #define PG8_WAIT_L(n) asm volatile("s_waitcnt lgkmcnt(" #n ")" ::: "memory")
; #define PG8_BAR __builtin_amdgcn_s_barrier()
; #define PG8_SCHED __builtin_amdgcn_sched_barrier(0)
; template <class Epi, class Sched, bool ALIGN_EPI = false, bool SP2 = false>
; __device__ __forceinline__ void gemm_phase(PG8_LAS unsigned char* lds, const Gemm g, const Sched& S, const Epi& E) {
;     ...
;             PG8_LDB(B0, 0, 0); PG8_LDB(B1, 0, 1); PG8_SCHED; PG8_LDA(At, 0, 0); PG8_STAGE(PG8_SA(1, 1), a1 + hstep, voffA);
;             PG8_WAIT_V(8); PG8_WAIT_L(0); PG8_BAR; PG8_MMA(0, 0, At, B0); PG8_MMA(0, 1, At, B1); PG8_BAR; PG8_SCHED;
	s_add_i32 m0, s60, 0xe000
	s_nop 0
	global_load_lds_dwordx4 v170, s[10:11]
	s_waitcnt vmcnt(8)
	s_waitcnt lgkmcnt(0)
	s_barrier
	s_setprio 1
	s_waitcnt lgkmcnt(0)
	v_mfma_f32_16x16x32_bf16 v[124:127], v[128:131], v[176:179], v[124:127]
	v_mfma_f32_16x16x32_bf16 v[120:123], v[136:139], v[176:179], v[120:123]
	v_mfma_f32_16x16x32_bf16 v[112:115], v[128:131], v[184:187], v[112:115]
	v_mfma_f32_16x16x32_bf16 v[104:107], v[136:139], v[184:187], v[104:107]
	v_mfma_f32_16x16x32_bf16 v[100:103], v[128:131], v[210:213], v[100:103]
	v_mfma_f32_16x16x32_bf16 v[88:91], v[136:139], v[210:213], v[88:91]
	v_mfma_f32_16x16x32_bf16 v[84:87], v[128:131], v[218:221], v[84:87]
	v_mfma_f32_16x16x32_bf16 v[72:75], v[136:139], v[218:221], v[72:75]
	v_mfma_f32_16x16x32_bf16 v[124:127], v[132:135], v[180:183], v[124:127]
	v_mfma_f32_16x16x32_bf16 v[120:123], v[140:143], v[180:183], v[120:123]
	v_mfma_f32_16x16x32_bf16 v[112:115], v[132:135], v[192:195], v[112:115]
	v_mfma_f32_16x16x32_bf16 v[104:107], v[140:143], v[192:195], v[104:107]
	v_mfma_f32_16x16x32_bf16 v[100:103], v[132:135], v[214:217], v[100:103]
	v_mfma_f32_16x16x32_bf16 v[88:91], v[140:143], v[214:217], v[88:91]
	v_mfma_f32_16x16x32_bf16 v[84:87], v[132:135], v[222:225], v[84:87]
	v_mfma_f32_16x16x32_bf16 v[72:75], v[140:143], v[222:225], v[72:75]


; #define PG8_STAGE(bufoff, gbase, voff) do { _Pragma("unroll") for (int _i = 0; _i < 2; ++_i) \
;         __builtin_amdgcn_global_load_lds((const unsigned*)((const char*)(gbase) + (voff)[_i]), (PG8_LAS unsigned*)(lds + (bufoff) + ldsw + _i * 8192), 16, 0, 0); } while (0)
; #define PG8_LDA(dst, b, h) do { _Pragma("unroll") for (int m = 0; m < 4; ++m) _Pragma("unroll") for (int k = 0; k < 2; ++k) dst[m][k] = *(const PG8_LAS bf16x8*)(lds + PG8_SA(b, h) + aoff + m * 2048 + k * 1024); } while (0)
; #define PG8_MMA(ai, bj, At, Bt) do { __builtin_amdgcn_s_setprio(1); _Pragma("unroll") for (int m = 0; m < 4; ++m) _Pragma("unroll") for (int n = 0; n < 2; ++n) _Pragma("unroll") for (int k = 0; k < 2; ++k) \
;         acc[ai][bj][m][n] = __builtin_amdgcn_mfma_f32_16x16x32_bf16(Bt[n][k], At[m][k], acc[ai][bj][m][n], 0, 0, 0); __builtin_amdgcn_s_setprio(0); } while (0)
; #define PG8_WAIT_V(n) asm volatile("s_waitcnt vmcnt(" #n ")" ::: "memory")
; #define PG8_WAIT_L(n) asm volatile("s_waitcnt lgkmcnt(" #n ")" ::: "memory")
; #define PG8_BAR __builtin_amdgcn_s_barrier()
; #define PG8_SCHED __builtin_amdgcn_sched_barrier(0)
; template <class Epi, class Sched, bool ALIGN_EPI = false, bool SP2 = false>
; __device__ __forceinline__ void gemm_phase(PG8_LAS unsigned char* lds, const Gemm g, const Sched& S, const Epi& E) {
;     ...
;             PG8_WAIT_V(8); PG8_WAIT_L(0); PG8_BAR; PG8_MMA(0, 0, At, B0); PG8_MMA(0, 1, At, B1); PG8_BAR; PG8_SCHED;
;             PG8_LDA(At, 0, 1); PG8_STAGE(PG8_SB(0, 0), b2, voffB); PG8_STAGE(PG8_SB(0, 1), b2 + hstep, voffB); PG8_STAGE(PG8_SA(0, 0), a2, voffA);
	v_mfma_f32_16x16x32_bf16 v[116:119], v[144:147], v[176:179], v[116:119]
	v_mfma_f32_16x16x32_bf16 v[108:111], v[152:155], v[176:179], v[108:111]
	v_mfma_f32_16x16x32_bf16 v[96:99], v[144:147], v[184:187], v[96:99]
	v_mfma_f32_16x16x32_bf16 v[92:95], v[152:155], v[184:187], v[92:95]
	v_mfma_f32_16x16x32_bf16 v[80:83], v[144:147], v[210:213], v[80:83]
	v_mfma_f32_16x16x32_bf16 v[76:79], v[152:155], v[210:213], v[76:79]
	v_mfma_f32_16x16x32_bf16 v[68:71], v[144:147], v[218:221], v[68:71]
	v_mfma_f32_16x16x32_bf16 v[64:67], v[152:155], v[218:221], v[64:67]
	v_mfma_f32_16x16x32_bf16 v[116:119], v[148:151], v[180:183], v[116:119]
	v_mfma_f32_16x16x32_bf16 v[108:111], v[156:159], v[180:183], v[108:111]
	v_mfma_f32_16x16x32_bf16 v[96:99], v[148:151], v[192:195], v[96:99]
	v_mfma_f32_16x16x32_bf16 v[92:95], v[156:159], v[192:195], v[92:95]
	v_mfma_f32_16x16x32_bf16 v[80:83], v[148:151], v[214:217], v[80:83]
	v_mfma_f32_16x16x32_bf16 v[76:79], v[156:159], v[214:217], v[76:79]
	v_mfma_f32_16x16x32_bf16 v[68:71], v[148:151], v[222:225], v[68:71]
	v_mfma_f32_16x16x32_bf16 v[64:67], v[156:159], v[222:225], v[64:67]
	s_setprio 0
	s_barrier
	s_add_i32 s79, s70, s57
	s_mov_b64 s[96:97], s[12:13]

; #define PG8_STAGE(bufoff, gbase, voff) do { _Pragma("unroll") for (int _i = 0; _i < 2; ++_i) \
;         __builtin_amdgcn_global_load_lds((const unsigned*)((const char*)(gbase) + (voff)[_i]), (PG8_LAS unsigned*)(lds + (bufoff) + ldsw + _i * 8192), 16, 0, 0); } while (0)
; #define PG8_LDA(dst, b, h) do { _Pragma("unroll") for (int m = 0; m < 4; ++m) _Pragma("unroll") for (int k = 0; k < 2; ++k) dst[m][k] = *(const PG8_LAS bf16x8*)(lds + PG8_SA(b, h) + aoff + m * 2048 + k * 1024); } while (0)
; template <class Epi, class Sched, bool ALIGN_EPI = false, bool SP2 = false>
; __device__ __forceinline__ void gemm_phase(PG8_LAS unsigned char* lds, const Gemm g, const Sched& S, const Epi& E) {
;     ...
;             PG8_LDA(At, 0, 1); PG8_STAGE(PG8_SB(0, 0), b2, voffB); PG8_STAGE(PG8_SB(0, 1), b2 + hstep, voffB); PG8_STAGE(PG8_SA(0, 0), a2, voffA);
	s_mov_b32 m0, s79
	ds_read_b128 v[176:179], v207 offset:16384
	ds_read_b128 v[180:183], v207 offset:17408
	ds_read_b128 v[184:187], v207 offset:18432
	ds_read_b128 v[192:195], v207 offset:19456
	ds_read_b128 v[210:213], v207 offset:20480
	ds_read_b128 v[214:217], v207 offset:21504
	ds_read_b128 v[218:221], v207 offset:22528
	ds_read_b128 v[222:225], v207 offset:23552
	global_load_lds_dwordx4 v164, s[12:13]
	s_add_i32 m0, s79, 0x2000
	s_add_u32 s80, s12, 0x80000

; #define PG8_STAGE(bufoff, gbase, voff) do { _Pragma("unroll") for (int _i = 0; _i < 2; ++_i) \
;         __builtin_amdgcn_global_load_lds((const unsigned*)((const char*)(gbase) + (voff)[_i]), (PG8_LAS unsigned*)(lds + (bufoff) + ldsw + _i * 8192), 16, 0, 0); } while (0)
; #define PG8_LDA(dst, b, h) do { _Pragma("unroll") for (int m = 0; m < 4; ++m) _Pragma("unroll") for (int k = 0; k < 2; ++k) dst[m][k] = *(const PG8_LAS bf16x8*)(lds + PG8_SA(b, h) + aoff + m * 2048 + k * 1024); } while (0)
; template <class Epi, class Sched, bool ALIGN_EPI = false, bool SP2 = false>
; __device__ __forceinline__ void gemm_phase(PG8_LAS unsigned char* lds, const Gemm g, const Sched& S, const Epi& E) {
;     ...
;             PG8_LDA(At, 0, 1); PG8_STAGE(PG8_SB(0, 0), b2, voffB); PG8_STAGE(PG8_SB(0, 1), b2 + hstep, voffB); PG8_STAGE(PG8_SA(0, 0), a2, voffA);
	s_addc_u32 s81, s13, 0
	s_add_i32 s79, s71, s57
	global_load_lds_dwordx4 v160, s[12:13]

; #define PG8_STAGE(bufoff, gbase, voff) do { _Pragma("unroll") for (int _i = 0; _i < 2; ++_i) \
;         __builtin_amdgcn_global_load_lds((const unsigned*)((const char*)(gbase) + (voff)[_i]), (PG8_LAS unsigned*)(lds + (bufoff) + ldsw + _i * 8192), 16, 0, 0); } while (0)
; #define PG8_LDA(dst, b, h) do { _Pragma("unroll") for (int m = 0; m < 4; ++m) _Pragma("unroll") for (int k = 0; k < 2; ++k) dst[m][k] = *(const PG8_LAS bf16x8*)(lds + PG8_SA(b, h) + aoff + m * 2048 + k * 1024); } while (0)
; template <class Epi, class Sched, bool ALIGN_EPI = false, bool SP2 = false>
; __device__ __forceinline__ void gemm_phase(PG8_LAS unsigned char* lds, const Gemm g, const Sched& S, const Epi& E) {
;     ...
;             PG8_LDA(At, 0, 1); PG8_STAGE(PG8_SB(0, 0), b2, voffB); PG8_STAGE(PG8_SB(0, 1), b2 + hstep, voffB); PG8_STAGE(PG8_SA(0, 0), a2, voffA);
	s_mov_b32 m0, s79
	s_nop 0
	global_load_lds_dwordx4 v164, s[80:81]

; #define PG8_STAGE(bufoff, gbase, voff) do { _Pragma("unroll") for (int _i = 0; _i < 2; ++_i) \
;         __builtin_amdgcn_global_load_lds((const unsigned*)((const char*)(gbase) + (voff)[_i]), (PG8_LAS unsigned*)(lds + (bufoff) + ldsw + _i * 8192), 16, 0, 0); } while (0)
; #define PG8_LDA(dst, b, h) do { _Pragma("unroll") for (int m = 0; m < 4; ++m) _Pragma("unroll") for (int k = 0; k < 2; ++k) dst[m][k] = *(const PG8_LAS bf16x8*)(lds + PG8_SA(b, h) + aoff + m * 2048 + k * 1024); } while (0)
; template <class Epi, class Sched, bool ALIGN_EPI = false, bool SP2 = false>
; __device__ __forceinline__ void gemm_phase(PG8_LAS unsigned char* lds, const Gemm g, const Sched& S, const Epi& E) {
;     ...
;             PG8_LDA(At, 0, 1); PG8_STAGE(PG8_SB(0, 0), b2, voffB); PG8_STAGE(PG8_SB(0, 1), b2 + hstep, voffB); PG8_STAGE(PG8_SA(0, 0), a2, voffA);
	s_add_i32 m0, s79, 0x2000
	s_nop 0
	global_load_lds_dwordx4 v160, s[80:81]
	s_mov_b64 s[98:99], s[54:55]

; #define PG8_STAGE(bufoff, gbase, voff) do { _Pragma("unroll") for (int _i = 0; _i < 2; ++_i) \
;         __builtin_amdgcn_global_load_lds((const unsigned*)((const char*)(gbase) + (voff)[_i]), (PG8_LAS unsigned*)(lds + (bufoff) + ldsw + _i * 8192), 16, 0, 0); } while (0)
; #define PG8_LDA(dst, b, h) do { _Pragma("unroll") for (int m = 0; m < 4; ++m) _Pragma("unroll") for (int k = 0; k < 2; ++k) dst[m][k] = *(const PG8_LAS bf16x8*)(lds + PG8_SA(b, h) + aoff + m * 2048 + k * 1024); } while (0)
; #define PG8_MMA(ai, bj, At, Bt) do { __builtin_amdgcn_s_setprio(1); _Pragma("unroll") for (int m = 0; m < 4; ++m) _Pragma("unroll") for (int n = 0; n < 2; ++n) _Pragma("unroll") for (int k = 0; k < 2; ++k) \
;         acc[ai][bj][m][n] = __builtin_amdgcn_mfma_f32_16x16x32_bf16(Bt[n][k], At[m][k], acc[ai][bj][m][n], 0, 0, 0); __builtin_amdgcn_s_setprio(0); } while (0)
; #define PG8_WAIT_V(n) asm volatile("s_waitcnt vmcnt(" #n ")" ::: "memory")
; #define PG8_WAIT_L(n) asm volatile("s_waitcnt lgkmcnt(" #n ")" ::: "memory")
; #define PG8_BAR __builtin_amdgcn_s_barrier()
; #define PG8_SCHED __builtin_amdgcn_sched_barrier(0)
; template <class Epi, class Sched, bool ALIGN_EPI = false, bool SP2 = false>
; __device__ __forceinline__ void gemm_phase(PG8_LAS unsigned char* lds, const Gemm g, const Sched& S, const Epi& E) {
;     ...
;             PG8_LDA(At, 0, 1); PG8_STAGE(PG8_SB(0, 0), b2, voffB); PG8_STAGE(PG8_SB(0, 1), b2 + hstep, voffB); PG8_STAGE(PG8_SA(0, 0), a2, voffA);
;             PG8_WAIT_V(8); PG8_WAIT_L(0); PG8_BAR; PG8_MMA(1, 0, At, B0); PG8_MMA(1, 1, At, B1); PG8_BAR; PG8_SCHED;
	s_mov_b32 m0, s60
	s_nop 0
	global_load_lds_dwordx4 v166, s[54:55]
	s_mov_b32 m0, s61
	s_nop 0
	global_load_lds_dwordx4 v162, s[54:55]
	s_waitcnt vmcnt(8)
	s_waitcnt lgkmcnt(0)
	s_barrier
	s_setprio 1
	s_waitcnt lgkmcnt(0)
	v_mfma_f32_16x16x32_bf16 v[60:63], v[128:131], v[176:179], v[60:63]
	v_mfma_f32_16x16x32_bf16 v[56:59], v[136:139], v[176:179], v[56:59]
	v_mfma_f32_16x16x32_bf16 v[52:55], v[128:131], v[184:187], v[52:55]
	v_mfma_f32_16x16x32_bf16 v[40:43], v[136:139], v[184:187], v[40:43]
	v_mfma_f32_16x16x32_bf16 v[36:39], v[128:131], v[210:213], v[36:39]
	v_mfma_f32_16x16x32_bf16 v[24:27], v[136:139], v[210:213], v[24:27]
	v_mfma_f32_16x16x32_bf16 v[20:23], v[128:131], v[218:221], v[20:23]
	v_mfma_f32_16x16x32_bf16 v[8:11], v[136:139], v[218:221], v[8:11]
	v_mfma_f32_16x16x32_bf16 v[60:63], v[132:135], v[180:183], v[60:63]
	v_mfma_f32_16x16x32_bf16 v[56:59], v[140:143], v[180:183], v[56:59]
	v_mfma_f32_16x16x32_bf16 v[52:55], v[132:135], v[192:195], v[52:55]
	v_mfma_f32_16x16x32_bf16 v[40:43], v[140:143], v[192:195], v[40:43]
	v_mfma_f32_16x16x32_bf16 v[36:39], v[132:135], v[214:217], v[36:39]
	v_mfma_f32_16x16x32_bf16 v[24:27], v[140:143], v[214:217], v[24:27]
	v_mfma_f32_16x16x32_bf16 v[20:23], v[132:135], v[222:225], v[20:23]
	v_mfma_f32_16x16x32_bf16 v[8:11], v[140:143], v[222:225], v[8:11]


; #define PG8_STAGE(bufoff, gbase, voff) do { _Pragma("unroll") for (int _i = 0; _i < 2; ++_i) \
;         __builtin_amdgcn_global_load_lds((const unsigned*)((const char*)(gbase) + (voff)[_i]), (PG8_LAS unsigned*)(lds + (bufoff) + ldsw + _i * 8192), 16, 0, 0); } while (0)
; #define PG8_LDA(dst, b, h) do { _Pragma("unroll") for (int m = 0; m < 4; ++m) _Pragma("unroll") for (int k = 0; k < 2; ++k) dst[m][k] = *(const PG8_LAS bf16x8*)(lds + PG8_SA(b, h) + aoff + m * 2048 + k * 1024); } while (0)
; #define PG8_LDB(dst, b, h) do { _Pragma("unroll") for (int n = 0; n < 2; ++n) _Pragma("unroll") for (int k = 0; k < 2; ++k) dst[n][k] = *(const PG8_LAS bf16x8*)(lds + PG8_SB(b, h) + boff + n * 2048 + k * 1024); } while (0)
; #define PG8_MMA(ai, bj, At, Bt) do { __builtin_amdgcn_s_setprio(1); _Pragma("unroll") for (int m = 0; m < 4; ++m) _Pragma("unroll") for (int n = 0; n < 2; ++n) _Pragma("unroll") for (int k = 0; k < 2; ++k) \
;         acc[ai][bj][m][n] = __builtin_amdgcn_mfma_f32_16x16x32_bf16(Bt[n][k], At[m][k], acc[ai][bj][m][n], 0, 0, 0); __builtin_amdgcn_s_setprio(0); } while (0)
; #define PG8_WAIT_V(n) asm volatile("s_waitcnt vmcnt(" #n ")" ::: "memory")
; #define PG8_WAIT_L(n) asm volatile("s_waitcnt lgkmcnt(" #n ")" ::: "memory")
; #define PG8_BAR __builtin_amdgcn_s_barrier()
; #define PG8_SCHED __builtin_amdgcn_sched_barrier(0)
; template <class Epi, class Sched, bool ALIGN_EPI = false, bool SP2 = false>
; __device__ __forceinline__ void gemm_phase(PG8_LAS unsigned char* lds, const Gemm g, const Sched& S, const Epi& E) {
;     ...
;             PG8_WAIT_V(8); PG8_WAIT_L(0); PG8_BAR; PG8_MMA(1, 0, At, B0); PG8_MMA(1, 1, At, B1); PG8_BAR; PG8_SCHED;
;             PG8_LDB(B0, 1, 0); PG8_LDB(B1, 1, 1); PG8_SCHED; PG8_LDA(At, 1, 0); PG8_STAGE(PG8_SA(0, 1), a2 + hstep, voffA);
	v_mfma_f32_16x16x32_bf16 v[48:51], v[144:147], v[176:179], v[48:51]
	v_mfma_f32_16x16x32_bf16 v[44:47], v[152:155], v[176:179], v[44:47]
	v_mfma_f32_16x16x32_bf16 v[32:35], v[144:147], v[184:187], v[32:35]
	v_mfma_f32_16x16x32_bf16 v[28:31], v[152:155], v[184:187], v[28:31]
	v_mfma_f32_16x16x32_bf16 v[16:19], v[144:147], v[210:213], v[16:19]
	v_mfma_f32_16x16x32_bf16 v[12:15], v[152:155], v[210:213], v[12:15]
	v_mfma_f32_16x16x32_bf16 v[4:7], v[144:147], v[218:221], v[4:7]
	v_mfma_f32_16x16x32_bf16 v[0:3], v[152:155], v[218:221], v[0:3]
	v_mfma_f32_16x16x32_bf16 v[48:51], v[148:151], v[180:183], v[48:51]
	v_mfma_f32_16x16x32_bf16 v[44:47], v[156:159], v[180:183], v[44:47]
	v_mfma_f32_16x16x32_bf16 v[32:35], v[148:151], v[192:195], v[32:35]
	v_mfma_f32_16x16x32_bf16 v[28:31], v[156:159], v[192:195], v[28:31]
	v_mfma_f32_16x16x32_bf16 v[16:19], v[148:151], v[214:217], v[16:19]
	v_mfma_f32_16x16x32_bf16 v[12:15], v[156:159], v[214:217], v[12:15]
	v_mfma_f32_16x16x32_bf16 v[4:7], v[148:151], v[222:225], v[4:7]
	v_mfma_f32_16x16x32_bf16 v[0:3], v[156:159], v[222:225], v[0:3]
	s_setprio 0
	s_barrier
	s_add_i32 s79, 0, 0x18000
	s_add_i32 s80, 0, 0x1c000
	v_add_u32_e32 v140, s79, v197
	v_add_u32_e32 v156, s80, v197
	ds_read_b128 v[128:131], v140
	ds_read_b128 v[132:135], v140 offset:1024
	ds_read_b128 v[136:139], v140 offset:2048
	ds_read_b128 v[140:143], v140 offset:3072
	ds_read_b128 v[144:147], v156
	ds_read_b128 v[148:151], v156 offset:1024
	ds_read_b128 v[152:155], v156 offset:2048
	ds_read_b128 v[156:159], v156 offset:3072
	s_add_u32 s54, s54, 0x80000
	s_addc_u32 s55, s55, 0
	s_mov_b32 m0, s62

; #define PG8_STAGE(bufoff, gbase, voff) do { _Pragma("unroll") for (int _i = 0; _i < 2; ++_i) \
;         __builtin_amdgcn_global_load_lds((const unsigned*)((const char*)(gbase) + (voff)[_i]), (PG8_LAS unsigned*)(lds + (bufoff) + ldsw + _i * 8192), 16, 0, 0); } while (0)
; #define PG8_LDA(dst, b, h) do { _Pragma("unroll") for (int m = 0; m < 4; ++m) _Pragma("unroll") for (int k = 0; k < 2; ++k) dst[m][k] = *(const PG8_LAS bf16x8*)(lds + PG8_SA(b, h) + aoff + m * 2048 + k * 1024); } while (0)
; #define PG8_LDB(dst, b, h) do { _Pragma("unroll") for (int n = 0; n < 2; ++n) _Pragma("unroll") for (int k = 0; k < 2; ++k) dst[n][k] = *(const PG8_LAS bf16x8*)(lds + PG8_SB(b, h) + boff + n * 2048 + k * 1024); } while (0)
; #define PG8_SCHED __builtin_amdgcn_sched_barrier(0)
; template <class Epi, class Sched, bool ALIGN_EPI = false, bool SP2 = false>
; __device__ __forceinline__ void gemm_phase(PG8_LAS unsigned char* lds, const Gemm g, const Sched& S, const Epi& E) {
;     ...
;             PG8_LDB(B0, 1, 0); PG8_LDB(B1, 1, 1); PG8_SCHED; PG8_LDA(At, 1, 0); PG8_STAGE(PG8_SA(0, 1), a2 + hstep, voffA);
	ds_read_b128 v[176:179], v207 offset:32768
	ds_read_b128 v[180:183], v207 offset:33792
	ds_read_b128 v[184:187], v207 offset:34816
	ds_read_b128 v[192:195], v207 offset:35840
	ds_read_b128 v[210:213], v207 offset:36864
	ds_read_b128 v[214:217], v207 offset:37888
	ds_read_b128 v[218:221], v207 offset:38912
	ds_read_b128 v[222:225], v207 offset:39936
	global_load_lds_dwordx4 v166, s[54:55]

; #define PG8_STAGE(bufoff, gbase, voff) do { _Pragma("unroll") for (int _i = 0; _i < 2; ++_i) \
;         __builtin_amdgcn_global_load_lds((const unsigned*)((const char*)(gbase) + (voff)[_i]), (PG8_LAS unsigned*)(lds + (bufoff) + ldsw + _i * 8192), 16, 0, 0); } while (0)
; #define PG8_LDA(dst, b, h) do { _Pragma("unroll") for (int m = 0; m < 4; ++m) _Pragma("unroll") for (int k = 0; k < 2; ++k) dst[m][k] = *(const PG8_LAS bf16x8*)(lds + PG8_SA(b, h) + aoff + m * 2048 + k * 1024); } while (0)
; #define PG8_LDB(dst, b, h) do { _Pragma("unroll") for (int n = 0; n < 2; ++n) _Pragma("unroll") for (int k = 0; k < 2; ++k) dst[n][k] = *(const PG8_LAS bf16x8*)(lds + PG8_SB(b, h) + boff + n * 2048 + k * 1024); } while (0)
; #define PG8_MMA(ai, bj, At, Bt) do { __builtin_amdgcn_s_setprio(1); _Pragma("unroll") for (int m = 0; m < 4; ++m) _Pragma("unroll") for (int n = 0; n < 2; ++n) _Pragma("unroll") for (int k = 0; k < 2; ++k) \
;         acc[ai][bj][m][n] = __builtin_amdgcn_mfma_f32_16x16x32_bf16(Bt[n][k], At[m][k], acc[ai][bj][m][n], 0, 0, 0); __builtin_amdgcn_s_setprio(0); } while (0)
; #define PG8_WAIT_V(n) asm volatile("s_waitcnt vmcnt(" #n ")" ::: "memory")
; #define PG8_WAIT_L(n) asm volatile("s_waitcnt lgkmcnt(" #n ")" ::: "memory")
; #define PG8_BAR __builtin_amdgcn_s_barrier()
; #define PG8_SCHED __builtin_amdgcn_sched_barrier(0)
; template <class Epi, class Sched, bool ALIGN_EPI = false, bool SP2 = false>
; __device__ __forceinline__ void gemm_phase(PG8_LAS unsigned char* lds, const Gemm g, const Sched& S, const Epi& E) {
;     ...
;             PG8_LDB(B0, 1, 0); PG8_LDB(B1, 1, 1); PG8_SCHED; PG8_LDA(At, 1, 0); PG8_STAGE(PG8_SA(0, 1), a2 + hstep, voffA);
;             PG8_WAIT_V(8); PG8_WAIT_L(0); PG8_BAR; PG8_MMA(0, 0, At, B0); PG8_MMA(0, 1, At, B1); PG8_BAR; PG8_SCHED;
	s_mov_b32 m0, s63
	s_nop 0
	global_load_lds_dwordx4 v162, s[54:55]
	s_waitcnt vmcnt(8)
	s_waitcnt lgkmcnt(0)
	s_barrier
	s_setprio 1
	s_waitcnt lgkmcnt(0)
	v_mfma_f32_16x16x32_bf16 v[124:127], v[128:131], v[176:179], v[124:127]
	v_mfma_f32_16x16x32_bf16 v[120:123], v[136:139], v[176:179], v[120:123]
	v_mfma_f32_16x16x32_bf16 v[112:115], v[128:131], v[184:187], v[112:115]
	v_mfma_f32_16x16x32_bf16 v[104:107], v[136:139], v[184:187], v[104:107]
	v_mfma_f32_16x16x32_bf16 v[100:103], v[128:131], v[210:213], v[100:103]
	v_mfma_f32_16x16x32_bf16 v[88:91], v[136:139], v[210:213], v[88:91]
	v_mfma_f32_16x16x32_bf16 v[84:87], v[128:131], v[218:221], v[84:87]
	v_mfma_f32_16x16x32_bf16 v[72:75], v[136:139], v[218:221], v[72:75]
	v_mfma_f32_16x16x32_bf16 v[124:127], v[132:135], v[180:183], v[124:127]
	v_mfma_f32_16x16x32_bf16 v[120:123], v[140:143], v[180:183], v[120:123]
	v_mfma_f32_16x16x32_bf16 v[112:115], v[132:135], v[192:195], v[112:115]
	v_mfma_f32_16x16x32_bf16 v[104:107], v[140:143], v[192:195], v[104:107]
	v_mfma_f32_16x16x32_bf16 v[100:103], v[132:135], v[214:217], v[100:103]
	v_mfma_f32_16x16x32_bf16 v[88:91], v[140:143], v[214:217], v[88:91]
	v_mfma_f32_16x16x32_bf16 v[84:87], v[132:135], v[222:225], v[84:87]
	v_mfma_f32_16x16x32_bf16 v[72:75], v[140:143], v[222:225], v[72:75]


; #define PG8_STAGE(bufoff, gbase, voff) do { _Pragma("unroll") for (int _i = 0; _i < 2; ++_i) \
;         __builtin_amdgcn_global_load_lds((const unsigned*)((const char*)(gbase) + (voff)[_i]), (PG8_LAS unsigned*)(lds + (bufoff) + ldsw + _i * 8192), 16, 0, 0); } while (0)
; #define PG8_LDA(dst, b, h) do { _Pragma("unroll") for (int m = 0; m < 4; ++m) _Pragma("unroll") for (int k = 0; k < 2; ++k) dst[m][k] = *(const PG8_LAS bf16x8*)(lds + PG8_SA(b, h) + aoff + m * 2048 + k * 1024); } while (0)
; #define PG8_MMA(ai, bj, At, Bt) do { __builtin_amdgcn_s_setprio(1); _Pragma("unroll") for (int m = 0; m < 4; ++m) _Pragma("unroll") for (int n = 0; n < 2; ++n) _Pragma("unroll") for (int k = 0; k < 2; ++k) \
;         acc[ai][bj][m][n] = __builtin_amdgcn_mfma_f32_16x16x32_bf16(Bt[n][k], At[m][k], acc[ai][bj][m][n], 0, 0, 0); __builtin_amdgcn_s_setprio(0); } while (0)
; #define PG8_WAIT_V(n) asm volatile("s_waitcnt vmcnt(" #n ")" ::: "memory")
; #define PG8_WAIT_L(n) asm volatile("s_waitcnt lgkmcnt(" #n ")" ::: "memory")
; #define PG8_BAR __builtin_amdgcn_s_barrier()
; #define PG8_SCHED __builtin_amdgcn_sched_barrier(0)
; template <class Epi, class Sched, bool ALIGN_EPI = false, bool SP2 = false>
; __device__ __forceinline__ void gemm_phase(PG8_LAS unsigned char* lds, const Gemm g, const Sched& S, const Epi& E) {
;     ...
;             PG8_WAIT_V(8); PG8_WAIT_L(0); PG8_BAR; PG8_MMA(0, 0, At, B0); PG8_MMA(0, 1, At, B1); PG8_BAR; PG8_SCHED;
;             PG8_LDA(At, 1, 1); PG8_STAGE(PG8_SB(1, 0), b3, voffB); PG8_STAGE(PG8_SB(1, 1), b3 + hstep, voffB); PG8_STAGE(PG8_SA(1, 0), a3, voffA);
	v_mfma_f32_16x16x32_bf16 v[116:119], v[144:147], v[176:179], v[116:119]
	v_mfma_f32_16x16x32_bf16 v[108:111], v[152:155], v[176:179], v[108:111]
	v_mfma_f32_16x16x32_bf16 v[96:99], v[144:147], v[184:187], v[96:99]
	v_mfma_f32_16x16x32_bf16 v[92:95], v[152:155], v[184:187], v[92:95]
	v_mfma_f32_16x16x32_bf16 v[80:83], v[144:147], v[210:213], v[80:83]
	v_mfma_f32_16x16x32_bf16 v[76:79], v[152:155], v[210:213], v[76:79]
	v_mfma_f32_16x16x32_bf16 v[68:71], v[144:147], v[218:221], v[68:71]
	v_mfma_f32_16x16x32_bf16 v[64:67], v[152:155], v[218:221], v[64:67]
	v_mfma_f32_16x16x32_bf16 v[116:119], v[148:151], v[180:183], v[116:119]
	v_mfma_f32_16x16x32_bf16 v[108:111], v[156:159], v[180:183], v[108:111]
	v_mfma_f32_16x16x32_bf16 v[96:99], v[148:151], v[192:195], v[96:99]
	v_mfma_f32_16x16x32_bf16 v[92:95], v[156:159], v[192:195], v[92:95]
	v_mfma_f32_16x16x32_bf16 v[80:83], v[148:151], v[214:217], v[80:83]
	v_mfma_f32_16x16x32_bf16 v[76:79], v[156:159], v[214:217], v[76:79]
	v_mfma_f32_16x16x32_bf16 v[68:71], v[148:151], v[222:225], v[68:71]
	v_mfma_f32_16x16x32_bf16 v[64:67], v[156:159], v[222:225], v[64:67]
	s_setprio 0
	s_barrier
	s_add_i32 s54, s79, s57

; #define PG8_STAGE(bufoff, gbase, voff) do { _Pragma("unroll") for (int _i = 0; _i < 2; ++_i) \
;         __builtin_amdgcn_global_load_lds((const unsigned*)((const char*)(gbase) + (voff)[_i]), (PG8_LAS unsigned*)(lds + (bufoff) + ldsw + _i * 8192), 16, 0, 0); } while (0)
; #define PG8_LDA(dst, b, h) do { _Pragma("unroll") for (int m = 0; m < 4; ++m) _Pragma("unroll") for (int k = 0; k < 2; ++k) dst[m][k] = *(const PG8_LAS bf16x8*)(lds + PG8_SA(b, h) + aoff + m * 2048 + k * 1024); } while (0)
; template <class Epi, class Sched, bool ALIGN_EPI = false, bool SP2 = false>
; __device__ __forceinline__ void gemm_phase(PG8_LAS unsigned char* lds, const Gemm g, const Sched& S, const Epi& E) {
;     ...
;             PG8_LDA(At, 1, 1); PG8_STAGE(PG8_SB(1, 0), b3, voffB); PG8_STAGE(PG8_SB(1, 1), b3 + hstep, voffB); PG8_STAGE(PG8_SA(1, 0), a3, voffA);
	s_mov_b32 m0, s54
	ds_read_b128 v[176:179], v207 offset:49152
	ds_read_b128 v[180:183], v207 offset:50176
	ds_read_b128 v[184:187], v207 offset:51200
	ds_read_b128 v[192:195], v207 offset:52224
	ds_read_b128 v[210:213], v207 offset:53248
	ds_read_b128 v[214:217], v207 offset:54272
	ds_read_b128 v[218:221], v207 offset:55296
	ds_read_b128 v[222:225], v207 offset:56320
	global_load_lds_dwordx4 v250, s[96:97]
	s_add_i32 m0, s54, 0x2000
	s_add_u32 s12, s12, 0x80080

; #define PG8_STAGE(bufoff, gbase, voff) do { _Pragma("unroll") for (int _i = 0; _i < 2; ++_i) \
;         __builtin_amdgcn_global_load_lds((const unsigned*)((const char*)(gbase) + (voff)[_i]), (PG8_LAS unsigned*)(lds + (bufoff) + ldsw + _i * 8192), 16, 0, 0); } while (0)
; #define PG8_LDA(dst, b, h) do { _Pragma("unroll") for (int m = 0; m < 4; ++m) _Pragma("unroll") for (int k = 0; k < 2; ++k) dst[m][k] = *(const PG8_LAS bf16x8*)(lds + PG8_SA(b, h) + aoff + m * 2048 + k * 1024); } while (0)
; template <class Epi, class Sched, bool ALIGN_EPI = false, bool SP2 = false>
; __device__ __forceinline__ void gemm_phase(PG8_LAS unsigned char* lds, const Gemm g, const Sched& S, const Epi& E) {
;     ...
;             PG8_LDA(At, 1, 1); PG8_STAGE(PG8_SB(1, 0), b3, voffB); PG8_STAGE(PG8_SB(1, 1), b3 + hstep, voffB); PG8_STAGE(PG8_SA(1, 0), a3, voffA);
	s_addc_u32 s13, s13, 0
	s_add_i32 s54, s80, s57
	global_load_lds_dwordx4 v251, s[96:97]

; #define PG8_STAGE(bufoff, gbase, voff) do { _Pragma("unroll") for (int _i = 0; _i < 2; ++_i) \
;         __builtin_amdgcn_global_load_lds((const unsigned*)((const char*)(gbase) + (voff)[_i]), (PG8_LAS unsigned*)(lds + (bufoff) + ldsw + _i * 8192), 16, 0, 0); } while (0)
; #define PG8_LDA(dst, b, h) do { _Pragma("unroll") for (int m = 0; m < 4; ++m) _Pragma("unroll") for (int k = 0; k < 2; ++k) dst[m][k] = *(const PG8_LAS bf16x8*)(lds + PG8_SA(b, h) + aoff + m * 2048 + k * 1024); } while (0)
; template <class Epi, class Sched, bool ALIGN_EPI = false, bool SP2 = false>
; __device__ __forceinline__ void gemm_phase(PG8_LAS unsigned char* lds, const Gemm g, const Sched& S, const Epi& E) {
;     ...
;             PG8_LDA(At, 1, 1); PG8_STAGE(PG8_SB(1, 0), b3, voffB); PG8_STAGE(PG8_SB(1, 1), b3 + hstep, voffB); PG8_STAGE(PG8_SA(1, 0), a3, voffA);
	s_mov_b32 m0, s54
	s_nop 0
	global_load_lds_dwordx4 v164, s[12:13]

; #define PG8_STAGE(bufoff, gbase, voff) do { _Pragma("unroll") for (int _i = 0; _i < 2; ++_i) \
;         __builtin_amdgcn_global_load_lds((const unsigned*)((const char*)(gbase) + (voff)[_i]), (PG8_LAS unsigned*)(lds + (bufoff) + ldsw + _i * 8192), 16, 0, 0); } while (0)
; #define PG8_LDA(dst, b, h) do { _Pragma("unroll") for (int m = 0; m < 4; ++m) _Pragma("unroll") for (int k = 0; k < 2; ++k) dst[m][k] = *(const PG8_LAS bf16x8*)(lds + PG8_SA(b, h) + aoff + m * 2048 + k * 1024); } while (0)
; template <class Epi, class Sched, bool ALIGN_EPI = false, bool SP2 = false>
; __device__ __forceinline__ void gemm_phase(PG8_LAS unsigned char* lds, const Gemm g, const Sched& S, const Epi& E) {
;     ...
;             PG8_LDA(At, 1, 1); PG8_STAGE(PG8_SB(1, 0), b3, voffB); PG8_STAGE(PG8_SB(1, 1), b3 + hstep, voffB); PG8_STAGE(PG8_SA(1, 0), a3, voffA);
	s_add_i32 m0, s54, 0x2000
	s_nop 0
	global_load_lds_dwordx4 v160, s[12:13]

; #define PG8_STAGE(bufoff, gbase, voff) do { _Pragma("unroll") for (int _i = 0; _i < 2; ++_i) \
;         __builtin_amdgcn_global_load_lds((const unsigned*)((const char*)(gbase) + (voff)[_i]), (PG8_LAS unsigned*)(lds + (bufoff) + ldsw + _i * 8192), 16, 0, 0); } while (0)
; #define PG8_LDA(dst, b, h) do { _Pragma("unroll") for (int m = 0; m < 4; ++m) _Pragma("unroll") for (int k = 0; k < 2; ++k) dst[m][k] = *(const PG8_LAS bf16x8*)(lds + PG8_SA(b, h) + aoff + m * 2048 + k * 1024); } while (0)
; template <class Epi, class Sched, bool ALIGN_EPI = false, bool SP2 = false>
; __device__ __forceinline__ void gemm_phase(PG8_LAS unsigned char* lds, const Gemm g, const Sched& S, const Epi& E) {
;     ...
;             PG8_LDA(At, 1, 1); PG8_STAGE(PG8_SB(1, 0), b3, voffB); PG8_STAGE(PG8_SB(1, 1), b3 + hstep, voffB); PG8_STAGE(PG8_SA(1, 0), a3, voffA);
	s_mov_b32 m0, s65
	s_nop 0
	global_load_lds_dwordx4 v252, s[98:99]

; #define PG8_STAGE(bufoff, gbase, voff) do { _Pragma("unroll") for (int _i = 0; _i < 2; ++_i) \
;         __builtin_amdgcn_global_load_lds((const unsigned*)((const char*)(gbase) + (voff)[_i]), (PG8_LAS unsigned*)(lds + (bufoff) + ldsw + _i * 8192), 16, 0, 0); } while (0)
; #define PG8_LDA(dst, b, h) do { _Pragma("unroll") for (int m = 0; m < 4; ++m) _Pragma("unroll") for (int k = 0; k < 2; ++k) dst[m][k] = *(const PG8_LAS bf16x8*)(lds + PG8_SA(b, h) + aoff + m * 2048 + k * 1024); } while (0)
; #define PG8_MMA(ai, bj, At, Bt) do { __builtin_amdgcn_s_setprio(1); _Pragma("unroll") for (int m = 0; m < 4; ++m) _Pragma("unroll") for (int n = 0; n < 2; ++n) _Pragma("unroll") for (int k = 0; k < 2; ++k) \
;         acc[ai][bj][m][n] = __builtin_amdgcn_mfma_f32_16x16x32_bf16(Bt[n][k], At[m][k], acc[ai][bj][m][n], 0, 0, 0); __builtin_amdgcn_s_setprio(0); } while (0)
; #define PG8_WAIT_V(n) asm volatile("s_waitcnt vmcnt(" #n ")" ::: "memory")
; #define PG8_WAIT_L(n) asm volatile("s_waitcnt lgkmcnt(" #n ")" ::: "memory")
; #define PG8_BAR __builtin_amdgcn_s_barrier()
; #define PG8_SCHED __builtin_amdgcn_sched_barrier(0)
; template <class Epi, class Sched, bool ALIGN_EPI = false, bool SP2 = false>
; __device__ __forceinline__ void gemm_phase(PG8_LAS unsigned char* lds, const Gemm g, const Sched& S, const Epi& E) {
;     ...
;             PG8_LDA(At, 1, 1); PG8_STAGE(PG8_SB(1, 0), b3, voffB); PG8_STAGE(PG8_SB(1, 1), b3 + hstep, voffB); PG8_STAGE(PG8_SA(1, 0), a3, voffA);
;             PG8_WAIT_V(8); PG8_WAIT_L(0); PG8_BAR; PG8_MMA(1, 0, At, B0); PG8_MMA(1, 1, At, B1); PG8_BAR; PG8_SCHED;
	s_mov_b32 m0, s67
	s_nop 0
	global_load_lds_dwordx4 v253, s[98:99]
	s_waitcnt vmcnt(8)
	s_waitcnt lgkmcnt(0)
	s_barrier
	s_setprio 1
	s_waitcnt lgkmcnt(0)
	v_mfma_f32_16x16x32_bf16 v[60:63], v[128:131], v[176:179], v[60:63]
	v_mfma_f32_16x16x32_bf16 v[56:59], v[136:139], v[176:179], v[56:59]
	v_mfma_f32_16x16x32_bf16 v[52:55], v[128:131], v[184:187], v[52:55]
	v_mfma_f32_16x16x32_bf16 v[40:43], v[136:139], v[184:187], v[40:43]
	v_mfma_f32_16x16x32_bf16 v[36:39], v[128:131], v[210:213], v[36:39]
	v_mfma_f32_16x16x32_bf16 v[24:27], v[136:139], v[210:213], v[24:27]
	v_mfma_f32_16x16x32_bf16 v[20:23], v[128:131], v[218:221], v[20:23]
	v_mfma_f32_16x16x32_bf16 v[8:11], v[136:139], v[218:221], v[8:11]
	v_mfma_f32_16x16x32_bf16 v[60:63], v[132:135], v[180:183], v[60:63]
	v_mfma_f32_16x16x32_bf16 v[56:59], v[140:143], v[180:183], v[56:59]
	v_mfma_f32_16x16x32_bf16 v[52:55], v[132:135], v[192:195], v[52:55]
	v_mfma_f32_16x16x32_bf16 v[40:43], v[140:143], v[192:195], v[40:43]
	v_mfma_f32_16x16x32_bf16 v[36:39], v[132:135], v[214:217], v[36:39]
	v_mfma_f32_16x16x32_bf16 v[24:27], v[140:143], v[214:217], v[24:27]
	v_mfma_f32_16x16x32_bf16 v[20:23], v[132:135], v[222:225], v[20:23]
	v_mfma_f32_16x16x32_bf16 v[8:11], v[140:143], v[222:225], v[8:11]


; #define PG8_MMA(ai, bj, At, Bt) do { __builtin_amdgcn_s_setprio(1); _Pragma("unroll") for (int m = 0; m < 4; ++m) _Pragma("unroll") for (int n = 0; n < 2; ++n) _Pragma("unroll") for (int k = 0; k < 2; ++k) \
;         acc[ai][bj][m][n] = __builtin_amdgcn_mfma_f32_16x16x32_bf16(Bt[n][k], At[m][k], acc[ai][bj][m][n], 0, 0, 0); __builtin_amdgcn_s_setprio(0); } while (0)
; #define PG8_WAIT_V(n) asm volatile("s_waitcnt vmcnt(" #n ")" ::: "memory")
; #define PG8_WAIT_L(n) asm volatile("s_waitcnt lgkmcnt(" #n ")" ::: "memory")
; #define PG8_BAR __builtin_amdgcn_s_barrier()
; #define PG8_SCHED __builtin_amdgcn_sched_barrier(0)
; template <class Epi, class Sched, bool ALIGN_EPI = false, bool SP2 = false>
; __device__ __forceinline__ void gemm_phase(PG8_LAS unsigned char* lds, const Gemm g, const Sched& S, const Epi& E) {
;     ...
;         for (int t = 0; t < nt; t += 2) {
;     ...
;             PG8_WAIT_V(8); PG8_WAIT_L(0); PG8_BAR; PG8_MMA(1, 0, At, B0); PG8_MMA(1, 1, At, B1); PG8_BAR; PG8_SCHED;
;     ...
;         if constexpr (ALIGN_EPI) { if (wr == 0) PG8_BAR; }
	v_mfma_f32_16x16x32_bf16 v[48:51], v[144:147], v[176:179], v[48:51]
	v_mfma_f32_16x16x32_bf16 v[44:47], v[152:155], v[176:179], v[44:47]
	v_mfma_f32_16x16x32_bf16 v[32:35], v[144:147], v[184:187], v[32:35]
	v_mfma_f32_16x16x32_bf16 v[28:31], v[152:155], v[184:187], v[28:31]
	v_mfma_f32_16x16x32_bf16 v[16:19], v[144:147], v[210:213], v[16:19]
	v_mfma_f32_16x16x32_bf16 v[12:15], v[152:155], v[210:213], v[12:15]
	v_mfma_f32_16x16x32_bf16 v[4:7], v[144:147], v[218:221], v[4:7]
	v_mfma_f32_16x16x32_bf16 v[0:3], v[152:155], v[218:221], v[0:3]
	v_mfma_f32_16x16x32_bf16 v[48:51], v[148:151], v[180:183], v[48:51]
	v_mfma_f32_16x16x32_bf16 v[44:47], v[156:159], v[180:183], v[44:47]
	v_mfma_f32_16x16x32_bf16 v[32:35], v[148:151], v[192:195], v[32:35]
	v_mfma_f32_16x16x32_bf16 v[28:31], v[156:159], v[192:195], v[28:31]
	v_mfma_f32_16x16x32_bf16 v[16:19], v[148:151], v[214:217], v[16:19]
	v_mfma_f32_16x16x32_bf16 v[12:15], v[156:159], v[214:217], v[12:15]
	v_mfma_f32_16x16x32_bf16 v[4:7], v[148:151], v[222:225], v[4:7]
	v_mfma_f32_16x16x32_bf16 v[0:3], v[156:159], v[222:225], v[0:3]
	s_setprio 0
	s_barrier
	s_add_i32 s78, s78, 2
	s_add_u32 s10, s10, 0x100
	s_addc_u32 s11, s11, 0
	s_add_u32 s76, s76, 0x100
	s_addc_u32 s77, s77, 0
	s_cmp_gt_u32 s78, 29
	s_cbranch_scc0 .LBB0_679
	s_and_b64 vcc, exec, s[42:43]
	s_cbranch_vccz .LBB0_682
	s_barrier

; #define PG8_STAGE(bufoff, gbase, voff) do { _Pragma("unroll") for (int _i = 0; _i < 2; ++_i) \
;         __builtin_amdgcn_global_load_lds((const unsigned*)((const char*)(gbase) + (voff)[_i]), (PG8_LAS unsigned*)(lds + (bufoff) + ldsw + _i * 8192), 16, 0, 0); } while (0)
; #define PG8_LDA(dst, b, h) do { _Pragma("unroll") for (int m = 0; m < 4; ++m) _Pragma("unroll") for (int k = 0; k < 2; ++k) dst[m][k] = *(const PG8_LAS bf16x8*)(lds + PG8_SA(b, h) + aoff + m * 2048 + k * 1024); } while (0)
; #define PG8_LDB(dst, b, h) do { _Pragma("unroll") for (int n = 0; n < 2; ++n) _Pragma("unroll") for (int k = 0; k < 2; ++k) dst[n][k] = *(const PG8_LAS bf16x8*)(lds + PG8_SB(b, h) + boff + n * 2048 + k * 1024); } while (0)
; #define PG8_SCHED __builtin_amdgcn_sched_barrier(0)
; template <class Epi, class Sched, bool ALIGN_EPI = false, bool SP2 = false>
; __device__ __forceinline__ void gemm_phase(PG8_LAS unsigned char* lds, const Gemm g, const Sched& S, const Epi& E) {
;     ...
;             const bool last = (t == nt - 2);
;             const char* a1 = cA + (size_t)(t + 1) * kstep;
;             const char* a2 = last ? nA : cA + (size_t)(t + 2) * kstep; const char* b2 = last ? nB : cB + (size_t)(t + 2) * kstep;
;             const char* a3 = a2 + kstep; const char* b3 = b2 + kstep;
;     ...
;             PG8_LDB(B0, 0, 0); PG8_LDB(B1, 0, 1); PG8_SCHED; PG8_LDA(At, 0, 0); PG8_STAGE(PG8_SA(1, 1), a1 + hstep, voffA);
.LBB0_939:
	ds_read_b128 v[64:67], v213
	ds_read_b128 v[68:71], v213 offset:1024
	ds_read_b128 v[72:75], v213 offset:2048
	ds_read_b128 v[76:79], v213 offset:3072
	ds_read_b128 v[144:147], v214
	ds_read_b128 v[148:151], v214 offset:1024
	ds_read_b128 v[152:155], v214 offset:2048
	ds_read_b128 v[156:159], v214 offset:3072
	s_add_u32 s60, s58, 0xfff80080
	s_addc_u32 s61, s59, -1
	s_cmp_eq_u32 s81, 28
	s_cselect_b32 s63, s11, s61
	s_cselect_b32 s62, s51, s60
	s_cselect_b32 s61, s49, s80
	s_cselect_b32 s60, s78, s79

; #define PG8_STAGE(bufoff, gbase, voff) do { _Pragma("unroll") for (int _i = 0; _i < 2; ++_i) \
;         __builtin_amdgcn_global_load_lds((const unsigned*)((const char*)(gbase) + (voff)[_i]), (PG8_LAS unsigned*)(lds + (bufoff) + ldsw + _i * 8192), 16, 0, 0); } while (0)
; #define PG8_LDA(dst, b, h) do { _Pragma("unroll") for (int m = 0; m < 4; ++m) _Pragma("unroll") for (int k = 0; k < 2; ++k) dst[m][k] = *(const PG8_LAS bf16x8*)(lds + PG8_SA(b, h) + aoff + m * 2048 + k * 1024); } while (0)
; #define PG8_LDB(dst, b, h) do { _Pragma("unroll") for (int n = 0; n < 2; ++n) _Pragma("unroll") for (int k = 0; k < 2; ++k) dst[n][k] = *(const PG8_LAS bf16x8*)(lds + PG8_SB(b, h) + boff + n * 2048 + k * 1024); } while (0)
; #define PG8_SCHED __builtin_amdgcn_sched_barrier(0)
; template <class Epi, class Sched, bool ALIGN_EPI = false, bool SP2 = false>
; __device__ __forceinline__ void gemm_phase(PG8_LAS unsigned char* lds, const Gemm g, const Sched& S, const Epi& E) {
;     ...
;             PG8_LDB(B0, 0, 0); PG8_LDB(B1, 0, 1); PG8_SCHED; PG8_LDA(At, 0, 0); PG8_STAGE(PG8_SA(1, 1), a1 + hstep, voffA);
	s_add_i32 m0, s57, 0xc000
	ds_read_b128 v[176:179], v215
	ds_read_b128 v[180:183], v215 offset:1024
	ds_read_b128 v[184:187], v215 offset:2048
	ds_read_b128 v[188:191], v215 offset:3072
	ds_read_b128 v[192:195], v215 offset:4096
	ds_read_b128 v[196:199], v215 offset:5120
	ds_read_b128 v[200:203], v215 offset:6144
	ds_read_b128 v[204:207], v215 offset:7168
	global_load_lds_dwordx4 v168, s[58:59]

; #define PG8_STAGE(bufoff, gbase, voff) do { _Pragma("unroll") for (int _i = 0; _i < 2; ++_i) \
;         __builtin_amdgcn_global_load_lds((const unsigned*)((const char*)(gbase) + (voff)[_i]), (PG8_LAS unsigned*)(lds + (bufoff) + ldsw + _i * 8192), 16, 0, 0); } while (0)
; #define PG8_LDA(dst, b, h) do { _Pragma("unroll") for (int m = 0; m < 4; ++m) _Pragma("unroll") for (int k = 0; k < 2; ++k) dst[m][k] = *(const PG8_LAS bf16x8*)(lds + PG8_SA(b, h) + aoff + m * 2048 + k * 1024); } while (0)
; #define PG8_LDB(dst, b, h) do { _Pragma("unroll") for (int n = 0; n < 2; ++n) _Pragma("unroll") for (int k = 0; k < 2; ++k) dst[n][k] = *(const PG8_LAS bf16x8*)(lds + PG8_SB(b, h) + boff + n * 2048 + k * 1024); } while (0)
; #define PG8_MMA(ai, bj, At, Bt) do { __builtin_amdgcn_s_setprio(1); _Pragma("unroll") for (int m = 0; m < 4; ++m) _Pragma("unroll") for (int n = 0; n < 2; ++n) _Pragma("unroll") for (int k = 0; k < 2; ++k) \
;         acc[ai][bj][m][n] = __builtin_amdgcn_mfma_f32_16x16x32_bf16(Bt[n][k], At[m][k], acc[ai][bj][m][n], 0, 0, 0); __builtin_amdgcn_s_setprio(0); } while (0)
; #define PG8_WAIT_V(n) asm volatile("s_waitcnt vmcnt(" #n ")" ::: "memory")
; #define PG8_WAIT_L(n) asm volatile("s_waitcnt lgkmcnt(" #n ")" ::: "memory")
; #define PG8_BAR __builtin_amdgcn_s_barrier()
; #define PG8_SCHED __builtin_amdgcn_sched_barrier(0)
; template <class Epi, class Sched, bool ALIGN_EPI = false, bool SP2 = false>
; __device__ __forceinline__ void gemm_phase(PG8_LAS unsigned char* lds, const Gemm g, const Sched& S, const Epi& E) {
;     ...
;             PG8_LDB(B0, 0, 0); PG8_LDB(B1, 0, 1); PG8_SCHED; PG8_LDA(At, 0, 0); PG8_STAGE(PG8_SA(1, 1), a1 + hstep, voffA);
;             PG8_WAIT_V(8); PG8_WAIT_L(0); PG8_BAR; PG8_MMA(0, 0, At, B0); PG8_MMA(0, 1, At, B1); PG8_BAR; PG8_SCHED;
	s_add_i32 m0, s57, 0xe000
	s_nop 0
	global_load_lds_dwordx4 v170, s[58:59]
	s_waitcnt vmcnt(8)
	s_waitcnt lgkmcnt(0)
	s_barrier
	s_setprio 1
	s_waitcnt lgkmcnt(0)
	v_mfma_f32_16x16x32_bf16 v[140:143], v[64:67], v[176:179], v[140:143]
	v_mfma_f32_16x16x32_bf16 v[136:139], v[72:75], v[176:179], v[136:139]
	v_mfma_f32_16x16x32_bf16 v[124:127], v[64:67], v[184:187], v[124:127]
	v_mfma_f32_16x16x32_bf16 v[120:123], v[72:75], v[184:187], v[120:123]
	v_mfma_f32_16x16x32_bf16 v[108:111], v[64:67], v[192:195], v[108:111]
	v_mfma_f32_16x16x32_bf16 v[104:107], v[72:75], v[192:195], v[104:107]
	v_mfma_f32_16x16x32_bf16 v[92:95], v[64:67], v[200:203], v[92:95]
	v_mfma_f32_16x16x32_bf16 v[88:91], v[72:75], v[200:203], v[88:91]
	v_mfma_f32_16x16x32_bf16 v[140:143], v[68:71], v[180:183], v[140:143]
	v_mfma_f32_16x16x32_bf16 v[136:139], v[76:79], v[180:183], v[136:139]
	v_mfma_f32_16x16x32_bf16 v[124:127], v[68:71], v[188:191], v[124:127]
	v_mfma_f32_16x16x32_bf16 v[120:123], v[76:79], v[188:191], v[120:123]
	v_mfma_f32_16x16x32_bf16 v[108:111], v[68:71], v[196:199], v[108:111]
	v_mfma_f32_16x16x32_bf16 v[104:107], v[76:79], v[196:199], v[104:107]
	v_mfma_f32_16x16x32_bf16 v[92:95], v[68:71], v[204:207], v[92:95]
	v_mfma_f32_16x16x32_bf16 v[88:91], v[76:79], v[204:207], v[88:91]


; #define PG8_STAGE(bufoff, gbase, voff) do { _Pragma("unroll") for (int _i = 0; _i < 2; ++_i) \
;         __builtin_amdgcn_global_load_lds((const unsigned*)((const char*)(gbase) + (voff)[_i]), (PG8_LAS unsigned*)(lds + (bufoff) + ldsw + _i * 8192), 16, 0, 0); } while (0)
; #define PG8_LDA(dst, b, h) do { _Pragma("unroll") for (int m = 0; m < 4; ++m) _Pragma("unroll") for (int k = 0; k < 2; ++k) dst[m][k] = *(const PG8_LAS bf16x8*)(lds + PG8_SA(b, h) + aoff + m * 2048 + k * 1024); } while (0)
; #define PG8_MMA(ai, bj, At, Bt) do { __builtin_amdgcn_s_setprio(1); _Pragma("unroll") for (int m = 0; m < 4; ++m) _Pragma("unroll") for (int n = 0; n < 2; ++n) _Pragma("unroll") for (int k = 0; k < 2; ++k) \
;         acc[ai][bj][m][n] = __builtin_amdgcn_mfma_f32_16x16x32_bf16(Bt[n][k], At[m][k], acc[ai][bj][m][n], 0, 0, 0); __builtin_amdgcn_s_setprio(0); } while (0)
; #define PG8_WAIT_V(n) asm volatile("s_waitcnt vmcnt(" #n ")" ::: "memory")
; #define PG8_WAIT_L(n) asm volatile("s_waitcnt lgkmcnt(" #n ")" ::: "memory")
; #define PG8_BAR __builtin_amdgcn_s_barrier()
; #define PG8_SCHED __builtin_amdgcn_sched_barrier(0)
; template <class Epi, class Sched, bool ALIGN_EPI = false, bool SP2 = false>
; __device__ __forceinline__ void gemm_phase(PG8_LAS unsigned char* lds, const Gemm g, const Sched& S, const Epi& E) {
;     ...
;             PG8_WAIT_V(8); PG8_WAIT_L(0); PG8_BAR; PG8_MMA(0, 0, At, B0); PG8_MMA(0, 1, At, B1); PG8_BAR; PG8_SCHED;
;             PG8_LDA(At, 0, 1); PG8_STAGE(PG8_SB(0, 0), b2, voffB); PG8_STAGE(PG8_SB(0, 1), b2 + hstep, voffB); PG8_STAGE(PG8_SA(0, 0), a2, voffA);
	v_mfma_f32_16x16x32_bf16 v[132:135], v[144:147], v[176:179], v[132:135]
	v_mfma_f32_16x16x32_bf16 v[128:131], v[152:155], v[176:179], v[128:131]
	v_mfma_f32_16x16x32_bf16 v[116:119], v[144:147], v[184:187], v[116:119]
	v_mfma_f32_16x16x32_bf16 v[112:115], v[152:155], v[184:187], v[112:115]
	v_mfma_f32_16x16x32_bf16 v[100:103], v[144:147], v[192:195], v[100:103]
	v_mfma_f32_16x16x32_bf16 v[96:99], v[152:155], v[192:195], v[96:99]
	v_mfma_f32_16x16x32_bf16 v[84:87], v[144:147], v[200:203], v[84:87]
	v_mfma_f32_16x16x32_bf16 v[80:83], v[152:155], v[200:203], v[80:83]
	v_mfma_f32_16x16x32_bf16 v[132:135], v[148:151], v[180:183], v[132:135]
	v_mfma_f32_16x16x32_bf16 v[128:131], v[156:159], v[180:183], v[128:131]
	v_mfma_f32_16x16x32_bf16 v[116:119], v[148:151], v[188:191], v[116:119]
	v_mfma_f32_16x16x32_bf16 v[112:115], v[156:159], v[188:191], v[112:115]
	v_mfma_f32_16x16x32_bf16 v[100:103], v[148:151], v[196:199], v[100:103]
	v_mfma_f32_16x16x32_bf16 v[96:99], v[156:159], v[196:199], v[96:99]
	v_mfma_f32_16x16x32_bf16 v[84:87], v[148:151], v[204:207], v[84:87]
	v_mfma_f32_16x16x32_bf16 v[80:83], v[156:159], v[204:207], v[80:83]
	s_setprio 0
	s_barrier
	s_add_i32 s82, s75, s64
	s_mov_b64 s[96:97], s[60:61]

; #define PG8_STAGE(bufoff, gbase, voff) do { _Pragma("unroll") for (int _i = 0; _i < 2; ++_i) \
;         __builtin_amdgcn_global_load_lds((const unsigned*)((const char*)(gbase) + (voff)[_i]), (PG8_LAS unsigned*)(lds + (bufoff) + ldsw + _i * 8192), 16, 0, 0); } while (0)
; #define PG8_LDA(dst, b, h) do { _Pragma("unroll") for (int m = 0; m < 4; ++m) _Pragma("unroll") for (int k = 0; k < 2; ++k) dst[m][k] = *(const PG8_LAS bf16x8*)(lds + PG8_SA(b, h) + aoff + m * 2048 + k * 1024); } while (0)
; template <class Epi, class Sched, bool ALIGN_EPI = false, bool SP2 = false>
; __device__ __forceinline__ void gemm_phase(PG8_LAS unsigned char* lds, const Gemm g, const Sched& S, const Epi& E) {
;     ...
;             PG8_LDA(At, 0, 1); PG8_STAGE(PG8_SB(0, 0), b2, voffB); PG8_STAGE(PG8_SB(0, 1), b2 + hstep, voffB); PG8_STAGE(PG8_SA(0, 0), a2, voffA);
	s_mov_b32 m0, s82
	ds_read_b128 v[176:179], v215 offset:16384
	ds_read_b128 v[180:183], v215 offset:17408
	ds_read_b128 v[184:187], v215 offset:18432
	ds_read_b128 v[188:191], v215 offset:19456
	ds_read_b128 v[192:195], v215 offset:20480
	ds_read_b128 v[196:199], v215 offset:21504
	ds_read_b128 v[200:203], v215 offset:22528
	ds_read_b128 v[204:207], v215 offset:23552
	global_load_lds_dwordx4 v162, s[60:61]
	s_add_i32 m0, s82, 0x2000
	s_add_u32 s82, s60, 0x80000

; #define PG8_STAGE(bufoff, gbase, voff) do { _Pragma("unroll") for (int _i = 0; _i < 2; ++_i) \
;         __builtin_amdgcn_global_load_lds((const unsigned*)((const char*)(gbase) + (voff)[_i]), (PG8_LAS unsigned*)(lds + (bufoff) + ldsw + _i * 8192), 16, 0, 0); } while (0)
; #define PG8_LDA(dst, b, h) do { _Pragma("unroll") for (int m = 0; m < 4; ++m) _Pragma("unroll") for (int k = 0; k < 2; ++k) dst[m][k] = *(const PG8_LAS bf16x8*)(lds + PG8_SA(b, h) + aoff + m * 2048 + k * 1024); } while (0)
; template <class Epi, class Sched, bool ALIGN_EPI = false, bool SP2 = false>
; __device__ __forceinline__ void gemm_phase(PG8_LAS unsigned char* lds, const Gemm g, const Sched& S, const Epi& E) {
;     ...
;             PG8_LDA(At, 0, 1); PG8_STAGE(PG8_SB(0, 0), b2, voffB); PG8_STAGE(PG8_SB(0, 1), b2 + hstep, voffB); PG8_STAGE(PG8_SA(0, 0), a2, voffA);
	s_addc_u32 s83, s61, 0
	s_add_i32 s84, s76, s64
	global_load_lds_dwordx4 v166, s[60:61]

; #define PG8_STAGE(bufoff, gbase, voff) do { _Pragma("unroll") for (int _i = 0; _i < 2; ++_i) \
;         __builtin_amdgcn_global_load_lds((const unsigned*)((const char*)(gbase) + (voff)[_i]), (PG8_LAS unsigned*)(lds + (bufoff) + ldsw + _i * 8192), 16, 0, 0); } while (0)
; #define PG8_LDA(dst, b, h) do { _Pragma("unroll") for (int m = 0; m < 4; ++m) _Pragma("unroll") for (int k = 0; k < 2; ++k) dst[m][k] = *(const PG8_LAS bf16x8*)(lds + PG8_SA(b, h) + aoff + m * 2048 + k * 1024); } while (0)
; template <class Epi, class Sched, bool ALIGN_EPI = false, bool SP2 = false>
; __device__ __forceinline__ void gemm_phase(PG8_LAS unsigned char* lds, const Gemm g, const Sched& S, const Epi& E) {
;     ...
;             PG8_LDA(At, 0, 1); PG8_STAGE(PG8_SB(0, 0), b2, voffB); PG8_STAGE(PG8_SB(0, 1), b2 + hstep, voffB); PG8_STAGE(PG8_SA(0, 0), a2, voffA);
	s_mov_b32 m0, s84
	s_nop 0
	global_load_lds_dwordx4 v162, s[82:83]

; #define PG8_STAGE(bufoff, gbase, voff) do { _Pragma("unroll") for (int _i = 0; _i < 2; ++_i) \
;         __builtin_amdgcn_global_load_lds((const unsigned*)((const char*)(gbase) + (voff)[_i]), (PG8_LAS unsigned*)(lds + (bufoff) + ldsw + _i * 8192), 16, 0, 0); } while (0)
; #define PG8_LDA(dst, b, h) do { _Pragma("unroll") for (int m = 0; m < 4; ++m) _Pragma("unroll") for (int k = 0; k < 2; ++k) dst[m][k] = *(const PG8_LAS bf16x8*)(lds + PG8_SA(b, h) + aoff + m * 2048 + k * 1024); } while (0)
; template <class Epi, class Sched, bool ALIGN_EPI = false, bool SP2 = false>
; __device__ __forceinline__ void gemm_phase(PG8_LAS unsigned char* lds, const Gemm g, const Sched& S, const Epi& E) {
;     ...
;             PG8_LDA(At, 0, 1); PG8_STAGE(PG8_SB(0, 0), b2, voffB); PG8_STAGE(PG8_SB(0, 1), b2 + hstep, voffB); PG8_STAGE(PG8_SA(0, 0), a2, voffA);
	s_add_i32 m0, s84, 0x2000
	s_nop 0
	global_load_lds_dwordx4 v166, s[82:83]
	s_mov_b64 s[98:99], s[62:63]

; #define PG8_STAGE(bufoff, gbase, voff) do { _Pragma("unroll") for (int _i = 0; _i < 2; ++_i) \
;         __builtin_amdgcn_global_load_lds((const unsigned*)((const char*)(gbase) + (voff)[_i]), (PG8_LAS unsigned*)(lds + (bufoff) + ldsw + _i * 8192), 16, 0, 0); } while (0)
; #define PG8_LDA(dst, b, h) do { _Pragma("unroll") for (int m = 0; m < 4; ++m) _Pragma("unroll") for (int k = 0; k < 2; ++k) dst[m][k] = *(const PG8_LAS bf16x8*)(lds + PG8_SA(b, h) + aoff + m * 2048 + k * 1024); } while (0)
; #define PG8_MMA(ai, bj, At, Bt) do { __builtin_amdgcn_s_setprio(1); _Pragma("unroll") for (int m = 0; m < 4; ++m) _Pragma("unroll") for (int n = 0; n < 2; ++n) _Pragma("unroll") for (int k = 0; k < 2; ++k) \
;         acc[ai][bj][m][n] = __builtin_amdgcn_mfma_f32_16x16x32_bf16(Bt[n][k], At[m][k], acc[ai][bj][m][n], 0, 0, 0); __builtin_amdgcn_s_setprio(0); } while (0)
; #define PG8_WAIT_V(n) asm volatile("s_waitcnt vmcnt(" #n ")" ::: "memory")
; #define PG8_WAIT_L(n) asm volatile("s_waitcnt lgkmcnt(" #n ")" ::: "memory")
; #define PG8_BAR __builtin_amdgcn_s_barrier()
; #define PG8_SCHED __builtin_amdgcn_sched_barrier(0)
; template <class Epi, class Sched, bool ALIGN_EPI = false, bool SP2 = false>
; __device__ __forceinline__ void gemm_phase(PG8_LAS unsigned char* lds, const Gemm g, const Sched& S, const Epi& E) {
;     ...
;             PG8_LDA(At, 0, 1); PG8_STAGE(PG8_SB(0, 0), b2, voffB); PG8_STAGE(PG8_SB(0, 1), b2 + hstep, voffB); PG8_STAGE(PG8_SA(0, 0), a2, voffA);
;             PG8_WAIT_V(8); PG8_WAIT_L(0); PG8_BAR; PG8_MMA(1, 0, At, B0); PG8_MMA(1, 1, At, B1); PG8_BAR; PG8_SCHED;
	s_mov_b32 m0, s57
	s_nop 0
	global_load_lds_dwordx4 v160, s[62:63]
	s_mov_b32 m0, s65
	s_nop 0
	global_load_lds_dwordx4 v164, s[62:63]
	s_waitcnt vmcnt(8)
	s_waitcnt lgkmcnt(0)
	s_barrier
	s_setprio 1
	s_waitcnt lgkmcnt(0)
	v_mfma_f32_16x16x32_bf16 v[60:63], v[64:67], v[176:179], v[60:63]
	v_mfma_f32_16x16x32_bf16 v[56:59], v[72:75], v[176:179], v[56:59]
	v_mfma_f32_16x16x32_bf16 v[44:47], v[64:67], v[184:187], v[44:47]
	v_mfma_f32_16x16x32_bf16 v[40:43], v[72:75], v[184:187], v[40:43]
	v_mfma_f32_16x16x32_bf16 v[28:31], v[64:67], v[192:195], v[28:31]
	v_mfma_f32_16x16x32_bf16 v[24:27], v[72:75], v[192:195], v[24:27]
	v_mfma_f32_16x16x32_bf16 v[12:15], v[64:67], v[200:203], v[12:15]
	v_mfma_f32_16x16x32_bf16 v[8:11], v[72:75], v[200:203], v[8:11]
	v_mfma_f32_16x16x32_bf16 v[60:63], v[68:71], v[180:183], v[60:63]
	v_mfma_f32_16x16x32_bf16 v[56:59], v[76:79], v[180:183], v[56:59]
	v_mfma_f32_16x16x32_bf16 v[44:47], v[68:71], v[188:191], v[44:47]
	v_mfma_f32_16x16x32_bf16 v[40:43], v[76:79], v[188:191], v[40:43]
	v_mfma_f32_16x16x32_bf16 v[28:31], v[68:71], v[196:199], v[28:31]
	v_mfma_f32_16x16x32_bf16 v[24:27], v[76:79], v[196:199], v[24:27]
	v_mfma_f32_16x16x32_bf16 v[12:15], v[68:71], v[204:207], v[12:15]
	v_mfma_f32_16x16x32_bf16 v[8:11], v[76:79], v[204:207], v[8:11]


; #define PG8_STAGE(bufoff, gbase, voff) do { _Pragma("unroll") for (int _i = 0; _i < 2; ++_i) \
;         __builtin_amdgcn_global_load_lds((const unsigned*)((const char*)(gbase) + (voff)[_i]), (PG8_LAS unsigned*)(lds + (bufoff) + ldsw + _i * 8192), 16, 0, 0); } while (0)
; #define PG8_LDA(dst, b, h) do { _Pragma("unroll") for (int m = 0; m < 4; ++m) _Pragma("unroll") for (int k = 0; k < 2; ++k) dst[m][k] = *(const PG8_LAS bf16x8*)(lds + PG8_SA(b, h) + aoff + m * 2048 + k * 1024); } while (0)
; #define PG8_LDB(dst, b, h) do { _Pragma("unroll") for (int n = 0; n < 2; ++n) _Pragma("unroll") for (int k = 0; k < 2; ++k) dst[n][k] = *(const PG8_LAS bf16x8*)(lds + PG8_SB(b, h) + boff + n * 2048 + k * 1024); } while (0)
; #define PG8_MMA(ai, bj, At, Bt) do { __builtin_amdgcn_s_setprio(1); _Pragma("unroll") for (int m = 0; m < 4; ++m) _Pragma("unroll") for (int n = 0; n < 2; ++n) _Pragma("unroll") for (int k = 0; k < 2; ++k) \
;         acc[ai][bj][m][n] = __builtin_amdgcn_mfma_f32_16x16x32_bf16(Bt[n][k], At[m][k], acc[ai][bj][m][n], 0, 0, 0); __builtin_amdgcn_s_setprio(0); } while (0)
; #define PG8_WAIT_V(n) asm volatile("s_waitcnt vmcnt(" #n ")" ::: "memory")
; #define PG8_WAIT_L(n) asm volatile("s_waitcnt lgkmcnt(" #n ")" ::: "memory")
; #define PG8_BAR __builtin_amdgcn_s_barrier()
; #define PG8_SCHED __builtin_amdgcn_sched_barrier(0)
; template <class Epi, class Sched, bool ALIGN_EPI = false, bool SP2 = false>
; __device__ __forceinline__ void gemm_phase(PG8_LAS unsigned char* lds, const Gemm g, const Sched& S, const Epi& E) {
;     ...
;             PG8_WAIT_V(8); PG8_WAIT_L(0); PG8_BAR; PG8_MMA(1, 0, At, B0); PG8_MMA(1, 1, At, B1); PG8_BAR; PG8_SCHED;
;             PG8_LDB(B0, 1, 0); PG8_LDB(B1, 1, 1); PG8_SCHED; PG8_LDA(At, 1, 0); PG8_STAGE(PG8_SA(0, 1), a2 + hstep, voffA);
	v_mfma_f32_16x16x32_bf16 v[52:55], v[144:147], v[176:179], v[52:55]
	v_mfma_f32_16x16x32_bf16 v[48:51], v[152:155], v[176:179], v[48:51]
	v_mfma_f32_16x16x32_bf16 v[36:39], v[144:147], v[184:187], v[36:39]
	v_mfma_f32_16x16x32_bf16 v[32:35], v[152:155], v[184:187], v[32:35]
	v_mfma_f32_16x16x32_bf16 v[20:23], v[144:147], v[192:195], v[20:23]
	v_mfma_f32_16x16x32_bf16 v[16:19], v[152:155], v[192:195], v[16:19]
	v_mfma_f32_16x16x32_bf16 v[4:7], v[144:147], v[200:203], v[4:7]
	v_mfma_f32_16x16x32_bf16 v[0:3], v[152:155], v[200:203], v[0:3]
	v_mfma_f32_16x16x32_bf16 v[52:55], v[148:151], v[180:183], v[52:55]
	v_mfma_f32_16x16x32_bf16 v[48:51], v[156:159], v[180:183], v[48:51]
	v_mfma_f32_16x16x32_bf16 v[36:39], v[148:151], v[188:191], v[36:39]
	v_mfma_f32_16x16x32_bf16 v[32:35], v[156:159], v[188:191], v[32:35]
	v_mfma_f32_16x16x32_bf16 v[20:23], v[148:151], v[196:199], v[20:23]
	v_mfma_f32_16x16x32_bf16 v[16:19], v[156:159], v[196:199], v[16:19]
	v_mfma_f32_16x16x32_bf16 v[4:7], v[148:151], v[204:207], v[4:7]
	v_mfma_f32_16x16x32_bf16 v[0:3], v[156:159], v[204:207], v[0:3]
	s_setprio 0
	s_barrier
	s_add_i32 s82, 0, 0x18000
	s_add_i32 s83, 0, 0x1c000
	v_add_u32_e32 v76, s82, v211
	v_add_u32_e32 v156, s83, v211
	ds_read_b128 v[64:67], v76
	ds_read_b128 v[68:71], v76 offset:1024
	ds_read_b128 v[72:75], v76 offset:2048
	ds_read_b128 v[76:79], v76 offset:3072
	ds_read_b128 v[144:147], v156
	ds_read_b128 v[148:151], v156 offset:1024
	ds_read_b128 v[152:155], v156 offset:2048
	ds_read_b128 v[156:159], v156 offset:3072
	s_add_u32 s62, s62, 0x80000
	s_addc_u32 s63, s63, 0
	s_mov_b32 m0, s67

; #define PG8_STAGE(bufoff, gbase, voff) do { _Pragma("unroll") for (int _i = 0; _i < 2; ++_i) \
;         __builtin_amdgcn_global_load_lds((const unsigned*)((const char*)(gbase) + (voff)[_i]), (PG8_LAS unsigned*)(lds + (bufoff) + ldsw + _i * 8192), 16, 0, 0); } while (0)
; #define PG8_LDA(dst, b, h) do { _Pragma("unroll") for (int m = 0; m < 4; ++m) _Pragma("unroll") for (int k = 0; k < 2; ++k) dst[m][k] = *(const PG8_LAS bf16x8*)(lds + PG8_SA(b, h) + aoff + m * 2048 + k * 1024); } while (0)
; #define PG8_LDB(dst, b, h) do { _Pragma("unroll") for (int n = 0; n < 2; ++n) _Pragma("unroll") for (int k = 0; k < 2; ++k) dst[n][k] = *(const PG8_LAS bf16x8*)(lds + PG8_SB(b, h) + boff + n * 2048 + k * 1024); } while (0)
; #define PG8_SCHED __builtin_amdgcn_sched_barrier(0)
; template <class Epi, class Sched, bool ALIGN_EPI = false, bool SP2 = false>
; __device__ __forceinline__ void gemm_phase(PG8_LAS unsigned char* lds, const Gemm g, const Sched& S, const Epi& E) {
;     ...
;             PG8_LDB(B0, 1, 0); PG8_LDB(B1, 1, 1); PG8_SCHED; PG8_LDA(At, 1, 0); PG8_STAGE(PG8_SA(0, 1), a2 + hstep, voffA);
	ds_read_b128 v[176:179], v215 offset:32768
	ds_read_b128 v[180:183], v215 offset:33792
	ds_read_b128 v[184:187], v215 offset:34816
	ds_read_b128 v[188:191], v215 offset:35840
	ds_read_b128 v[192:195], v215 offset:36864
	ds_read_b128 v[196:199], v215 offset:37888
	ds_read_b128 v[200:203], v215 offset:38912
	ds_read_b128 v[204:207], v215 offset:39936
	global_load_lds_dwordx4 v160, s[62:63]

; #define PG8_STAGE(bufoff, gbase, voff) do { _Pragma("unroll") for (int _i = 0; _i < 2; ++_i) \
;         __builtin_amdgcn_global_load_lds((const unsigned*)((const char*)(gbase) + (voff)[_i]), (PG8_LAS unsigned*)(lds + (bufoff) + ldsw + _i * 8192), 16, 0, 0); } while (0)
; #define PG8_LDA(dst, b, h) do { _Pragma("unroll") for (int m = 0; m < 4; ++m) _Pragma("unroll") for (int k = 0; k < 2; ++k) dst[m][k] = *(const PG8_LAS bf16x8*)(lds + PG8_SA(b, h) + aoff + m * 2048 + k * 1024); } while (0)
; #define PG8_LDB(dst, b, h) do { _Pragma("unroll") for (int n = 0; n < 2; ++n) _Pragma("unroll") for (int k = 0; k < 2; ++k) dst[n][k] = *(const PG8_LAS bf16x8*)(lds + PG8_SB(b, h) + boff + n * 2048 + k * 1024); } while (0)
; #define PG8_MMA(ai, bj, At, Bt) do { __builtin_amdgcn_s_setprio(1); _Pragma("unroll") for (int m = 0; m < 4; ++m) _Pragma("unroll") for (int n = 0; n < 2; ++n) _Pragma("unroll") for (int k = 0; k < 2; ++k) \
;         acc[ai][bj][m][n] = __builtin_amdgcn_mfma_f32_16x16x32_bf16(Bt[n][k], At[m][k], acc[ai][bj][m][n], 0, 0, 0); __builtin_amdgcn_s_setprio(0); } while (0)
; #define PG8_WAIT_V(n) asm volatile("s_waitcnt vmcnt(" #n ")" ::: "memory")
; #define PG8_WAIT_L(n) asm volatile("s_waitcnt lgkmcnt(" #n ")" ::: "memory")
; #define PG8_BAR __builtin_amdgcn_s_barrier()
; #define PG8_SCHED __builtin_amdgcn_sched_barrier(0)
; template <class Epi, class Sched, bool ALIGN_EPI = false, bool SP2 = false>
; __device__ __forceinline__ void gemm_phase(PG8_LAS unsigned char* lds, const Gemm g, const Sched& S, const Epi& E) {
;     ...
;             PG8_LDB(B0, 1, 0); PG8_LDB(B1, 1, 1); PG8_SCHED; PG8_LDA(At, 1, 0); PG8_STAGE(PG8_SA(0, 1), a2 + hstep, voffA);
;             PG8_WAIT_V(8); PG8_WAIT_L(0); PG8_BAR; PG8_MMA(0, 0, At, B0); PG8_MMA(0, 1, At, B1); PG8_BAR; PG8_SCHED;
	s_mov_b32 m0, s68
	s_nop 0
	global_load_lds_dwordx4 v164, s[62:63]
	s_waitcnt vmcnt(8)
	s_waitcnt lgkmcnt(0)
	s_barrier
	s_setprio 1
	s_waitcnt lgkmcnt(0)
	v_mfma_f32_16x16x32_bf16 v[140:143], v[64:67], v[176:179], v[140:143]
	v_mfma_f32_16x16x32_bf16 v[136:139], v[72:75], v[176:179], v[136:139]
	v_mfma_f32_16x16x32_bf16 v[124:127], v[64:67], v[184:187], v[124:127]
	v_mfma_f32_16x16x32_bf16 v[120:123], v[72:75], v[184:187], v[120:123]
	v_mfma_f32_16x16x32_bf16 v[108:111], v[64:67], v[192:195], v[108:111]
	v_mfma_f32_16x16x32_bf16 v[104:107], v[72:75], v[192:195], v[104:107]
	v_mfma_f32_16x16x32_bf16 v[92:95], v[64:67], v[200:203], v[92:95]
	v_mfma_f32_16x16x32_bf16 v[88:91], v[72:75], v[200:203], v[88:91]
	v_mfma_f32_16x16x32_bf16 v[140:143], v[68:71], v[180:183], v[140:143]
	v_mfma_f32_16x16x32_bf16 v[136:139], v[76:79], v[180:183], v[136:139]
	v_mfma_f32_16x16x32_bf16 v[124:127], v[68:71], v[188:191], v[124:127]
	v_mfma_f32_16x16x32_bf16 v[120:123], v[76:79], v[188:191], v[120:123]
	v_mfma_f32_16x16x32_bf16 v[108:111], v[68:71], v[196:199], v[108:111]
	v_mfma_f32_16x16x32_bf16 v[104:107], v[76:79], v[196:199], v[104:107]
	v_mfma_f32_16x16x32_bf16 v[92:95], v[68:71], v[204:207], v[92:95]
	v_mfma_f32_16x16x32_bf16 v[88:91], v[76:79], v[204:207], v[88:91]


; #define PG8_MMA(ai, bj, At, Bt) do { __builtin_amdgcn_s_setprio(1); _Pragma("unroll") for (int m = 0; m < 4; ++m) _Pragma("unroll") for (int n = 0; n < 2; ++n) _Pragma("unroll") for (int k = 0; k < 2; ++k) \
;         acc[ai][bj][m][n] = __builtin_amdgcn_mfma_f32_16x16x32_bf16(Bt[n][k], At[m][k], acc[ai][bj][m][n], 0, 0, 0); __builtin_amdgcn_s_setprio(0); } while (0)
; #define PG8_WAIT_V(n) asm volatile("s_waitcnt vmcnt(" #n ")" ::: "memory")
; #define PG8_WAIT_L(n) asm volatile("s_waitcnt lgkmcnt(" #n ")" ::: "memory")
; #define PG8_BAR __builtin_amdgcn_s_barrier()
; #define PG8_SCHED __builtin_amdgcn_sched_barrier(0)
; template <class Epi, class Sched, bool ALIGN_EPI = false, bool SP2 = false>
; __device__ __forceinline__ void gemm_phase(PG8_LAS unsigned char* lds, const Gemm g, const Sched& S, const Epi& E) {
;     ...
;             PG8_WAIT_V(8); PG8_WAIT_L(0); PG8_BAR; PG8_MMA(0, 0, At, B0); PG8_MMA(0, 1, At, B1); PG8_BAR; PG8_SCHED;
	v_mfma_f32_16x16x32_bf16 v[132:135], v[144:147], v[176:179], v[132:135]
	v_mfma_f32_16x16x32_bf16 v[128:131], v[152:155], v[176:179], v[128:131]
	v_mfma_f32_16x16x32_bf16 v[116:119], v[144:147], v[184:187], v[116:119]
	v_mfma_f32_16x16x32_bf16 v[112:115], v[152:155], v[184:187], v[112:115]
	v_mfma_f32_16x16x32_bf16 v[100:103], v[144:147], v[192:195], v[100:103]
	v_mfma_f32_16x16x32_bf16 v[96:99], v[152:155], v[192:195], v[96:99]
	v_mfma_f32_16x16x32_bf16 v[84:87], v[144:147], v[200:203], v[84:87]
	v_mfma_f32_16x16x32_bf16 v[80:83], v[152:155], v[200:203], v[80:83]
	v_mfma_f32_16x16x32_bf16 v[132:135], v[148:151], v[180:183], v[132:135]
	v_mfma_f32_16x16x32_bf16 v[128:131], v[156:159], v[180:183], v[128:131]
	v_mfma_f32_16x16x32_bf16 v[116:119], v[148:151], v[188:191], v[116:119]
	v_mfma_f32_16x16x32_bf16 v[112:115], v[156:159], v[188:191], v[112:115]
	v_mfma_f32_16x16x32_bf16 v[100:103], v[148:151], v[196:199], v[100:103]
	v_mfma_f32_16x16x32_bf16 v[96:99], v[156:159], v[196:199], v[96:99]
	v_mfma_f32_16x16x32_bf16 v[84:87], v[148:151], v[204:207], v[84:87]
	v_mfma_f32_16x16x32_bf16 v[80:83], v[156:159], v[204:207], v[80:83]
	s_setprio 0
	s_barrier
	s_add_i32 s62, s82, s64

; #define PG8_STAGE(bufoff, gbase, voff) do { _Pragma("unroll") for (int _i = 0; _i < 2; ++_i) \
;         __builtin_amdgcn_global_load_lds((const unsigned*)((const char*)(gbase) + (voff)[_i]), (PG8_LAS unsigned*)(lds + (bufoff) + ldsw + _i * 8192), 16, 0, 0); } while (0)
; #define PG8_LDA(dst, b, h) do { _Pragma("unroll") for (int m = 0; m < 4; ++m) _Pragma("unroll") for (int k = 0; k < 2; ++k) dst[m][k] = *(const PG8_LAS bf16x8*)(lds + PG8_SA(b, h) + aoff + m * 2048 + k * 1024); } while (0)
; template <class Epi, class Sched, bool ALIGN_EPI = false, bool SP2 = false>
; __device__ __forceinline__ void gemm_phase(PG8_LAS unsigned char* lds, const Gemm g, const Sched& S, const Epi& E) {
;     ...
;             PG8_LDA(At, 1, 1); PG8_STAGE(PG8_SB(1, 0), b3, voffB); PG8_STAGE(PG8_SB(1, 1), b3 + hstep, voffB); PG8_STAGE(PG8_SA(1, 0), a3, voffA);
	s_mov_b32 m0, s62
	ds_read_b128 v[176:179], v215 offset:49152
	ds_read_b128 v[180:183], v215 offset:50176
	ds_read_b128 v[184:187], v215 offset:51200
	ds_read_b128 v[188:191], v215 offset:52224
	ds_read_b128 v[192:195], v215 offset:53248
	ds_read_b128 v[196:199], v215 offset:54272
	ds_read_b128 v[200:203], v215 offset:55296
	ds_read_b128 v[204:207], v215 offset:56320
	global_load_lds_dwordx4 v250, s[96:97]
	s_add_i32 m0, s62, 0x2000
	s_add_u32 s60, s60, 0x80080

; #define PG8_STAGE(bufoff, gbase, voff) do { _Pragma("unroll") for (int _i = 0; _i < 2; ++_i) \
;         __builtin_amdgcn_global_load_lds((const unsigned*)((const char*)(gbase) + (voff)[_i]), (PG8_LAS unsigned*)(lds + (bufoff) + ldsw + _i * 8192), 16, 0, 0); } while (0)
; #define PG8_LDA(dst, b, h) do { _Pragma("unroll") for (int m = 0; m < 4; ++m) _Pragma("unroll") for (int k = 0; k < 2; ++k) dst[m][k] = *(const PG8_LAS bf16x8*)(lds + PG8_SA(b, h) + aoff + m * 2048 + k * 1024); } while (0)
; template <class Epi, class Sched, bool ALIGN_EPI = false, bool SP2 = false>
; __device__ __forceinline__ void gemm_phase(PG8_LAS unsigned char* lds, const Gemm g, const Sched& S, const Epi& E) {
;     ...
;             PG8_LDA(At, 1, 1); PG8_STAGE(PG8_SB(1, 0), b3, voffB); PG8_STAGE(PG8_SB(1, 1), b3 + hstep, voffB); PG8_STAGE(PG8_SA(1, 0), a3, voffA);
	s_addc_u32 s61, s61, 0
	s_add_i32 s62, s83, s64
	global_load_lds_dwordx4 v251, s[96:97]

; #define PG8_STAGE(bufoff, gbase, voff) do { _Pragma("unroll") for (int _i = 0; _i < 2; ++_i) \
;         __builtin_amdgcn_global_load_lds((const unsigned*)((const char*)(gbase) + (voff)[_i]), (PG8_LAS unsigned*)(lds + (bufoff) + ldsw + _i * 8192), 16, 0, 0); } while (0)
; #define PG8_LDA(dst, b, h) do { _Pragma("unroll") for (int m = 0; m < 4; ++m) _Pragma("unroll") for (int k = 0; k < 2; ++k) dst[m][k] = *(const PG8_LAS bf16x8*)(lds + PG8_SA(b, h) + aoff + m * 2048 + k * 1024); } while (0)
; template <class Epi, class Sched, bool ALIGN_EPI = false, bool SP2 = false>
; __device__ __forceinline__ void gemm_phase(PG8_LAS unsigned char* lds, const Gemm g, const Sched& S, const Epi& E) {
;     ...
;             PG8_LDA(At, 1, 1); PG8_STAGE(PG8_SB(1, 0), b3, voffB); PG8_STAGE(PG8_SB(1, 1), b3 + hstep, voffB); PG8_STAGE(PG8_SA(1, 0), a3, voffA);
	s_mov_b32 m0, s62
	s_nop 0
	global_load_lds_dwordx4 v162, s[60:61]

; #define PG8_STAGE(bufoff, gbase, voff) do { _Pragma("unroll") for (int _i = 0; _i < 2; ++_i) \
;         __builtin_amdgcn_global_load_lds((const unsigned*)((const char*)(gbase) + (voff)[_i]), (PG8_LAS unsigned*)(lds + (bufoff) + ldsw + _i * 8192), 16, 0, 0); } while (0)
; #define PG8_LDA(dst, b, h) do { _Pragma("unroll") for (int m = 0; m < 4; ++m) _Pragma("unroll") for (int k = 0; k < 2; ++k) dst[m][k] = *(const PG8_LAS bf16x8*)(lds + PG8_SA(b, h) + aoff + m * 2048 + k * 1024); } while (0)
; template <class Epi, class Sched, bool ALIGN_EPI = false, bool SP2 = false>
; __device__ __forceinline__ void gemm_phase(PG8_LAS unsigned char* lds, const Gemm g, const Sched& S, const Epi& E) {
;     ...
;             PG8_LDA(At, 1, 1); PG8_STAGE(PG8_SB(1, 0), b3, voffB); PG8_STAGE(PG8_SB(1, 1), b3 + hstep, voffB); PG8_STAGE(PG8_SA(1, 0), a3, voffA);
	s_add_i32 m0, s62, 0x2000
	s_nop 0
	global_load_lds_dwordx4 v166, s[60:61]

; #define PG8_STAGE(bufoff, gbase, voff) do { _Pragma("unroll") for (int _i = 0; _i < 2; ++_i) \
;         __builtin_amdgcn_global_load_lds((const unsigned*)((const char*)(gbase) + (voff)[_i]), (PG8_LAS unsigned*)(lds + (bufoff) + ldsw + _i * 8192), 16, 0, 0); } while (0)
; #define PG8_LDA(dst, b, h) do { _Pragma("unroll") for (int m = 0; m < 4; ++m) _Pragma("unroll") for (int k = 0; k < 2; ++k) dst[m][k] = *(const PG8_LAS bf16x8*)(lds + PG8_SA(b, h) + aoff + m * 2048 + k * 1024); } while (0)
; template <class Epi, class Sched, bool ALIGN_EPI = false, bool SP2 = false>
; __device__ __forceinline__ void gemm_phase(PG8_LAS unsigned char* lds, const Gemm g, const Sched& S, const Epi& E) {
;     ...
;             PG8_LDA(At, 1, 1); PG8_STAGE(PG8_SB(1, 0), b3, voffB); PG8_STAGE(PG8_SB(1, 1), b3 + hstep, voffB); PG8_STAGE(PG8_SA(1, 0), a3, voffA);
	s_mov_b32 m0, s70
	s_nop 0
	global_load_lds_dwordx4 v252, s[98:99]

; #define PG8_STAGE(bufoff, gbase, voff) do { _Pragma("unroll") for (int _i = 0; _i < 2; ++_i) \
;         __builtin_amdgcn_global_load_lds((const unsigned*)((const char*)(gbase) + (voff)[_i]), (PG8_LAS unsigned*)(lds + (bufoff) + ldsw + _i * 8192), 16, 0, 0); } while (0)
; #define PG8_LDA(dst, b, h) do { _Pragma("unroll") for (int m = 0; m < 4; ++m) _Pragma("unroll") for (int k = 0; k < 2; ++k) dst[m][k] = *(const PG8_LAS bf16x8*)(lds + PG8_SA(b, h) + aoff + m * 2048 + k * 1024); } while (0)
; #define PG8_MMA(ai, bj, At, Bt) do { __builtin_amdgcn_s_setprio(1); _Pragma("unroll") for (int m = 0; m < 4; ++m) _Pragma("unroll") for (int n = 0; n < 2; ++n) _Pragma("unroll") for (int k = 0; k < 2; ++k) \
;         acc[ai][bj][m][n] = __builtin_amdgcn_mfma_f32_16x16x32_bf16(Bt[n][k], At[m][k], acc[ai][bj][m][n], 0, 0, 0); __builtin_amdgcn_s_setprio(0); } while (0)
; #define PG8_WAIT_V(n) asm volatile("s_waitcnt vmcnt(" #n ")" ::: "memory")
; #define PG8_WAIT_L(n) asm volatile("s_waitcnt lgkmcnt(" #n ")" ::: "memory")
; #define PG8_BAR __builtin_amdgcn_s_barrier()
; #define PG8_SCHED __builtin_amdgcn_sched_barrier(0)
; template <class Epi, class Sched, bool ALIGN_EPI = false, bool SP2 = false>
; __device__ __forceinline__ void gemm_phase(PG8_LAS unsigned char* lds, const Gemm g, const Sched& S, const Epi& E) {
;     ...
;             PG8_LDA(At, 1, 1); PG8_STAGE(PG8_SB(1, 0), b3, voffB); PG8_STAGE(PG8_SB(1, 1), b3 + hstep, voffB); PG8_STAGE(PG8_SA(1, 0), a3, voffA);
;             PG8_WAIT_V(8); PG8_WAIT_L(0); PG8_BAR; PG8_MMA(1, 0, At, B0); PG8_MMA(1, 1, At, B1); PG8_BAR; PG8_SCHED;
	s_mov_b32 m0, s71
	s_nop 0
	global_load_lds_dwordx4 v253, s[98:99]
	s_waitcnt vmcnt(8)
	s_waitcnt lgkmcnt(0)
	s_barrier
	s_setprio 1
	s_waitcnt lgkmcnt(0)
	v_mfma_f32_16x16x32_bf16 v[60:63], v[64:67], v[176:179], v[60:63]
	v_mfma_f32_16x16x32_bf16 v[56:59], v[72:75], v[176:179], v[56:59]
	v_mfma_f32_16x16x32_bf16 v[44:47], v[64:67], v[184:187], v[44:47]
	v_mfma_f32_16x16x32_bf16 v[40:43], v[72:75], v[184:187], v[40:43]
	v_mfma_f32_16x16x32_bf16 v[28:31], v[64:67], v[192:195], v[28:31]
	v_mfma_f32_16x16x32_bf16 v[24:27], v[72:75], v[192:195], v[24:27]
	v_mfma_f32_16x16x32_bf16 v[12:15], v[64:67], v[200:203], v[12:15]
	v_mfma_f32_16x16x32_bf16 v[8:11], v[72:75], v[200:203], v[8:11]
	v_mfma_f32_16x16x32_bf16 v[60:63], v[68:71], v[180:183], v[60:63]
	v_mfma_f32_16x16x32_bf16 v[56:59], v[76:79], v[180:183], v[56:59]
	v_mfma_f32_16x16x32_bf16 v[44:47], v[68:71], v[188:191], v[44:47]
	v_mfma_f32_16x16x32_bf16 v[40:43], v[76:79], v[188:191], v[40:43]
	v_mfma_f32_16x16x32_bf16 v[28:31], v[68:71], v[196:199], v[28:31]
	v_mfma_f32_16x16x32_bf16 v[24:27], v[76:79], v[196:199], v[24:27]
	v_mfma_f32_16x16x32_bf16 v[12:15], v[68:71], v[204:207], v[12:15]
	v_mfma_f32_16x16x32_bf16 v[8:11], v[76:79], v[204:207], v[8:11]


; #define PG8_MMA(ai, bj, At, Bt) do { __builtin_amdgcn_s_setprio(1); _Pragma("unroll") for (int m = 0; m < 4; ++m) _Pragma("unroll") for (int n = 0; n < 2; ++n) _Pragma("unroll") for (int k = 0; k < 2; ++k) \
;         acc[ai][bj][m][n] = __builtin_amdgcn_mfma_f32_16x16x32_bf16(Bt[n][k], At[m][k], acc[ai][bj][m][n], 0, 0, 0); __builtin_amdgcn_s_setprio(0); } while (0)
; #define PG8_WAIT_V(n) asm volatile("s_waitcnt vmcnt(" #n ")" ::: "memory")
; #define PG8_WAIT_L(n) asm volatile("s_waitcnt lgkmcnt(" #n ")" ::: "memory")
; #define PG8_BAR __builtin_amdgcn_s_barrier()
; #define PG8_SCHED __builtin_amdgcn_sched_barrier(0)
; template <class Epi, class Sched, bool ALIGN_EPI = false, bool SP2 = false>
; __device__ __forceinline__ void gemm_phase(PG8_LAS unsigned char* lds, const Gemm g, const Sched& S, const Epi& E) {
;     ...
;             PG8_WAIT_V(8); PG8_WAIT_L(0); PG8_BAR; PG8_MMA(1, 0, At, B0); PG8_MMA(1, 1, At, B1); PG8_BAR; PG8_SCHED;
	v_mfma_f32_16x16x32_bf16 v[52:55], v[144:147], v[176:179], v[52:55]
	v_mfma_f32_16x16x32_bf16 v[48:51], v[152:155], v[176:179], v[48:51]
	v_mfma_f32_16x16x32_bf16 v[36:39], v[144:147], v[184:187], v[36:39]
	v_mfma_f32_16x16x32_bf16 v[32:35], v[152:155], v[184:187], v[32:35]
	v_mfma_f32_16x16x32_bf16 v[20:23], v[144:147], v[192:195], v[20:23]
	v_mfma_f32_16x16x32_bf16 v[16:19], v[152:155], v[192:195], v[16:19]
	v_mfma_f32_16x16x32_bf16 v[4:7], v[144:147], v[200:203], v[4:7]
	v_mfma_f32_16x16x32_bf16 v[0:3], v[152:155], v[200:203], v[0:3]
	v_mfma_f32_16x16x32_bf16 v[52:55], v[148:151], v[180:183], v[52:55]
	v_mfma_f32_16x16x32_bf16 v[48:51], v[156:159], v[180:183], v[48:51]
	v_mfma_f32_16x16x32_bf16 v[36:39], v[148:151], v[188:191], v[36:39]
	v_mfma_f32_16x16x32_bf16 v[32:35], v[156:159], v[188:191], v[32:35]
	v_mfma_f32_16x16x32_bf16 v[20:23], v[148:151], v[196:199], v[20:23]
	v_mfma_f32_16x16x32_bf16 v[16:19], v[156:159], v[196:199], v[16:19]
	v_mfma_f32_16x16x32_bf16 v[4:7], v[148:151], v[204:207], v[4:7]
	v_mfma_f32_16x16x32_bf16 v[0:3], v[156:159], v[204:207], v[0:3]
	s_setprio 0
	s_barrier
	s_add_i32 s81, s81, 2
	s_add_u32 s58, s58, 0x100
	s_addc_u32 s59, s59, 0
	s_add_u32 s79, s79, 0x100
	s_addc_u32 s80, s80, 0
	s_cmp_gt_u32 s81, 29
	s_cbranch_scc0 .LBB0_939
	s_and_b64 vcc, exec, s[42:43]
	s_cbranch_vccz .LBB0_942
	s_barrier

; #define PG8_STAGE(bufoff, gbase, voff) do { _Pragma("unroll") for (int _i = 0; _i < 2; ++_i) \
;         __builtin_amdgcn_global_load_lds((const unsigned*)((const char*)(gbase) + (voff)[_i]), (PG8_LAS unsigned*)(lds + (bufoff) + ldsw + _i * 8192), 16, 0, 0); } while (0)
; #define PG8_LDA(dst, b, h) do { _Pragma("unroll") for (int m = 0; m < 4; ++m) _Pragma("unroll") for (int k = 0; k < 2; ++k) dst[m][k] = *(const PG8_LAS bf16x8*)(lds + PG8_SA(b, h) + aoff + m * 2048 + k * 1024); } while (0)
; #define PG8_LDB(dst, b, h) do { _Pragma("unroll") for (int n = 0; n < 2; ++n) _Pragma("unroll") for (int k = 0; k < 2; ++k) dst[n][k] = *(const PG8_LAS bf16x8*)(lds + PG8_SB(b, h) + boff + n * 2048 + k * 1024); } while (0)
; #define PG8_SCHED __builtin_amdgcn_sched_barrier(0)
; template <class Epi, class Sched, bool ALIGN_EPI = false, bool SP2 = false>
; __device__ __forceinline__ void gemm_phase(PG8_LAS unsigned char* lds, const Gemm g, const Sched& S, const Epi& E) {
;     ...
;             const char* a1 = cA + (size_t)(t + 1) * kstep;
;             const char* a2 = last ? nA : cA + (size_t)(t + 2) * kstep; const char* b2 = last ? nB : cB + (size_t)(t + 2) * kstep;
;             const char* a3 = a2 + kstep; const char* b3 = b2 + kstep;
;             if (last && has_next) S.a_ready(nxt);
;             if constexpr (SP2) {
;             PG8_LDB(B0, 0, 0); PG8_LDB(B1, 0, 1); PG8_SCHED; PG8_LDA(At, 0, 0); PG8_STAGE(PG8_SA(1, 1), a1 + hstep, voffA);
.LBB0_1034:
	ds_read_b128 v[128:131], v201
	ds_read_b128 v[132:135], v201 offset:1024
	ds_read_b128 v[136:139], v201 offset:2048
	ds_read_b128 v[140:143], v201 offset:3072
	ds_read_b128 v[144:147], v205
	ds_read_b128 v[148:151], v205 offset:1024
	ds_read_b128 v[152:155], v205 offset:2048
	ds_read_b128 v[156:159], v205 offset:3072
	s_add_u32 s12, s10, 0xfff80080
	s_addc_u32 s13, s11, -1
	s_cmp_eq_u32 s83, 28
	s_cselect_b32 s59, s53, s13
	s_cselect_b32 s58, s79, s12
	s_cselect_b32 s13, s51, s82
	s_cselect_b32 s12, s80, s81

; #define PG8_STAGE(bufoff, gbase, voff) do { _Pragma("unroll") for (int _i = 0; _i < 2; ++_i) \
;         __builtin_amdgcn_global_load_lds((const unsigned*)((const char*)(gbase) + (voff)[_i]), (PG8_LAS unsigned*)(lds + (bufoff) + ldsw + _i * 8192), 16, 0, 0); } while (0)
; #define PG8_LDA(dst, b, h) do { _Pragma("unroll") for (int m = 0; m < 4; ++m) _Pragma("unroll") for (int k = 0; k < 2; ++k) dst[m][k] = *(const PG8_LAS bf16x8*)(lds + PG8_SA(b, h) + aoff + m * 2048 + k * 1024); } while (0)
; #define PG8_LDB(dst, b, h) do { _Pragma("unroll") for (int n = 0; n < 2; ++n) _Pragma("unroll") for (int k = 0; k < 2; ++k) dst[n][k] = *(const PG8_LAS bf16x8*)(lds + PG8_SB(b, h) + boff + n * 2048 + k * 1024); } while (0)
; #define PG8_SCHED __builtin_amdgcn_sched_barrier(0)
; template <class Epi, class Sched, bool ALIGN_EPI = false, bool SP2 = false>
; __device__ __forceinline__ void gemm_phase(PG8_LAS unsigned char* lds, const Gemm g, const Sched& S, const Epi& E) {
;     ...
;             PG8_LDB(B0, 0, 0); PG8_LDB(B1, 0, 1); PG8_SCHED; PG8_LDA(At, 0, 0); PG8_STAGE(PG8_SA(1, 1), a1 + hstep, voffA);
	s_add_i32 m0, s63, 0xc000
	ds_read_b128 v[176:179], v207
	ds_read_b128 v[184:187], v207 offset:1024
	ds_read_b128 v[190:193], v207 offset:2048
	ds_read_b128 v[210:213], v207 offset:3072
	ds_read_b128 v[214:217], v207 offset:4096
	ds_read_b128 v[218:221], v207 offset:5120
	ds_read_b128 v[222:225], v207 offset:6144
	ds_read_b128 v[226:229], v207 offset:7168
	global_load_lds_dwordx4 v168, s[10:11]

; #define PG8_STAGE(bufoff, gbase, voff) do { _Pragma("unroll") for (int _i = 0; _i < 2; ++_i) \
;         __builtin_amdgcn_global_load_lds((const unsigned*)((const char*)(gbase) + (voff)[_i]), (PG8_LAS unsigned*)(lds + (bufoff) + ldsw + _i * 8192), 16, 0, 0); } while (0)
; #define PG8_LDA(dst, b, h) do { _Pragma("unroll") for (int m = 0; m < 4; ++m) _Pragma("unroll") for (int k = 0; k < 2; ++k) dst[m][k] = *(const PG8_LAS bf16x8*)(lds + PG8_SA(b, h) + aoff + m * 2048 + k * 1024); } while (0)
; #define PG8_LDB(dst, b, h) do { _Pragma("unroll") for (int n = 0; n < 2; ++n) _Pragma("unroll") for (int k = 0; k < 2; ++k) dst[n][k] = *(const PG8_LAS bf16x8*)(lds + PG8_SB(b, h) + boff + n * 2048 + k * 1024); } while (0)
; #define PG8_MMA(ai, bj, At, Bt) do { __builtin_amdgcn_s_setprio(1); _Pragma("unroll") for (int m = 0; m < 4; ++m) _Pragma("unroll") for (int n = 0; n < 2; ++n) _Pragma("unroll") for (int k = 0; k < 2; ++k) \
;         acc[ai][bj][m][n] = __builtin_amdgcn_mfma_f32_16x16x32_bf16(Bt[n][k], At[m][k], acc[ai][bj][m][n], 0, 0, 0); __builtin_amdgcn_s_setprio(0); } while (0)
; #define PG8_WAIT_V(n) asm volatile("s_waitcnt vmcnt(" #n ")" ::: "memory")
; #define PG8_WAIT_L(n) asm volatile("s_waitcnt lgkmcnt(" #n ")" ::: "memory")
; #define PG8_BAR __builtin_amdgcn_s_barrier()
; #define PG8_SCHED __builtin_amdgcn_sched_barrier(0)
; template <class Epi, class Sched, bool ALIGN_EPI = false, bool SP2 = false>
; __device__ __forceinline__ void gemm_phase(PG8_LAS unsigned char* lds, const Gemm g, const Sched& S, const Epi& E) {
;     ...
;             PG8_LDB(B0, 0, 0); PG8_LDB(B1, 0, 1); PG8_SCHED; PG8_LDA(At, 0, 0); PG8_STAGE(PG8_SA(1, 1), a1 + hstep, voffA);
;             PG8_WAIT_V(8); PG8_WAIT_L(0); PG8_BAR; PG8_MMA(0, 0, At, B0); PG8_MMA(0, 1, At, B1); PG8_BAR; PG8_SCHED;
	s_add_i32 m0, s63, 0xe000
	s_nop 0
	global_load_lds_dwordx4 v170, s[10:11]
	s_waitcnt vmcnt(8)
	s_waitcnt lgkmcnt(0)
	s_barrier
	s_setprio 1
	s_waitcnt lgkmcnt(0)
	v_mfma_f32_16x16x32_bf16 v[124:127], v[128:131], v[176:179], v[124:127]
	v_mfma_f32_16x16x32_bf16 v[120:123], v[136:139], v[176:179], v[120:123]
	v_mfma_f32_16x16x32_bf16 v[108:111], v[128:131], v[190:193], v[108:111]
	v_mfma_f32_16x16x32_bf16 v[104:107], v[136:139], v[190:193], v[104:107]
	v_mfma_f32_16x16x32_bf16 v[92:95], v[128:131], v[214:217], v[92:95]
	v_mfma_f32_16x16x32_bf16 v[88:91], v[136:139], v[214:217], v[88:91]
	v_mfma_f32_16x16x32_bf16 v[76:79], v[128:131], v[222:225], v[76:79]
	v_mfma_f32_16x16x32_bf16 v[72:75], v[136:139], v[222:225], v[72:75]
	v_mfma_f32_16x16x32_bf16 v[124:127], v[132:135], v[184:187], v[124:127]
	v_mfma_f32_16x16x32_bf16 v[120:123], v[140:143], v[184:187], v[120:123]
	v_mfma_f32_16x16x32_bf16 v[108:111], v[132:135], v[210:213], v[108:111]
	v_mfma_f32_16x16x32_bf16 v[104:107], v[140:143], v[210:213], v[104:107]
	v_mfma_f32_16x16x32_bf16 v[92:95], v[132:135], v[218:221], v[92:95]
	v_mfma_f32_16x16x32_bf16 v[88:91], v[140:143], v[218:221], v[88:91]
	v_mfma_f32_16x16x32_bf16 v[76:79], v[132:135], v[226:229], v[76:79]
	v_mfma_f32_16x16x32_bf16 v[72:75], v[140:143], v[226:229], v[72:75]


; #define PG8_MMA(ai, bj, At, Bt) do { __builtin_amdgcn_s_setprio(1); _Pragma("unroll") for (int m = 0; m < 4; ++m) _Pragma("unroll") for (int n = 0; n < 2; ++n) _Pragma("unroll") for (int k = 0; k < 2; ++k) \
;         acc[ai][bj][m][n] = __builtin_amdgcn_mfma_f32_16x16x32_bf16(Bt[n][k], At[m][k], acc[ai][bj][m][n], 0, 0, 0); __builtin_amdgcn_s_setprio(0); } while (0)
; #define PG8_WAIT_V(n) asm volatile("s_waitcnt vmcnt(" #n ")" ::: "memory")
; #define PG8_WAIT_L(n) asm volatile("s_waitcnt lgkmcnt(" #n ")" ::: "memory")
; #define PG8_BAR __builtin_amdgcn_s_barrier()
; #define PG8_SCHED __builtin_amdgcn_sched_barrier(0)
; template <class Epi, class Sched, bool ALIGN_EPI = false, bool SP2 = false>
; __device__ __forceinline__ void gemm_phase(PG8_LAS unsigned char* lds, const Gemm g, const Sched& S, const Epi& E) {
;     ...
;             PG8_WAIT_V(8); PG8_WAIT_L(0); PG8_BAR; PG8_MMA(0, 0, At, B0); PG8_MMA(0, 1, At, B1); PG8_BAR; PG8_SCHED;
	v_mfma_f32_16x16x32_bf16 v[116:119], v[144:147], v[176:179], v[116:119]
	v_mfma_f32_16x16x32_bf16 v[112:115], v[152:155], v[176:179], v[112:115]
	v_mfma_f32_16x16x32_bf16 v[100:103], v[144:147], v[190:193], v[100:103]
	v_mfma_f32_16x16x32_bf16 v[96:99], v[152:155], v[190:193], v[96:99]
	v_mfma_f32_16x16x32_bf16 v[84:87], v[144:147], v[214:217], v[84:87]
	v_mfma_f32_16x16x32_bf16 v[80:83], v[152:155], v[214:217], v[80:83]
	v_mfma_f32_16x16x32_bf16 v[68:71], v[144:147], v[222:225], v[68:71]
	v_mfma_f32_16x16x32_bf16 v[64:67], v[152:155], v[222:225], v[64:67]
	v_mfma_f32_16x16x32_bf16 v[116:119], v[148:151], v[184:187], v[116:119]
	v_mfma_f32_16x16x32_bf16 v[112:115], v[156:159], v[184:187], v[112:115]
	v_mfma_f32_16x16x32_bf16 v[100:103], v[148:151], v[210:213], v[100:103]
	v_mfma_f32_16x16x32_bf16 v[96:99], v[156:159], v[210:213], v[96:99]
	v_mfma_f32_16x16x32_bf16 v[84:87], v[148:151], v[218:221], v[84:87]
	v_mfma_f32_16x16x32_bf16 v[80:83], v[156:159], v[218:221], v[80:83]
	v_mfma_f32_16x16x32_bf16 v[68:71], v[148:151], v[226:229], v[68:71]
	v_mfma_f32_16x16x32_bf16 v[64:67], v[156:159], v[226:229], v[64:67]
	s_setprio 0
	s_barrier
	s_add_i32 s84, s73, s62
	s_mov_b64 s[96:97], s[12:13]

; #define PG8_STAGE(bufoff, gbase, voff) do { _Pragma("unroll") for (int _i = 0; _i < 2; ++_i) \
;         __builtin_amdgcn_global_load_lds((const unsigned*)((const char*)(gbase) + (voff)[_i]), (PG8_LAS unsigned*)(lds + (bufoff) + ldsw + _i * 8192), 16, 0, 0); } while (0)
; #define PG8_LDA(dst, b, h) do { _Pragma("unroll") for (int m = 0; m < 4; ++m) _Pragma("unroll") for (int k = 0; k < 2; ++k) dst[m][k] = *(const PG8_LAS bf16x8*)(lds + PG8_SA(b, h) + aoff + m * 2048 + k * 1024); } while (0)
; template <class Epi, class Sched, bool ALIGN_EPI = false, bool SP2 = false>
; __device__ __forceinline__ void gemm_phase(PG8_LAS unsigned char* lds, const Gemm g, const Sched& S, const Epi& E) {
;     ...
;             PG8_LDA(At, 0, 1); PG8_STAGE(PG8_SB(0, 0), b2, voffB); PG8_STAGE(PG8_SB(0, 1), b2 + hstep, voffB); PG8_STAGE(PG8_SA(0, 0), a2, voffA);
	s_mov_b32 m0, s84
	ds_read_b128 v[176:179], v207 offset:16384
	ds_read_b128 v[184:187], v207 offset:17408
	ds_read_b128 v[190:193], v207 offset:18432
	ds_read_b128 v[210:213], v207 offset:19456
	ds_read_b128 v[214:217], v207 offset:20480
	ds_read_b128 v[218:221], v207 offset:21504
	ds_read_b128 v[222:225], v207 offset:22528
	ds_read_b128 v[226:229], v207 offset:23552
	global_load_lds_dwordx4 v162, s[12:13]
	s_add_i32 m0, s84, 0x2000
	s_add_u32 s84, s12, 0x80000

; #define PG8_STAGE(bufoff, gbase, voff) do { _Pragma("unroll") for (int _i = 0; _i < 2; ++_i) \
;         __builtin_amdgcn_global_load_lds((const unsigned*)((const char*)(gbase) + (voff)[_i]), (PG8_LAS unsigned*)(lds + (bufoff) + ldsw + _i * 8192), 16, 0, 0); } while (0)
; #define PG8_LDA(dst, b, h) do { _Pragma("unroll") for (int m = 0; m < 4; ++m) _Pragma("unroll") for (int k = 0; k < 2; ++k) dst[m][k] = *(const PG8_LAS bf16x8*)(lds + PG8_SA(b, h) + aoff + m * 2048 + k * 1024); } while (0)
; template <class Epi, class Sched, bool ALIGN_EPI = false, bool SP2 = false>
; __device__ __forceinline__ void gemm_phase(PG8_LAS unsigned char* lds, const Gemm g, const Sched& S, const Epi& E) {
;     ...
;             PG8_LDA(At, 0, 1); PG8_STAGE(PG8_SB(0, 0), b2, voffB); PG8_STAGE(PG8_SB(0, 1), b2 + hstep, voffB); PG8_STAGE(PG8_SA(0, 0), a2, voffA);
	s_addc_u32 s85, s13, 0
	s_add_i32 s86, s74, s62
	global_load_lds_dwordx4 v166, s[12:13]

; #define PG8_STAGE(bufoff, gbase, voff) do { _Pragma("unroll") for (int _i = 0; _i < 2; ++_i) \
;         __builtin_amdgcn_global_load_lds((const unsigned*)((const char*)(gbase) + (voff)[_i]), (PG8_LAS unsigned*)(lds + (bufoff) + ldsw + _i * 8192), 16, 0, 0); } while (0)
; #define PG8_LDA(dst, b, h) do { _Pragma("unroll") for (int m = 0; m < 4; ++m) _Pragma("unroll") for (int k = 0; k < 2; ++k) dst[m][k] = *(const PG8_LAS bf16x8*)(lds + PG8_SA(b, h) + aoff + m * 2048 + k * 1024); } while (0)
; template <class Epi, class Sched, bool ALIGN_EPI = false, bool SP2 = false>
; __device__ __forceinline__ void gemm_phase(PG8_LAS unsigned char* lds, const Gemm g, const Sched& S, const Epi& E) {
;     ...
;             PG8_LDA(At, 0, 1); PG8_STAGE(PG8_SB(0, 0), b2, voffB); PG8_STAGE(PG8_SB(0, 1), b2 + hstep, voffB); PG8_STAGE(PG8_SA(0, 0), a2, voffA);
	s_mov_b32 m0, s86
	s_nop 0
	global_load_lds_dwordx4 v162, s[84:85]

; #define PG8_STAGE(bufoff, gbase, voff) do { _Pragma("unroll") for (int _i = 0; _i < 2; ++_i) \
;         __builtin_amdgcn_global_load_lds((const unsigned*)((const char*)(gbase) + (voff)[_i]), (PG8_LAS unsigned*)(lds + (bufoff) + ldsw + _i * 8192), 16, 0, 0); } while (0)
; #define PG8_LDA(dst, b, h) do { _Pragma("unroll") for (int m = 0; m < 4; ++m) _Pragma("unroll") for (int k = 0; k < 2; ++k) dst[m][k] = *(const PG8_LAS bf16x8*)(lds + PG8_SA(b, h) + aoff + m * 2048 + k * 1024); } while (0)
; template <class Epi, class Sched, bool ALIGN_EPI = false, bool SP2 = false>
; __device__ __forceinline__ void gemm_phase(PG8_LAS unsigned char* lds, const Gemm g, const Sched& S, const Epi& E) {
;     ...
;             PG8_LDA(At, 0, 1); PG8_STAGE(PG8_SB(0, 0), b2, voffB); PG8_STAGE(PG8_SB(0, 1), b2 + hstep, voffB); PG8_STAGE(PG8_SA(0, 0), a2, voffA);
	s_add_i32 m0, s86, 0x2000
	s_nop 0
	global_load_lds_dwordx4 v166, s[84:85]
	s_mov_b64 s[98:99], s[58:59]

; #define PG8_STAGE(bufoff, gbase, voff) do { _Pragma("unroll") for (int _i = 0; _i < 2; ++_i) \
;         __builtin_amdgcn_global_load_lds((const unsigned*)((const char*)(gbase) + (voff)[_i]), (PG8_LAS unsigned*)(lds + (bufoff) + ldsw + _i * 8192), 16, 0, 0); } while (0)
; #define PG8_LDA(dst, b, h) do { _Pragma("unroll") for (int m = 0; m < 4; ++m) _Pragma("unroll") for (int k = 0; k < 2; ++k) dst[m][k] = *(const PG8_LAS bf16x8*)(lds + PG8_SA(b, h) + aoff + m * 2048 + k * 1024); } while (0)
; #define PG8_MMA(ai, bj, At, Bt) do { __builtin_amdgcn_s_setprio(1); _Pragma("unroll") for (int m = 0; m < 4; ++m) _Pragma("unroll") for (int n = 0; n < 2; ++n) _Pragma("unroll") for (int k = 0; k < 2; ++k) \
;         acc[ai][bj][m][n] = __builtin_amdgcn_mfma_f32_16x16x32_bf16(Bt[n][k], At[m][k], acc[ai][bj][m][n], 0, 0, 0); __builtin_amdgcn_s_setprio(0); } while (0)
; #define PG8_WAIT_V(n) asm volatile("s_waitcnt vmcnt(" #n ")" ::: "memory")
; #define PG8_WAIT_L(n) asm volatile("s_waitcnt lgkmcnt(" #n ")" ::: "memory")
; #define PG8_BAR __builtin_amdgcn_s_barrier()
; #define PG8_SCHED __builtin_amdgcn_sched_barrier(0)
; template <class Epi, class Sched, bool ALIGN_EPI = false, bool SP2 = false>
; __device__ __forceinline__ void gemm_phase(PG8_LAS unsigned char* lds, const Gemm g, const Sched& S, const Epi& E) {
;     ...
;             PG8_LDA(At, 0, 1); PG8_STAGE(PG8_SB(0, 0), b2, voffB); PG8_STAGE(PG8_SB(0, 1), b2 + hstep, voffB); PG8_STAGE(PG8_SA(0, 0), a2, voffA);
;             PG8_WAIT_V(8); PG8_WAIT_L(0); PG8_BAR; PG8_MMA(1, 0, At, B0); PG8_MMA(1, 1, At, B1); PG8_BAR; PG8_SCHED;
	s_mov_b32 m0, s63
	s_nop 0
	global_load_lds_dwordx4 v160, s[58:59]
	s_mov_b32 m0, s64
	s_nop 0
	global_load_lds_dwordx4 v164, s[58:59]
	s_waitcnt vmcnt(8)
	s_waitcnt lgkmcnt(0)
	s_barrier
	s_setprio 1
	s_waitcnt lgkmcnt(0)
	v_mfma_f32_16x16x32_bf16 v[60:63], v[128:131], v[176:179], v[60:63]
	v_mfma_f32_16x16x32_bf16 v[56:59], v[136:139], v[176:179], v[56:59]
	v_mfma_f32_16x16x32_bf16 v[44:47], v[128:131], v[190:193], v[44:47]
	v_mfma_f32_16x16x32_bf16 v[40:43], v[136:139], v[190:193], v[40:43]
	v_mfma_f32_16x16x32_bf16 v[28:31], v[128:131], v[214:217], v[28:31]
	v_mfma_f32_16x16x32_bf16 v[24:27], v[136:139], v[214:217], v[24:27]
	v_mfma_f32_16x16x32_bf16 v[12:15], v[128:131], v[222:225], v[12:15]
	v_mfma_f32_16x16x32_bf16 v[8:11], v[136:139], v[222:225], v[8:11]
	v_mfma_f32_16x16x32_bf16 v[60:63], v[132:135], v[184:187], v[60:63]
	v_mfma_f32_16x16x32_bf16 v[56:59], v[140:143], v[184:187], v[56:59]
	v_mfma_f32_16x16x32_bf16 v[44:47], v[132:135], v[210:213], v[44:47]
	v_mfma_f32_16x16x32_bf16 v[40:43], v[140:143], v[210:213], v[40:43]
	v_mfma_f32_16x16x32_bf16 v[28:31], v[132:135], v[218:221], v[28:31]
	v_mfma_f32_16x16x32_bf16 v[24:27], v[140:143], v[218:221], v[24:27]
	v_mfma_f32_16x16x32_bf16 v[12:15], v[132:135], v[226:229], v[12:15]
	v_mfma_f32_16x16x32_bf16 v[8:11], v[140:143], v[226:229], v[8:11]


; #define PG8_STAGE(bufoff, gbase, voff) do { _Pragma("unroll") for (int _i = 0; _i < 2; ++_i) \
;         __builtin_amdgcn_global_load_lds((const unsigned*)((const char*)(gbase) + (voff)[_i]), (PG8_LAS unsigned*)(lds + (bufoff) + ldsw + _i * 8192), 16, 0, 0); } while (0)
; #define PG8_LDA(dst, b, h) do { _Pragma("unroll") for (int m = 0; m < 4; ++m) _Pragma("unroll") for (int k = 0; k < 2; ++k) dst[m][k] = *(const PG8_LAS bf16x8*)(lds + PG8_SA(b, h) + aoff + m * 2048 + k * 1024); } while (0)
; #define PG8_LDB(dst, b, h) do { _Pragma("unroll") for (int n = 0; n < 2; ++n) _Pragma("unroll") for (int k = 0; k < 2; ++k) dst[n][k] = *(const PG8_LAS bf16x8*)(lds + PG8_SB(b, h) + boff + n * 2048 + k * 1024); } while (0)
; #define PG8_MMA(ai, bj, At, Bt) do { __builtin_amdgcn_s_setprio(1); _Pragma("unroll") for (int m = 0; m < 4; ++m) _Pragma("unroll") for (int n = 0; n < 2; ++n) _Pragma("unroll") for (int k = 0; k < 2; ++k) \
;         acc[ai][bj][m][n] = __builtin_amdgcn_mfma_f32_16x16x32_bf16(Bt[n][k], At[m][k], acc[ai][bj][m][n], 0, 0, 0); __builtin_amdgcn_s_setprio(0); } while (0)
; #define PG8_WAIT_V(n) asm volatile("s_waitcnt vmcnt(" #n ")" ::: "memory")
; #define PG8_WAIT_L(n) asm volatile("s_waitcnt lgkmcnt(" #n ")" ::: "memory")
; #define PG8_BAR __builtin_amdgcn_s_barrier()
; #define PG8_SCHED __builtin_amdgcn_sched_barrier(0)
; template <class Epi, class Sched, bool ALIGN_EPI = false, bool SP2 = false>
; __device__ __forceinline__ void gemm_phase(PG8_LAS unsigned char* lds, const Gemm g, const Sched& S, const Epi& E) {
;     ...
;             PG8_WAIT_V(8); PG8_WAIT_L(0); PG8_BAR; PG8_MMA(1, 0, At, B0); PG8_MMA(1, 1, At, B1); PG8_BAR; PG8_SCHED;
;             PG8_LDB(B0, 1, 0); PG8_LDB(B1, 1, 1); PG8_SCHED; PG8_LDA(At, 1, 0); PG8_STAGE(PG8_SA(0, 1), a2 + hstep, voffA);
	v_mfma_f32_16x16x32_bf16 v[52:55], v[144:147], v[176:179], v[52:55]
	v_mfma_f32_16x16x32_bf16 v[48:51], v[152:155], v[176:179], v[48:51]
	v_mfma_f32_16x16x32_bf16 v[36:39], v[144:147], v[190:193], v[36:39]
	v_mfma_f32_16x16x32_bf16 v[32:35], v[152:155], v[190:193], v[32:35]
	v_mfma_f32_16x16x32_bf16 v[20:23], v[144:147], v[214:217], v[20:23]
	v_mfma_f32_16x16x32_bf16 v[16:19], v[152:155], v[214:217], v[16:19]
	v_mfma_f32_16x16x32_bf16 v[4:7], v[144:147], v[222:225], v[4:7]
	v_mfma_f32_16x16x32_bf16 v[0:3], v[152:155], v[222:225], v[0:3]
	v_mfma_f32_16x16x32_bf16 v[52:55], v[148:151], v[184:187], v[52:55]
	v_mfma_f32_16x16x32_bf16 v[48:51], v[156:159], v[184:187], v[48:51]
	v_mfma_f32_16x16x32_bf16 v[36:39], v[148:151], v[210:213], v[36:39]
	v_mfma_f32_16x16x32_bf16 v[32:35], v[156:159], v[210:213], v[32:35]
	v_mfma_f32_16x16x32_bf16 v[20:23], v[148:151], v[218:221], v[20:23]
	v_mfma_f32_16x16x32_bf16 v[16:19], v[156:159], v[218:221], v[16:19]
	v_mfma_f32_16x16x32_bf16 v[4:7], v[148:151], v[226:229], v[4:7]
	v_mfma_f32_16x16x32_bf16 v[0:3], v[156:159], v[226:229], v[0:3]
	s_setprio 0
	s_barrier
	s_add_i32 s84, 0, 0x18000
	s_add_i32 s85, 0, 0x1c000
	v_add_u32_e32 v140, s84, v189
	v_add_u32_e32 v156, s85, v189
	ds_read_b128 v[128:131], v140
	ds_read_b128 v[132:135], v140 offset:1024
	ds_read_b128 v[136:139], v140 offset:2048
	ds_read_b128 v[140:143], v140 offset:3072
	ds_read_b128 v[144:147], v156
	ds_read_b128 v[148:151], v156 offset:1024
	ds_read_b128 v[152:155], v156 offset:2048
	ds_read_b128 v[156:159], v156 offset:3072
	s_add_u32 s58, s58, 0x80000
	s_addc_u32 s59, s59, 0
	s_mov_b32 m0, s65

; #define PG8_STAGE(bufoff, gbase, voff) do { _Pragma("unroll") for (int _i = 0; _i < 2; ++_i) \
;         __builtin_amdgcn_global_load_lds((const unsigned*)((const char*)(gbase) + (voff)[_i]), (PG8_LAS unsigned*)(lds + (bufoff) + ldsw + _i * 8192), 16, 0, 0); } while (0)
; #define PG8_LDA(dst, b, h) do { _Pragma("unroll") for (int m = 0; m < 4; ++m) _Pragma("unroll") for (int k = 0; k < 2; ++k) dst[m][k] = *(const PG8_LAS bf16x8*)(lds + PG8_SA(b, h) + aoff + m * 2048 + k * 1024); } while (0)
; #define PG8_LDB(dst, b, h) do { _Pragma("unroll") for (int n = 0; n < 2; ++n) _Pragma("unroll") for (int k = 0; k < 2; ++k) dst[n][k] = *(const PG8_LAS bf16x8*)(lds + PG8_SB(b, h) + boff + n * 2048 + k * 1024); } while (0)
; #define PG8_SCHED __builtin_amdgcn_sched_barrier(0)
; template <class Epi, class Sched, bool ALIGN_EPI = false, bool SP2 = false>
; __device__ __forceinline__ void gemm_phase(PG8_LAS unsigned char* lds, const Gemm g, const Sched& S, const Epi& E) {
;     ...
;             PG8_LDB(B0, 1, 0); PG8_LDB(B1, 1, 1); PG8_SCHED; PG8_LDA(At, 1, 0); PG8_STAGE(PG8_SA(0, 1), a2 + hstep, voffA);
	ds_read_b128 v[176:179], v207 offset:32768
	ds_read_b128 v[184:187], v207 offset:33792
	ds_read_b128 v[190:193], v207 offset:34816
	ds_read_b128 v[210:213], v207 offset:35840
	ds_read_b128 v[214:217], v207 offset:36864
	ds_read_b128 v[218:221], v207 offset:37888
	ds_read_b128 v[222:225], v207 offset:38912
	ds_read_b128 v[226:229], v207 offset:39936
	global_load_lds_dwordx4 v160, s[58:59]

; #define PG8_STAGE(bufoff, gbase, voff) do { _Pragma("unroll") for (int _i = 0; _i < 2; ++_i) \
;         __builtin_amdgcn_global_load_lds((const unsigned*)((const char*)(gbase) + (voff)[_i]), (PG8_LAS unsigned*)(lds + (bufoff) + ldsw + _i * 8192), 16, 0, 0); } while (0)
; #define PG8_LDA(dst, b, h) do { _Pragma("unroll") for (int m = 0; m < 4; ++m) _Pragma("unroll") for (int k = 0; k < 2; ++k) dst[m][k] = *(const PG8_LAS bf16x8*)(lds + PG8_SA(b, h) + aoff + m * 2048 + k * 1024); } while (0)
; #define PG8_LDB(dst, b, h) do { _Pragma("unroll") for (int n = 0; n < 2; ++n) _Pragma("unroll") for (int k = 0; k < 2; ++k) dst[n][k] = *(const PG8_LAS bf16x8*)(lds + PG8_SB(b, h) + boff + n * 2048 + k * 1024); } while (0)
; #define PG8_MMA(ai, bj, At, Bt) do { __builtin_amdgcn_s_setprio(1); _Pragma("unroll") for (int m = 0; m < 4; ++m) _Pragma("unroll") for (int n = 0; n < 2; ++n) _Pragma("unroll") for (int k = 0; k < 2; ++k) \
;         acc[ai][bj][m][n] = __builtin_amdgcn_mfma_f32_16x16x32_bf16(Bt[n][k], At[m][k], acc[ai][bj][m][n], 0, 0, 0); __builtin_amdgcn_s_setprio(0); } while (0)
; #define PG8_WAIT_V(n) asm volatile("s_waitcnt vmcnt(" #n ")" ::: "memory")
; #define PG8_WAIT_L(n) asm volatile("s_waitcnt lgkmcnt(" #n ")" ::: "memory")
; #define PG8_BAR __builtin_amdgcn_s_barrier()
; #define PG8_SCHED __builtin_amdgcn_sched_barrier(0)
; template <class Epi, class Sched, bool ALIGN_EPI = false, bool SP2 = false>
; __device__ __forceinline__ void gemm_phase(PG8_LAS unsigned char* lds, const Gemm g, const Sched& S, const Epi& E) {
;     ...
;             PG8_LDB(B0, 1, 0); PG8_LDB(B1, 1, 1); PG8_SCHED; PG8_LDA(At, 1, 0); PG8_STAGE(PG8_SA(0, 1), a2 + hstep, voffA);
;             PG8_WAIT_V(8); PG8_WAIT_L(0); PG8_BAR; PG8_MMA(0, 0, At, B0); PG8_MMA(0, 1, At, B1); PG8_BAR; PG8_SCHED;
	s_mov_b32 m0, s67
	s_nop 0
	global_load_lds_dwordx4 v164, s[58:59]
	s_waitcnt vmcnt(8)
	s_waitcnt lgkmcnt(0)
	s_barrier
	s_setprio 1
	s_waitcnt lgkmcnt(0)
	v_mfma_f32_16x16x32_bf16 v[124:127], v[128:131], v[176:179], v[124:127]
	v_mfma_f32_16x16x32_bf16 v[120:123], v[136:139], v[176:179], v[120:123]
	v_mfma_f32_16x16x32_bf16 v[108:111], v[128:131], v[190:193], v[108:111]
	v_mfma_f32_16x16x32_bf16 v[104:107], v[136:139], v[190:193], v[104:107]
	v_mfma_f32_16x16x32_bf16 v[92:95], v[128:131], v[214:217], v[92:95]
	v_mfma_f32_16x16x32_bf16 v[88:91], v[136:139], v[214:217], v[88:91]
	v_mfma_f32_16x16x32_bf16 v[76:79], v[128:131], v[222:225], v[76:79]
	v_mfma_f32_16x16x32_bf16 v[72:75], v[136:139], v[222:225], v[72:75]
	v_mfma_f32_16x16x32_bf16 v[124:127], v[132:135], v[184:187], v[124:127]
	v_mfma_f32_16x16x32_bf16 v[120:123], v[140:143], v[184:187], v[120:123]
	v_mfma_f32_16x16x32_bf16 v[108:111], v[132:135], v[210:213], v[108:111]
	v_mfma_f32_16x16x32_bf16 v[104:107], v[140:143], v[210:213], v[104:107]
	v_mfma_f32_16x16x32_bf16 v[92:95], v[132:135], v[218:221], v[92:95]
	v_mfma_f32_16x16x32_bf16 v[88:91], v[140:143], v[218:221], v[88:91]
	v_mfma_f32_16x16x32_bf16 v[76:79], v[132:135], v[226:229], v[76:79]
	v_mfma_f32_16x16x32_bf16 v[72:75], v[140:143], v[226:229], v[72:75]


; #define PG8_MMA(ai, bj, At, Bt) do { __builtin_amdgcn_s_setprio(1); _Pragma("unroll") for (int m = 0; m < 4; ++m) _Pragma("unroll") for (int n = 0; n < 2; ++n) _Pragma("unroll") for (int k = 0; k < 2; ++k) \
;         acc[ai][bj][m][n] = __builtin_amdgcn_mfma_f32_16x16x32_bf16(Bt[n][k], At[m][k], acc[ai][bj][m][n], 0, 0, 0); __builtin_amdgcn_s_setprio(0); } while (0)
; #define PG8_WAIT_V(n) asm volatile("s_waitcnt vmcnt(" #n ")" ::: "memory")
; #define PG8_WAIT_L(n) asm volatile("s_waitcnt lgkmcnt(" #n ")" ::: "memory")
; #define PG8_BAR __builtin_amdgcn_s_barrier()
; #define PG8_SCHED __builtin_amdgcn_sched_barrier(0)
; template <class Epi, class Sched, bool ALIGN_EPI = false, bool SP2 = false>
; __device__ __forceinline__ void gemm_phase(PG8_LAS unsigned char* lds, const Gemm g, const Sched& S, const Epi& E) {
;     ...
;             PG8_WAIT_V(8); PG8_WAIT_L(0); PG8_BAR; PG8_MMA(0, 0, At, B0); PG8_MMA(0, 1, At, B1); PG8_BAR; PG8_SCHED;
	v_mfma_f32_16x16x32_bf16 v[116:119], v[144:147], v[176:179], v[116:119]
	v_mfma_f32_16x16x32_bf16 v[112:115], v[152:155], v[176:179], v[112:115]
	v_mfma_f32_16x16x32_bf16 v[100:103], v[144:147], v[190:193], v[100:103]
	v_mfma_f32_16x16x32_bf16 v[96:99], v[152:155], v[190:193], v[96:99]
	v_mfma_f32_16x16x32_bf16 v[84:87], v[144:147], v[214:217], v[84:87]
	v_mfma_f32_16x16x32_bf16 v[80:83], v[152:155], v[214:217], v[80:83]
	v_mfma_f32_16x16x32_bf16 v[68:71], v[144:147], v[222:225], v[68:71]
	v_mfma_f32_16x16x32_bf16 v[64:67], v[152:155], v[222:225], v[64:67]
	v_mfma_f32_16x16x32_bf16 v[116:119], v[148:151], v[184:187], v[116:119]
	v_mfma_f32_16x16x32_bf16 v[112:115], v[156:159], v[184:187], v[112:115]
	v_mfma_f32_16x16x32_bf16 v[100:103], v[148:151], v[210:213], v[100:103]
	v_mfma_f32_16x16x32_bf16 v[96:99], v[156:159], v[210:213], v[96:99]
	v_mfma_f32_16x16x32_bf16 v[84:87], v[148:151], v[218:221], v[84:87]
	v_mfma_f32_16x16x32_bf16 v[80:83], v[156:159], v[218:221], v[80:83]
	v_mfma_f32_16x16x32_bf16 v[68:71], v[148:151], v[226:229], v[68:71]
	v_mfma_f32_16x16x32_bf16 v[64:67], v[156:159], v[226:229], v[64:67]
	s_setprio 0
	s_barrier
	s_add_i32 s58, s84, s62

; #define PG8_STAGE(bufoff, gbase, voff) do { _Pragma("unroll") for (int _i = 0; _i < 2; ++_i) \
;         __builtin_amdgcn_global_load_lds((const unsigned*)((const char*)(gbase) + (voff)[_i]), (PG8_LAS unsigned*)(lds + (bufoff) + ldsw + _i * 8192), 16, 0, 0); } while (0)
; #define PG8_LDA(dst, b, h) do { _Pragma("unroll") for (int m = 0; m < 4; ++m) _Pragma("unroll") for (int k = 0; k < 2; ++k) dst[m][k] = *(const PG8_LAS bf16x8*)(lds + PG8_SA(b, h) + aoff + m * 2048 + k * 1024); } while (0)
; template <class Epi, class Sched, bool ALIGN_EPI = false, bool SP2 = false>
; __device__ __forceinline__ void gemm_phase(PG8_LAS unsigned char* lds, const Gemm g, const Sched& S, const Epi& E) {
;     ...
;             PG8_LDA(At, 1, 1); PG8_STAGE(PG8_SB(1, 0), b3, voffB); PG8_STAGE(PG8_SB(1, 1), b3 + hstep, voffB); PG8_STAGE(PG8_SA(1, 0), a3, voffA);
	s_mov_b32 m0, s58
	ds_read_b128 v[176:179], v207 offset:49152
	ds_read_b128 v[184:187], v207 offset:50176
	ds_read_b128 v[190:193], v207 offset:51200
	ds_read_b128 v[210:213], v207 offset:52224
	ds_read_b128 v[214:217], v207 offset:53248
	ds_read_b128 v[218:221], v207 offset:54272
	ds_read_b128 v[222:225], v207 offset:55296
	ds_read_b128 v[226:229], v207 offset:56320
	global_load_lds_dwordx4 v250, s[96:97]
	s_add_i32 m0, s58, 0x2000
	s_add_u32 s12, s12, 0x80080

; #define PG8_STAGE(bufoff, gbase, voff) do { _Pragma("unroll") for (int _i = 0; _i < 2; ++_i) \
;         __builtin_amdgcn_global_load_lds((const unsigned*)((const char*)(gbase) + (voff)[_i]), (PG8_LAS unsigned*)(lds + (bufoff) + ldsw + _i * 8192), 16, 0, 0); } while (0)
; #define PG8_LDA(dst, b, h) do { _Pragma("unroll") for (int m = 0; m < 4; ++m) _Pragma("unroll") for (int k = 0; k < 2; ++k) dst[m][k] = *(const PG8_LAS bf16x8*)(lds + PG8_SA(b, h) + aoff + m * 2048 + k * 1024); } while (0)
; template <class Epi, class Sched, bool ALIGN_EPI = false, bool SP2 = false>
; __device__ __forceinline__ void gemm_phase(PG8_LAS unsigned char* lds, const Gemm g, const Sched& S, const Epi& E) {
;     ...
;             PG8_LDA(At, 1, 1); PG8_STAGE(PG8_SB(1, 0), b3, voffB); PG8_STAGE(PG8_SB(1, 1), b3 + hstep, voffB); PG8_STAGE(PG8_SA(1, 0), a3, voffA);
	s_addc_u32 s13, s13, 0
	s_add_i32 s58, s85, s62
	global_load_lds_dwordx4 v251, s[96:97]

; #define PG8_STAGE(bufoff, gbase, voff) do { _Pragma("unroll") for (int _i = 0; _i < 2; ++_i) \
;         __builtin_amdgcn_global_load_lds((const unsigned*)((const char*)(gbase) + (voff)[_i]), (PG8_LAS unsigned*)(lds + (bufoff) + ldsw + _i * 8192), 16, 0, 0); } while (0)
; #define PG8_LDA(dst, b, h) do { _Pragma("unroll") for (int m = 0; m < 4; ++m) _Pragma("unroll") for (int k = 0; k < 2; ++k) dst[m][k] = *(const PG8_LAS bf16x8*)(lds + PG8_SA(b, h) + aoff + m * 2048 + k * 1024); } while (0)
; template <class Epi, class Sched, bool ALIGN_EPI = false, bool SP2 = false>
; __device__ __forceinline__ void gemm_phase(PG8_LAS unsigned char* lds, const Gemm g, const Sched& S, const Epi& E) {
;     ...
;             PG8_LDA(At, 1, 1); PG8_STAGE(PG8_SB(1, 0), b3, voffB); PG8_STAGE(PG8_SB(1, 1), b3 + hstep, voffB); PG8_STAGE(PG8_SA(1, 0), a3, voffA);
	s_mov_b32 m0, s58
	s_nop 0
	global_load_lds_dwordx4 v162, s[12:13]

; #define PG8_STAGE(bufoff, gbase, voff) do { _Pragma("unroll") for (int _i = 0; _i < 2; ++_i) \
;         __builtin_amdgcn_global_load_lds((const unsigned*)((const char*)(gbase) + (voff)[_i]), (PG8_LAS unsigned*)(lds + (bufoff) + ldsw + _i * 8192), 16, 0, 0); } while (0)
; #define PG8_LDA(dst, b, h) do { _Pragma("unroll") for (int m = 0; m < 4; ++m) _Pragma("unroll") for (int k = 0; k < 2; ++k) dst[m][k] = *(const PG8_LAS bf16x8*)(lds + PG8_SA(b, h) + aoff + m * 2048 + k * 1024); } while (0)
; template <class Epi, class Sched, bool ALIGN_EPI = false, bool SP2 = false>
; __device__ __forceinline__ void gemm_phase(PG8_LAS unsigned char* lds, const Gemm g, const Sched& S, const Epi& E) {
;     ...
;             PG8_LDA(At, 1, 1); PG8_STAGE(PG8_SB(1, 0), b3, voffB); PG8_STAGE(PG8_SB(1, 1), b3 + hstep, voffB); PG8_STAGE(PG8_SA(1, 0), a3, voffA);
	s_add_i32 m0, s58, 0x2000
	s_nop 0
	global_load_lds_dwordx4 v166, s[12:13]

; #define PG8_STAGE(bufoff, gbase, voff) do { _Pragma("unroll") for (int _i = 0; _i < 2; ++_i) \
;         __builtin_amdgcn_global_load_lds((const unsigned*)((const char*)(gbase) + (voff)[_i]), (PG8_LAS unsigned*)(lds + (bufoff) + ldsw + _i * 8192), 16, 0, 0); } while (0)
; #define PG8_LDA(dst, b, h) do { _Pragma("unroll") for (int m = 0; m < 4; ++m) _Pragma("unroll") for (int k = 0; k < 2; ++k) dst[m][k] = *(const PG8_LAS bf16x8*)(lds + PG8_SA(b, h) + aoff + m * 2048 + k * 1024); } while (0)
; template <class Epi, class Sched, bool ALIGN_EPI = false, bool SP2 = false>
; __device__ __forceinline__ void gemm_phase(PG8_LAS unsigned char* lds, const Gemm g, const Sched& S, const Epi& E) {
;     ...
;             PG8_LDA(At, 1, 1); PG8_STAGE(PG8_SB(1, 0), b3, voffB); PG8_STAGE(PG8_SB(1, 1), b3 + hstep, voffB); PG8_STAGE(PG8_SA(1, 0), a3, voffA);
	s_mov_b32 m0, s69
	s_nop 0
	global_load_lds_dwordx4 v252, s[98:99]

; #define PG8_STAGE(bufoff, gbase, voff) do { _Pragma("unroll") for (int _i = 0; _i < 2; ++_i) \
;         __builtin_amdgcn_global_load_lds((const unsigned*)((const char*)(gbase) + (voff)[_i]), (PG8_LAS unsigned*)(lds + (bufoff) + ldsw + _i * 8192), 16, 0, 0); } while (0)
; #define PG8_LDA(dst, b, h) do { _Pragma("unroll") for (int m = 0; m < 4; ++m) _Pragma("unroll") for (int k = 0; k < 2; ++k) dst[m][k] = *(const PG8_LAS bf16x8*)(lds + PG8_SA(b, h) + aoff + m * 2048 + k * 1024); } while (0)
; #define PG8_MMA(ai, bj, At, Bt) do { __builtin_amdgcn_s_setprio(1); _Pragma("unroll") for (int m = 0; m < 4; ++m) _Pragma("unroll") for (int n = 0; n < 2; ++n) _Pragma("unroll") for (int k = 0; k < 2; ++k) \
;         acc[ai][bj][m][n] = __builtin_amdgcn_mfma_f32_16x16x32_bf16(Bt[n][k], At[m][k], acc[ai][bj][m][n], 0, 0, 0); __builtin_amdgcn_s_setprio(0); } while (0)
; #define PG8_WAIT_V(n) asm volatile("s_waitcnt vmcnt(" #n ")" ::: "memory")
; #define PG8_WAIT_L(n) asm volatile("s_waitcnt lgkmcnt(" #n ")" ::: "memory")
; #define PG8_BAR __builtin_amdgcn_s_barrier()
; #define PG8_SCHED __builtin_amdgcn_sched_barrier(0)
; template <class Epi, class Sched, bool ALIGN_EPI = false, bool SP2 = false>
; __device__ __forceinline__ void gemm_phase(PG8_LAS unsigned char* lds, const Gemm g, const Sched& S, const Epi& E) {
;     ...
;             PG8_LDA(At, 1, 1); PG8_STAGE(PG8_SB(1, 0), b3, voffB); PG8_STAGE(PG8_SB(1, 1), b3 + hstep, voffB); PG8_STAGE(PG8_SA(1, 0), a3, voffA);
;             PG8_WAIT_V(8); PG8_WAIT_L(0); PG8_BAR; PG8_MMA(1, 0, At, B0); PG8_MMA(1, 1, At, B1); PG8_BAR; PG8_SCHED;
	s_mov_b32 m0, s70
	s_nop 0
	global_load_lds_dwordx4 v253, s[98:99]
	s_waitcnt vmcnt(8)
	s_waitcnt lgkmcnt(0)
	s_barrier
	s_setprio 1
	s_waitcnt lgkmcnt(0)
	v_mfma_f32_16x16x32_bf16 v[60:63], v[128:131], v[176:179], v[60:63]
	v_mfma_f32_16x16x32_bf16 v[56:59], v[136:139], v[176:179], v[56:59]
	v_mfma_f32_16x16x32_bf16 v[44:47], v[128:131], v[190:193], v[44:47]
	v_mfma_f32_16x16x32_bf16 v[40:43], v[136:139], v[190:193], v[40:43]
	v_mfma_f32_16x16x32_bf16 v[28:31], v[128:131], v[214:217], v[28:31]
	v_mfma_f32_16x16x32_bf16 v[24:27], v[136:139], v[214:217], v[24:27]
	v_mfma_f32_16x16x32_bf16 v[12:15], v[128:131], v[222:225], v[12:15]
	v_mfma_f32_16x16x32_bf16 v[8:11], v[136:139], v[222:225], v[8:11]
	v_mfma_f32_16x16x32_bf16 v[60:63], v[132:135], v[184:187], v[60:63]
	v_mfma_f32_16x16x32_bf16 v[56:59], v[140:143], v[184:187], v[56:59]
	v_mfma_f32_16x16x32_bf16 v[44:47], v[132:135], v[210:213], v[44:47]
	v_mfma_f32_16x16x32_bf16 v[40:43], v[140:143], v[210:213], v[40:43]
	v_mfma_f32_16x16x32_bf16 v[28:31], v[132:135], v[218:221], v[28:31]
	v_mfma_f32_16x16x32_bf16 v[24:27], v[140:143], v[218:221], v[24:27]
	v_mfma_f32_16x16x32_bf16 v[12:15], v[132:135], v[226:229], v[12:15]
	v_mfma_f32_16x16x32_bf16 v[8:11], v[140:143], v[226:229], v[8:11]


; #define PG8_MMA(ai, bj, At, Bt) do { __builtin_amdgcn_s_setprio(1); _Pragma("unroll") for (int m = 0; m < 4; ++m) _Pragma("unroll") for (int n = 0; n < 2; ++n) _Pragma("unroll") for (int k = 0; k < 2; ++k) \
;         acc[ai][bj][m][n] = __builtin_amdgcn_mfma_f32_16x16x32_bf16(Bt[n][k], At[m][k], acc[ai][bj][m][n], 0, 0, 0); __builtin_amdgcn_s_setprio(0); } while (0)
; #define PG8_WAIT_V(n) asm volatile("s_waitcnt vmcnt(" #n ")" ::: "memory")
; #define PG8_WAIT_L(n) asm volatile("s_waitcnt lgkmcnt(" #n ")" ::: "memory")
; #define PG8_BAR __builtin_amdgcn_s_barrier()
; #define PG8_SCHED __builtin_amdgcn_sched_barrier(0)
; template <class Epi, class Sched, bool ALIGN_EPI = false, bool SP2 = false>
; __device__ __forceinline__ void gemm_phase(PG8_LAS unsigned char* lds, const Gemm g, const Sched& S, const Epi& E) {
;     ...
;             PG8_WAIT_V(8); PG8_WAIT_L(0); PG8_BAR; PG8_MMA(1, 0, At, B0); PG8_MMA(1, 1, At, B1); PG8_BAR; PG8_SCHED;
	v_mfma_f32_16x16x32_bf16 v[52:55], v[144:147], v[176:179], v[52:55]
	v_mfma_f32_16x16x32_bf16 v[48:51], v[152:155], v[176:179], v[48:51]
	v_mfma_f32_16x16x32_bf16 v[36:39], v[144:147], v[190:193], v[36:39]
	v_mfma_f32_16x16x32_bf16 v[32:35], v[152:155], v[190:193], v[32:35]
	v_mfma_f32_16x16x32_bf16 v[20:23], v[144:147], v[214:217], v[20:23]
	v_mfma_f32_16x16x32_bf16 v[16:19], v[152:155], v[214:217], v[16:19]
	v_mfma_f32_16x16x32_bf16 v[4:7], v[144:147], v[222:225], v[4:7]
	v_mfma_f32_16x16x32_bf16 v[0:3], v[152:155], v[222:225], v[0:3]
	v_mfma_f32_16x16x32_bf16 v[52:55], v[148:151], v[184:187], v[52:55]
	v_mfma_f32_16x16x32_bf16 v[48:51], v[156:159], v[184:187], v[48:51]
	v_mfma_f32_16x16x32_bf16 v[36:39], v[148:151], v[210:213], v[36:39]
	v_mfma_f32_16x16x32_bf16 v[32:35], v[156:159], v[210:213], v[32:35]
	v_mfma_f32_16x16x32_bf16 v[20:23], v[148:151], v[218:221], v[20:23]
	v_mfma_f32_16x16x32_bf16 v[16:19], v[156:159], v[218:221], v[16:19]
	v_mfma_f32_16x16x32_bf16 v[4:7], v[148:151], v[226:229], v[4:7]
	v_mfma_f32_16x16x32_bf16 v[0:3], v[156:159], v[226:229], v[0:3]
	s_setprio 0
	s_barrier
	s_add_i32 s83, s83, 2
	s_add_u32 s10, s10, 0x100
	s_addc_u32 s11, s11, 0
	s_add_u32 s81, s81, 0x100
	s_addc_u32 s82, s82, 0
	s_cmp_gt_u32 s83, 29
	s_cbranch_scc0 .LBB0_1034
	s_and_b64 vcc, exec, s[40:41]
	s_cbranch_vccz .LBB0_1037
	s_barrier

; #define PG8_STAGE(bufoff, gbase, voff) do { _Pragma("unroll") for (int _i = 0; _i < 2; ++_i) \
;         __builtin_amdgcn_global_load_lds((const unsigned*)((const char*)(gbase) + (voff)[_i]), (PG8_LAS unsigned*)(lds + (bufoff) + ldsw + _i * 8192), 16, 0, 0); } while (0)
; #define PG8_LDA(dst, b, h) do { _Pragma("unroll") for (int m = 0; m < 4; ++m) _Pragma("unroll") for (int k = 0; k < 2; ++k) dst[m][k] = *(const PG8_LAS bf16x8*)(lds + PG8_SA(b, h) + aoff + m * 2048 + k * 1024); } while (0)
; #define PG8_LDB(dst, b, h) do { _Pragma("unroll") for (int n = 0; n < 2; ++n) _Pragma("unroll") for (int k = 0; k < 2; ++k) dst[n][k] = *(const PG8_LAS bf16x8*)(lds + PG8_SB(b, h) + boff + n * 2048 + k * 1024); } while (0)
; #define PG8_SCHED __builtin_amdgcn_sched_barrier(0)
; template <class Epi, class Sched, bool ALIGN_EPI = false, bool SP2 = false>
; __device__ __forceinline__ void gemm_phase(PG8_LAS unsigned char* lds, const Gemm g, const Sched& S, const Epi& E) {
;     ...
;             const char* a1 = cA + (size_t)(t + 1) * kstep;
;             const char* a2 = last ? nA : cA + (size_t)(t + 2) * kstep; const char* b2 = last ? nB : cB + (size_t)(t + 2) * kstep;
;             const char* a3 = a2 + kstep; const char* b3 = b2 + kstep;
;             if (last && has_next) S.a_ready(nxt);
;             if constexpr (SP2) {
;             PG8_LDB(B0, 0, 0); PG8_LDB(B1, 0, 1); PG8_SCHED; PG8_LDA(At, 0, 0); PG8_STAGE(PG8_SA(1, 1), a1 + hstep, voffA);
.LBB0_1114:
	ds_read_b128 v[96:99], v197
	ds_read_b128 v[100:103], v197 offset:1024
	ds_read_b128 v[104:107], v197 offset:2048
	ds_read_b128 v[112:115], v197 offset:3072
	ds_read_b128 v[144:147], v198
	ds_read_b128 v[148:151], v198 offset:1024
	ds_read_b128 v[152:155], v198 offset:2048
	ds_read_b128 v[172:175], v198 offset:3072
	s_add_u32 s50, s48, 0xffe00080
	s_addc_u32 s51, s49, -1
	s_cmpk_eq_i32 s73, 0x7c
	s_cselect_b32 s53, s43, s51
	s_cselect_b32 s52, s69, s50
	s_cselect_b32 s51, s41, s72
	s_cselect_b32 s50, s70, s71

; #define PG8_STAGE(bufoff, gbase, voff) do { _Pragma("unroll") for (int _i = 0; _i < 2; ++_i) \
;         __builtin_amdgcn_global_load_lds((const unsigned*)((const char*)(gbase) + (voff)[_i]), (PG8_LAS unsigned*)(lds + (bufoff) + ldsw + _i * 8192), 16, 0, 0); } while (0)
; #define PG8_LDA(dst, b, h) do { _Pragma("unroll") for (int m = 0; m < 4; ++m) _Pragma("unroll") for (int k = 0; k < 2; ++k) dst[m][k] = *(const PG8_LAS bf16x8*)(lds + PG8_SA(b, h) + aoff + m * 2048 + k * 1024); } while (0)
; #define PG8_LDB(dst, b, h) do { _Pragma("unroll") for (int n = 0; n < 2; ++n) _Pragma("unroll") for (int k = 0; k < 2; ++k) dst[n][k] = *(const PG8_LAS bf16x8*)(lds + PG8_SB(b, h) + boff + n * 2048 + k * 1024); } while (0)
; #define PG8_SCHED __builtin_amdgcn_sched_barrier(0)
; template <class Epi, class Sched, bool ALIGN_EPI = false, bool SP2 = false>
; __device__ __forceinline__ void gemm_phase(PG8_LAS unsigned char* lds, const Gemm g, const Sched& S, const Epi& E) {
;     ...
;             PG8_LDB(B0, 0, 0); PG8_LDB(B1, 0, 1); PG8_SCHED; PG8_LDA(At, 0, 0); PG8_STAGE(PG8_SA(1, 1), a1 + hstep, voffA);
	s_add_i32 m0, s56, 0xc000
	ds_read_b128 v[176:179], v199
	ds_read_b128 v[180:183], v199 offset:1024
	ds_read_b128 v[184:187], v199 offset:2048
	ds_read_b128 v[188:191], v199 offset:3072
	ds_read_b128 v[202:205], v199 offset:4096
	ds_read_b128 v[206:209], v199 offset:5120
	ds_read_b128 v[210:213], v199 offset:6144
	ds_read_b128 v[214:217], v199 offset:7168
	global_load_lds_dwordx4 v164, s[48:49]

; #define PG8_STAGE(bufoff, gbase, voff) do { _Pragma("unroll") for (int _i = 0; _i < 2; ++_i) \
;         __builtin_amdgcn_global_load_lds((const unsigned*)((const char*)(gbase) + (voff)[_i]), (PG8_LAS unsigned*)(lds + (bufoff) + ldsw + _i * 8192), 16, 0, 0); } while (0)
; #define PG8_LDA(dst, b, h) do { _Pragma("unroll") for (int m = 0; m < 4; ++m) _Pragma("unroll") for (int k = 0; k < 2; ++k) dst[m][k] = *(const PG8_LAS bf16x8*)(lds + PG8_SA(b, h) + aoff + m * 2048 + k * 1024); } while (0)
; #define PG8_LDB(dst, b, h) do { _Pragma("unroll") for (int n = 0; n < 2; ++n) _Pragma("unroll") for (int k = 0; k < 2; ++k) dst[n][k] = *(const PG8_LAS bf16x8*)(lds + PG8_SB(b, h) + boff + n * 2048 + k * 1024); } while (0)
; #define PG8_MMA(ai, bj, At, Bt) do { __builtin_amdgcn_s_setprio(1); _Pragma("unroll") for (int m = 0; m < 4; ++m) _Pragma("unroll") for (int n = 0; n < 2; ++n) _Pragma("unroll") for (int k = 0; k < 2; ++k) \
;         acc[ai][bj][m][n] = __builtin_amdgcn_mfma_f32_16x16x32_bf16(Bt[n][k], At[m][k], acc[ai][bj][m][n], 0, 0, 0); __builtin_amdgcn_s_setprio(0); } while (0)
; #define PG8_WAIT_V(n) asm volatile("s_waitcnt vmcnt(" #n ")" ::: "memory")
; #define PG8_WAIT_L(n) asm volatile("s_waitcnt lgkmcnt(" #n ")" ::: "memory")
; #define PG8_BAR __builtin_amdgcn_s_barrier()
; #define PG8_SCHED __builtin_amdgcn_sched_barrier(0)
; template <class Epi, class Sched, bool ALIGN_EPI = false, bool SP2 = false>
; __device__ __forceinline__ void gemm_phase(PG8_LAS unsigned char* lds, const Gemm g, const Sched& S, const Epi& E) {
;     ...
;             PG8_LDB(B0, 0, 0); PG8_LDB(B1, 0, 1); PG8_SCHED; PG8_LDA(At, 0, 0); PG8_STAGE(PG8_SA(1, 1), a1 + hstep, voffA);
;             PG8_WAIT_V(8); PG8_WAIT_L(0); PG8_BAR; PG8_MMA(0, 0, At, B0); PG8_MMA(0, 1, At, B1); PG8_BAR; PG8_SCHED;
	s_add_i32 m0, s56, 0xe000
	s_nop 0
	global_load_lds_dwordx4 v166, s[48:49]
	s_waitcnt vmcnt(8)
	s_waitcnt lgkmcnt(0)
	s_barrier
	s_setprio 1
	s_waitcnt lgkmcnt(0)
	v_mfma_f32_16x16x32_bf16 v[140:143], v[96:99], v[176:179], v[140:143]
	v_mfma_f32_16x16x32_bf16 v[136:139], v[104:107], v[176:179], v[136:139]
	v_mfma_f32_16x16x32_bf16 v[124:127], v[96:99], v[184:187], v[124:127]
	v_mfma_f32_16x16x32_bf16 v[120:123], v[104:107], v[184:187], v[120:123]
	v_mfma_f32_16x16x32_bf16 v[92:95], v[96:99], v[202:205], v[92:95]
	v_mfma_f32_16x16x32_bf16 v[88:91], v[104:107], v[202:205], v[88:91]
	v_mfma_f32_16x16x32_bf16 v[76:79], v[96:99], v[210:213], v[76:79]
	v_mfma_f32_16x16x32_bf16 v[72:75], v[104:107], v[210:213], v[72:75]
	v_mfma_f32_16x16x32_bf16 v[140:143], v[100:103], v[180:183], v[140:143]
	v_mfma_f32_16x16x32_bf16 v[136:139], v[112:115], v[180:183], v[136:139]
	v_mfma_f32_16x16x32_bf16 v[124:127], v[100:103], v[188:191], v[124:127]
	v_mfma_f32_16x16x32_bf16 v[120:123], v[112:115], v[188:191], v[120:123]
	v_mfma_f32_16x16x32_bf16 v[92:95], v[100:103], v[206:209], v[92:95]
	v_mfma_f32_16x16x32_bf16 v[88:91], v[112:115], v[206:209], v[88:91]
	v_mfma_f32_16x16x32_bf16 v[76:79], v[100:103], v[214:217], v[76:79]
	v_mfma_f32_16x16x32_bf16 v[72:75], v[112:115], v[214:217], v[72:75]


; #define PG8_MMA(ai, bj, At, Bt) do { __builtin_amdgcn_s_setprio(1); _Pragma("unroll") for (int m = 0; m < 4; ++m) _Pragma("unroll") for (int n = 0; n < 2; ++n) _Pragma("unroll") for (int k = 0; k < 2; ++k) \
;         acc[ai][bj][m][n] = __builtin_amdgcn_mfma_f32_16x16x32_bf16(Bt[n][k], At[m][k], acc[ai][bj][m][n], 0, 0, 0); __builtin_amdgcn_s_setprio(0); } while (0)
; #define PG8_WAIT_V(n) asm volatile("s_waitcnt vmcnt(" #n ")" ::: "memory")
; #define PG8_WAIT_L(n) asm volatile("s_waitcnt lgkmcnt(" #n ")" ::: "memory")
; #define PG8_BAR __builtin_amdgcn_s_barrier()
; #define PG8_SCHED __builtin_amdgcn_sched_barrier(0)
; template <class Epi, class Sched, bool ALIGN_EPI = false, bool SP2 = false>
; __device__ __forceinline__ void gemm_phase(PG8_LAS unsigned char* lds, const Gemm g, const Sched& S, const Epi& E) {
;     ...
;             PG8_WAIT_V(8); PG8_WAIT_L(0); PG8_BAR; PG8_MMA(0, 0, At, B0); PG8_MMA(0, 1, At, B1); PG8_BAR; PG8_SCHED;
	v_mfma_f32_16x16x32_bf16 v[132:135], v[144:147], v[176:179], v[132:135]
	v_mfma_f32_16x16x32_bf16 v[128:131], v[152:155], v[176:179], v[128:131]
	v_mfma_f32_16x16x32_bf16 v[116:119], v[144:147], v[184:187], v[116:119]
	v_mfma_f32_16x16x32_bf16 v[108:111], v[152:155], v[184:187], v[108:111]
	v_mfma_f32_16x16x32_bf16 v[84:87], v[144:147], v[202:205], v[84:87]
	v_mfma_f32_16x16x32_bf16 v[80:83], v[152:155], v[202:205], v[80:83]
	v_mfma_f32_16x16x32_bf16 v[68:71], v[144:147], v[210:213], v[68:71]
	v_mfma_f32_16x16x32_bf16 v[64:67], v[152:155], v[210:213], v[64:67]
	v_mfma_f32_16x16x32_bf16 v[132:135], v[148:151], v[180:183], v[132:135]
	v_mfma_f32_16x16x32_bf16 v[128:131], v[172:175], v[180:183], v[128:131]
	v_mfma_f32_16x16x32_bf16 v[116:119], v[148:151], v[188:191], v[116:119]
	v_mfma_f32_16x16x32_bf16 v[108:111], v[172:175], v[188:191], v[108:111]
	v_mfma_f32_16x16x32_bf16 v[84:87], v[148:151], v[206:209], v[84:87]
	v_mfma_f32_16x16x32_bf16 v[80:83], v[172:175], v[206:209], v[80:83]
	v_mfma_f32_16x16x32_bf16 v[68:71], v[148:151], v[214:217], v[68:71]
	v_mfma_f32_16x16x32_bf16 v[64:67], v[172:175], v[214:217], v[64:67]
	s_setprio 0
	s_barrier
	s_add_i32 s74, s65, s55
	s_mov_b64 s[96:97], s[50:51]

; #define PG8_STAGE(bufoff, gbase, voff) do { _Pragma("unroll") for (int _i = 0; _i < 2; ++_i) \
;         __builtin_amdgcn_global_load_lds((const unsigned*)((const char*)(gbase) + (voff)[_i]), (PG8_LAS unsigned*)(lds + (bufoff) + ldsw + _i * 8192), 16, 0, 0); } while (0)
; #define PG8_LDA(dst, b, h) do { _Pragma("unroll") for (int m = 0; m < 4; ++m) _Pragma("unroll") for (int k = 0; k < 2; ++k) dst[m][k] = *(const PG8_LAS bf16x8*)(lds + PG8_SA(b, h) + aoff + m * 2048 + k * 1024); } while (0)
; template <class Epi, class Sched, bool ALIGN_EPI = false, bool SP2 = false>
; __device__ __forceinline__ void gemm_phase(PG8_LAS unsigned char* lds, const Gemm g, const Sched& S, const Epi& E) {
;     ...
;             PG8_LDA(At, 0, 1); PG8_STAGE(PG8_SB(0, 0), b2, voffB); PG8_STAGE(PG8_SB(0, 1), b2 + hstep, voffB); PG8_STAGE(PG8_SA(0, 0), a2, voffA);
	s_mov_b32 m0, s74
	ds_read_b128 v[176:179], v199 offset:16384
	ds_read_b128 v[180:183], v199 offset:17408
	ds_read_b128 v[184:187], v199 offset:18432
	ds_read_b128 v[188:191], v199 offset:19456
	ds_read_b128 v[202:205], v199 offset:20480
	ds_read_b128 v[206:209], v199 offset:21504
	ds_read_b128 v[210:213], v199 offset:22528
	ds_read_b128 v[214:217], v199 offset:23552
	global_load_lds_dwordx4 v158, s[50:51]
	s_add_i32 m0, s74, 0x2000
	s_add_u32 s74, s50, 0x200000

; #define PG8_STAGE(bufoff, gbase, voff) do { _Pragma("unroll") for (int _i = 0; _i < 2; ++_i) \
;         __builtin_amdgcn_global_load_lds((const unsigned*)((const char*)(gbase) + (voff)[_i]), (PG8_LAS unsigned*)(lds + (bufoff) + ldsw + _i * 8192), 16, 0, 0); } while (0)
; #define PG8_LDA(dst, b, h) do { _Pragma("unroll") for (int m = 0; m < 4; ++m) _Pragma("unroll") for (int k = 0; k < 2; ++k) dst[m][k] = *(const PG8_LAS bf16x8*)(lds + PG8_SA(b, h) + aoff + m * 2048 + k * 1024); } while (0)
; template <class Epi, class Sched, bool ALIGN_EPI = false, bool SP2 = false>
; __device__ __forceinline__ void gemm_phase(PG8_LAS unsigned char* lds, const Gemm g, const Sched& S, const Epi& E) {
;     ...
;             PG8_LDA(At, 0, 1); PG8_STAGE(PG8_SB(0, 0), b2, voffB); PG8_STAGE(PG8_SB(0, 1), b2 + hstep, voffB); PG8_STAGE(PG8_SA(0, 0), a2, voffA);
	s_addc_u32 s75, s51, 0
	s_add_i32 s76, s67, s55
	global_load_lds_dwordx4 v162, s[50:51]

; #define PG8_STAGE(bufoff, gbase, voff) do { _Pragma("unroll") for (int _i = 0; _i < 2; ++_i) \
;         __builtin_amdgcn_global_load_lds((const unsigned*)((const char*)(gbase) + (voff)[_i]), (PG8_LAS unsigned*)(lds + (bufoff) + ldsw + _i * 8192), 16, 0, 0); } while (0)
; #define PG8_LDA(dst, b, h) do { _Pragma("unroll") for (int m = 0; m < 4; ++m) _Pragma("unroll") for (int k = 0; k < 2; ++k) dst[m][k] = *(const PG8_LAS bf16x8*)(lds + PG8_SA(b, h) + aoff + m * 2048 + k * 1024); } while (0)
; template <class Epi, class Sched, bool ALIGN_EPI = false, bool SP2 = false>
; __device__ __forceinline__ void gemm_phase(PG8_LAS unsigned char* lds, const Gemm g, const Sched& S, const Epi& E) {
;     ...
;             PG8_LDA(At, 0, 1); PG8_STAGE(PG8_SB(0, 0), b2, voffB); PG8_STAGE(PG8_SB(0, 1), b2 + hstep, voffB); PG8_STAGE(PG8_SA(0, 0), a2, voffA);
	s_mov_b32 m0, s76
	s_nop 0
	global_load_lds_dwordx4 v158, s[74:75]

; #define PG8_STAGE(bufoff, gbase, voff) do { _Pragma("unroll") for (int _i = 0; _i < 2; ++_i) \
;         __builtin_amdgcn_global_load_lds((const unsigned*)((const char*)(gbase) + (voff)[_i]), (PG8_LAS unsigned*)(lds + (bufoff) + ldsw + _i * 8192), 16, 0, 0); } while (0)
; #define PG8_LDA(dst, b, h) do { _Pragma("unroll") for (int m = 0; m < 4; ++m) _Pragma("unroll") for (int k = 0; k < 2; ++k) dst[m][k] = *(const PG8_LAS bf16x8*)(lds + PG8_SA(b, h) + aoff + m * 2048 + k * 1024); } while (0)
; template <class Epi, class Sched, bool ALIGN_EPI = false, bool SP2 = false>
; __device__ __forceinline__ void gemm_phase(PG8_LAS unsigned char* lds, const Gemm g, const Sched& S, const Epi& E) {
;     ...
;             PG8_LDA(At, 0, 1); PG8_STAGE(PG8_SB(0, 0), b2, voffB); PG8_STAGE(PG8_SB(0, 1), b2 + hstep, voffB); PG8_STAGE(PG8_SA(0, 0), a2, voffA);
	s_add_i32 m0, s76, 0x2000
	s_nop 0
	global_load_lds_dwordx4 v162, s[74:75]
	s_mov_b64 s[98:99], s[52:53]

; #define PG8_STAGE(bufoff, gbase, voff) do { _Pragma("unroll") for (int _i = 0; _i < 2; ++_i) \
;         __builtin_amdgcn_global_load_lds((const unsigned*)((const char*)(gbase) + (voff)[_i]), (PG8_LAS unsigned*)(lds + (bufoff) + ldsw + _i * 8192), 16, 0, 0); } while (0)
; #define PG8_LDA(dst, b, h) do { _Pragma("unroll") for (int m = 0; m < 4; ++m) _Pragma("unroll") for (int k = 0; k < 2; ++k) dst[m][k] = *(const PG8_LAS bf16x8*)(lds + PG8_SA(b, h) + aoff + m * 2048 + k * 1024); } while (0)
; #define PG8_MMA(ai, bj, At, Bt) do { __builtin_amdgcn_s_setprio(1); _Pragma("unroll") for (int m = 0; m < 4; ++m) _Pragma("unroll") for (int n = 0; n < 2; ++n) _Pragma("unroll") for (int k = 0; k < 2; ++k) \
;         acc[ai][bj][m][n] = __builtin_amdgcn_mfma_f32_16x16x32_bf16(Bt[n][k], At[m][k], acc[ai][bj][m][n], 0, 0, 0); __builtin_amdgcn_s_setprio(0); } while (0)
; #define PG8_WAIT_V(n) asm volatile("s_waitcnt vmcnt(" #n ")" ::: "memory")
; #define PG8_WAIT_L(n) asm volatile("s_waitcnt lgkmcnt(" #n ")" ::: "memory")
; #define PG8_BAR __builtin_amdgcn_s_barrier()
; #define PG8_SCHED __builtin_amdgcn_sched_barrier(0)
; template <class Epi, class Sched, bool ALIGN_EPI = false, bool SP2 = false>
; __device__ __forceinline__ void gemm_phase(PG8_LAS unsigned char* lds, const Gemm g, const Sched& S, const Epi& E) {
;     ...
;             PG8_LDA(At, 0, 1); PG8_STAGE(PG8_SB(0, 0), b2, voffB); PG8_STAGE(PG8_SB(0, 1), b2 + hstep, voffB); PG8_STAGE(PG8_SA(0, 0), a2, voffA);
;             PG8_WAIT_V(8); PG8_WAIT_L(0); PG8_BAR; PG8_MMA(1, 0, At, B0); PG8_MMA(1, 1, At, B1); PG8_BAR; PG8_SCHED;
	s_mov_b32 m0, s56
	s_nop 0
	global_load_lds_dwordx4 v156, s[52:53]
	s_mov_b32 m0, s57
	s_nop 0
	global_load_lds_dwordx4 v160, s[52:53]
	s_waitcnt vmcnt(8)
	s_waitcnt lgkmcnt(0)
	s_barrier
	s_setprio 1
	s_waitcnt lgkmcnt(0)
	v_mfma_f32_16x16x32_bf16 v[60:63], v[96:99], v[176:179], v[60:63]
	v_mfma_f32_16x16x32_bf16 v[56:59], v[104:107], v[176:179], v[56:59]
	v_mfma_f32_16x16x32_bf16 v[44:47], v[96:99], v[184:187], v[44:47]
	v_mfma_f32_16x16x32_bf16 v[40:43], v[104:107], v[184:187], v[40:43]
	v_mfma_f32_16x16x32_bf16 v[28:31], v[96:99], v[202:205], v[28:31]
	v_mfma_f32_16x16x32_bf16 v[24:27], v[104:107], v[202:205], v[24:27]
	v_mfma_f32_16x16x32_bf16 v[12:15], v[96:99], v[210:213], v[12:15]
	v_mfma_f32_16x16x32_bf16 v[8:11], v[104:107], v[210:213], v[8:11]
	v_mfma_f32_16x16x32_bf16 v[60:63], v[100:103], v[180:183], v[60:63]
	v_mfma_f32_16x16x32_bf16 v[56:59], v[112:115], v[180:183], v[56:59]
	v_mfma_f32_16x16x32_bf16 v[44:47], v[100:103], v[188:191], v[44:47]
	v_mfma_f32_16x16x32_bf16 v[40:43], v[112:115], v[188:191], v[40:43]
	v_mfma_f32_16x16x32_bf16 v[28:31], v[100:103], v[206:209], v[28:31]
	v_mfma_f32_16x16x32_bf16 v[24:27], v[112:115], v[206:209], v[24:27]
	v_mfma_f32_16x16x32_bf16 v[12:15], v[100:103], v[214:217], v[12:15]
	v_mfma_f32_16x16x32_bf16 v[8:11], v[112:115], v[214:217], v[8:11]


; #define PG8_STAGE(bufoff, gbase, voff) do { _Pragma("unroll") for (int _i = 0; _i < 2; ++_i) \
;         __builtin_amdgcn_global_load_lds((const unsigned*)((const char*)(gbase) + (voff)[_i]), (PG8_LAS unsigned*)(lds + (bufoff) + ldsw + _i * 8192), 16, 0, 0); } while (0)
; #define PG8_LDA(dst, b, h) do { _Pragma("unroll") for (int m = 0; m < 4; ++m) _Pragma("unroll") for (int k = 0; k < 2; ++k) dst[m][k] = *(const PG8_LAS bf16x8*)(lds + PG8_SA(b, h) + aoff + m * 2048 + k * 1024); } while (0)
; #define PG8_LDB(dst, b, h) do { _Pragma("unroll") for (int n = 0; n < 2; ++n) _Pragma("unroll") for (int k = 0; k < 2; ++k) dst[n][k] = *(const PG8_LAS bf16x8*)(lds + PG8_SB(b, h) + boff + n * 2048 + k * 1024); } while (0)
; #define PG8_MMA(ai, bj, At, Bt) do { __builtin_amdgcn_s_setprio(1); _Pragma("unroll") for (int m = 0; m < 4; ++m) _Pragma("unroll") for (int n = 0; n < 2; ++n) _Pragma("unroll") for (int k = 0; k < 2; ++k) \
;         acc[ai][bj][m][n] = __builtin_amdgcn_mfma_f32_16x16x32_bf16(Bt[n][k], At[m][k], acc[ai][bj][m][n], 0, 0, 0); __builtin_amdgcn_s_setprio(0); } while (0)
; #define PG8_WAIT_V(n) asm volatile("s_waitcnt vmcnt(" #n ")" ::: "memory")
; #define PG8_WAIT_L(n) asm volatile("s_waitcnt lgkmcnt(" #n ")" ::: "memory")
; #define PG8_BAR __builtin_amdgcn_s_barrier()
; #define PG8_SCHED __builtin_amdgcn_sched_barrier(0)
; template <class Epi, class Sched, bool ALIGN_EPI = false, bool SP2 = false>
; __device__ __forceinline__ void gemm_phase(PG8_LAS unsigned char* lds, const Gemm g, const Sched& S, const Epi& E) {
;     ...
;             PG8_WAIT_V(8); PG8_WAIT_L(0); PG8_BAR; PG8_MMA(1, 0, At, B0); PG8_MMA(1, 1, At, B1); PG8_BAR; PG8_SCHED;
;             PG8_LDB(B0, 1, 0); PG8_LDB(B1, 1, 1); PG8_SCHED; PG8_LDA(At, 1, 0); PG8_STAGE(PG8_SA(0, 1), a2 + hstep, voffA);
	v_mfma_f32_16x16x32_bf16 v[52:55], v[144:147], v[176:179], v[52:55]
	v_mfma_f32_16x16x32_bf16 v[48:51], v[152:155], v[176:179], v[48:51]
	v_mfma_f32_16x16x32_bf16 v[36:39], v[144:147], v[184:187], v[36:39]
	v_mfma_f32_16x16x32_bf16 v[32:35], v[152:155], v[184:187], v[32:35]
	v_mfma_f32_16x16x32_bf16 v[20:23], v[144:147], v[202:205], v[20:23]
	v_mfma_f32_16x16x32_bf16 v[16:19], v[152:155], v[202:205], v[16:19]
	v_mfma_f32_16x16x32_bf16 v[4:7], v[144:147], v[210:213], v[4:7]
	v_mfma_f32_16x16x32_bf16 v[0:3], v[152:155], v[210:213], v[0:3]
	v_mfma_f32_16x16x32_bf16 v[52:55], v[148:151], v[180:183], v[52:55]
	v_mfma_f32_16x16x32_bf16 v[48:51], v[172:175], v[180:183], v[48:51]
	v_mfma_f32_16x16x32_bf16 v[36:39], v[148:151], v[188:191], v[36:39]
	v_mfma_f32_16x16x32_bf16 v[32:35], v[172:175], v[188:191], v[32:35]
	v_mfma_f32_16x16x32_bf16 v[20:23], v[148:151], v[206:209], v[20:23]
	v_mfma_f32_16x16x32_bf16 v[16:19], v[172:175], v[206:209], v[16:19]
	v_mfma_f32_16x16x32_bf16 v[4:7], v[148:151], v[214:217], v[4:7]
	v_mfma_f32_16x16x32_bf16 v[0:3], v[172:175], v[214:217], v[0:3]
	s_setprio 0
	s_barrier
	s_add_i32 s74, 0, 0x18000
	s_add_i32 s75, 0, 0x1c000
	v_add_u32_e32 v112, s74, v195
	v_add_u32_e32 v172, s75, v195
	ds_read_b128 v[96:99], v112
	ds_read_b128 v[100:103], v112 offset:1024
	ds_read_b128 v[104:107], v112 offset:2048
	ds_read_b128 v[112:115], v112 offset:3072
	ds_read_b128 v[144:147], v172
	ds_read_b128 v[148:151], v172 offset:1024
	ds_read_b128 v[152:155], v172 offset:2048
	ds_read_b128 v[172:175], v172 offset:3072
	s_add_u32 s52, s52, 0x200000
	s_addc_u32 s53, s53, 0
	s_mov_b32 m0, s58

; #define PG8_STAGE(bufoff, gbase, voff) do { _Pragma("unroll") for (int _i = 0; _i < 2; ++_i) \
;         __builtin_amdgcn_global_load_lds((const unsigned*)((const char*)(gbase) + (voff)[_i]), (PG8_LAS unsigned*)(lds + (bufoff) + ldsw + _i * 8192), 16, 0, 0); } while (0)
; #define PG8_LDA(dst, b, h) do { _Pragma("unroll") for (int m = 0; m < 4; ++m) _Pragma("unroll") for (int k = 0; k < 2; ++k) dst[m][k] = *(const PG8_LAS bf16x8*)(lds + PG8_SA(b, h) + aoff + m * 2048 + k * 1024); } while (0)
; #define PG8_LDB(dst, b, h) do { _Pragma("unroll") for (int n = 0; n < 2; ++n) _Pragma("unroll") for (int k = 0; k < 2; ++k) dst[n][k] = *(const PG8_LAS bf16x8*)(lds + PG8_SB(b, h) + boff + n * 2048 + k * 1024); } while (0)
; #define PG8_SCHED __builtin_amdgcn_sched_barrier(0)
; template <class Epi, class Sched, bool ALIGN_EPI = false, bool SP2 = false>
; __device__ __forceinline__ void gemm_phase(PG8_LAS unsigned char* lds, const Gemm g, const Sched& S, const Epi& E) {
;     ...
;             PG8_LDB(B0, 1, 0); PG8_LDB(B1, 1, 1); PG8_SCHED; PG8_LDA(At, 1, 0); PG8_STAGE(PG8_SA(0, 1), a2 + hstep, voffA);
	ds_read_b128 v[176:179], v199 offset:32768
	ds_read_b128 v[180:183], v199 offset:33792
	ds_read_b128 v[184:187], v199 offset:34816
	ds_read_b128 v[188:191], v199 offset:35840
	ds_read_b128 v[202:205], v199 offset:36864
	ds_read_b128 v[206:209], v199 offset:37888
	ds_read_b128 v[210:213], v199 offset:38912
	ds_read_b128 v[214:217], v199 offset:39936
	global_load_lds_dwordx4 v156, s[52:53]

; #define PG8_STAGE(bufoff, gbase, voff) do { _Pragma("unroll") for (int _i = 0; _i < 2; ++_i) \
;         __builtin_amdgcn_global_load_lds((const unsigned*)((const char*)(gbase) + (voff)[_i]), (PG8_LAS unsigned*)(lds + (bufoff) + ldsw + _i * 8192), 16, 0, 0); } while (0)
; #define PG8_LDA(dst, b, h) do { _Pragma("unroll") for (int m = 0; m < 4; ++m) _Pragma("unroll") for (int k = 0; k < 2; ++k) dst[m][k] = *(const PG8_LAS bf16x8*)(lds + PG8_SA(b, h) + aoff + m * 2048 + k * 1024); } while (0)
; #define PG8_LDB(dst, b, h) do { _Pragma("unroll") for (int n = 0; n < 2; ++n) _Pragma("unroll") for (int k = 0; k < 2; ++k) dst[n][k] = *(const PG8_LAS bf16x8*)(lds + PG8_SB(b, h) + boff + n * 2048 + k * 1024); } while (0)
; #define PG8_MMA(ai, bj, At, Bt) do { __builtin_amdgcn_s_setprio(1); _Pragma("unroll") for (int m = 0; m < 4; ++m) _Pragma("unroll") for (int n = 0; n < 2; ++n) _Pragma("unroll") for (int k = 0; k < 2; ++k) \
;         acc[ai][bj][m][n] = __builtin_amdgcn_mfma_f32_16x16x32_bf16(Bt[n][k], At[m][k], acc[ai][bj][m][n], 0, 0, 0); __builtin_amdgcn_s_setprio(0); } while (0)
; #define PG8_WAIT_V(n) asm volatile("s_waitcnt vmcnt(" #n ")" ::: "memory")
; #define PG8_WAIT_L(n) asm volatile("s_waitcnt lgkmcnt(" #n ")" ::: "memory")
; #define PG8_BAR __builtin_amdgcn_s_barrier()
; #define PG8_SCHED __builtin_amdgcn_sched_barrier(0)
; template <class Epi, class Sched, bool ALIGN_EPI = false, bool SP2 = false>
; __device__ __forceinline__ void gemm_phase(PG8_LAS unsigned char* lds, const Gemm g, const Sched& S, const Epi& E) {
;     ...
;             PG8_LDB(B0, 1, 0); PG8_LDB(B1, 1, 1); PG8_SCHED; PG8_LDA(At, 1, 0); PG8_STAGE(PG8_SA(0, 1), a2 + hstep, voffA);
;             PG8_WAIT_V(8); PG8_WAIT_L(0); PG8_BAR; PG8_MMA(0, 0, At, B0); PG8_MMA(0, 1, At, B1); PG8_BAR; PG8_SCHED;
	s_mov_b32 m0, s59
	s_nop 0
	global_load_lds_dwordx4 v160, s[52:53]
	s_waitcnt vmcnt(8)
	s_waitcnt lgkmcnt(0)
	s_barrier
	s_setprio 1
	s_waitcnt lgkmcnt(0)
	v_mfma_f32_16x16x32_bf16 v[140:143], v[96:99], v[176:179], v[140:143]
	v_mfma_f32_16x16x32_bf16 v[136:139], v[104:107], v[176:179], v[136:139]
	v_mfma_f32_16x16x32_bf16 v[124:127], v[96:99], v[184:187], v[124:127]
	v_mfma_f32_16x16x32_bf16 v[120:123], v[104:107], v[184:187], v[120:123]
	v_mfma_f32_16x16x32_bf16 v[92:95], v[96:99], v[202:205], v[92:95]
	v_mfma_f32_16x16x32_bf16 v[88:91], v[104:107], v[202:205], v[88:91]
	v_mfma_f32_16x16x32_bf16 v[76:79], v[96:99], v[210:213], v[76:79]
	v_mfma_f32_16x16x32_bf16 v[72:75], v[104:107], v[210:213], v[72:75]
	v_mfma_f32_16x16x32_bf16 v[140:143], v[100:103], v[180:183], v[140:143]
	v_mfma_f32_16x16x32_bf16 v[136:139], v[112:115], v[180:183], v[136:139]
	v_mfma_f32_16x16x32_bf16 v[124:127], v[100:103], v[188:191], v[124:127]
	v_mfma_f32_16x16x32_bf16 v[120:123], v[112:115], v[188:191], v[120:123]
	v_mfma_f32_16x16x32_bf16 v[92:95], v[100:103], v[206:209], v[92:95]
	v_mfma_f32_16x16x32_bf16 v[88:91], v[112:115], v[206:209], v[88:91]
	v_mfma_f32_16x16x32_bf16 v[76:79], v[100:103], v[214:217], v[76:79]
	v_mfma_f32_16x16x32_bf16 v[72:75], v[112:115], v[214:217], v[72:75]


; #define PG8_MMA(ai, bj, At, Bt) do { __builtin_amdgcn_s_setprio(1); _Pragma("unroll") for (int m = 0; m < 4; ++m) _Pragma("unroll") for (int n = 0; n < 2; ++n) _Pragma("unroll") for (int k = 0; k < 2; ++k) \
;         acc[ai][bj][m][n] = __builtin_amdgcn_mfma_f32_16x16x32_bf16(Bt[n][k], At[m][k], acc[ai][bj][m][n], 0, 0, 0); __builtin_amdgcn_s_setprio(0); } while (0)
; #define PG8_WAIT_V(n) asm volatile("s_waitcnt vmcnt(" #n ")" ::: "memory")
; #define PG8_WAIT_L(n) asm volatile("s_waitcnt lgkmcnt(" #n ")" ::: "memory")
; #define PG8_BAR __builtin_amdgcn_s_barrier()
; #define PG8_SCHED __builtin_amdgcn_sched_barrier(0)
; template <class Epi, class Sched, bool ALIGN_EPI = false, bool SP2 = false>
; __device__ __forceinline__ void gemm_phase(PG8_LAS unsigned char* lds, const Gemm g, const Sched& S, const Epi& E) {
;     ...
;             PG8_WAIT_V(8); PG8_WAIT_L(0); PG8_BAR; PG8_MMA(0, 0, At, B0); PG8_MMA(0, 1, At, B1); PG8_BAR; PG8_SCHED;
	v_mfma_f32_16x16x32_bf16 v[132:135], v[144:147], v[176:179], v[132:135]
	v_mfma_f32_16x16x32_bf16 v[128:131], v[152:155], v[176:179], v[128:131]
	v_mfma_f32_16x16x32_bf16 v[116:119], v[144:147], v[184:187], v[116:119]
	v_mfma_f32_16x16x32_bf16 v[108:111], v[152:155], v[184:187], v[108:111]
	v_mfma_f32_16x16x32_bf16 v[84:87], v[144:147], v[202:205], v[84:87]
	v_mfma_f32_16x16x32_bf16 v[80:83], v[152:155], v[202:205], v[80:83]
	v_mfma_f32_16x16x32_bf16 v[68:71], v[144:147], v[210:213], v[68:71]
	v_mfma_f32_16x16x32_bf16 v[64:67], v[152:155], v[210:213], v[64:67]
	v_mfma_f32_16x16x32_bf16 v[132:135], v[148:151], v[180:183], v[132:135]
	v_mfma_f32_16x16x32_bf16 v[128:131], v[172:175], v[180:183], v[128:131]
	v_mfma_f32_16x16x32_bf16 v[116:119], v[148:151], v[188:191], v[116:119]
	v_mfma_f32_16x16x32_bf16 v[108:111], v[172:175], v[188:191], v[108:111]
	v_mfma_f32_16x16x32_bf16 v[84:87], v[148:151], v[206:209], v[84:87]
	v_mfma_f32_16x16x32_bf16 v[80:83], v[172:175], v[206:209], v[80:83]
	v_mfma_f32_16x16x32_bf16 v[68:71], v[148:151], v[214:217], v[68:71]
	v_mfma_f32_16x16x32_bf16 v[64:67], v[172:175], v[214:217], v[64:67]
	s_setprio 0
	s_barrier
	s_add_i32 s52, s74, s55

; #define PG8_STAGE(bufoff, gbase, voff) do { _Pragma("unroll") for (int _i = 0; _i < 2; ++_i) \
;         __builtin_amdgcn_global_load_lds((const unsigned*)((const char*)(gbase) + (voff)[_i]), (PG8_LAS unsigned*)(lds + (bufoff) + ldsw + _i * 8192), 16, 0, 0); } while (0)
; #define PG8_LDA(dst, b, h) do { _Pragma("unroll") for (int m = 0; m < 4; ++m) _Pragma("unroll") for (int k = 0; k < 2; ++k) dst[m][k] = *(const PG8_LAS bf16x8*)(lds + PG8_SA(b, h) + aoff + m * 2048 + k * 1024); } while (0)
; template <class Epi, class Sched, bool ALIGN_EPI = false, bool SP2 = false>
; __device__ __forceinline__ void gemm_phase(PG8_LAS unsigned char* lds, const Gemm g, const Sched& S, const Epi& E) {
;     ...
;             PG8_LDA(At, 1, 1); PG8_STAGE(PG8_SB(1, 0), b3, voffB); PG8_STAGE(PG8_SB(1, 1), b3 + hstep, voffB); PG8_STAGE(PG8_SA(1, 0), a3, voffA);
	s_mov_b32 m0, s52
	ds_read_b128 v[176:179], v199 offset:49152
	ds_read_b128 v[180:183], v199 offset:50176
	ds_read_b128 v[184:187], v199 offset:51200
	ds_read_b128 v[188:191], v199 offset:52224
	ds_read_b128 v[202:205], v199 offset:53248
	ds_read_b128 v[206:209], v199 offset:54272
	ds_read_b128 v[210:213], v199 offset:55296
	ds_read_b128 v[214:217], v199 offset:56320
	global_load_lds_dwordx4 v250, s[96:97]
	s_add_i32 m0, s52, 0x2000
	s_add_u32 s50, s50, 0x200080

; #define PG8_STAGE(bufoff, gbase, voff) do { _Pragma("unroll") for (int _i = 0; _i < 2; ++_i) \
;         __builtin_amdgcn_global_load_lds((const unsigned*)((const char*)(gbase) + (voff)[_i]), (PG8_LAS unsigned*)(lds + (bufoff) + ldsw + _i * 8192), 16, 0, 0); } while (0)
; #define PG8_LDA(dst, b, h) do { _Pragma("unroll") for (int m = 0; m < 4; ++m) _Pragma("unroll") for (int k = 0; k < 2; ++k) dst[m][k] = *(const PG8_LAS bf16x8*)(lds + PG8_SA(b, h) + aoff + m * 2048 + k * 1024); } while (0)
; template <class Epi, class Sched, bool ALIGN_EPI = false, bool SP2 = false>
; __device__ __forceinline__ void gemm_phase(PG8_LAS unsigned char* lds, const Gemm g, const Sched& S, const Epi& E) {
;     ...
;             PG8_LDA(At, 1, 1); PG8_STAGE(PG8_SB(1, 0), b3, voffB); PG8_STAGE(PG8_SB(1, 1), b3 + hstep, voffB); PG8_STAGE(PG8_SA(1, 0), a3, voffA);
	s_addc_u32 s51, s51, 0
	s_add_i32 s52, s75, s55
	global_load_lds_dwordx4 v251, s[96:97]

; #define PG8_STAGE(bufoff, gbase, voff) do { _Pragma("unroll") for (int _i = 0; _i < 2; ++_i) \
;         __builtin_amdgcn_global_load_lds((const unsigned*)((const char*)(gbase) + (voff)[_i]), (PG8_LAS unsigned*)(lds + (bufoff) + ldsw + _i * 8192), 16, 0, 0); } while (0)
; #define PG8_LDA(dst, b, h) do { _Pragma("unroll") for (int m = 0; m < 4; ++m) _Pragma("unroll") for (int k = 0; k < 2; ++k) dst[m][k] = *(const PG8_LAS bf16x8*)(lds + PG8_SA(b, h) + aoff + m * 2048 + k * 1024); } while (0)
; template <class Epi, class Sched, bool ALIGN_EPI = false, bool SP2 = false>
; __device__ __forceinline__ void gemm_phase(PG8_LAS unsigned char* lds, const Gemm g, const Sched& S, const Epi& E) {
;     ...
;             PG8_LDA(At, 1, 1); PG8_STAGE(PG8_SB(1, 0), b3, voffB); PG8_STAGE(PG8_SB(1, 1), b3 + hstep, voffB); PG8_STAGE(PG8_SA(1, 0), a3, voffA);
	s_mov_b32 m0, s52
	s_nop 0
	global_load_lds_dwordx4 v158, s[50:51]

; #define PG8_STAGE(bufoff, gbase, voff) do { _Pragma("unroll") for (int _i = 0; _i < 2; ++_i) \
;         __builtin_amdgcn_global_load_lds((const unsigned*)((const char*)(gbase) + (voff)[_i]), (PG8_LAS unsigned*)(lds + (bufoff) + ldsw + _i * 8192), 16, 0, 0); } while (0)
; #define PG8_LDA(dst, b, h) do { _Pragma("unroll") for (int m = 0; m < 4; ++m) _Pragma("unroll") for (int k = 0; k < 2; ++k) dst[m][k] = *(const PG8_LAS bf16x8*)(lds + PG8_SA(b, h) + aoff + m * 2048 + k * 1024); } while (0)
; template <class Epi, class Sched, bool ALIGN_EPI = false, bool SP2 = false>
; __device__ __forceinline__ void gemm_phase(PG8_LAS unsigned char* lds, const Gemm g, const Sched& S, const Epi& E) {
;     ...
;             PG8_LDA(At, 1, 1); PG8_STAGE(PG8_SB(1, 0), b3, voffB); PG8_STAGE(PG8_SB(1, 1), b3 + hstep, voffB); PG8_STAGE(PG8_SA(1, 0), a3, voffA);
	s_add_i32 m0, s52, 0x2000
	s_nop 0
	global_load_lds_dwordx4 v162, s[50:51]

; #define PG8_STAGE(bufoff, gbase, voff) do { _Pragma("unroll") for (int _i = 0; _i < 2; ++_i) \
;         __builtin_amdgcn_global_load_lds((const unsigned*)((const char*)(gbase) + (voff)[_i]), (PG8_LAS unsigned*)(lds + (bufoff) + ldsw + _i * 8192), 16, 0, 0); } while (0)
; #define PG8_LDA(dst, b, h) do { _Pragma("unroll") for (int m = 0; m < 4; ++m) _Pragma("unroll") for (int k = 0; k < 2; ++k) dst[m][k] = *(const PG8_LAS bf16x8*)(lds + PG8_SA(b, h) + aoff + m * 2048 + k * 1024); } while (0)
; template <class Epi, class Sched, bool ALIGN_EPI = false, bool SP2 = false>
; __device__ __forceinline__ void gemm_phase(PG8_LAS unsigned char* lds, const Gemm g, const Sched& S, const Epi& E) {
;     ...
;             PG8_LDA(At, 1, 1); PG8_STAGE(PG8_SB(1, 0), b3, voffB); PG8_STAGE(PG8_SB(1, 1), b3 + hstep, voffB); PG8_STAGE(PG8_SA(1, 0), a3, voffA);
	s_mov_b32 m0, s61
	s_nop 0
	global_load_lds_dwordx4 v252, s[98:99]

; #define PG8_STAGE(bufoff, gbase, voff) do { _Pragma("unroll") for (int _i = 0; _i < 2; ++_i) \
;         __builtin_amdgcn_global_load_lds((const unsigned*)((const char*)(gbase) + (voff)[_i]), (PG8_LAS unsigned*)(lds + (bufoff) + ldsw + _i * 8192), 16, 0, 0); } while (0)
; #define PG8_LDA(dst, b, h) do { _Pragma("unroll") for (int m = 0; m < 4; ++m) _Pragma("unroll") for (int k = 0; k < 2; ++k) dst[m][k] = *(const PG8_LAS bf16x8*)(lds + PG8_SA(b, h) + aoff + m * 2048 + k * 1024); } while (0)
; #define PG8_MMA(ai, bj, At, Bt) do { __builtin_amdgcn_s_setprio(1); _Pragma("unroll") for (int m = 0; m < 4; ++m) _Pragma("unroll") for (int n = 0; n < 2; ++n) _Pragma("unroll") for (int k = 0; k < 2; ++k) \
;         acc[ai][bj][m][n] = __builtin_amdgcn_mfma_f32_16x16x32_bf16(Bt[n][k], At[m][k], acc[ai][bj][m][n], 0, 0, 0); __builtin_amdgcn_s_setprio(0); } while (0)
; #define PG8_WAIT_V(n) asm volatile("s_waitcnt vmcnt(" #n ")" ::: "memory")
; #define PG8_WAIT_L(n) asm volatile("s_waitcnt lgkmcnt(" #n ")" ::: "memory")
; #define PG8_BAR __builtin_amdgcn_s_barrier()
; #define PG8_SCHED __builtin_amdgcn_sched_barrier(0)
; template <class Epi, class Sched, bool ALIGN_EPI = false, bool SP2 = false>
; __device__ __forceinline__ void gemm_phase(PG8_LAS unsigned char* lds, const Gemm g, const Sched& S, const Epi& E) {
;     ...
;             PG8_LDA(At, 1, 1); PG8_STAGE(PG8_SB(1, 0), b3, voffB); PG8_STAGE(PG8_SB(1, 1), b3 + hstep, voffB); PG8_STAGE(PG8_SA(1, 0), a3, voffA);
;             PG8_WAIT_V(8); PG8_WAIT_L(0); PG8_BAR; PG8_MMA(1, 0, At, B0); PG8_MMA(1, 1, At, B1); PG8_BAR; PG8_SCHED;
	s_mov_b32 m0, s62
	s_nop 0
	global_load_lds_dwordx4 v253, s[98:99]
	s_waitcnt vmcnt(8)
	s_waitcnt lgkmcnt(0)
	s_barrier
	s_setprio 1
	s_waitcnt lgkmcnt(0)
	v_mfma_f32_16x16x32_bf16 v[60:63], v[96:99], v[176:179], v[60:63]
	v_mfma_f32_16x16x32_bf16 v[56:59], v[104:107], v[176:179], v[56:59]
	v_mfma_f32_16x16x32_bf16 v[44:47], v[96:99], v[184:187], v[44:47]
	v_mfma_f32_16x16x32_bf16 v[40:43], v[104:107], v[184:187], v[40:43]
	v_mfma_f32_16x16x32_bf16 v[28:31], v[96:99], v[202:205], v[28:31]
	v_mfma_f32_16x16x32_bf16 v[24:27], v[104:107], v[202:205], v[24:27]
	v_mfma_f32_16x16x32_bf16 v[12:15], v[96:99], v[210:213], v[12:15]
	v_mfma_f32_16x16x32_bf16 v[8:11], v[104:107], v[210:213], v[8:11]
	v_mfma_f32_16x16x32_bf16 v[60:63], v[100:103], v[180:183], v[60:63]
	v_mfma_f32_16x16x32_bf16 v[56:59], v[112:115], v[180:183], v[56:59]
	v_mfma_f32_16x16x32_bf16 v[44:47], v[100:103], v[188:191], v[44:47]
	v_mfma_f32_16x16x32_bf16 v[40:43], v[112:115], v[188:191], v[40:43]
	v_mfma_f32_16x16x32_bf16 v[28:31], v[100:103], v[206:209], v[28:31]
	v_mfma_f32_16x16x32_bf16 v[24:27], v[112:115], v[206:209], v[24:27]
	v_mfma_f32_16x16x32_bf16 v[12:15], v[100:103], v[214:217], v[12:15]
	v_mfma_f32_16x16x32_bf16 v[8:11], v[112:115], v[214:217], v[8:11]


; #define PG8_MMA(ai, bj, At, Bt) do { __builtin_amdgcn_s_setprio(1); _Pragma("unroll") for (int m = 0; m < 4; ++m) _Pragma("unroll") for (int n = 0; n < 2; ++n) _Pragma("unroll") for (int k = 0; k < 2; ++k) \
;         acc[ai][bj][m][n] = __builtin_amdgcn_mfma_f32_16x16x32_bf16(Bt[n][k], At[m][k], acc[ai][bj][m][n], 0, 0, 0); __builtin_amdgcn_s_setprio(0); } while (0)
; #define PG8_WAIT_V(n) asm volatile("s_waitcnt vmcnt(" #n ")" ::: "memory")
; #define PG8_WAIT_L(n) asm volatile("s_waitcnt lgkmcnt(" #n ")" ::: "memory")
; #define PG8_BAR __builtin_amdgcn_s_barrier()
; #define PG8_SCHED __builtin_amdgcn_sched_barrier(0)
; template <class Epi, class Sched, bool ALIGN_EPI = false, bool SP2 = false>
; __device__ __forceinline__ void gemm_phase(PG8_LAS unsigned char* lds, const Gemm g, const Sched& S, const Epi& E) {
;     ...
;             PG8_WAIT_V(8); PG8_WAIT_L(0); PG8_BAR; PG8_MMA(1, 0, At, B0); PG8_MMA(1, 1, At, B1); PG8_BAR; PG8_SCHED;
	v_mfma_f32_16x16x32_bf16 v[52:55], v[144:147], v[176:179], v[52:55]
	v_mfma_f32_16x16x32_bf16 v[48:51], v[152:155], v[176:179], v[48:51]
	v_mfma_f32_16x16x32_bf16 v[36:39], v[144:147], v[184:187], v[36:39]
	v_mfma_f32_16x16x32_bf16 v[32:35], v[152:155], v[184:187], v[32:35]
	v_mfma_f32_16x16x32_bf16 v[20:23], v[144:147], v[202:205], v[20:23]
	v_mfma_f32_16x16x32_bf16 v[16:19], v[152:155], v[202:205], v[16:19]
	v_mfma_f32_16x16x32_bf16 v[4:7], v[144:147], v[210:213], v[4:7]
	v_mfma_f32_16x16x32_bf16 v[0:3], v[152:155], v[210:213], v[0:3]
	v_mfma_f32_16x16x32_bf16 v[52:55], v[148:151], v[180:183], v[52:55]
	v_mfma_f32_16x16x32_bf16 v[48:51], v[172:175], v[180:183], v[48:51]
	v_mfma_f32_16x16x32_bf16 v[36:39], v[148:151], v[188:191], v[36:39]
	v_mfma_f32_16x16x32_bf16 v[32:35], v[172:175], v[188:191], v[32:35]
	v_mfma_f32_16x16x32_bf16 v[20:23], v[148:151], v[206:209], v[20:23]
	v_mfma_f32_16x16x32_bf16 v[16:19], v[172:175], v[206:209], v[16:19]
	v_mfma_f32_16x16x32_bf16 v[4:7], v[148:151], v[214:217], v[4:7]
	v_mfma_f32_16x16x32_bf16 v[0:3], v[172:175], v[214:217], v[0:3]
	s_setprio 0
	s_barrier
	s_add_i32 s73, s73, 2
	s_add_u32 s48, s48, 0x100
	s_addc_u32 s49, s49, 0
	s_add_u32 s71, s71, 0x100
	s_addc_u32 s72, s72, 0
	s_cmpk_gt_u32 s73, 0x7d
	s_cbranch_scc0 .LBB0_1114
	s_and_b64 vcc, exec, s[34:35]
	s_cbranch_vccz .LBB0_1117
	s_barrier
